# g3 plus eligible GEMM LDS-DMA loads switched to SGPR-base + 32-bit VGPR offset form (drops 64-bit VALU address adds)
# speedup vs baseline: 1.0068x; 1.0011x over previous
; #define PG8_STAGE(bufoff, gbase, voff) do { _Pragma("unroll") for (int _i = 0; _i < 2; ++_i) \
;         __builtin_amdgcn_global_load_lds((const unsigned*)((const char*)(gbase) + (voff)[_i]), (LAS unsigned*)(lds + (bufoff) + ldsw + _i * 8192), 16, 0, 0); } while (0)
; #define PG8_LDA(dst, b, h) do { _Pragma("unroll") for (int m = 0; m < 4; ++m) _Pragma("unroll") for (int k = 0; k < 2; ++k) dst[m][k] = *(const LAS bf16x8*)(lds + PG8_SA(b, h) + aoff + m * 2048 + k * 1024); } while (0)
; #define PG8_LDB(dst, b, h) do { _Pragma("unroll") for (int n = 0; n < 2; ++n) _Pragma("unroll") for (int k = 0; k < 2; ++k) dst[n][k] = *(const LAS bf16x8*)(lds + PG8_SB(b, h) + boff + n * 2048 + k * 1024); } while (0)
; #define PG8_MMA(ai, bj, At, Bt) do { __builtin_amdgcn_s_setprio(1); _Pragma("unroll") for (int m = 0; m < 4; ++m) _Pragma("unroll") for (int n = 0; n < 2; ++n) _Pragma("unroll") for (int k = 0; k < 2; ++k) \
;         acc[ai][bj][m][n] = __builtin_amdgcn_mfma_f32_16x16x32_bf16(Bt[n][k], At[m][k], acc[ai][bj][m][n], 0, 0, 0); __builtin_amdgcn_s_setprio(0); } while (0)
; #define PG8_WAIT_V(n) asm volatile("s_waitcnt vmcnt(" #n ")" ::: "memory")
; #define PG8_WAIT_L(n) asm volatile("s_waitcnt lgkmcnt(" #n ")" ::: "memory")
; #define PG8_BAR __builtin_amdgcn_s_barrier()
; template <class Epi>
; __device__ __forceinline__ void gemm_phase(LAS unsigned char* lds, const Gemm g, const StaticOrder& S, const Epi& E) {
;     ...
;             const bool last = (t == nt - 2);
;             const char* a1 = cA + (size_t)(t + 1) * kstep;
;             const char* a2 = last ? nA : cA + (size_t)(t + 2) * kstep; const char* b2 = last ? nB : cB + (size_t)(t + 2) * kstep;
;             const char* a3 = a2 + kstep; const char* b3 = b2 + kstep;
;             PG8_LDB(B0, 0, 0); PG8_SCHED; PG8_LDA(At, 0, 0); PG8_STAGE(PG8_SA(1, 1), a1 + hA, voffA);
;             PG8_WAIT_L(8); PG8_BAR; PG8_WAIT_L(0); PG8_MMA(0, 0, At, B0); PG8_BAR; PG8_SCHED;
;             PG8_LDB(B1, 0, 1); PG8_STAGE(PG8_SB(0, 0), b2, voffB);
;             PG8_BAR; PG8_WAIT_L(0); PG8_MMA(0, 1, At, B1); PG8_BAR;
;             PG8_LDA(At, 0, 1); PG8_STAGE(PG8_SA(0, 0), a2, voffA);
;             PG8_BAR; PG8_WAIT_L(0); PG8_MMA(1, 0, At, B0); PG8_BAR; PG8_SCHED;
;             PG8_STAGE(PG8_SB(0, 1), b2 + hB, voffB);
;             PG8_WAIT_V(6); PG8_BAR; PG8_MMA(1, 1, At, B1); PG8_BAR;
.LBB0_281:
	s_add_u32 s16, s12, 0xfffc0080
	s_addc_u32 s17, s13, -1
	s_add_i32 s26, 0, 0x10000
	v_add_u32_e32 v139, s26, v137
	ds_read_b128 v[140:143], v139
	ds_read_b128 v[146:149], v139 offset:1024
	ds_read_b128 v[150:153], v139 offset:2048
	ds_read_b128 v[154:157], v139 offset:3072
	s_cmp_eq_u32 s78, 12
	s_cselect_b32 s21, s72, s17
	s_cselect_b32 s20, s76, s16
	s_cselect_b32 s17, s7, s77
	s_cselect_b32 s16, s24, s25
	s_add_i32 m0, s61, 0xc000
	ds_read_b128 v[158:161], v138
	ds_read_b128 v[162:165], v138 offset:1024
	ds_read_b128 v[166:169], v138 offset:2048
	ds_read_b128 v[170:173], v138 offset:3072
	ds_read_b128 v[174:177], v138 offset:4096
	ds_read_b128 v[178:181], v138 offset:5120
	ds_read_b128 v[182:185], v138 offset:6144
	ds_read_b128 v[196:199], v138 offset:7168
	global_load_lds_dwordx4 v132, s[12:13]
	s_add_i32 m0, s61, 0xe000
	s_nop 0
	global_load_lds_dwordx4 v134, s[12:13]
	s_waitcnt lgkmcnt(8)
	s_barrier
	s_waitcnt lgkmcnt(0)
	v_mfma_f32_16x16x32_bf16 v[120:123], v[140:143], v[158:161], v[120:123]
	v_mfma_f32_16x16x32_bf16 v[124:127], v[150:153], v[158:161], v[124:127]
	v_mfma_f32_16x16x32_bf16 v[104:107], v[140:143], v[166:169], v[104:107]
	v_mfma_f32_16x16x32_bf16 v[108:111], v[150:153], v[166:169], v[108:111]
	v_mfma_f32_16x16x32_bf16 v[88:91], v[140:143], v[174:177], v[88:91]
	v_mfma_f32_16x16x32_bf16 v[92:95], v[150:153], v[174:177], v[92:95]
	v_mfma_f32_16x16x32_bf16 v[72:75], v[140:143], v[182:185], v[72:75]
	v_mfma_f32_16x16x32_bf16 v[76:79], v[150:153], v[182:185], v[76:79]
	v_mfma_f32_16x16x32_bf16 v[120:123], v[146:149], v[162:165], v[120:123]
	v_mfma_f32_16x16x32_bf16 v[124:127], v[154:157], v[162:165], v[124:127]
	v_mfma_f32_16x16x32_bf16 v[104:107], v[146:149], v[170:173], v[104:107]
	v_mfma_f32_16x16x32_bf16 v[108:111], v[154:157], v[170:173], v[108:111]
	v_mfma_f32_16x16x32_bf16 v[88:91], v[146:149], v[178:181], v[88:91]
	v_mfma_f32_16x16x32_bf16 v[92:95], v[154:157], v[178:181], v[92:95]
	v_mfma_f32_16x16x32_bf16 v[72:75], v[146:149], v[196:199], v[72:75]
	v_mfma_f32_16x16x32_bf16 v[76:79], v[154:157], v[196:199], v[76:79]
	s_barrier
	s_add_i32 s28, 0, 0x14000
	s_add_i32 s26, s26, s35
	v_add_u32_e32 v139, s28, v137
	v_lshl_add_u64 v[186:187], s[16:17], 0, v[130:131]
	s_mov_b32 m0, s26
	ds_read_b128 v[200:203], v139
	ds_read_b128 v[204:207], v139 offset:1024
	ds_read_b128 v[214:217], v139 offset:2048
	ds_read_b128 v[218:221], v139 offset:3072
	global_load_lds_dwordx4 v[186:187], off
	s_add_i32 m0, s26, 0x2000
	v_lshl_add_u64 v[188:189], s[16:17], 0, v[128:129]
	global_load_lds_dwordx4 v[188:189], off
	s_barrier
	s_waitcnt lgkmcnt(0)
	v_mfma_f32_16x16x32_bf16 v[112:115], v[200:203], v[158:161], v[112:115]
	v_mfma_f32_16x16x32_bf16 v[116:119], v[214:217], v[158:161], v[116:119]
	v_mfma_f32_16x16x32_bf16 v[96:99], v[200:203], v[166:169], v[96:99]
	v_mfma_f32_16x16x32_bf16 v[100:103], v[214:217], v[166:169], v[100:103]
	v_mfma_f32_16x16x32_bf16 v[80:83], v[200:203], v[174:177], v[80:83]
	v_mfma_f32_16x16x32_bf16 v[84:87], v[214:217], v[174:177], v[84:87]
	v_mfma_f32_16x16x32_bf16 v[64:67], v[200:203], v[182:185], v[64:67]
	v_mfma_f32_16x16x32_bf16 v[68:71], v[214:217], v[182:185], v[68:71]
	v_mfma_f32_16x16x32_bf16 v[112:115], v[204:207], v[162:165], v[112:115]
	v_mfma_f32_16x16x32_bf16 v[116:119], v[218:221], v[162:165], v[116:119]
	v_mfma_f32_16x16x32_bf16 v[96:99], v[204:207], v[170:173], v[96:99]
	v_mfma_f32_16x16x32_bf16 v[100:103], v[218:221], v[170:173], v[100:103]
	v_mfma_f32_16x16x32_bf16 v[80:83], v[204:207], v[178:181], v[80:83]
	v_mfma_f32_16x16x32_bf16 v[84:87], v[218:221], v[178:181], v[84:87]
	v_mfma_f32_16x16x32_bf16 v[64:67], v[204:207], v[196:199], v[64:67]
	v_mfma_f32_16x16x32_bf16 v[68:71], v[218:221], v[196:199], v[68:71]
	s_mov_b32 m0, s61
	v_lshl_add_u64 v[192:193], s[20:21], 0, v[130:131]
	s_barrier
	ds_read_b128 v[158:161], v138 offset:16384
	ds_read_b128 v[162:165], v138 offset:17408
	ds_read_b128 v[166:169], v138 offset:18432
	ds_read_b128 v[170:173], v138 offset:19456
	ds_read_b128 v[174:177], v138 offset:20480
	ds_read_b128 v[178:181], v138 offset:21504
	ds_read_b128 v[182:185], v138 offset:22528
	ds_read_b128 v[196:199], v138 offset:23552
	global_load_lds_dwordx4 v[192:193], off
	s_mov_b32 m0, s62
	v_lshl_add_u64 v[222:223], s[20:21], 0, v[128:129]
	global_load_lds_dwordx4 v[222:223], off
	s_barrier
	s_waitcnt lgkmcnt(0)
	v_mfma_f32_16x16x32_bf16 v[56:59], v[140:143], v[158:161], v[56:59]
	v_mfma_f32_16x16x32_bf16 v[60:63], v[150:153], v[158:161], v[60:63]
	v_mfma_f32_16x16x32_bf16 v[40:43], v[140:143], v[166:169], v[40:43]
	v_mfma_f32_16x16x32_bf16 v[44:47], v[150:153], v[166:169], v[44:47]
	v_mfma_f32_16x16x32_bf16 v[24:27], v[140:143], v[174:177], v[24:27]
	v_mfma_f32_16x16x32_bf16 v[28:31], v[150:153], v[174:177], v[28:31]
	v_mfma_f32_16x16x32_bf16 v[8:11], v[140:143], v[182:185], v[8:11]
	v_mfma_f32_16x16x32_bf16 v[12:15], v[150:153], v[182:185], v[12:15]
	v_mfma_f32_16x16x32_bf16 v[56:59], v[146:149], v[162:165], v[56:59]
	v_mfma_f32_16x16x32_bf16 v[60:63], v[154:157], v[162:165], v[60:63]
	v_mfma_f32_16x16x32_bf16 v[40:43], v[146:149], v[170:173], v[40:43]
	v_mfma_f32_16x16x32_bf16 v[44:47], v[154:157], v[170:173], v[44:47]
	v_mfma_f32_16x16x32_bf16 v[24:27], v[146:149], v[178:181], v[24:27]
	v_mfma_f32_16x16x32_bf16 v[28:31], v[154:157], v[178:181], v[28:31]
	v_mfma_f32_16x16x32_bf16 v[8:11], v[146:149], v[196:199], v[8:11]
	v_mfma_f32_16x16x32_bf16 v[12:15], v[154:157], v[196:199], v[12:15]
	s_barrier
	s_add_u32 s26, s16, 0x40000
	s_addc_u32 s27, s17, 0
	s_add_i32 s28, s28, s35
	s_mov_b32 m0, s28
	s_nop 0
	global_load_lds_dwordx4 v130, s[26:27]
	s_add_i32 m0, s28, 0x2000
	s_nop 0
	global_load_lds_dwordx4 v128, s[26:27]
	s_waitcnt vmcnt(6)
	s_barrier
; #define PG8_STAGE(bufoff, gbase, voff) do { _Pragma("unroll") for (int _i = 0; _i < 2; ++_i) \
;         __builtin_amdgcn_global_load_lds((const unsigned*)((const char*)(gbase) + (voff)[_i]), (LAS unsigned*)(lds + (bufoff) + ldsw + _i * 8192), 16, 0, 0); } while (0)
; #define PG8_LDA(dst, b, h) do { _Pragma("unroll") for (int m = 0; m < 4; ++m) _Pragma("unroll") for (int k = 0; k < 2; ++k) dst[m][k] = *(const LAS bf16x8*)(lds + PG8_SA(b, h) + aoff + m * 2048 + k * 1024); } while (0)
; #define PG8_LDB(dst, b, h) do { _Pragma("unroll") for (int n = 0; n < 2; ++n) _Pragma("unroll") for (int k = 0; k < 2; ++k) dst[n][k] = *(const LAS bf16x8*)(lds + PG8_SB(b, h) + boff + n * 2048 + k * 1024); } while (0)
; #define PG8_MMA(ai, bj, At, Bt) do { __builtin_amdgcn_s_setprio(1); _Pragma("unroll") for (int m = 0; m < 4; ++m) _Pragma("unroll") for (int n = 0; n < 2; ++n) _Pragma("unroll") for (int k = 0; k < 2; ++k) \
;         acc[ai][bj][m][n] = __builtin_amdgcn_mfma_f32_16x16x32_bf16(Bt[n][k], At[m][k], acc[ai][bj][m][n], 0, 0, 0); __builtin_amdgcn_s_setprio(0); } while (0)
; #define PG8_WAIT_V(n) asm volatile("s_waitcnt vmcnt(" #n ")" ::: "memory")
; #define PG8_WAIT_L(n) asm volatile("s_waitcnt lgkmcnt(" #n ")" ::: "memory")
; #define PG8_BAR __builtin_amdgcn_s_barrier()
; #define PG8_SCHED __builtin_amdgcn_sched_barrier(0)
; template <class Epi>
; __device__ __forceinline__ void gemm_phase(LAS unsigned char* lds, const Gemm g, const StaticOrder& S, const Epi& E) {
;     ...
;             PG8_WAIT_V(6); PG8_BAR; PG8_MMA(1, 1, At, B1); PG8_BAR;
;             PG8_LDB(B0, 1, 0); PG8_SCHED; PG8_LDA(At, 1, 0); PG8_STAGE(PG8_SA(0, 1), a2 + hA, voffA);
;             PG8_WAIT_L(8); PG8_BAR; PG8_WAIT_L(0); PG8_MMA(0, 0, At, B0); PG8_BAR; PG8_SCHED;
;             PG8_LDB(B1, 1, 1); PG8_STAGE(PG8_SB(1, 0), b3, voffB);
;             PG8_BAR; PG8_WAIT_L(0); PG8_MMA(0, 1, At, B1); PG8_BAR;
;             PG8_LDA(At, 1, 1); PG8_STAGE(PG8_SA(1, 0), a3, voffA);
	v_mfma_f32_16x16x32_bf16 v[48:51], v[200:203], v[158:161], v[48:51]
	v_mfma_f32_16x16x32_bf16 v[52:55], v[214:217], v[158:161], v[52:55]
	v_mfma_f32_16x16x32_bf16 v[32:35], v[200:203], v[166:169], v[32:35]
	v_mfma_f32_16x16x32_bf16 v[36:39], v[214:217], v[166:169], v[36:39]
	v_mfma_f32_16x16x32_bf16 v[16:19], v[200:203], v[174:177], v[16:19]
	v_mfma_f32_16x16x32_bf16 v[20:23], v[214:217], v[174:177], v[20:23]
	v_mfma_f32_16x16x32_bf16 v[0:3], v[200:203], v[182:185], v[0:3]
	v_mfma_f32_16x16x32_bf16 v[4:7], v[214:217], v[182:185], v[4:7]
	v_mfma_f32_16x16x32_bf16 v[48:51], v[204:207], v[162:165], v[48:51]
	v_mfma_f32_16x16x32_bf16 v[52:55], v[218:221], v[162:165], v[52:55]
	v_mfma_f32_16x16x32_bf16 v[32:35], v[204:207], v[170:173], v[32:35]
	v_mfma_f32_16x16x32_bf16 v[36:39], v[218:221], v[170:173], v[36:39]
	v_mfma_f32_16x16x32_bf16 v[16:19], v[204:207], v[178:181], v[16:19]
	v_mfma_f32_16x16x32_bf16 v[20:23], v[218:221], v[178:181], v[20:23]
	v_mfma_f32_16x16x32_bf16 v[0:3], v[204:207], v[196:199], v[0:3]
	v_mfma_f32_16x16x32_bf16 v[4:7], v[218:221], v[196:199], v[4:7]
	s_add_i32 s26, 0, 0x18000
	v_add_u32_e32 v139, s26, v137
	s_barrier
	ds_read_b128 v[140:143], v139
	ds_read_b128 v[146:149], v139 offset:1024
	ds_read_b128 v[150:153], v139 offset:2048
	ds_read_b128 v[154:157], v139 offset:3072
	s_add_u32 s20, s20, 0x40000
	s_addc_u32 s21, s21, 0
	s_mov_b32 m0, s63
	ds_read_b128 v[158:161], v138 offset:32768
	ds_read_b128 v[162:165], v138 offset:33792
	ds_read_b128 v[166:169], v138 offset:34816
	ds_read_b128 v[170:173], v138 offset:35840
	ds_read_b128 v[174:177], v138 offset:36864
	ds_read_b128 v[178:181], v138 offset:37888
	ds_read_b128 v[182:185], v138 offset:38912
	ds_read_b128 v[196:199], v138 offset:39936
	global_load_lds_dwordx4 v130, s[20:21]
	s_mov_b32 m0, s64
	s_nop 0
	global_load_lds_dwordx4 v128, s[20:21]
	s_waitcnt lgkmcnt(8)
	s_barrier
	s_waitcnt lgkmcnt(0)
	v_mfma_f32_16x16x32_bf16 v[120:123], v[140:143], v[158:161], v[120:123]
	v_mfma_f32_16x16x32_bf16 v[124:127], v[150:153], v[158:161], v[124:127]
	v_mfma_f32_16x16x32_bf16 v[104:107], v[140:143], v[166:169], v[104:107]
	v_mfma_f32_16x16x32_bf16 v[108:111], v[150:153], v[166:169], v[108:111]
	v_mfma_f32_16x16x32_bf16 v[88:91], v[140:143], v[174:177], v[88:91]
	v_mfma_f32_16x16x32_bf16 v[92:95], v[150:153], v[174:177], v[92:95]
	v_mfma_f32_16x16x32_bf16 v[72:75], v[140:143], v[182:185], v[72:75]
	v_mfma_f32_16x16x32_bf16 v[76:79], v[150:153], v[182:185], v[76:79]
	v_mfma_f32_16x16x32_bf16 v[120:123], v[146:149], v[162:165], v[120:123]
	v_mfma_f32_16x16x32_bf16 v[124:127], v[154:157], v[162:165], v[124:127]
	v_mfma_f32_16x16x32_bf16 v[104:107], v[146:149], v[170:173], v[104:107]
	v_mfma_f32_16x16x32_bf16 v[108:111], v[154:157], v[170:173], v[108:111]
	v_mfma_f32_16x16x32_bf16 v[88:91], v[146:149], v[178:181], v[88:91]
	v_mfma_f32_16x16x32_bf16 v[92:95], v[154:157], v[178:181], v[92:95]
	v_mfma_f32_16x16x32_bf16 v[72:75], v[146:149], v[196:199], v[72:75]
	v_mfma_f32_16x16x32_bf16 v[76:79], v[154:157], v[196:199], v[76:79]
	s_barrier
	s_add_i32 s20, 0, 0x1c000
	s_add_i32 s21, s26, s35
	v_add_u32_e32 v139, s20, v137
	v_lshl_add_u64 v[186:187], v[186:187], 0, s[88:89]
	s_mov_b32 m0, s21
	ds_read_b128 v[200:203], v139
	ds_read_b128 v[204:207], v139 offset:1024
	ds_read_b128 v[214:217], v139 offset:2048
	ds_read_b128 v[218:221], v139 offset:3072
	global_load_lds_dwordx4 v[186:187], off
	s_add_i32 m0, s21, 0x2000
	v_lshl_add_u64 v[186:187], v[188:189], 0, s[88:89]
	global_load_lds_dwordx4 v[186:187], off
	s_barrier
	s_waitcnt lgkmcnt(0)
	v_mfma_f32_16x16x32_bf16 v[112:115], v[200:203], v[158:161], v[112:115]
	v_mfma_f32_16x16x32_bf16 v[116:119], v[214:217], v[158:161], v[116:119]
	v_mfma_f32_16x16x32_bf16 v[96:99], v[200:203], v[166:169], v[96:99]
	v_mfma_f32_16x16x32_bf16 v[100:103], v[214:217], v[166:169], v[100:103]
	v_mfma_f32_16x16x32_bf16 v[80:83], v[200:203], v[174:177], v[80:83]
	v_mfma_f32_16x16x32_bf16 v[84:87], v[214:217], v[174:177], v[84:87]
	v_mfma_f32_16x16x32_bf16 v[64:67], v[200:203], v[182:185], v[64:67]
	v_mfma_f32_16x16x32_bf16 v[68:71], v[214:217], v[182:185], v[68:71]
	v_mfma_f32_16x16x32_bf16 v[112:115], v[204:207], v[162:165], v[112:115]
	v_mfma_f32_16x16x32_bf16 v[116:119], v[218:221], v[162:165], v[116:119]
	v_mfma_f32_16x16x32_bf16 v[96:99], v[204:207], v[170:173], v[96:99]
	v_mfma_f32_16x16x32_bf16 v[100:103], v[218:221], v[170:173], v[100:103]
	v_mfma_f32_16x16x32_bf16 v[80:83], v[204:207], v[178:181], v[80:83]
	v_mfma_f32_16x16x32_bf16 v[84:87], v[218:221], v[178:181], v[84:87]
	v_mfma_f32_16x16x32_bf16 v[64:67], v[204:207], v[196:199], v[64:67]
	v_mfma_f32_16x16x32_bf16 v[68:71], v[218:221], v[196:199], v[68:71]
	s_mov_b32 m0, s65
	v_lshl_add_u64 v[186:187], v[192:193], 0, s[88:89]
	s_barrier
	ds_read_b128 v[158:161], v138 offset:49152
	ds_read_b128 v[162:165], v138 offset:50176
	ds_read_b128 v[166:169], v138 offset:51200
	ds_read_b128 v[170:173], v138 offset:52224
	ds_read_b128 v[174:177], v138 offset:53248
	ds_read_b128 v[178:181], v138 offset:54272
	ds_read_b128 v[182:185], v138 offset:55296
	ds_read_b128 v[196:199], v138 offset:56320
	global_load_lds_dwordx4 v[186:187], off
	s_mov_b32 m0, s68
	v_lshl_add_u64 v[186:187], v[222:223], 0, s[88:89]
	global_load_lds_dwordx4 v[186:187], off
	s_barrier
; __device__ __forceinline__ unsigned pk2(float lo, float hi) { unsigned r; asm("v_cvt_pk_bf16_f32 %0, %1, %2" : "=v"(r) : "v"(lo), "v"(hi)); return r; }
; #define PG8_STAGE(bufoff, gbase, voff) do { _Pragma("unroll") for (int _i = 0; _i < 2; ++_i) \
;         __builtin_amdgcn_global_load_lds((const unsigned*)((const char*)(gbase) + (voff)[_i]), (LAS unsigned*)(lds + (bufoff) + ldsw + _i * 8192), 16, 0, 0); } while (0)
; #define PG8_MMA(ai, bj, At, Bt) do { __builtin_amdgcn_s_setprio(1); _Pragma("unroll") for (int m = 0; m < 4; ++m) _Pragma("unroll") for (int n = 0; n < 2; ++n) _Pragma("unroll") for (int k = 0; k < 2; ++k) \
;         acc[ai][bj][m][n] = __builtin_amdgcn_mfma_f32_16x16x32_bf16(Bt[n][k], At[m][k], acc[ai][bj][m][n], 0, 0, 0); __builtin_amdgcn_s_setprio(0); } while (0)
; #define PG8_WAIT_V(n) asm volatile("s_waitcnt vmcnt(" #n ")" ::: "memory")
; #define PG8_WAIT_L(n) asm volatile("s_waitcnt lgkmcnt(" #n ")" ::: "memory")
; #define PG8_BAR __builtin_amdgcn_s_barrier()
; #define PG8_SCHED __builtin_amdgcn_sched_barrier(0)
; template <class Epi>
; __device__ __forceinline__ void gemm_phase(LAS unsigned char* lds, const Gemm g, const StaticOrder& S, const Epi& E) {
;     ...
;             PG8_BAR; PG8_WAIT_L(0); PG8_MMA(1, 0, At, B0); PG8_BAR; PG8_SCHED;
;             PG8_STAGE(PG8_SB(1, 1), b3 + hB, voffB);
;             PG8_WAIT_V(6); PG8_BAR; PG8_MMA(1, 1, At, B1); PG8_BAR;
;     static __device__ __forceinline__ float sg(float g, float u) { return (g * u) * __builtin_amdgcn_rcpf(1.f + __builtin_amdgcn_exp2f(-g)); }
;     __device__ __forceinline__ void operator()(const f32x4 (&acc)[2][2][4][2], const Unit& u, int wr, int wc, int fr, int fq) const {
; #pragma unroll
;         for (int ai = 0; ai < 2; ++ai)
; #pragma unroll
;             for (int m = 0; m < 4; ++m) {
;                 const int row = u.pm * BM + ai * HALF + wr * 64 + m * 16 + fr;
;                 const f32x4 g0 = acc[ai][0][m][0], u0 = acc[ai][0][m][1], g1 = acc[ai][1][m][0], u1 = acc[ai][1][m][1];
;                 u32x4 o; o.x = pk2(sg(g0[0], u0[0]), sg(g0[1], u0[1])); o.y = pk2(sg(g0[2], u0[2]), sg(g0[3], u0[3]));
;                 o.z = pk2(sg(g1[0], u1[0]), sg(g1[1], u1[1])); o.w = pk2(sg(g1[2], u1[2]), sg(g1[3], u1[3]));
	s_waitcnt lgkmcnt(0)
	v_mfma_f32_16x16x32_bf16 v[56:59], v[140:143], v[158:161], v[56:59]
	v_mfma_f32_16x16x32_bf16 v[60:63], v[150:153], v[158:161], v[60:63]
	v_mfma_f32_16x16x32_bf16 v[40:43], v[140:143], v[166:169], v[40:43]
	v_mfma_f32_16x16x32_bf16 v[44:47], v[150:153], v[166:169], v[44:47]
	v_mfma_f32_16x16x32_bf16 v[24:27], v[140:143], v[174:177], v[24:27]
	v_mfma_f32_16x16x32_bf16 v[28:31], v[150:153], v[174:177], v[28:31]
	v_mfma_f32_16x16x32_bf16 v[8:11], v[140:143], v[182:185], v[8:11]
	v_mfma_f32_16x16x32_bf16 v[12:15], v[150:153], v[182:185], v[12:15]
	v_mfma_f32_16x16x32_bf16 v[56:59], v[146:149], v[162:165], v[56:59]
	v_mfma_f32_16x16x32_bf16 v[60:63], v[154:157], v[162:165], v[60:63]
	v_mfma_f32_16x16x32_bf16 v[40:43], v[146:149], v[170:173], v[40:43]
	v_mfma_f32_16x16x32_bf16 v[44:47], v[154:157], v[170:173], v[44:47]
	v_mfma_f32_16x16x32_bf16 v[24:27], v[146:149], v[178:181], v[24:27]
	v_mfma_f32_16x16x32_bf16 v[28:31], v[154:157], v[178:181], v[28:31]
	v_mfma_f32_16x16x32_bf16 v[8:11], v[146:149], v[196:199], v[8:11]
	v_mfma_f32_16x16x32_bf16 v[12:15], v[154:157], v[196:199], v[12:15]
	s_barrier
	s_add_u32 s16, s16, 0x40080
	s_addc_u32 s17, s17, 0
	s_add_i32 s20, s20, s35
	s_mov_b32 m0, s20
	s_nop 0
	global_load_lds_dwordx4 v130, s[16:17]
	s_add_i32 m0, s20, 0x2000
	s_nop 0
	global_load_lds_dwordx4 v128, s[16:17]
	s_waitcnt vmcnt(6)
	s_barrier
	v_mfma_f32_16x16x32_bf16 v[48:51], v[200:203], v[158:161], v[48:51]
	v_mfma_f32_16x16x32_bf16 v[52:55], v[214:217], v[158:161], v[52:55]
	v_mfma_f32_16x16x32_bf16 v[32:35], v[200:203], v[166:169], v[32:35]
	v_mfma_f32_16x16x32_bf16 v[36:39], v[214:217], v[166:169], v[36:39]
	v_mfma_f32_16x16x32_bf16 v[16:19], v[200:203], v[174:177], v[16:19]
	v_mfma_f32_16x16x32_bf16 v[20:23], v[214:217], v[174:177], v[20:23]
	v_mfma_f32_16x16x32_bf16 v[0:3], v[200:203], v[182:185], v[0:3]
	v_mfma_f32_16x16x32_bf16 v[4:7], v[214:217], v[182:185], v[4:7]
	v_mfma_f32_16x16x32_bf16 v[48:51], v[204:207], v[162:165], v[48:51]
	v_mfma_f32_16x16x32_bf16 v[52:55], v[218:221], v[162:165], v[52:55]
	v_mfma_f32_16x16x32_bf16 v[32:35], v[204:207], v[170:173], v[32:35]
	v_mfma_f32_16x16x32_bf16 v[36:39], v[218:221], v[170:173], v[36:39]
	v_mfma_f32_16x16x32_bf16 v[16:19], v[204:207], v[178:181], v[16:19]
	v_mfma_f32_16x16x32_bf16 v[20:23], v[218:221], v[178:181], v[20:23]
	v_mfma_f32_16x16x32_bf16 v[0:3], v[204:207], v[196:199], v[0:3]
	v_mfma_f32_16x16x32_bf16 v[4:7], v[218:221], v[196:199], v[4:7]
	s_add_i32 s78, s78, 2
	s_add_u32 s12, s12, 0x100
	s_addc_u32 s13, s13, 0
	s_add_u32 s25, s25, 0x100
	s_addc_u32 s77, s77, 0
	s_cmp_gt_u32 s78, 13
	s_barrier
	s_cbranch_scc0 .LBB0_281
	v_mul_f32_e32 v124, v120, v124
	v_exp_f32_e64 v120, -v120
	v_mul_f32_e32 v108, v104, v108
	v_exp_f32_e64 v104, -v104
	v_mul_f32_e32 v92, v88, v92
	v_add_f32_e32 v120, 1.0, v120
	v_rcp_f32_e32 v120, v120
	v_add_f32_e32 v104, 1.0, v104
	v_rcp_f32_e32 v104, v104
	v_exp_f32_e64 v88, -v88
	v_mul_f32_e32 v120, v124, v120
	v_mul_f32_e32 v124, v121, v125
	v_exp_f32_e64 v121, -v121
	v_mul_f32_e32 v104, v108, v104
	v_mul_f32_e32 v108, v105, v109
	v_exp_f32_e64 v105, -v105
	v_add_f32_e32 v121, 1.0, v121
	v_rcp_f32_e32 v121, v121
	v_add_f32_e32 v88, 1.0, v88
	v_rcp_f32_e32 v88, v88
	v_mul_f32_e32 v76, v72, v76
	v_exp_f32_e64 v72, -v72
	v_mul_f32_e32 v121, v124, v121
	v_cvt_pk_bf16_f32 v120, v120, v121
	v_mul_f32_e32 v121, v122, v126
	v_exp_f32_e64 v122, -v122
	v_mul_f32_e32 v116, v112, v116
	v_exp_f32_e64 v112, -v112
	v_add_f32_e32 v105, 1.0, v105
	v_rcp_f32_e32 v105, v105
	v_mul_f32_e32 v88, v92, v88
	v_mul_f32_e32 v92, v89, v93
	v_exp_f32_e64 v89, -v89
	v_add_f32_e32 v72, 1.0, v72
	v_rcp_f32_e32 v72, v72
	v_mul_f32_e32 v60, v56, v60
	v_exp_f32_e64 v56, -v56
	v_add_f32_e32 v122, 1.0, v122
	v_add_f32_e32 v112, 1.0, v112
	v_rcp_f32_e32 v122, v122
	v_rcp_f32_e32 v112, v112
	v_mul_f32_e32 v105, v108, v105
	v_add_f32_e32 v89, 1.0, v89
	v_cvt_pk_bf16_f32 v104, v104, v105
	v_mul_f32_e32 v105, v106, v110
	v_exp_f32_e64 v106, -v106
	v_mul_f32_e32 v100, v96, v100
	v_exp_f32_e64 v96, -v96
	v_rcp_f32_e32 v89, v89
	v_mul_f32_e32 v72, v76, v72
	v_mul_f32_e32 v76, v73, v77
	v_exp_f32_e64 v73, -v73
	v_add_f32_e32 v56, 1.0, v56
	v_rcp_f32_e32 v56, v56
	v_mul_f32_e32 v44, v40, v44
	v_exp_f32_e64 v40, -v40
	v_mul_f32_e32 v121, v121, v122
	v_mul_f32_e32 v122, v123, v127
	v_exp_f32_e64 v123, -v123
	v_mul_f32_e32 v112, v116, v112
	v_mul_f32_e32 v116, v113, v117
	v_exp_f32_e64 v113, -v113
	v_add_f32_e32 v106, 1.0, v106
	v_add_f32_e32 v96, 1.0, v96
	v_mul_f32_e32 v89, v92, v89
	v_add_f32_e32 v73, 1.0, v73
	v_rcp_f32_e32 v106, v106
	v_rcp_f32_e32 v96, v96
	v_cvt_pk_bf16_f32 v88, v88, v89
	v_mul_f32_e32 v89, v90, v94
	v_exp_f32_e64 v90, -v90
	v_mul_f32_e32 v84, v80, v84
	v_exp_f32_e64 v80, -v80
	v_rcp_f32_e32 v73, v73
	v_mul_f32_e32 v56, v60, v56
	v_mul_f32_e32 v60, v57, v61
	v_exp_f32_e64 v57, -v57
	v_add_f32_e32 v40, 1.0, v40
	v_rcp_f32_e32 v40, v40
	v_mul_f32_e32 v28, v24, v28
	v_exp_f32_e64 v24, -v24
	v_add_f32_e32 v123, 1.0, v123
	v_add_f32_e32 v113, 1.0, v113
	v_rcp_f32_e32 v123, v123
	v_rcp_f32_e32 v113, v113
	v_mul_f32_e32 v105, v105, v106
	v_mul_f32_e32 v106, v107, v111
	v_exp_f32_e64 v107, -v107
	v_mul_f32_e32 v96, v100, v96
	v_mul_f32_e32 v100, v97, v101
	v_exp_f32_e64 v97, -v97
	v_add_f32_e32 v90, 1.0, v90
	v_add_f32_e32 v80, 1.0, v80
	v_mul_f32_e32 v73, v76, v73
	v_add_f32_e32 v57, 1.0, v57
	v_rcp_f32_e32 v90, v90
	v_rcp_f32_e32 v80, v80
	v_cvt_pk_bf16_f32 v72, v72, v73
	v_mul_f32_e32 v73, v74, v78
	v_exp_f32_e64 v74, -v74
	v_mul_f32_e32 v68, v64, v68
	v_exp_f32_e64 v64, -v64
	v_rcp_f32_e32 v57, v57
	v_mul_f32_e32 v40, v44, v40
	v_mul_f32_e32 v44, v41, v45
; __device__ __forceinline__ unsigned pk2(float lo, float hi) { unsigned r; asm("v_cvt_pk_bf16_f32 %0, %1, %2" : "=v"(r) : "v"(lo), "v"(hi)); return r; }
;     static __device__ __forceinline__ float sg(float g, float u) { return (g * u) * __builtin_amdgcn_rcpf(1.f + __builtin_amdgcn_exp2f(-g)); }
;     __device__ __forceinline__ void operator()(const f32x4 (&acc)[2][2][4][2], const Unit& u, int wr, int wc, int fr, int fq) const {
; #pragma unroll
;         for (int ai = 0; ai < 2; ++ai)
; #pragma unroll
;             for (int m = 0; m < 4; ++m) {
;                 const int row = u.pm * BM + ai * HALF + wr * 64 + m * 16 + fr;
;                 const f32x4 g0 = acc[ai][0][m][0], u0 = acc[ai][0][m][1], g1 = acc[ai][1][m][0], u1 = acc[ai][1][m][1];
;                 u32x4 o; o.x = pk2(sg(g0[0], u0[0]), sg(g0[1], u0[1])); o.y = pk2(sg(g0[2], u0[2]), sg(g0[3], u0[3]));
;                 o.z = pk2(sg(g1[0], u1[0]), sg(g1[1], u1[1])); o.w = pk2(sg(g1[2], u1[2]), sg(g1[3], u1[3]));
;                 *(u32x4*)(O + (size_t)row * DFF + u.pn * 128 + wc * 32 + fq * 8) = o;
	v_exp_f32_e64 v41, -v41
	v_add_f32_e32 v24, 1.0, v24
	v_rcp_f32_e32 v24, v24
	v_mul_f32_e32 v12, v8, v12
	v_exp_f32_e64 v8, -v8
	v_mul_f32_e32 v122, v122, v123
	v_mul_f32_e32 v113, v116, v113
	v_cvt_pk_bf16_f32 v121, v121, v122
	v_cvt_pk_bf16_f32 v122, v112, v113
	v_exp_f32_e64 v113, -v114
	v_add_f32_e32 v107, 1.0, v107
	v_add_f32_e32 v97, 1.0, v97
	v_mul_f32_e32 v112, v114, v118
	v_exp_f32_e64 v114, -v115
	v_rcp_f32_e32 v107, v107
	v_rcp_f32_e32 v97, v97
	v_mul_f32_e32 v89, v89, v90
	v_mul_f32_e32 v90, v91, v95
	v_exp_f32_e64 v91, -v91
	v_mul_f32_e32 v80, v84, v80
	v_mul_f32_e32 v84, v81, v85
	v_exp_f32_e64 v81, -v81
	v_add_f32_e32 v74, 1.0, v74
	v_add_f32_e32 v64, 1.0, v64
	v_mul_f32_e32 v57, v60, v57
	v_add_f32_e32 v41, 1.0, v41
	v_rcp_f32_e32 v74, v74
	v_rcp_f32_e32 v64, v64
	v_cvt_pk_bf16_f32 v56, v56, v57
	v_mul_f32_e32 v57, v58, v62
	v_exp_f32_e64 v58, -v58
	v_mul_f32_e32 v52, v48, v52
	v_exp_f32_e64 v48, -v48
	v_rcp_f32_e32 v41, v41
	v_mul_f32_e32 v24, v28, v24
	v_mul_f32_e32 v28, v25, v29
	v_exp_f32_e64 v25, -v25
	v_add_f32_e32 v8, 1.0, v8
	v_rcp_f32_e32 v8, v8
	v_add_f32_e32 v113, 1.0, v113
	v_rcp_f32_e32 v113, v113
	v_add_f32_e32 v114, 1.0, v114
	v_mul_f32_e32 v106, v106, v107
	v_mul_f32_e32 v97, v100, v97
	v_add_f32_e32 v91, 1.0, v91
	v_add_f32_e32 v81, 1.0, v81
	v_rcp_f32_e32 v114, v114
	v_cvt_pk_bf16_f32 v105, v105, v106
	v_cvt_pk_bf16_f32 v106, v96, v97
	v_exp_f32_e64 v97, -v98
	v_rcp_f32_e32 v91, v91
	v_rcp_f32_e32 v81, v81
	v_mul_f32_e32 v73, v73, v74
	v_mul_f32_e32 v74, v75, v79
	v_exp_f32_e64 v75, -v75
	v_mul_f32_e32 v64, v68, v64
	v_mul_f32_e32 v68, v65, v69
	v_exp_f32_e64 v65, -v65
	v_add_f32_e32 v58, 1.0, v58
	v_add_f32_e32 v48, 1.0, v48
	v_mul_f32_e32 v41, v44, v41
	v_add_f32_e32 v25, 1.0, v25
	v_mul_f32_e32 v96, v98, v102
	v_exp_f32_e64 v98, -v99
	v_rcp_f32_e32 v58, v58
	v_rcp_f32_e32 v48, v48
	v_cvt_pk_bf16_f32 v40, v40, v41
	v_mul_f32_e32 v41, v42, v46
	v_exp_f32_e64 v42, -v42
	v_mul_f32_e32 v36, v32, v36
	v_exp_f32_e64 v32, -v32
	v_rcp_f32_e32 v25, v25
	v_mul_f32_e32 v8, v12, v8
	v_mul_f32_e32 v12, v9, v13
	v_exp_f32_e64 v9, -v9
	v_mul_f32_e32 v112, v112, v113
	v_mul_f32_e32 v113, v115, v119
	s_lshl_b32 s12, s15, 7
	v_mul_f32_e32 v113, v113, v114
	v_add_f32_e32 v97, 1.0, v97
	v_mul_f32_e32 v90, v90, v91
	v_mul_f32_e32 v81, v84, v81
	v_add_f32_e32 v75, 1.0, v75
	v_add_f32_e32 v65, 1.0, v65
	v_lshl_add_u32 v139, s71, 8, v136
	s_ashr_i32 s13, s12, 31
	v_cvt_pk_bf16_f32 v123, v112, v113
	v_mov_b64_e32 v[112:113], s[4:5]
	v_rcp_f32_e32 v97, v97
	v_add_f32_e32 v98, 1.0, v98
	v_cvt_pk_bf16_f32 v89, v89, v90
	v_cvt_pk_bf16_f32 v90, v80, v81
	v_exp_f32_e64 v81, -v82
	v_rcp_f32_e32 v75, v75
	v_rcp_f32_e32 v65, v65
	v_mul_f32_e32 v57, v57, v58
	v_mul_f32_e32 v58, v59, v63
	v_exp_f32_e64 v59, -v59
	v_mul_f32_e32 v48, v52, v48
	v_mul_f32_e32 v52, v49, v53
	v_exp_f32_e64 v49, -v49
	v_add_f32_e32 v42, 1.0, v42
	v_add_f32_e32 v32, 1.0, v32
	v_mul_f32_e32 v25, v28, v25
	v_add_f32_e32 v9, 1.0, v9
	v_mad_i64_i32 v[114:115], s[16:17], v139, s33, v[112:113]
	s_lshl_b64 s[12:13], s[12:13], 1
	v_rcp_f32_e32 v98, v98
	v_mul_f32_e32 v80, v82, v86
	v_exp_f32_e64 v82, -v83
	v_rcp_f32_e32 v42, v42
	v_rcp_f32_e32 v32, v32
	v_cvt_pk_bf16_f32 v24, v24, v25
	v_mul_f32_e32 v25, v26, v30
	v_exp_f32_e64 v26, -v26
	v_mul_f32_e32 v20, v16, v20
	v_exp_f32_e64 v16, -v16
	v_rcp_f32_e32 v9, v9
	v_lshl_add_u64 v[114:115], v[114:115], 0, s[12:13]
	v_lshl_add_u64 v[114:115], v[114:115], 0, s[66:67]
	v_lshl_add_u64 v[114:115], v[114:115], 0, v[144:145]
	v_mul_f32_e32 v96, v96, v97
	v_mul_f32_e32 v97, v99, v103
	v_add_f32_e32 v81, 1.0, v81
	v_mul_f32_e32 v74, v74, v75
	v_mul_f32_e32 v65, v68, v65
	v_add_f32_e32 v59, 1.0, v59
	v_add_f32_e32 v49, 1.0, v49
	global_store_dwordx4 v[114:115], v[120:123], off
	v_or_b32_e32 v114, 16, v139
	v_mul_f32_e32 v97, v97, v98
	v_rcp_f32_e32 v81, v81
	v_add_f32_e32 v82, 1.0, v82
	v_cvt_pk_bf16_f32 v73, v73, v74
	v_cvt_pk_bf16_f32 v74, v64, v65
	v_exp_f32_e64 v65, -v66
	v_rcp_f32_e32 v59, v59
	v_rcp_f32_e32 v49, v49
	v_mul_f32_e32 v41, v41, v42
	v_mul_f32_e32 v42, v43, v47
	v_exp_f32_e64 v43, -v43
	v_mul_f32_e32 v32, v36, v32
	v_mul_f32_e32 v36, v33, v37
	v_exp_f32_e64 v33, -v33
	v_add_f32_e32 v26, 1.0, v26
	v_add_f32_e32 v16, 1.0, v16
	v_mul_f32_e32 v9, v12, v9
	v_cvt_pk_bf16_f32 v107, v96, v97
	v_mad_i64_i32 v[96:97], s[16:17], v114, s33, v[112:113]
	v_rcp_f32_e32 v82, v82
	v_mul_f32_e32 v64, v66, v70
	v_exp_f32_e64 v66, -v67
	v_rcp_f32_e32 v26, v26
	v_rcp_f32_e32 v16, v16
	v_cvt_pk_bf16_f32 v8, v8, v9
	v_mul_f32_e32 v9, v10, v14
	v_exp_f32_e64 v10, -v10
	v_mul_f32_e32 v4, v0, v4
	v_exp_f32_e64 v0, -v0
	v_lshl_add_u64 v[96:97], v[96:97], 0, s[12:13]
	v_lshl_add_u64 v[96:97], v[96:97], 0, s[66:67]
; __device__ __forceinline__ unsigned pk2(float lo, float hi) { unsigned r; asm("v_cvt_pk_bf16_f32 %0, %1, %2" : "=v"(r) : "v"(lo), "v"(hi)); return r; }
; #define PG8_WAIT_V(n) asm volatile("s_waitcnt vmcnt(" #n ")" ::: "memory")
; #define PG8_BAR __builtin_amdgcn_s_barrier()
;     static __device__ __forceinline__ float sg(float g, float u) { return (g * u) * __builtin_amdgcn_rcpf(1.f + __builtin_amdgcn_exp2f(-g)); }
; template <class Epi>
; __device__ __forceinline__ void gemm_phase(LAS unsigned char* lds, const Gemm g, const StaticOrder& S, const Epi& E) {
;     ...
;         cur = nxt; cA = nA; cB = nB; ++ui;
;     }
;     PG8_WAIT_V(0);
;     if (wr == 0) PG8_BAR;
;     PG8_BAR;
;     __device__ __forceinline__ void operator()(const f32x4 (&acc)[2][2][4][2], const Unit& u, int wr, int wc, int fr, int fq) const {
;     ...
;                 const int row = u.pm * BM + ai * HALF + wr * 64 + m * 16 + fr;
;                 const f32x4 g0 = acc[ai][0][m][0], u0 = acc[ai][0][m][1], g1 = acc[ai][1][m][0], u1 = acc[ai][1][m][1];
;                 u32x4 o; o.x = pk2(sg(g0[0], u0[0]), sg(g0[1], u0[1])); o.y = pk2(sg(g0[2], u0[2]), sg(g0[3], u0[3]));
;                 o.z = pk2(sg(g1[0], u1[0]), sg(g1[1], u1[1])); o.w = pk2(sg(g1[2], u1[2]), sg(g1[3], u1[3]));
;                 *(u32x4*)(O + (size_t)row * DFF + u.pn * 128 + wc * 32 + fq * 8) = o;
	v_lshl_add_u64 v[96:97], v[96:97], 0, v[144:145]
	v_mul_f32_e32 v80, v80, v81
	v_mul_f32_e32 v81, v83, v87
	v_add_f32_e32 v65, 1.0, v65
	v_mul_f32_e32 v58, v58, v59
	v_mul_f32_e32 v49, v52, v49
	v_add_f32_e32 v43, 1.0, v43
	v_add_f32_e32 v33, 1.0, v33
	global_store_dwordx4 v[96:97], v[104:107], off
	v_or_b32_e32 v96, 32, v139
	v_mul_f32_e32 v81, v81, v82
	v_rcp_f32_e32 v65, v65
	v_add_f32_e32 v66, 1.0, v66
	v_cvt_pk_bf16_f32 v57, v57, v58
	v_cvt_pk_bf16_f32 v58, v48, v49
	v_exp_f32_e64 v49, -v50
	v_rcp_f32_e32 v43, v43
	v_rcp_f32_e32 v33, v33
	v_mul_f32_e32 v25, v25, v26
	v_mul_f32_e32 v26, v27, v31
	v_exp_f32_e64 v27, -v27
	v_mul_f32_e32 v16, v20, v16
	v_mul_f32_e32 v20, v17, v21
	v_exp_f32_e64 v17, -v17
	v_add_f32_e32 v10, 1.0, v10
	v_add_f32_e32 v0, 1.0, v0
	v_cvt_pk_bf16_f32 v91, v80, v81
	v_mad_i64_i32 v[80:81], s[16:17], v96, s33, v[112:113]
	v_rcp_f32_e32 v66, v66
	v_mul_f32_e32 v48, v50, v54
	v_exp_f32_e64 v50, -v51
	v_rcp_f32_e32 v10, v10
	v_rcp_f32_e32 v0, v0
	v_lshl_add_u64 v[80:81], v[80:81], 0, s[12:13]
	v_lshl_add_u64 v[80:81], v[80:81], 0, s[66:67]
	v_lshl_add_u64 v[80:81], v[80:81], 0, v[144:145]
	v_mul_f32_e32 v64, v64, v65
	v_mul_f32_e32 v65, v67, v71
	v_add_f32_e32 v49, 1.0, v49
	v_mul_f32_e32 v42, v42, v43
	v_mul_f32_e32 v33, v36, v33
	v_add_f32_e32 v27, 1.0, v27
	v_add_f32_e32 v17, 1.0, v17
	global_store_dwordx4 v[80:81], v[88:91], off
	v_or_b32_e32 v80, 48, v139
	v_mul_f32_e32 v65, v65, v66
	v_rcp_f32_e32 v49, v49
	v_add_f32_e32 v50, 1.0, v50
	v_cvt_pk_bf16_f32 v41, v41, v42
	v_cvt_pk_bf16_f32 v42, v32, v33
	v_exp_f32_e64 v33, -v34
	v_rcp_f32_e32 v27, v27
	v_rcp_f32_e32 v17, v17
	v_mul_f32_e32 v9, v9, v10
	v_mul_f32_e32 v10, v11, v15
	v_exp_f32_e64 v11, -v11
	v_mul_f32_e32 v0, v4, v0
	v_mul_f32_e32 v4, v1, v5
	v_exp_f32_e64 v1, -v1
	v_cvt_pk_bf16_f32 v75, v64, v65
	v_mad_i64_i32 v[64:65], s[16:17], v80, s33, v[112:113]
	v_rcp_f32_e32 v50, v50
	v_mul_f32_e32 v32, v34, v38
	v_exp_f32_e64 v34, -v35
	v_lshl_add_u64 v[64:65], v[64:65], 0, s[12:13]
	v_lshl_add_u64 v[64:65], v[64:65], 0, s[66:67]
	v_lshl_add_u64 v[64:65], v[64:65], 0, v[144:145]
	v_mul_f32_e32 v48, v48, v49
	v_mul_f32_e32 v49, v51, v55
	v_add_f32_e32 v33, 1.0, v33
	v_mul_f32_e32 v26, v26, v27
	v_mul_f32_e32 v17, v20, v17
	v_add_f32_e32 v11, 1.0, v11
	v_add_f32_e32 v1, 1.0, v1
	global_store_dwordx4 v[64:65], v[72:75], off
	v_add_u32_e32 v64, 0x80, v139
	v_mul_f32_e32 v49, v49, v50
	v_rcp_f32_e32 v33, v33
	v_add_f32_e32 v34, 1.0, v34
	v_cvt_pk_bf16_f32 v25, v25, v26
	v_cvt_pk_bf16_f32 v26, v16, v17
	v_exp_f32_e64 v17, -v18
	v_rcp_f32_e32 v11, v11
	v_rcp_f32_e32 v1, v1
	v_cvt_pk_bf16_f32 v59, v48, v49
	v_mad_i64_i32 v[48:49], s[16:17], v64, s33, v[112:113]
	v_rcp_f32_e32 v34, v34
	v_mul_f32_e32 v16, v18, v22
	v_exp_f32_e64 v18, -v19
	v_lshl_add_u64 v[48:49], v[48:49], 0, s[12:13]
	v_lshl_add_u64 v[48:49], v[48:49], 0, s[66:67]
	v_lshl_add_u64 v[48:49], v[48:49], 0, v[144:145]
	v_mul_f32_e32 v32, v32, v33
	v_mul_f32_e32 v33, v35, v39
	v_add_f32_e32 v17, 1.0, v17
	v_mul_f32_e32 v10, v10, v11
	v_mul_f32_e32 v1, v4, v1
	global_store_dwordx4 v[48:49], v[56:59], off
	v_add_u32_e32 v48, 0x90, v139
	v_mul_f32_e32 v33, v33, v34
	v_rcp_f32_e32 v17, v17
	v_add_f32_e32 v18, 1.0, v18
	v_cvt_pk_bf16_f32 v9, v9, v10
	v_cvt_pk_bf16_f32 v10, v0, v1
	v_exp_f32_e64 v1, -v2
	v_cvt_pk_bf16_f32 v43, v32, v33
	v_mad_i64_i32 v[32:33], s[16:17], v48, s33, v[112:113]
	v_rcp_f32_e32 v18, v18
	v_mul_f32_e32 v0, v2, v6
	v_exp_f32_e64 v2, -v3
	v_lshl_add_u64 v[32:33], v[32:33], 0, s[12:13]
	v_lshl_add_u64 v[32:33], v[32:33], 0, s[66:67]
	v_lshl_add_u64 v[32:33], v[32:33], 0, v[144:145]
	v_mul_f32_e32 v16, v16, v17
	v_mul_f32_e32 v17, v19, v23
	v_add_f32_e32 v1, 1.0, v1
	global_store_dwordx4 v[32:33], v[40:43], off
	v_add_u32_e32 v32, 0xa0, v139
	v_mul_f32_e32 v17, v17, v18
	v_rcp_f32_e32 v1, v1
	v_add_f32_e32 v2, 1.0, v2
	v_cvt_pk_bf16_f32 v27, v16, v17
	v_mad_i64_i32 v[16:17], s[16:17], v32, s33, v[112:113]
	v_rcp_f32_e32 v2, v2
	v_lshl_add_u64 v[16:17], v[16:17], 0, s[12:13]
	v_lshl_add_u64 v[16:17], v[16:17], 0, s[66:67]
	v_lshl_add_u64 v[16:17], v[16:17], 0, v[144:145]
	v_mul_f32_e32 v0, v0, v1
	v_mul_f32_e32 v1, v3, v7
	global_store_dwordx4 v[16:17], v[24:27], off
	v_add_u32_e32 v16, 0xb0, v139
	v_mul_f32_e32 v1, v1, v2
	v_cvt_pk_bf16_f32 v11, v0, v1
	v_mad_i64_i32 v[0:1], s[16:17], v16, s33, v[112:113]
	v_lshl_add_u64 v[0:1], v[0:1], 0, s[12:13]
	v_lshl_add_u64 v[0:1], v[0:1], 0, s[66:67]
	v_lshl_add_u64 v[0:1], v[0:1], 0, v[144:145]
	s_and_b64 vcc, exec, s[0:1]
	s_mov_b32 s15, s6
	s_mov_b32 s71, s70
	s_mov_b64 s[16:17], s[10:11]
	s_mov_b64 s[12:13], s[8:9]
	global_store_dwordx4 v[0:1], v[8:11], off
	s_cbranch_vccz .LBB0_278
	s_waitcnt vmcnt(0)
	s_cmpk_gt_u32 s3, 0xff
	s_cbranch_scc1 .LBB0_285
	s_barrier

; #define PG8_STAGE(bufoff, gbase, voff) do { _Pragma("unroll") for (int _i = 0; _i < 2; ++_i) \
;         __builtin_amdgcn_global_load_lds((const unsigned*)((const char*)(gbase) + (voff)[_i]), (LAS unsigned*)(lds + (bufoff) + ldsw + _i * 8192), 16, 0, 0); } while (0)
; #define PG8_LDA(dst, b, h) do { _Pragma("unroll") for (int m = 0; m < 4; ++m) _Pragma("unroll") for (int k = 0; k < 2; ++k) dst[m][k] = *(const LAS bf16x8*)(lds + PG8_SA(b, h) + aoff + m * 2048 + k * 1024); } while (0)
; #define PG8_LDB(dst, b, h) do { _Pragma("unroll") for (int n = 0; n < 2; ++n) _Pragma("unroll") for (int k = 0; k < 2; ++k) dst[n][k] = *(const LAS bf16x8*)(lds + PG8_SB(b, h) + boff + n * 2048 + k * 1024); } while (0)
; #define PG8_MMA(ai, bj, At, Bt) do { __builtin_amdgcn_s_setprio(1); _Pragma("unroll") for (int m = 0; m < 4; ++m) _Pragma("unroll") for (int n = 0; n < 2; ++n) _Pragma("unroll") for (int k = 0; k < 2; ++k) \
;         acc[ai][bj][m][n] = __builtin_amdgcn_mfma_f32_16x16x32_bf16(Bt[n][k], At[m][k], acc[ai][bj][m][n], 0, 0, 0); __builtin_amdgcn_s_setprio(0); } while (0)
; #define PG8_WAIT_L(n) asm volatile("s_waitcnt lgkmcnt(" #n ")" ::: "memory")
; #define PG8_BAR __builtin_amdgcn_s_barrier()
; template <class Epi>
; __device__ __forceinline__ void gemm_phase(LAS unsigned char* lds, const Gemm g, const StaticOrder& S, const Epi& E) {
;     ...
;         const bool has_next = S.next(ui + 1, nxt);
;         const char* nA = has_next ? g.arow(nxt.pm) : cA; const char* nB = has_next ? (const char*)g.Bt + (size_t)nxt.pn * tB : cB;
;         for (int t = 0; t < nt; t += 2) {
;             const bool last = (t == nt - 2);
;             const char* a1 = cA + (size_t)(t + 1) * kstep;
;             const char* a2 = last ? nA : cA + (size_t)(t + 2) * kstep; const char* b2 = last ? nB : cB + (size_t)(t + 2) * kstep;
;             const char* a3 = a2 + kstep; const char* b3 = b2 + kstep;
;             PG8_LDB(B0, 0, 0); PG8_SCHED; PG8_LDA(At, 0, 0); PG8_STAGE(PG8_SA(1, 1), a1 + hA, voffA);
;             PG8_WAIT_L(8); PG8_BAR; PG8_WAIT_L(0); PG8_MMA(0, 0, At, B0); PG8_BAR; PG8_SCHED;
;             PG8_LDB(B1, 0, 1); PG8_STAGE(PG8_SB(0, 0), b2, voffB);
;             PG8_BAR; PG8_WAIT_L(0); PG8_MMA(0, 1, At, B1); PG8_BAR;
;             PG8_LDA(At, 0, 1); PG8_STAGE(PG8_SA(0, 0), a2, voffA);
;             PG8_BAR; PG8_WAIT_L(0); PG8_MMA(1, 0, At, B0); PG8_BAR; PG8_SCHED;
.LBB0_349:
	s_add_u32 s12, s10, 0x100
	s_addc_u32 s13, s11, 0
	s_add_i32 s26, 0, 0x10000
	v_add_u32_e32 v142, s26, v139
	ds_read_b128 v[134:137], v142
	ds_read_b128 v[146:149], v142 offset:1024
	ds_read_b128 v[150:153], v142 offset:2048
	ds_read_b128 v[154:157], v142 offset:3072
	s_cmp_eq_u32 s72, 40
	s_cselect_b32 s21, s5, s13
	s_cselect_b32 s20, s4, s12
	s_cselect_b32 s17, s7, s25
	s_cselect_b32 s16, s6, s24
	s_add_i32 m0, s61, 0xc000
	ds_read_b128 v[158:161], v141
	ds_read_b128 v[162:165], v141 offset:1024
	ds_read_b128 v[166:169], v141 offset:2048
	ds_read_b128 v[170:173], v141 offset:3072
	ds_read_b128 v[174:177], v141 offset:4096
	ds_read_b128 v[178:181], v141 offset:5120
	ds_read_b128 v[182:185], v141 offset:6144
	ds_read_b128 v[196:199], v141 offset:7168
	global_load_lds_dwordx4 v130, s[10:11]
	s_add_i32 m0, s61, 0xe000
	v_lshl_add_u64 v[142:143], s[10:11], 0, v[132:133]
	global_load_lds_dwordx4 v[142:143], off
	s_waitcnt lgkmcnt(8)
	s_barrier
	s_waitcnt lgkmcnt(0)
	v_mfma_f32_16x16x32_bf16 v[124:127], v[134:137], v[158:161], v[124:127]
	v_mfma_f32_16x16x32_bf16 v[120:123], v[150:153], v[158:161], v[120:123]
	v_mfma_f32_16x16x32_bf16 v[116:119], v[134:137], v[166:169], v[116:119]
	v_mfma_f32_16x16x32_bf16 v[108:111], v[150:153], v[166:169], v[108:111]
	v_mfma_f32_16x16x32_bf16 v[100:103], v[134:137], v[174:177], v[100:103]
	v_mfma_f32_16x16x32_bf16 v[92:95], v[150:153], v[174:177], v[92:95]
	v_mfma_f32_16x16x32_bf16 v[84:87], v[134:137], v[182:185], v[84:87]
	v_mfma_f32_16x16x32_bf16 v[76:79], v[150:153], v[182:185], v[76:79]
	v_mfma_f32_16x16x32_bf16 v[124:127], v[146:149], v[162:165], v[124:127]
	v_mfma_f32_16x16x32_bf16 v[120:123], v[154:157], v[162:165], v[120:123]
	v_mfma_f32_16x16x32_bf16 v[116:119], v[146:149], v[170:173], v[116:119]
	v_mfma_f32_16x16x32_bf16 v[108:111], v[154:157], v[170:173], v[108:111]
	v_mfma_f32_16x16x32_bf16 v[100:103], v[146:149], v[178:181], v[100:103]
	v_mfma_f32_16x16x32_bf16 v[92:95], v[154:157], v[178:181], v[92:95]
	v_mfma_f32_16x16x32_bf16 v[84:87], v[146:149], v[196:199], v[84:87]
	v_mfma_f32_16x16x32_bf16 v[76:79], v[154:157], v[196:199], v[76:79]
	s_barrier
	s_add_i32 s27, 0, 0x14000
	v_add_u32_e32 v142, s27, v139
	s_add_i32 s10, s26, s35
	ds_read_b128 v[200:203], v142
	ds_read_b128 v[204:207], v142 offset:1024
	ds_read_b128 v[214:217], v142 offset:2048
	ds_read_b128 v[218:221], v142 offset:3072
	v_lshl_add_u64 v[142:143], s[16:17], 0, v[144:145]
	s_mov_b32 m0, s10
	v_lshl_add_u64 v[186:187], s[16:17], 0, v[128:129]
	global_load_lds_dwordx4 v[142:143], off
	s_add_i32 m0, s10, 0x2000
	s_nop 0
	global_load_lds_dwordx4 v[186:187], off
	s_barrier
	s_waitcnt lgkmcnt(0)
	v_mfma_f32_16x16x32_bf16 v[112:115], v[200:203], v[158:161], v[112:115]
	v_mfma_f32_16x16x32_bf16 v[104:107], v[214:217], v[158:161], v[104:107]
	v_mfma_f32_16x16x32_bf16 v[96:99], v[200:203], v[166:169], v[96:99]
	v_mfma_f32_16x16x32_bf16 v[88:91], v[214:217], v[166:169], v[88:91]
	v_mfma_f32_16x16x32_bf16 v[80:83], v[200:203], v[174:177], v[80:83]
	v_mfma_f32_16x16x32_bf16 v[72:75], v[214:217], v[174:177], v[72:75]
	v_mfma_f32_16x16x32_bf16 v[68:71], v[200:203], v[182:185], v[68:71]
	v_mfma_f32_16x16x32_bf16 v[64:67], v[214:217], v[182:185], v[64:67]
	v_mfma_f32_16x16x32_bf16 v[112:115], v[204:207], v[162:165], v[112:115]
	v_mfma_f32_16x16x32_bf16 v[104:107], v[218:221], v[162:165], v[104:107]
	v_mfma_f32_16x16x32_bf16 v[96:99], v[204:207], v[170:173], v[96:99]
	v_mfma_f32_16x16x32_bf16 v[88:91], v[218:221], v[170:173], v[88:91]
	v_mfma_f32_16x16x32_bf16 v[80:83], v[204:207], v[178:181], v[80:83]
	v_mfma_f32_16x16x32_bf16 v[72:75], v[218:221], v[178:181], v[72:75]
	v_mfma_f32_16x16x32_bf16 v[68:71], v[204:207], v[196:199], v[68:71]
	v_mfma_f32_16x16x32_bf16 v[64:67], v[218:221], v[196:199], v[64:67]
	s_mov_b32 m0, s61
	v_lshl_add_u64 v[188:189], s[20:21], 0, v[144:145]
	s_barrier
	ds_read_b128 v[158:161], v141 offset:16384
	ds_read_b128 v[162:165], v141 offset:17408
	ds_read_b128 v[166:169], v141 offset:18432
	ds_read_b128 v[170:173], v141 offset:19456
	ds_read_b128 v[174:177], v141 offset:20480
	ds_read_b128 v[178:181], v141 offset:21504
	ds_read_b128 v[182:185], v141 offset:22528
	ds_read_b128 v[196:199], v141 offset:23552
	global_load_lds_dwordx4 v[188:189], off
	s_mov_b32 m0, s62
	v_lshl_add_u64 v[192:193], s[20:21], 0, v[128:129]
	global_load_lds_dwordx4 v[192:193], off
	s_barrier
	s_waitcnt lgkmcnt(0)
	v_mfma_f32_16x16x32_bf16 v[60:63], v[134:137], v[158:161], v[60:63]
	v_mfma_f32_16x16x32_bf16 v[56:59], v[150:153], v[158:161], v[56:59]
	v_mfma_f32_16x16x32_bf16 v[52:55], v[134:137], v[166:169], v[52:55]
	v_mfma_f32_16x16x32_bf16 v[44:47], v[150:153], v[166:169], v[44:47]
	v_mfma_f32_16x16x32_bf16 v[36:39], v[134:137], v[174:177], v[36:39]
	v_mfma_f32_16x16x32_bf16 v[28:31], v[150:153], v[174:177], v[28:31]
	v_mfma_f32_16x16x32_bf16 v[20:23], v[134:137], v[182:185], v[20:23]
	v_mfma_f32_16x16x32_bf16 v[12:15], v[150:153], v[182:185], v[12:15]
	v_mfma_f32_16x16x32_bf16 v[60:63], v[146:149], v[162:165], v[60:63]
	v_mfma_f32_16x16x32_bf16 v[56:59], v[154:157], v[162:165], v[56:59]
	v_mfma_f32_16x16x32_bf16 v[52:55], v[146:149], v[170:173], v[52:55]
	v_mfma_f32_16x16x32_bf16 v[44:47], v[154:157], v[170:173], v[44:47]
	v_mfma_f32_16x16x32_bf16 v[36:39], v[146:149], v[178:181], v[36:39]
	v_mfma_f32_16x16x32_bf16 v[28:31], v[154:157], v[178:181], v[28:31]
	v_mfma_f32_16x16x32_bf16 v[20:23], v[146:149], v[196:199], v[20:23]
	v_mfma_f32_16x16x32_bf16 v[12:15], v[154:157], v[196:199], v[12:15]
	s_barrier
; #define PG8_STAGE(bufoff, gbase, voff) do { _Pragma("unroll") for (int _i = 0; _i < 2; ++_i) \
;         __builtin_amdgcn_global_load_lds((const unsigned*)((const char*)(gbase) + (voff)[_i]), (LAS unsigned*)(lds + (bufoff) + ldsw + _i * 8192), 16, 0, 0); } while (0)
; #define PG8_LDA(dst, b, h) do { _Pragma("unroll") for (int m = 0; m < 4; ++m) _Pragma("unroll") for (int k = 0; k < 2; ++k) dst[m][k] = *(const LAS bf16x8*)(lds + PG8_SA(b, h) + aoff + m * 2048 + k * 1024); } while (0)
; #define PG8_LDB(dst, b, h) do { _Pragma("unroll") for (int n = 0; n < 2; ++n) _Pragma("unroll") for (int k = 0; k < 2; ++k) dst[n][k] = *(const LAS bf16x8*)(lds + PG8_SB(b, h) + boff + n * 2048 + k * 1024); } while (0)
; #define PG8_MMA(ai, bj, At, Bt) do { __builtin_amdgcn_s_setprio(1); _Pragma("unroll") for (int m = 0; m < 4; ++m) _Pragma("unroll") for (int n = 0; n < 2; ++n) _Pragma("unroll") for (int k = 0; k < 2; ++k) \
;         acc[ai][bj][m][n] = __builtin_amdgcn_mfma_f32_16x16x32_bf16(Bt[n][k], At[m][k], acc[ai][bj][m][n], 0, 0, 0); __builtin_amdgcn_s_setprio(0); } while (0)
; #define PG8_WAIT_V(n) asm volatile("s_waitcnt vmcnt(" #n ")" ::: "memory")
; #define PG8_WAIT_L(n) asm volatile("s_waitcnt lgkmcnt(" #n ")" ::: "memory")
; #define PG8_BAR __builtin_amdgcn_s_barrier()
; #define PG8_SCHED __builtin_amdgcn_sched_barrier(0)
; template <class Epi>
; __device__ __forceinline__ void gemm_phase(LAS unsigned char* lds, const Gemm g, const StaticOrder& S, const Epi& E) {
;     ...
;             PG8_STAGE(PG8_SB(0, 1), b2 + hB, voffB);
;             PG8_WAIT_V(6); PG8_BAR; PG8_MMA(1, 1, At, B1); PG8_BAR;
;             PG8_LDB(B0, 1, 0); PG8_SCHED; PG8_LDA(At, 1, 0); PG8_STAGE(PG8_SA(0, 1), a2 + hA, voffA);
;             PG8_WAIT_L(8); PG8_BAR; PG8_WAIT_L(0); PG8_MMA(0, 0, At, B0); PG8_BAR; PG8_SCHED;
;             PG8_LDB(B1, 1, 1); PG8_STAGE(PG8_SB(1, 0), b3, voffB);
;             PG8_BAR; PG8_WAIT_L(0); PG8_MMA(0, 1, At, B1); PG8_BAR;
;             PG8_LDA(At, 1, 1); PG8_STAGE(PG8_SA(1, 0), a3, voffA);
	s_add_u32 s10, s16, 0xb0000
	s_addc_u32 s11, s17, 0
	s_add_i32 s26, s27, s35
	s_mov_b32 m0, s26
	s_nop 0
	global_load_lds_dwordx4 v144, s[10:11]
	s_add_i32 m0, s26, 0x2000
	s_nop 0
	global_load_lds_dwordx4 v128, s[10:11]
	s_waitcnt vmcnt(6)
	s_barrier
	v_mfma_f32_16x16x32_bf16 v[48:51], v[200:203], v[158:161], v[48:51]
	v_mfma_f32_16x16x32_bf16 v[40:43], v[214:217], v[158:161], v[40:43]
	v_mfma_f32_16x16x32_bf16 v[32:35], v[200:203], v[166:169], v[32:35]
	v_mfma_f32_16x16x32_bf16 v[24:27], v[214:217], v[166:169], v[24:27]
	v_mfma_f32_16x16x32_bf16 v[16:19], v[200:203], v[174:177], v[16:19]
	v_mfma_f32_16x16x32_bf16 v[8:11], v[214:217], v[174:177], v[8:11]
	v_mfma_f32_16x16x32_bf16 v[4:7], v[200:203], v[182:185], v[4:7]
	v_mfma_f32_16x16x32_bf16 v[0:3], v[214:217], v[182:185], v[0:3]
	v_mfma_f32_16x16x32_bf16 v[48:51], v[204:207], v[162:165], v[48:51]
	v_mfma_f32_16x16x32_bf16 v[40:43], v[218:221], v[162:165], v[40:43]
	v_mfma_f32_16x16x32_bf16 v[32:35], v[204:207], v[170:173], v[32:35]
	v_mfma_f32_16x16x32_bf16 v[24:27], v[218:221], v[170:173], v[24:27]
	v_mfma_f32_16x16x32_bf16 v[16:19], v[204:207], v[178:181], v[16:19]
	v_mfma_f32_16x16x32_bf16 v[8:11], v[218:221], v[178:181], v[8:11]
	v_mfma_f32_16x16x32_bf16 v[4:7], v[204:207], v[196:199], v[4:7]
	v_mfma_f32_16x16x32_bf16 v[0:3], v[218:221], v[196:199], v[0:3]
	s_add_i32 s26, 0, 0x18000
	v_add_u32_e32 v154, s26, v139
	s_barrier
	ds_read_b128 v[134:137], v154
	ds_read_b128 v[146:149], v154 offset:1024
	ds_read_b128 v[150:153], v154 offset:2048
	ds_read_b128 v[154:157], v154 offset:3072
	s_add_u32 s10, s20, 0xb0000
	s_addc_u32 s11, s21, 0
	s_mov_b32 m0, s63
	ds_read_b128 v[158:161], v141 offset:32768
	ds_read_b128 v[162:165], v141 offset:33792
	ds_read_b128 v[166:169], v141 offset:34816
	ds_read_b128 v[170:173], v141 offset:35840
	ds_read_b128 v[174:177], v141 offset:36864
	ds_read_b128 v[178:181], v141 offset:37888
	ds_read_b128 v[182:185], v141 offset:38912
	ds_read_b128 v[196:199], v141 offset:39936
	global_load_lds_dwordx4 v144, s[10:11]
	s_mov_b32 m0, s64
	s_nop 0
	global_load_lds_dwordx4 v128, s[10:11]
	s_waitcnt lgkmcnt(8)
	s_barrier
	s_waitcnt lgkmcnt(0)
	v_mfma_f32_16x16x32_bf16 v[124:127], v[134:137], v[158:161], v[124:127]
	v_mfma_f32_16x16x32_bf16 v[120:123], v[150:153], v[158:161], v[120:123]
	v_mfma_f32_16x16x32_bf16 v[116:119], v[134:137], v[166:169], v[116:119]
	v_mfma_f32_16x16x32_bf16 v[108:111], v[150:153], v[166:169], v[108:111]
	v_mfma_f32_16x16x32_bf16 v[100:103], v[134:137], v[174:177], v[100:103]
	v_mfma_f32_16x16x32_bf16 v[92:95], v[150:153], v[174:177], v[92:95]
	v_mfma_f32_16x16x32_bf16 v[84:87], v[134:137], v[182:185], v[84:87]
	v_mfma_f32_16x16x32_bf16 v[76:79], v[150:153], v[182:185], v[76:79]
	v_mfma_f32_16x16x32_bf16 v[124:127], v[146:149], v[162:165], v[124:127]
	v_mfma_f32_16x16x32_bf16 v[120:123], v[154:157], v[162:165], v[120:123]
	v_mfma_f32_16x16x32_bf16 v[116:119], v[146:149], v[170:173], v[116:119]
	v_mfma_f32_16x16x32_bf16 v[108:111], v[154:157], v[170:173], v[108:111]
	v_mfma_f32_16x16x32_bf16 v[100:103], v[146:149], v[178:181], v[100:103]
	v_mfma_f32_16x16x32_bf16 v[92:95], v[154:157], v[178:181], v[92:95]
	v_mfma_f32_16x16x32_bf16 v[84:87], v[146:149], v[196:199], v[84:87]
	v_mfma_f32_16x16x32_bf16 v[76:79], v[154:157], v[196:199], v[76:79]
	s_barrier
	s_add_i32 s20, 0, 0x1c000
	s_add_i32 s10, s26, s35
	v_add_u32_e32 v190, s20, v139
	v_lshl_add_u64 v[142:143], v[142:143], 0, s[88:89]
	s_mov_b32 m0, s10
	ds_read_b128 v[200:203], v190
	ds_read_b128 v[204:207], v190 offset:1024
	ds_read_b128 v[214:217], v190 offset:2048
	ds_read_b128 v[218:221], v190 offset:3072
	global_load_lds_dwordx4 v[142:143], off
	s_add_i32 m0, s10, 0x2000
	v_lshl_add_u64 v[142:143], v[186:187], 0, s[88:89]
	global_load_lds_dwordx4 v[142:143], off
	s_barrier
	s_waitcnt lgkmcnt(0)
	v_mfma_f32_16x16x32_bf16 v[112:115], v[200:203], v[158:161], v[112:115]
	v_mfma_f32_16x16x32_bf16 v[104:107], v[214:217], v[158:161], v[104:107]
	v_mfma_f32_16x16x32_bf16 v[96:99], v[200:203], v[166:169], v[96:99]
	v_mfma_f32_16x16x32_bf16 v[88:91], v[214:217], v[166:169], v[88:91]
	v_mfma_f32_16x16x32_bf16 v[80:83], v[200:203], v[174:177], v[80:83]
	v_mfma_f32_16x16x32_bf16 v[72:75], v[214:217], v[174:177], v[72:75]
	v_mfma_f32_16x16x32_bf16 v[68:71], v[200:203], v[182:185], v[68:71]
	v_mfma_f32_16x16x32_bf16 v[64:67], v[214:217], v[182:185], v[64:67]
	v_mfma_f32_16x16x32_bf16 v[112:115], v[204:207], v[162:165], v[112:115]
	v_mfma_f32_16x16x32_bf16 v[104:107], v[218:221], v[162:165], v[104:107]
	v_mfma_f32_16x16x32_bf16 v[96:99], v[204:207], v[170:173], v[96:99]
	v_mfma_f32_16x16x32_bf16 v[88:91], v[218:221], v[170:173], v[88:91]
	v_mfma_f32_16x16x32_bf16 v[80:83], v[204:207], v[178:181], v[80:83]
	v_mfma_f32_16x16x32_bf16 v[72:75], v[218:221], v[178:181], v[72:75]
	v_mfma_f32_16x16x32_bf16 v[68:71], v[204:207], v[196:199], v[68:71]
	v_mfma_f32_16x16x32_bf16 v[64:67], v[218:221], v[196:199], v[64:67]
	s_mov_b32 m0, s65
	v_lshl_add_u64 v[142:143], v[188:189], 0, s[88:89]
	s_barrier
	ds_read_b128 v[158:161], v141 offset:49152
	ds_read_b128 v[162:165], v141 offset:50176
	ds_read_b128 v[166:169], v141 offset:51200
	ds_read_b128 v[170:173], v141 offset:52224
	ds_read_b128 v[174:177], v141 offset:53248
	ds_read_b128 v[178:181], v141 offset:54272
	ds_read_b128 v[182:185], v141 offset:55296
	ds_read_b128 v[196:199], v141 offset:56320
	global_load_lds_dwordx4 v[142:143], off
	s_mov_b32 m0, s66
	v_lshl_add_u64 v[142:143], v[192:193], 0, s[88:89]
	global_load_lds_dwordx4 v[142:143], off
	s_barrier
; #define PG8_STAGE(bufoff, gbase, voff) do { _Pragma("unroll") for (int _i = 0; _i < 2; ++_i) \
;         __builtin_amdgcn_global_load_lds((const unsigned*)((const char*)(gbase) + (voff)[_i]), (LAS unsigned*)(lds + (bufoff) + ldsw + _i * 8192), 16, 0, 0); } while (0)
; #define PG8_MMA(ai, bj, At, Bt) do { __builtin_amdgcn_s_setprio(1); _Pragma("unroll") for (int m = 0; m < 4; ++m) _Pragma("unroll") for (int n = 0; n < 2; ++n) _Pragma("unroll") for (int k = 0; k < 2; ++k) \
;         acc[ai][bj][m][n] = __builtin_amdgcn_mfma_f32_16x16x32_bf16(Bt[n][k], At[m][k], acc[ai][bj][m][n], 0, 0, 0); __builtin_amdgcn_s_setprio(0); } while (0)
; #define PG8_WAIT_V(n) asm volatile("s_waitcnt vmcnt(" #n ")" ::: "memory")
; #define PG8_WAIT_L(n) asm volatile("s_waitcnt lgkmcnt(" #n ")" ::: "memory")
; #define PG8_BAR __builtin_amdgcn_s_barrier()
; #define PG8_SCHED __builtin_amdgcn_sched_barrier(0)
; template <class Epi>
; __device__ __forceinline__ void gemm_phase(LAS unsigned char* lds, const Gemm g, const StaticOrder& S, const Epi& E) {
;     ...
;             PG8_BAR; PG8_WAIT_L(0); PG8_MMA(1, 0, At, B0); PG8_BAR; PG8_SCHED;
;             PG8_STAGE(PG8_SB(1, 1), b3 + hB, voffB);
;             PG8_WAIT_V(6); PG8_BAR; PG8_MMA(1, 1, At, B1); PG8_BAR;
	s_waitcnt lgkmcnt(0)
	v_mfma_f32_16x16x32_bf16 v[60:63], v[134:137], v[158:161], v[60:63]
	v_mfma_f32_16x16x32_bf16 v[56:59], v[150:153], v[158:161], v[56:59]
	v_mfma_f32_16x16x32_bf16 v[52:55], v[134:137], v[166:169], v[52:55]
	v_mfma_f32_16x16x32_bf16 v[44:47], v[150:153], v[166:169], v[44:47]
	v_mfma_f32_16x16x32_bf16 v[36:39], v[134:137], v[174:177], v[36:39]
	v_mfma_f32_16x16x32_bf16 v[28:31], v[150:153], v[174:177], v[28:31]
	v_mfma_f32_16x16x32_bf16 v[20:23], v[134:137], v[182:185], v[20:23]
	v_mfma_f32_16x16x32_bf16 v[12:15], v[150:153], v[182:185], v[12:15]
	v_mfma_f32_16x16x32_bf16 v[60:63], v[146:149], v[162:165], v[60:63]
	v_mfma_f32_16x16x32_bf16 v[56:59], v[154:157], v[162:165], v[56:59]
	v_mfma_f32_16x16x32_bf16 v[52:55], v[146:149], v[170:173], v[52:55]
	v_mfma_f32_16x16x32_bf16 v[44:47], v[154:157], v[170:173], v[44:47]
	v_mfma_f32_16x16x32_bf16 v[36:39], v[146:149], v[178:181], v[36:39]
	v_mfma_f32_16x16x32_bf16 v[28:31], v[154:157], v[178:181], v[28:31]
	v_mfma_f32_16x16x32_bf16 v[20:23], v[146:149], v[196:199], v[20:23]
	v_mfma_f32_16x16x32_bf16 v[12:15], v[154:157], v[196:199], v[12:15]
	s_barrier
	s_add_u32 s10, s16, 0xb0080
	s_addc_u32 s11, s17, 0
	s_add_i32 s16, s20, s35
	s_mov_b32 m0, s16
	s_nop 0
	global_load_lds_dwordx4 v144, s[10:11]
	s_add_i32 m0, s16, 0x2000
	s_nop 0
	global_load_lds_dwordx4 v128, s[10:11]
	s_waitcnt vmcnt(6)
	s_barrier
	v_mfma_f32_16x16x32_bf16 v[48:51], v[200:203], v[158:161], v[48:51]
	v_mfma_f32_16x16x32_bf16 v[40:43], v[214:217], v[158:161], v[40:43]
	v_mfma_f32_16x16x32_bf16 v[32:35], v[200:203], v[166:169], v[32:35]
	v_mfma_f32_16x16x32_bf16 v[24:27], v[214:217], v[166:169], v[24:27]
	v_mfma_f32_16x16x32_bf16 v[16:19], v[200:203], v[174:177], v[16:19]
	v_mfma_f32_16x16x32_bf16 v[8:11], v[214:217], v[174:177], v[8:11]
	v_mfma_f32_16x16x32_bf16 v[4:7], v[200:203], v[182:185], v[4:7]
	v_mfma_f32_16x16x32_bf16 v[0:3], v[214:217], v[182:185], v[0:3]
	v_mfma_f32_16x16x32_bf16 v[48:51], v[204:207], v[162:165], v[48:51]
	v_mfma_f32_16x16x32_bf16 v[40:43], v[218:221], v[162:165], v[40:43]
	v_mfma_f32_16x16x32_bf16 v[32:35], v[204:207], v[170:173], v[32:35]
	v_mfma_f32_16x16x32_bf16 v[24:27], v[218:221], v[170:173], v[24:27]
	v_mfma_f32_16x16x32_bf16 v[16:19], v[204:207], v[178:181], v[16:19]
	v_mfma_f32_16x16x32_bf16 v[8:11], v[218:221], v[178:181], v[8:11]
	v_mfma_f32_16x16x32_bf16 v[4:7], v[204:207], v[196:199], v[4:7]
	v_mfma_f32_16x16x32_bf16 v[0:3], v[218:221], v[196:199], v[0:3]
	s_add_i32 s72, s72, 2
	s_add_u32 s24, s24, 0x100
	s_addc_u32 s25, s25, 0
	s_cmp_gt_u32 s72, 41
	s_mov_b64 s[10:11], s[12:13]
	s_barrier
	s_cbranch_scc0 .LBB0_349
; __device__ __forceinline__ unsigned pk2(float lo, float hi) { unsigned r; asm("v_cvt_pk_bf16_f32 %0, %1, %2" : "=v"(r) : "v"(lo), "v"(hi)); return r; }
;     __device__ __forceinline__ void operator()(const f32x4 (&acc)[2][2][4][2], const Unit& u, int wr, int wc, int fr, int fq) const {
;     ...
;         const int row_t = rmap == 1 ? odd_phys_row0(u.pm, grp) : (rmap == 2 ? odd_phys_row0(u.pm % (BG * TPB), u.pm / (BG * TPB)) : u.pm * BM);
;         int c = col_t + 64 * wc + 16 * fq;
;         if (mode == 2) c = (c >> 6) * 96 + (c & 63);
; #pragma unroll
;         for (int ai = 0; ai < 2; ++ai)
; #pragma unroll
;             for (int m = 0; m < 4; ++m) {
;                 const int row = row_t + ai * HALF + wr * 64 + m * 16 + fr;
;                 bf16_t* rp = O + (size_t)row * ldc + c;
; #pragma unroll
;                 for (int bj = 0; bj < 2; ++bj) {
;                     const f32x4 v0 = acc[ai][bj][m][0], v1 = acc[ai][bj][m][1];
;                     u32x4 o; o.x = pk2(v0[0], v0[1]); o.y = pk2(v0[2], v0[3]); o.z = pk2(v1[0], v1[1]); o.w = pk2(v1[2], v1[3]);
;                     *(u32x4*)(rp + 8 * bj) = o;
;                 }
;             }
	v_lshl_add_u32 v134, s71, 8, v138
	v_cvt_pk_bf16_f32 v68, v68, v69
	v_cvt_pk_bf16_f32 v69, v70, v71
	v_cvt_pk_bf16_f32 v70, v64, v65
	v_add_u32_e32 v64, 0x80, v134
	v_lshl_or_b32 v136, s15, 8, v140
	v_ashrrev_i32_e32 v135, 31, v134
	v_cvt_pk_bf16_f32 v112, v112, v113
	v_cvt_pk_bf16_f32 v113, v114, v115
	v_cvt_pk_bf16_f32 v114, v104, v105
	v_or_b32_e32 v104, 16, v134
	v_ashrrev_i32_e32 v65, 31, v64
	v_cvt_pk_bf16_f32 v48, v48, v49
	v_cvt_pk_bf16_f32 v49, v50, v51
	v_cvt_pk_bf16_f32 v50, v40, v41
	v_add_u32_e32 v40, 0x90, v134
	v_ashrrev_i32_e32 v137, 31, v136
	v_lshlrev_b64 v[142:143], 11, v[134:135]
	v_ashrrev_i32_e32 v105, 31, v104
	v_cvt_pk_bf16_f32 v96, v96, v97
	v_cvt_pk_bf16_f32 v97, v98, v99
	v_cvt_pk_bf16_f32 v98, v88, v89
	v_or_b32_e32 v88, 32, v134
	v_lshlrev_b64 v[64:65], 11, v[64:65]
	v_ashrrev_i32_e32 v41, 31, v40
	v_cvt_pk_bf16_f32 v32, v32, v33
	v_cvt_pk_bf16_f32 v33, v34, v35
	v_cvt_pk_bf16_f32 v34, v24, v25
	v_add_u32_e32 v24, 0xa0, v134
	v_lshl_add_u64 v[142:143], s[8:9], 0, v[142:143]
	v_lshlrev_b64 v[136:137], 1, v[136:137]
	v_lshlrev_b64 v[104:105], 11, v[104:105]
	v_ashrrev_i32_e32 v89, 31, v88
	v_cvt_pk_bf16_f32 v80, v80, v81
	v_cvt_pk_bf16_f32 v81, v82, v83
	v_cvt_pk_bf16_f32 v82, v72, v73
	v_or_b32_e32 v72, 48, v134
	v_lshl_add_u64 v[64:65], s[8:9], 0, v[64:65]
	v_lshlrev_b64 v[40:41], 11, v[40:41]
	v_ashrrev_i32_e32 v25, 31, v24
	v_cvt_pk_bf16_f32 v16, v16, v17
	v_cvt_pk_bf16_f32 v17, v18, v19
	v_cvt_pk_bf16_f32 v18, v8, v9
	v_add_u32_e32 v8, 0xb0, v134
	v_lshl_add_u64 v[142:143], v[142:143], 0, v[136:137]
	v_lshl_add_u64 v[104:105], s[8:9], 0, v[104:105]
	v_lshlrev_b64 v[88:89], 11, v[88:89]
	v_ashrrev_i32_e32 v73, 31, v72
	v_lshl_add_u64 v[64:65], v[64:65], 0, v[136:137]
	v_lshl_add_u64 v[40:41], s[8:9], 0, v[40:41]
	v_lshlrev_b64 v[24:25], 11, v[24:25]
	v_ashrrev_i32_e32 v9, 31, v8
	v_cvt_pk_bf16_f32 v115, v106, v107
	global_store_dwordx4 v[142:143], v[112:115], off offset:16
	v_lshl_add_u64 v[88:89], s[8:9], 0, v[88:89]
	v_lshlrev_b64 v[72:73], 11, v[72:73]
	v_lshl_add_u64 v[112:113], v[104:105], 0, v[136:137]
	v_cvt_pk_bf16_f32 v51, v42, v43
	global_store_dwordx4 v[64:65], v[48:51], off offset:16
	v_lshl_add_u64 v[24:25], s[8:9], 0, v[24:25]
	v_lshlrev_b64 v[8:9], 11, v[8:9]
	v_lshl_add_u64 v[48:49], v[40:41], 0, v[136:137]
	v_cvt_pk_bf16_f32 v99, v90, v91
	global_store_dwordx4 v[112:113], v[96:99], off offset:16
	v_lshl_add_u64 v[72:73], s[8:9], 0, v[72:73]
	v_cvt_pk_bf16_f32 v35, v26, v27
	global_store_dwordx4 v[48:49], v[32:35], off offset:16
	v_lshl_add_u64 v[96:97], v[88:89], 0, v[136:137]
	v_lshl_add_u64 v[8:9], s[8:9], 0, v[8:9]
	v_lshl_add_u64 v[32:33], v[24:25], 0, v[136:137]
	v_cvt_pk_bf16_f32 v83, v74, v75
	global_store_dwordx4 v[96:97], v[80:83], off offset:16
	v_cvt_pk_bf16_f32 v19, v10, v11
	global_store_dwordx4 v[32:33], v[16:19], off offset:16
	s_and_b64 vcc, exec, s[0:1]
	v_lshl_add_u64 v[80:81], v[72:73], 0, v[136:137]
	v_lshl_add_u64 v[16:17], v[8:9], 0, v[136:137]
	s_mov_b32 s15, s69
	s_mov_b32 s71, s70
	s_mov_b64 s[12:13], s[6:7]
	s_mov_b64 s[10:11], s[4:5]
	v_cvt_pk_bf16_f32 v124, v124, v125
	v_cvt_pk_bf16_f32 v125, v126, v127
	v_cvt_pk_bf16_f32 v126, v120, v121
	v_cvt_pk_bf16_f32 v127, v122, v123
	global_store_dwordx4 v[142:143], v[124:127], off
	v_cvt_pk_bf16_f32 v104, v116, v117
	v_cvt_pk_bf16_f32 v105, v118, v119
	v_cvt_pk_bf16_f32 v106, v108, v109
	v_cvt_pk_bf16_f32 v107, v110, v111
	global_store_dwordx4 v[112:113], v[104:107], off
	v_cvt_pk_bf16_f32 v88, v100, v101
	v_cvt_pk_bf16_f32 v89, v102, v103
	v_cvt_pk_bf16_f32 v90, v92, v93
	v_cvt_pk_bf16_f32 v91, v94, v95
	global_store_dwordx4 v[96:97], v[88:91], off
	v_cvt_pk_bf16_f32 v72, v84, v85
	v_cvt_pk_bf16_f32 v73, v86, v87
	v_cvt_pk_bf16_f32 v74, v76, v77
	v_cvt_pk_bf16_f32 v75, v78, v79
	global_store_dwordx4 v[80:81], v[72:75], off
	v_cvt_pk_bf16_f32 v71, v66, v67
	global_store_dwordx4 v[80:81], v[68:71], off offset:16
	v_cvt_pk_bf16_f32 v60, v60, v61
	v_cvt_pk_bf16_f32 v61, v62, v63
	v_cvt_pk_bf16_f32 v62, v56, v57
	v_cvt_pk_bf16_f32 v63, v58, v59
	global_store_dwordx4 v[64:65], v[60:63], off
	v_cvt_pk_bf16_f32 v40, v52, v53
	v_cvt_pk_bf16_f32 v41, v54, v55
	v_cvt_pk_bf16_f32 v42, v44, v45
	v_cvt_pk_bf16_f32 v43, v46, v47
	global_store_dwordx4 v[48:49], v[40:43], off
	v_cvt_pk_bf16_f32 v24, v36, v37
	v_cvt_pk_bf16_f32 v25, v38, v39
	v_cvt_pk_bf16_f32 v26, v28, v29
	v_cvt_pk_bf16_f32 v27, v30, v31
	global_store_dwordx4 v[32:33], v[24:27], off
	v_cvt_pk_bf16_f32 v8, v20, v21
	v_cvt_pk_bf16_f32 v9, v22, v23
	v_cvt_pk_bf16_f32 v10, v12, v13
	v_cvt_pk_bf16_f32 v11, v14, v15
	global_store_dwordx4 v[16:17], v[8:11], off
	v_cvt_pk_bf16_f32 v4, v4, v5
	v_cvt_pk_bf16_f32 v5, v6, v7
	v_cvt_pk_bf16_f32 v6, v0, v1
	v_cvt_pk_bf16_f32 v7, v2, v3
	global_store_dwordx4 v[16:17], v[4:7], off offset:16
	s_cbranch_vccz .LBB0_342
	s_waitcnt vmcnt(0)
	s_cmpk_gt_u32 s3, 0xff
	s_cbranch_scc1 .LBB0_353
	s_barrier

; #define PG8_STAGE(bufoff, gbase, voff) do { _Pragma("unroll") for (int _i = 0; _i < 2; ++_i) \
;         __builtin_amdgcn_global_load_lds((const unsigned*)((const char*)(gbase) + (voff)[_i]), (LAS unsigned*)(lds + (bufoff) + ldsw + _i * 8192), 16, 0, 0); } while (0)
; #define PG8_LDA(dst, b, h) do { _Pragma("unroll") for (int m = 0; m < 4; ++m) _Pragma("unroll") for (int k = 0; k < 2; ++k) dst[m][k] = *(const LAS bf16x8*)(lds + PG8_SA(b, h) + aoff + m * 2048 + k * 1024); } while (0)
; #define PG8_LDB(dst, b, h) do { _Pragma("unroll") for (int n = 0; n < 2; ++n) _Pragma("unroll") for (int k = 0; k < 2; ++k) dst[n][k] = *(const LAS bf16x8*)(lds + PG8_SB(b, h) + boff + n * 2048 + k * 1024); } while (0)
; #define PG8_MMA(ai, bj, At, Bt) do { __builtin_amdgcn_s_setprio(1); _Pragma("unroll") for (int m = 0; m < 4; ++m) _Pragma("unroll") for (int n = 0; n < 2; ++n) _Pragma("unroll") for (int k = 0; k < 2; ++k) \
;         acc[ai][bj][m][n] = __builtin_amdgcn_mfma_f32_16x16x32_bf16(Bt[n][k], At[m][k], acc[ai][bj][m][n], 0, 0, 0); __builtin_amdgcn_s_setprio(0); } while (0)
; #define PG8_WAIT_L(n) asm volatile("s_waitcnt lgkmcnt(" #n ")" ::: "memory")
; #define PG8_BAR __builtin_amdgcn_s_barrier()
; template <class Epi>
; __device__ __forceinline__ void gemm_phase(LAS unsigned char* lds, const Gemm g, const StaticOrder& S, const Epi& E) {
;     ...
;         const bool has_next = S.next(ui + 1, nxt);
;         const char* nA = has_next ? g.arow(nxt.pm) : cA; const char* nB = has_next ? (const char*)g.Bt + (size_t)nxt.pn * tB : cB;
;         for (int t = 0; t < nt; t += 2) {
;             const bool last = (t == nt - 2);
;             const char* a1 = cA + (size_t)(t + 1) * kstep;
;             const char* a2 = last ? nA : cA + (size_t)(t + 2) * kstep; const char* b2 = last ? nB : cB + (size_t)(t + 2) * kstep;
;             const char* a3 = a2 + kstep; const char* b3 = b2 + kstep;
;             PG8_LDB(B0, 0, 0); PG8_SCHED; PG8_LDA(At, 0, 0); PG8_STAGE(PG8_SA(1, 1), a1 + hA, voffA);
;             PG8_WAIT_L(8); PG8_BAR; PG8_WAIT_L(0); PG8_MMA(0, 0, At, B0); PG8_BAR; PG8_SCHED;
;             PG8_LDB(B1, 0, 1); PG8_STAGE(PG8_SB(0, 0), b2, voffB);
;             PG8_BAR; PG8_WAIT_L(0); PG8_MMA(0, 1, At, B1); PG8_BAR;
;             PG8_LDA(At, 0, 1); PG8_STAGE(PG8_SA(0, 0), a2, voffA);
;             PG8_BAR; PG8_WAIT_L(0); PG8_MMA(1, 0, At, B0); PG8_BAR; PG8_SCHED;
.LBB0_499:
	s_add_u32 s26, s4, 0xfffc0080
	s_addc_u32 s27, s5, -1
	s_add_i32 s28, 0, 0x10000
	v_add_u32_e32 v146, s28, v149
	ds_read_b128 v[136:139], v146
	ds_read_b128 v[140:143], v146 offset:1024
	ds_read_b128 v[158:161], v146 offset:2048
	ds_read_b128 v[162:165], v146 offset:3072
	s_cmp_eq_u32 s84, 12
	s_cselect_b32 s65, s21, s27
	s_cselect_b32 s64, s20, s26
	s_cselect_b32 s35, s15, s25
	s_cselect_b32 s34, s17, s24
	s_add_i32 m0, s66, 0xc000
	ds_read_b128 v[166:169], v154
	ds_read_b128 v[170:173], v154 offset:1024
	ds_read_b128 v[174:177], v154 offset:2048
	ds_read_b128 v[178:181], v154 offset:3072
	ds_read_b128 v[182:185], v154 offset:4096
	ds_read_b128 v[196:199], v154 offset:5120
	ds_read_b128 v[200:203], v154 offset:6144
	ds_read_b128 v[204:207], v154 offset:7168
	global_load_lds_dwordx4 v132, s[4:5]
	s_add_i32 m0, s66, 0xe000
	v_lshl_add_u64 v[146:147], s[4:5], 0, v[134:135]
	global_load_lds_dwordx4 v[146:147], off
	s_waitcnt lgkmcnt(8)
	s_barrier
	s_waitcnt lgkmcnt(0)
	v_mfma_f32_16x16x32_bf16 v[124:127], v[136:139], v[166:169], v[124:127]
	v_mfma_f32_16x16x32_bf16 v[120:123], v[158:161], v[166:169], v[120:123]
	v_mfma_f32_16x16x32_bf16 v[116:119], v[136:139], v[174:177], v[116:119]
	v_mfma_f32_16x16x32_bf16 v[108:111], v[158:161], v[174:177], v[108:111]
	v_mfma_f32_16x16x32_bf16 v[100:103], v[136:139], v[182:185], v[100:103]
	v_mfma_f32_16x16x32_bf16 v[92:95], v[158:161], v[182:185], v[92:95]
	v_mfma_f32_16x16x32_bf16 v[84:87], v[136:139], v[200:203], v[84:87]
	v_mfma_f32_16x16x32_bf16 v[76:79], v[158:161], v[200:203], v[76:79]
	v_mfma_f32_16x16x32_bf16 v[124:127], v[140:143], v[170:173], v[124:127]
	v_mfma_f32_16x16x32_bf16 v[120:123], v[162:165], v[170:173], v[120:123]
	v_mfma_f32_16x16x32_bf16 v[116:119], v[140:143], v[178:181], v[116:119]
	v_mfma_f32_16x16x32_bf16 v[108:111], v[162:165], v[178:181], v[108:111]
	v_mfma_f32_16x16x32_bf16 v[100:103], v[140:143], v[196:199], v[100:103]
	v_mfma_f32_16x16x32_bf16 v[92:95], v[162:165], v[196:199], v[92:95]
	v_mfma_f32_16x16x32_bf16 v[84:87], v[140:143], v[204:207], v[84:87]
	v_mfma_f32_16x16x32_bf16 v[76:79], v[162:165], v[204:207], v[76:79]
	s_barrier
	s_add_i32 s29, 0, 0x14000
	v_add_u32_e32 v146, s29, v149
	s_add_i32 s26, s28, s71
	ds_read_b128 v[216:219], v146
	ds_read_b128 v[220:223], v146 offset:1024
	ds_read_b128 v[224:227], v146 offset:2048
	ds_read_b128 v[228:231], v146 offset:3072
	v_lshl_add_u64 v[146:147], s[34:35], 0, v[128:129]
	s_mov_b32 m0, s26
	v_lshl_add_u64 v[186:187], s[34:35], 0, v[130:131]
	global_load_lds_dwordx4 v[146:147], off
	s_add_i32 m0, s26, 0x2000
	s_nop 0
	global_load_lds_dwordx4 v[186:187], off
	s_barrier
	s_waitcnt lgkmcnt(0)
	v_mfma_f32_16x16x32_bf16 v[112:115], v[216:219], v[166:169], v[112:115]
	v_mfma_f32_16x16x32_bf16 v[104:107], v[224:227], v[166:169], v[104:107]
	v_mfma_f32_16x16x32_bf16 v[96:99], v[216:219], v[174:177], v[96:99]
	v_mfma_f32_16x16x32_bf16 v[88:91], v[224:227], v[174:177], v[88:91]
	v_mfma_f32_16x16x32_bf16 v[80:83], v[216:219], v[182:185], v[80:83]
	v_mfma_f32_16x16x32_bf16 v[72:75], v[224:227], v[182:185], v[72:75]
	v_mfma_f32_16x16x32_bf16 v[68:71], v[216:219], v[200:203], v[68:71]
	v_mfma_f32_16x16x32_bf16 v[64:67], v[224:227], v[200:203], v[64:67]
	v_mfma_f32_16x16x32_bf16 v[112:115], v[220:223], v[170:173], v[112:115]
	v_mfma_f32_16x16x32_bf16 v[104:107], v[228:231], v[170:173], v[104:107]
	v_mfma_f32_16x16x32_bf16 v[96:99], v[220:223], v[178:181], v[96:99]
	v_mfma_f32_16x16x32_bf16 v[88:91], v[228:231], v[178:181], v[88:91]
	v_mfma_f32_16x16x32_bf16 v[80:83], v[220:223], v[196:199], v[80:83]
	v_mfma_f32_16x16x32_bf16 v[72:75], v[228:231], v[196:199], v[72:75]
	v_mfma_f32_16x16x32_bf16 v[68:71], v[220:223], v[204:207], v[68:71]
	v_mfma_f32_16x16x32_bf16 v[64:67], v[228:231], v[204:207], v[64:67]
	s_mov_b32 m0, s66
	v_lshl_add_u64 v[188:189], s[64:65], 0, v[128:129]
	s_barrier
	ds_read_b128 v[166:169], v154 offset:16384
	ds_read_b128 v[170:173], v154 offset:17408
	ds_read_b128 v[174:177], v154 offset:18432
	ds_read_b128 v[178:181], v154 offset:19456
	ds_read_b128 v[182:185], v154 offset:20480
	ds_read_b128 v[196:199], v154 offset:21504
	ds_read_b128 v[200:203], v154 offset:22528
	ds_read_b128 v[204:207], v154 offset:23552
	global_load_lds_dwordx4 v[188:189], off
	s_mov_b32 m0, s72
	v_lshl_add_u64 v[192:193], s[64:65], 0, v[130:131]
	global_load_lds_dwordx4 v[192:193], off
	s_barrier
	s_waitcnt lgkmcnt(0)
	v_mfma_f32_16x16x32_bf16 v[60:63], v[136:139], v[166:169], v[60:63]
	v_mfma_f32_16x16x32_bf16 v[56:59], v[158:161], v[166:169], v[56:59]
	v_mfma_f32_16x16x32_bf16 v[52:55], v[136:139], v[174:177], v[52:55]
	v_mfma_f32_16x16x32_bf16 v[44:47], v[158:161], v[174:177], v[44:47]
	v_mfma_f32_16x16x32_bf16 v[36:39], v[136:139], v[182:185], v[36:39]
	v_mfma_f32_16x16x32_bf16 v[28:31], v[158:161], v[182:185], v[28:31]
	v_mfma_f32_16x16x32_bf16 v[20:23], v[136:139], v[200:203], v[20:23]
	v_mfma_f32_16x16x32_bf16 v[12:15], v[158:161], v[200:203], v[12:15]
	v_mfma_f32_16x16x32_bf16 v[60:63], v[140:143], v[170:173], v[60:63]
	v_mfma_f32_16x16x32_bf16 v[56:59], v[162:165], v[170:173], v[56:59]
	v_mfma_f32_16x16x32_bf16 v[52:55], v[140:143], v[178:181], v[52:55]
	v_mfma_f32_16x16x32_bf16 v[44:47], v[162:165], v[178:181], v[44:47]
	v_mfma_f32_16x16x32_bf16 v[36:39], v[140:143], v[196:199], v[36:39]
	v_mfma_f32_16x16x32_bf16 v[28:31], v[162:165], v[196:199], v[28:31]
	v_mfma_f32_16x16x32_bf16 v[20:23], v[140:143], v[204:207], v[20:23]
	v_mfma_f32_16x16x32_bf16 v[12:15], v[162:165], v[204:207], v[12:15]
	s_barrier
; #define PG8_STAGE(bufoff, gbase, voff) do { _Pragma("unroll") for (int _i = 0; _i < 2; ++_i) \
;         __builtin_amdgcn_global_load_lds((const unsigned*)((const char*)(gbase) + (voff)[_i]), (LAS unsigned*)(lds + (bufoff) + ldsw + _i * 8192), 16, 0, 0); } while (0)
; #define PG8_LDA(dst, b, h) do { _Pragma("unroll") for (int m = 0; m < 4; ++m) _Pragma("unroll") for (int k = 0; k < 2; ++k) dst[m][k] = *(const LAS bf16x8*)(lds + PG8_SA(b, h) + aoff + m * 2048 + k * 1024); } while (0)
; #define PG8_LDB(dst, b, h) do { _Pragma("unroll") for (int n = 0; n < 2; ++n) _Pragma("unroll") for (int k = 0; k < 2; ++k) dst[n][k] = *(const LAS bf16x8*)(lds + PG8_SB(b, h) + boff + n * 2048 + k * 1024); } while (0)
; #define PG8_MMA(ai, bj, At, Bt) do { __builtin_amdgcn_s_setprio(1); _Pragma("unroll") for (int m = 0; m < 4; ++m) _Pragma("unroll") for (int n = 0; n < 2; ++n) _Pragma("unroll") for (int k = 0; k < 2; ++k) \
;         acc[ai][bj][m][n] = __builtin_amdgcn_mfma_f32_16x16x32_bf16(Bt[n][k], At[m][k], acc[ai][bj][m][n], 0, 0, 0); __builtin_amdgcn_s_setprio(0); } while (0)
; #define PG8_WAIT_V(n) asm volatile("s_waitcnt vmcnt(" #n ")" ::: "memory")
; #define PG8_WAIT_L(n) asm volatile("s_waitcnt lgkmcnt(" #n ")" ::: "memory")
; #define PG8_BAR __builtin_amdgcn_s_barrier()
; #define PG8_SCHED __builtin_amdgcn_sched_barrier(0)
; template <class Epi>
; __device__ __forceinline__ void gemm_phase(LAS unsigned char* lds, const Gemm g, const StaticOrder& S, const Epi& E) {
;     ...
;             PG8_STAGE(PG8_SB(0, 1), b2 + hB, voffB);
;             PG8_WAIT_V(6); PG8_BAR; PG8_MMA(1, 1, At, B1); PG8_BAR;
;             PG8_LDB(B0, 1, 0); PG8_SCHED; PG8_LDA(At, 1, 0); PG8_STAGE(PG8_SA(0, 1), a2 + hA, voffA);
;             PG8_WAIT_L(8); PG8_BAR; PG8_WAIT_L(0); PG8_MMA(0, 0, At, B0); PG8_BAR; PG8_SCHED;
;             PG8_LDB(B1, 1, 1); PG8_STAGE(PG8_SB(1, 0), b3, voffB);
;             PG8_BAR; PG8_WAIT_L(0); PG8_MMA(0, 1, At, B1); PG8_BAR;
;             PG8_LDA(At, 1, 1); PG8_STAGE(PG8_SA(1, 0), a3, voffA);
	s_add_u32 s26, s34, 0x40000
	s_addc_u32 s27, s35, 0
	s_add_i32 s28, s29, s71
	s_mov_b32 m0, s28
	s_nop 0
	global_load_lds_dwordx4 v128, s[26:27]
	s_add_i32 m0, s28, 0x2000
	s_nop 0
	global_load_lds_dwordx4 v130, s[26:27]
	s_waitcnt vmcnt(6)
	s_barrier
	v_mfma_f32_16x16x32_bf16 v[48:51], v[216:219], v[166:169], v[48:51]
	v_mfma_f32_16x16x32_bf16 v[40:43], v[224:227], v[166:169], v[40:43]
	v_mfma_f32_16x16x32_bf16 v[32:35], v[216:219], v[174:177], v[32:35]
	v_mfma_f32_16x16x32_bf16 v[24:27], v[224:227], v[174:177], v[24:27]
	v_mfma_f32_16x16x32_bf16 v[16:19], v[216:219], v[182:185], v[16:19]
	v_mfma_f32_16x16x32_bf16 v[8:11], v[224:227], v[182:185], v[8:11]
	v_mfma_f32_16x16x32_bf16 v[4:7], v[216:219], v[200:203], v[4:7]
	v_mfma_f32_16x16x32_bf16 v[0:3], v[224:227], v[200:203], v[0:3]
	v_mfma_f32_16x16x32_bf16 v[48:51], v[220:223], v[170:173], v[48:51]
	v_mfma_f32_16x16x32_bf16 v[40:43], v[228:231], v[170:173], v[40:43]
	v_mfma_f32_16x16x32_bf16 v[32:35], v[220:223], v[178:181], v[32:35]
	v_mfma_f32_16x16x32_bf16 v[24:27], v[228:231], v[178:181], v[24:27]
	v_mfma_f32_16x16x32_bf16 v[16:19], v[220:223], v[196:199], v[16:19]
	v_mfma_f32_16x16x32_bf16 v[8:11], v[228:231], v[196:199], v[8:11]
	v_mfma_f32_16x16x32_bf16 v[4:7], v[220:223], v[204:207], v[4:7]
	v_mfma_f32_16x16x32_bf16 v[0:3], v[228:231], v[204:207], v[0:3]
	s_add_i32 s28, 0, 0x18000
	v_add_u32_e32 v157, s28, v149
	s_barrier
	ds_read_b128 v[136:139], v157
	ds_read_b128 v[140:143], v157 offset:1024
	ds_read_b128 v[158:161], v157 offset:2048
	ds_read_b128 v[162:165], v157 offset:3072
	s_add_u32 s26, s64, 0x40000
	s_addc_u32 s27, s65, 0
	s_mov_b32 m0, s76
	ds_read_b128 v[166:169], v154 offset:32768
	ds_read_b128 v[170:173], v154 offset:33792
	ds_read_b128 v[174:177], v154 offset:34816
	ds_read_b128 v[178:181], v154 offset:35840
	ds_read_b128 v[182:185], v154 offset:36864
	ds_read_b128 v[196:199], v154 offset:37888
	ds_read_b128 v[200:203], v154 offset:38912
	ds_read_b128 v[204:207], v154 offset:39936
	global_load_lds_dwordx4 v128, s[26:27]
	s_mov_b32 m0, s77
	s_nop 0
	global_load_lds_dwordx4 v130, s[26:27]
	s_waitcnt lgkmcnt(8)
	s_barrier
	s_waitcnt lgkmcnt(0)
	v_mfma_f32_16x16x32_bf16 v[124:127], v[136:139], v[166:169], v[124:127]
	v_mfma_f32_16x16x32_bf16 v[120:123], v[158:161], v[166:169], v[120:123]
	v_mfma_f32_16x16x32_bf16 v[116:119], v[136:139], v[174:177], v[116:119]
	v_mfma_f32_16x16x32_bf16 v[108:111], v[158:161], v[174:177], v[108:111]
	v_mfma_f32_16x16x32_bf16 v[100:103], v[136:139], v[182:185], v[100:103]
	v_mfma_f32_16x16x32_bf16 v[92:95], v[158:161], v[182:185], v[92:95]
	v_mfma_f32_16x16x32_bf16 v[84:87], v[136:139], v[200:203], v[84:87]
	v_mfma_f32_16x16x32_bf16 v[76:79], v[158:161], v[200:203], v[76:79]
	v_mfma_f32_16x16x32_bf16 v[124:127], v[140:143], v[170:173], v[124:127]
	v_mfma_f32_16x16x32_bf16 v[120:123], v[162:165], v[170:173], v[120:123]
	v_mfma_f32_16x16x32_bf16 v[116:119], v[140:143], v[178:181], v[116:119]
	v_mfma_f32_16x16x32_bf16 v[108:111], v[162:165], v[178:181], v[108:111]
	v_mfma_f32_16x16x32_bf16 v[100:103], v[140:143], v[196:199], v[100:103]
	v_mfma_f32_16x16x32_bf16 v[92:95], v[162:165], v[196:199], v[92:95]
	v_mfma_f32_16x16x32_bf16 v[84:87], v[140:143], v[204:207], v[84:87]
	v_mfma_f32_16x16x32_bf16 v[76:79], v[162:165], v[204:207], v[76:79]
	s_barrier
	s_add_i32 s29, 0, 0x1c000
	s_add_i32 s26, s28, s71
	v_add_u32_e32 v157, s29, v149
	v_lshl_add_u64 v[146:147], v[146:147], 0, s[88:89]
	s_mov_b32 m0, s26
	ds_read_b128 v[216:219], v157
	ds_read_b128 v[220:223], v157 offset:1024
	ds_read_b128 v[224:227], v157 offset:2048
	ds_read_b128 v[228:231], v157 offset:3072
	global_load_lds_dwordx4 v[146:147], off
	s_add_i32 m0, s26, 0x2000
	v_lshl_add_u64 v[146:147], v[186:187], 0, s[88:89]
	global_load_lds_dwordx4 v[146:147], off
	s_barrier
	s_waitcnt lgkmcnt(0)
	v_mfma_f32_16x16x32_bf16 v[112:115], v[216:219], v[166:169], v[112:115]
	v_mfma_f32_16x16x32_bf16 v[104:107], v[224:227], v[166:169], v[104:107]
	v_mfma_f32_16x16x32_bf16 v[96:99], v[216:219], v[174:177], v[96:99]
	v_mfma_f32_16x16x32_bf16 v[88:91], v[224:227], v[174:177], v[88:91]
	v_mfma_f32_16x16x32_bf16 v[80:83], v[216:219], v[182:185], v[80:83]
	v_mfma_f32_16x16x32_bf16 v[72:75], v[224:227], v[182:185], v[72:75]
	v_mfma_f32_16x16x32_bf16 v[68:71], v[216:219], v[200:203], v[68:71]
	v_mfma_f32_16x16x32_bf16 v[64:67], v[224:227], v[200:203], v[64:67]
	v_mfma_f32_16x16x32_bf16 v[112:115], v[220:223], v[170:173], v[112:115]
	v_mfma_f32_16x16x32_bf16 v[104:107], v[228:231], v[170:173], v[104:107]
	v_mfma_f32_16x16x32_bf16 v[96:99], v[220:223], v[178:181], v[96:99]
	v_mfma_f32_16x16x32_bf16 v[88:91], v[228:231], v[178:181], v[88:91]
	v_mfma_f32_16x16x32_bf16 v[80:83], v[220:223], v[196:199], v[80:83]
	v_mfma_f32_16x16x32_bf16 v[72:75], v[228:231], v[196:199], v[72:75]
	v_mfma_f32_16x16x32_bf16 v[68:71], v[220:223], v[204:207], v[68:71]
	v_mfma_f32_16x16x32_bf16 v[64:67], v[228:231], v[204:207], v[64:67]
	s_mov_b32 m0, s78
	v_lshl_add_u64 v[146:147], v[188:189], 0, s[88:89]
	s_barrier
	ds_read_b128 v[166:169], v154 offset:49152
	ds_read_b128 v[170:173], v154 offset:50176
	ds_read_b128 v[174:177], v154 offset:51200
	ds_read_b128 v[178:181], v154 offset:52224
	ds_read_b128 v[182:185], v154 offset:53248
	ds_read_b128 v[196:199], v154 offset:54272
	ds_read_b128 v[200:203], v154 offset:55296
	ds_read_b128 v[204:207], v154 offset:56320
	global_load_lds_dwordx4 v[146:147], off
	s_mov_b32 m0, s79
	v_lshl_add_u64 v[146:147], v[192:193], 0, s[88:89]
	global_load_lds_dwordx4 v[146:147], off
	s_barrier
; #define LAS __attribute__((address_space(3)))
; __device__ __forceinline__ unsigned pk2(float lo, float hi) { unsigned r; asm("v_cvt_pk_bf16_f32 %0, %1, %2" : "=v"(r) : "v"(lo), "v"(hi)); return r; }
; #define PG8_WAIT_V(n) asm volatile("s_waitcnt vmcnt(" #n ")" ::: "memory")
; #define PG8_WAIT_L(n) asm volatile("s_waitcnt lgkmcnt(" #n ")" ::: "memory")
; #define PG8_BAR __builtin_amdgcn_s_barrier()
; template <class Epi>
; __device__ __forceinline__ void gemm_phase(LAS unsigned char* lds, const Gemm g, const StaticOrder& S, const Epi& E) {
;     ...
;             PG8_BAR; PG8_WAIT_L(0); PG8_MMA(1, 0, At, B0); PG8_BAR; PG8_SCHED;
;             PG8_STAGE(PG8_SB(1, 1), b3 + hB, voffB);
;             PG8_WAIT_V(6); PG8_BAR; PG8_MMA(1, 1, At, B1); PG8_BAR;
;     __device__ __forceinline__ void operator()(const f32x4 (&acc)[2][2][4][2], const Unit& u, int wr, int wc, int fr, int fq) const {
;         const int col_t = u.pn * BM;
;         if (mode != 0 && col_t >= vt0) {
;             const int bl = u.pm / TPB, key0 = (u.pm - bl * TPB) * 256;
;             LAS bf16_t* sc = (LAS bf16_t*)(trs + (wr * 4 + wc) * 2304);
;             const int lane = fq * 16 + fr;
; #pragma unroll
;             for (int ai = 0; ai < 2; ++ai)
; #pragma unroll
;                 for (int bj = 0; bj < 2; ++bj)
; #pragma unroll
;                     for (int n = 0; n < 2; ++n) {
; #pragma unroll
;                         for (int m = 0; m < 4; ++m) {
;                             const f32x4 v = acc[ai][bj][m][n];
;                             const unsigned p0 = pk2(v[0], v[1]), p1 = pk2(v[2], v[3]);
;                             LAS bf16_t* w = sc + (4 * fq) * 72 + 16 * m + fr;
;                             w[0] = (bf16_t)(p0 & 0xffffu); w[72] = (bf16_t)(p0 >> 16); w[144] = (bf16_t)(p1 & 0xffffu); w[216] = (bf16_t)(p1 >> 16);
;                         }
; #pragma unroll
;                         for (int j = 0; j < 2; ++j) {
;                             const int ch = lane + 64 * j, fi = ch >> 3, seg = ch & 7;
;                             const u32x4 o = *(const LAS u32x4*)(sc + fi * 72 + 8 * seg);
;                             const int f = col_t - vt0 + 64 * wc + 16 * (fi >> 2) + 8 * bj + 4 * n + (fi & 3);
;                             *(u32x4*)(Vt + ((size_t)bl * vtnf + f) * KEYS + key0 + ai * HALF + wr * 64 + 8 * seg) = o;
;                         }
	s_waitcnt lgkmcnt(0)
	v_mfma_f32_16x16x32_bf16 v[60:63], v[136:139], v[166:169], v[60:63]
	v_mfma_f32_16x16x32_bf16 v[56:59], v[158:161], v[166:169], v[56:59]
	v_mfma_f32_16x16x32_bf16 v[52:55], v[136:139], v[174:177], v[52:55]
	v_mfma_f32_16x16x32_bf16 v[44:47], v[158:161], v[174:177], v[44:47]
	v_mfma_f32_16x16x32_bf16 v[36:39], v[136:139], v[182:185], v[36:39]
	v_mfma_f32_16x16x32_bf16 v[28:31], v[158:161], v[182:185], v[28:31]
	v_mfma_f32_16x16x32_bf16 v[20:23], v[136:139], v[200:203], v[20:23]
	v_mfma_f32_16x16x32_bf16 v[12:15], v[158:161], v[200:203], v[12:15]
	v_mfma_f32_16x16x32_bf16 v[60:63], v[140:143], v[170:173], v[60:63]
	v_mfma_f32_16x16x32_bf16 v[56:59], v[162:165], v[170:173], v[56:59]
	v_mfma_f32_16x16x32_bf16 v[52:55], v[140:143], v[178:181], v[52:55]
	v_mfma_f32_16x16x32_bf16 v[44:47], v[162:165], v[178:181], v[44:47]
	v_mfma_f32_16x16x32_bf16 v[36:39], v[140:143], v[196:199], v[36:39]
	v_mfma_f32_16x16x32_bf16 v[28:31], v[162:165], v[196:199], v[28:31]
	v_mfma_f32_16x16x32_bf16 v[20:23], v[140:143], v[204:207], v[20:23]
	v_mfma_f32_16x16x32_bf16 v[12:15], v[162:165], v[204:207], v[12:15]
	s_barrier
	s_add_u32 s26, s34, 0x40080
	s_addc_u32 s27, s35, 0
	s_add_i32 s28, s29, s71
	s_mov_b32 m0, s28
	s_nop 0
	global_load_lds_dwordx4 v128, s[26:27]
	s_add_i32 m0, s28, 0x2000
	s_nop 0
	global_load_lds_dwordx4 v130, s[26:27]
	s_waitcnt vmcnt(6)
	s_barrier
	v_mfma_f32_16x16x32_bf16 v[48:51], v[216:219], v[166:169], v[48:51]
	v_mfma_f32_16x16x32_bf16 v[40:43], v[224:227], v[166:169], v[40:43]
	v_mfma_f32_16x16x32_bf16 v[32:35], v[216:219], v[174:177], v[32:35]
	v_mfma_f32_16x16x32_bf16 v[24:27], v[224:227], v[174:177], v[24:27]
	v_mfma_f32_16x16x32_bf16 v[16:19], v[216:219], v[182:185], v[16:19]
	v_mfma_f32_16x16x32_bf16 v[8:11], v[224:227], v[182:185], v[8:11]
	v_mfma_f32_16x16x32_bf16 v[4:7], v[216:219], v[200:203], v[4:7]
	v_mfma_f32_16x16x32_bf16 v[0:3], v[224:227], v[200:203], v[0:3]
	v_mfma_f32_16x16x32_bf16 v[48:51], v[220:223], v[170:173], v[48:51]
	v_mfma_f32_16x16x32_bf16 v[40:43], v[228:231], v[170:173], v[40:43]
	v_mfma_f32_16x16x32_bf16 v[32:35], v[220:223], v[178:181], v[32:35]
	v_mfma_f32_16x16x32_bf16 v[24:27], v[228:231], v[178:181], v[24:27]
	v_mfma_f32_16x16x32_bf16 v[16:19], v[220:223], v[196:199], v[16:19]
	v_mfma_f32_16x16x32_bf16 v[8:11], v[228:231], v[196:199], v[8:11]
	v_mfma_f32_16x16x32_bf16 v[4:7], v[220:223], v[204:207], v[4:7]
	v_mfma_f32_16x16x32_bf16 v[0:3], v[228:231], v[204:207], v[0:3]
	s_add_i32 s84, s84, 2
	s_add_u32 s4, s4, 0x100
	s_addc_u32 s5, s5, 0
	s_add_u32 s24, s24, 0x100
	s_addc_u32 s25, s25, 0
	s_cmp_gt_u32 s84, 13
	s_barrier
	s_cbranch_scc0 .LBB0_499
	s_lshl_b32 s15, s3, 8
	s_cmp_lt_i32 s3, 11
	s_mov_b64 s[4:5], -1
	s_cbranch_scc1 .LBB0_502
	s_mul_hi_i32 s3, s80, 0x3e0f83e1
	s_lshr_b32 s4, s3, 31
	s_ashr_i32 s3, s3, 3
	s_add_i32 s4, s3, s4
	v_cvt_pk_bf16_f32 v136, v124, v125
	s_mul_i32 s3, s4, 0xffffffdf
	v_cvt_pk_bf16_f32 v137, v126, v127
	ds_write_b16 v151, v136
	ds_write_b16_d16_hi v151, v136 offset:144
	ds_write_b16 v151, v137 offset:288
	ds_write_b16_d16_hi v151, v137 offset:432
	v_cvt_pk_bf16_f32 v136, v116, v117
	s_add_i32 s3, s3, s80
	v_cvt_pk_bf16_f32 v137, v118, v119
	ds_write_b16 v151, v136 offset:32
	ds_write_b16_d16_hi v151, v136 offset:176
	ds_write_b16 v151, v137 offset:320
	ds_write_b16_d16_hi v151, v137 offset:464
	v_cvt_pk_bf16_f32 v136, v100, v101
	s_lshl_b32 s24, s3, 8
	s_or_b32 s3, s15, s81
	v_cvt_pk_bf16_f32 v137, v102, v103
	ds_write_b16 v151, v136 offset:64
	ds_write_b16_d16_hi v151, v136 offset:208
	ds_write_b16 v151, v137 offset:352
	ds_write_b16_d16_hi v151, v137 offset:496
	v_cvt_pk_bf16_f32 v136, v84, v85
	s_ashr_i32 s5, s4, 31
	v_cvt_pk_bf16_f32 v137, v86, v87
	ds_write_b16 v151, v136 offset:96
	ds_write_b16_d16_hi v151, v136 offset:240
	ds_write_b16 v151, v137 offset:384
	ds_write_b16_d16_hi v151, v137 offset:528
	v_add_u32_e32 v136, s3, v152
	s_lshl_b64 s[4:5], s[4:5], 10
	v_ashrrev_i32_e32 v137, 31, v136
	v_lshl_add_u64 v[136:137], s[4:5], 0, v[136:137]
	v_mov_b64_e32 v[162:163], s[10:11]
	s_ashr_i32 s25, s24, 31
	ds_read_b128 v[138:141], v155
	v_mad_u64_u32 v[142:143], s[26:27], v136, s91, v[162:163]
	v_mad_i32_i24 v143, v137, s91, v143
	s_lshl_b64 s[34:35], s[24:25], 1
	v_lshl_add_u64 v[136:137], v[142:143], 0, s[34:35]
	v_lshl_add_u64 v[136:137], v[136:137], 0, s[12:13]
	v_lshl_add_u64 v[136:137], v[136:137], 0, v[144:145]
	s_waitcnt lgkmcnt(0)
	global_store_dwordx4 v[136:137], v[138:141], off
	ds_read_b128 v[140:143], v156
	s_or_b32 s17, s3, 4
	v_add_u32_e32 v138, s3, v153
	v_ashrrev_i32_e32 v139, 31, v138
	v_lshl_add_u64 v[138:139], s[4:5], 0, v[138:139]
	v_mad_u64_u32 v[146:147], s[24:25], v138, s91, v[162:163]
	v_mad_i32_i24 v147, v139, s91, v147
	v_lshl_add_u64 v[138:139], v[146:147], 0, s[34:35]
	v_lshl_add_u64 v[138:139], v[138:139], 0, s[12:13]
	v_lshl_add_u64 v[138:139], v[138:139], 0, v[144:145]
	s_waitcnt lgkmcnt(0)
; #define LAS __attribute__((address_space(3)))
; __device__ __forceinline__ unsigned pk2(float lo, float hi) { unsigned r; asm("v_cvt_pk_bf16_f32 %0, %1, %2" : "=v"(r) : "v"(lo), "v"(hi)); return r; }
;     __device__ __forceinline__ void operator()(const f32x4 (&acc)[2][2][4][2], const Unit& u, int wr, int wc, int fr, int fq) const {
;     ...
; #pragma unroll
;             for (int ai = 0; ai < 2; ++ai)
; #pragma unroll
;                 for (int bj = 0; bj < 2; ++bj)
; #pragma unroll
;                     for (int n = 0; n < 2; ++n) {
; #pragma unroll
;                         for (int m = 0; m < 4; ++m) {
;                             const f32x4 v = acc[ai][bj][m][n];
;                             const unsigned p0 = pk2(v[0], v[1]), p1 = pk2(v[2], v[3]);
;                             LAS bf16_t* w = sc + (4 * fq) * 72 + 16 * m + fr;
;                             w[0] = (bf16_t)(p0 & 0xffffu); w[72] = (bf16_t)(p0 >> 16); w[144] = (bf16_t)(p1 & 0xffffu); w[216] = (bf16_t)(p1 >> 16);
;                         }
; #pragma unroll
;                         for (int j = 0; j < 2; ++j) {
;                             const int ch = lane + 64 * j, fi = ch >> 3, seg = ch & 7;
;                             const u32x4 o = *(const LAS u32x4*)(sc + fi * 72 + 8 * seg);
;                             const int f = col_t - vt0 + 64 * wc + 16 * (fi >> 2) + 8 * bj + 4 * n + (fi & 3);
;                             *(u32x4*)(Vt + ((size_t)bl * vtnf + f) * KEYS + key0 + ai * HALF + wr * 64 + 8 * seg) = o;
;                         }
	global_store_dwordx4 v[138:139], v[140:143], off
	v_cvt_pk_bf16_f32 v157, v104, v105
	s_nop 1
	v_cvt_pk_bf16_f32 v140, v120, v121
	v_cvt_pk_bf16_f32 v141, v122, v123
	ds_write_b16 v151, v140
	ds_write_b16_d16_hi v151, v140 offset:144
	ds_write_b16 v151, v141 offset:288
	ds_write_b16_d16_hi v151, v141 offset:432
	v_cvt_pk_bf16_f32 v140, v108, v109
	v_cvt_pk_bf16_f32 v141, v110, v111
	ds_write_b16 v151, v140 offset:32
	ds_write_b16_d16_hi v151, v140 offset:176
	ds_write_b16 v151, v141 offset:320
	ds_write_b16_d16_hi v151, v141 offset:464
	v_cvt_pk_bf16_f32 v140, v92, v93
	v_cvt_pk_bf16_f32 v141, v94, v95
	ds_write_b16 v151, v140 offset:64
	ds_write_b16_d16_hi v151, v140 offset:208
	ds_write_b16 v151, v141 offset:352
	ds_write_b16_d16_hi v151, v141 offset:496
	v_cvt_pk_bf16_f32 v140, v76, v77
	v_cvt_pk_bf16_f32 v141, v78, v79
	ds_write_b16 v151, v140 offset:96
	ds_write_b16_d16_hi v151, v140 offset:240
	ds_write_b16 v151, v141 offset:384
	ds_write_b16_d16_hi v151, v141 offset:528
	v_add_u32_e32 v140, s17, v152
	v_ashrrev_i32_e32 v141, 31, v140
	v_lshl_add_u64 v[140:141], s[4:5], 0, v[140:141]
	ds_read_b128 v[158:161], v155
	v_mad_u64_u32 v[142:143], s[24:25], v140, s91, v[162:163]
	v_mad_i32_i24 v143, v141, s91, v143
	v_lshl_add_u64 v[140:141], v[142:143], 0, s[34:35]
	v_add_u32_e32 v142, s17, v153
	v_lshl_add_u64 v[140:141], v[140:141], 0, s[12:13]
	v_ashrrev_i32_e32 v143, 31, v142
	v_lshl_add_u64 v[140:141], v[140:141], 0, v[144:145]
	v_lshl_add_u64 v[142:143], s[4:5], 0, v[142:143]
	s_waitcnt lgkmcnt(0)
	global_store_dwordx4 v[140:141], v[158:161], off
	ds_read_b128 v[158:161], v156
	v_mad_u64_u32 v[146:147], s[24:25], v142, s91, v[162:163]
	v_mad_i32_i24 v147, v143, s91, v147
	v_lshl_add_u64 v[142:143], v[146:147], 0, s[34:35]
	v_lshl_add_u64 v[142:143], v[142:143], 0, s[12:13]
	v_lshl_add_u64 v[142:143], v[142:143], 0, v[144:145]
	v_cvt_pk_bf16_f32 v146, v112, v113
	s_waitcnt lgkmcnt(0)
	global_store_dwordx4 v[142:143], v[158:161], off
	v_cvt_pk_bf16_f32 v147, v114, v115
	ds_write_b16 v151, v146
	ds_write_b16_d16_hi v151, v146 offset:144
	ds_write_b16 v151, v147 offset:288
	ds_write_b16_d16_hi v151, v147 offset:432
	v_cvt_pk_bf16_f32 v146, v96, v97
	v_cvt_pk_bf16_f32 v147, v98, v99
	ds_write_b16 v151, v146 offset:32
	ds_write_b16_d16_hi v151, v146 offset:176
	ds_write_b16 v151, v147 offset:320
	ds_write_b16_d16_hi v151, v147 offset:464
	v_cvt_pk_bf16_f32 v146, v80, v81
	s_or_b32 s17, s3, 8
	v_cvt_pk_bf16_f32 v147, v82, v83
	ds_write_b16 v151, v146 offset:64
	ds_write_b16_d16_hi v151, v146 offset:208
	ds_write_b16 v151, v147 offset:352
	ds_write_b16_d16_hi v151, v147 offset:496
	v_cvt_pk_bf16_f32 v146, v68, v69
	v_cvt_pk_bf16_f32 v147, v70, v71
	ds_write_b16 v151, v146 offset:96
	ds_write_b16_d16_hi v151, v146 offset:240
	ds_write_b16 v151, v147 offset:384
	ds_write_b16_d16_hi v151, v147 offset:528
	v_add_u32_e32 v146, s17, v152
	v_ashrrev_i32_e32 v147, 31, v146
	v_lshl_add_u64 v[146:147], s[4:5], 0, v[146:147]
	ds_read_b128 v[158:161], v155
	v_mad_u64_u32 v[164:165], s[24:25], v146, s91, v[162:163]
	v_mad_i32_i24 v165, v147, s91, v165
	v_lshl_add_u64 v[146:147], v[164:165], 0, s[34:35]
	v_add_u32_e32 v164, s17, v153
	v_lshl_add_u64 v[146:147], v[146:147], 0, s[12:13]
	v_ashrrev_i32_e32 v165, 31, v164
	v_lshl_add_u64 v[146:147], v[146:147], 0, v[144:145]
	v_lshl_add_u64 v[164:165], s[4:5], 0, v[164:165]
	s_waitcnt lgkmcnt(0)
	global_store_dwordx4 v[146:147], v[158:161], off
	ds_read_b128 v[158:161], v156
	v_mad_u64_u32 v[166:167], s[24:25], v164, s91, v[162:163]
	v_mad_i32_i24 v167, v165, s91, v167
	v_lshl_add_u64 v[164:165], v[166:167], 0, s[34:35]
	v_lshl_add_u64 v[164:165], v[164:165], 0, s[12:13]
	v_lshl_add_u64 v[164:165], v[164:165], 0, v[144:145]
	s_waitcnt lgkmcnt(0)
	global_store_dwordx4 v[164:165], v[158:161], off
	s_or_b32 s3, s3, 12
	v_add_u32_e32 v166, s3, v152
	v_cvt_pk_bf16_f32 v158, v106, v107
	ds_write_b16 v151, v157
	ds_write_b16_d16_hi v151, v157 offset:144
	ds_write_b16 v151, v158 offset:288
	ds_write_b16_d16_hi v151, v158 offset:432
	v_cvt_pk_bf16_f32 v157, v88, v89
	v_cvt_pk_bf16_f32 v158, v90, v91
	ds_write_b16 v151, v157 offset:32
	ds_write_b16_d16_hi v151, v157 offset:176
	ds_write_b16 v151, v158 offset:320
	ds_write_b16_d16_hi v151, v158 offset:464
	v_cvt_pk_bf16_f32 v157, v72, v73
	v_cvt_pk_bf16_f32 v158, v74, v75
	ds_write_b16 v151, v157 offset:64
	ds_write_b16_d16_hi v151, v157 offset:208
	ds_write_b16 v151, v158 offset:352
	ds_write_b16_d16_hi v151, v158 offset:496
	v_cvt_pk_bf16_f32 v157, v64, v65
	v_ashrrev_i32_e32 v167, 31, v166
	v_cvt_pk_bf16_f32 v158, v66, v67
	ds_write_b16 v151, v157 offset:96
	ds_write_b16_d16_hi v151, v157 offset:240
	ds_write_b16 v151, v158 offset:384
	ds_write_b16_d16_hi v151, v158 offset:528
	v_lshl_add_u64 v[166:167], s[4:5], 0, v[166:167]
	ds_read_b128 v[158:161], v155
	v_mad_u64_u32 v[168:169], s[24:25], v166, s91, v[162:163]
	v_mad_i32_i24 v169, v167, s91, v169
	v_lshl_add_u64 v[166:167], v[168:169], 0, s[34:35]
	v_add_u32_e32 v168, s3, v153
	v_lshl_add_u64 v[166:167], v[166:167], 0, s[12:13]
	v_ashrrev_i32_e32 v169, 31, v168
	v_lshl_add_u64 v[166:167], v[166:167], 0, v[144:145]
	v_lshl_add_u64 v[168:169], s[4:5], 0, v[168:169]
	s_waitcnt lgkmcnt(0)
; #define LAS __attribute__((address_space(3)))
; __device__ __forceinline__ unsigned pk2(float lo, float hi) { unsigned r; asm("v_cvt_pk_bf16_f32 %0, %1, %2" : "=v"(r) : "v"(lo), "v"(hi)); return r; }
;     __device__ __forceinline__ void operator()(const f32x4 (&acc)[2][2][4][2], const Unit& u, int wr, int wc, int fr, int fq) const {
;     ...
; #pragma unroll
;             for (int ai = 0; ai < 2; ++ai)
; #pragma unroll
;                 for (int bj = 0; bj < 2; ++bj)
; #pragma unroll
;                     for (int n = 0; n < 2; ++n) {
; #pragma unroll
;                         for (int m = 0; m < 4; ++m) {
;                             const f32x4 v = acc[ai][bj][m][n];
;                             const unsigned p0 = pk2(v[0], v[1]), p1 = pk2(v[2], v[3]);
;                             LAS bf16_t* w = sc + (4 * fq) * 72 + 16 * m + fr;
;                             w[0] = (bf16_t)(p0 & 0xffffu); w[72] = (bf16_t)(p0 >> 16); w[144] = (bf16_t)(p1 & 0xffffu); w[216] = (bf16_t)(p1 >> 16);
;                         }
; #pragma unroll
;                         for (int j = 0; j < 2; ++j) {
;                             const int ch = lane + 64 * j, fi = ch >> 3, seg = ch & 7;
;                             const u32x4 o = *(const LAS u32x4*)(sc + fi * 72 + 8 * seg);
;                             const int f = col_t - vt0 + 64 * wc + 16 * (fi >> 2) + 8 * bj + 4 * n + (fi & 3);
;                             *(u32x4*)(Vt + ((size_t)bl * vtnf + f) * KEYS + key0 + ai * HALF + wr * 64 + 8 * seg) = o;
;                         }
	global_store_dwordx4 v[166:167], v[158:161], off
	ds_read_b128 v[158:161], v156
	v_mad_u64_u32 v[162:163], s[4:5], v168, s91, v[162:163]
	v_mad_i32_i24 v163, v169, s91, v163
	v_lshl_add_u64 v[162:163], v[162:163], 0, s[34:35]
	v_lshl_add_u64 v[162:163], v[162:163], 0, s[12:13]
	v_lshl_add_u64 v[162:163], v[162:163], 0, v[144:145]
	v_cvt_pk_bf16_f32 v157, v60, v61
	s_waitcnt lgkmcnt(0)
	global_store_dwordx4 v[162:163], v[158:161], off
	s_mov_b64 s[4:5], 0
	s_nop 0
	v_cvt_pk_bf16_f32 v158, v62, v63
	ds_write_b16 v151, v157
	ds_write_b16_d16_hi v151, v157 offset:144
	ds_write_b16 v151, v158 offset:288
	ds_write_b16_d16_hi v151, v158 offset:432
	v_cvt_pk_bf16_f32 v157, v52, v53
	v_cvt_pk_bf16_f32 v158, v54, v55
	ds_write_b16 v151, v157 offset:32
	ds_write_b16_d16_hi v151, v157 offset:176
	ds_write_b16 v151, v158 offset:320
	ds_write_b16_d16_hi v151, v158 offset:464
	v_cvt_pk_bf16_f32 v157, v36, v37
	v_cvt_pk_bf16_f32 v158, v38, v39
	ds_write_b16 v151, v157 offset:64
	ds_write_b16_d16_hi v151, v157 offset:208
	ds_write_b16 v151, v158 offset:352
	ds_write_b16_d16_hi v151, v158 offset:496
	v_cvt_pk_bf16_f32 v157, v20, v21
	v_cvt_pk_bf16_f32 v158, v22, v23
	ds_write_b16 v151, v157 offset:96
	ds_write_b16_d16_hi v151, v157 offset:240
	ds_write_b16 v151, v158 offset:384
	ds_write_b16_d16_hi v151, v158 offset:528
	ds_read_b128 v[158:161], v155
	s_waitcnt lgkmcnt(0)
	global_store_dwordx4 v[136:137], v[158:161], off offset:256
	ds_read_b128 v[158:161], v156
	v_cvt_pk_bf16_f32 v136, v56, v57
	v_cvt_pk_bf16_f32 v137, v58, v59
	s_waitcnt lgkmcnt(0)
	global_store_dwordx4 v[138:139], v[158:161], off offset:256
	ds_write_b16 v151, v136
	ds_write_b16_d16_hi v151, v136 offset:144
	ds_write_b16 v151, v137 offset:288
	ds_write_b16_d16_hi v151, v137 offset:432
	v_cvt_pk_bf16_f32 v136, v44, v45
	v_cvt_pk_bf16_f32 v137, v46, v47
	ds_write_b16 v151, v136 offset:32
	ds_write_b16_d16_hi v151, v136 offset:176
	ds_write_b16 v151, v137 offset:320
	ds_write_b16_d16_hi v151, v137 offset:464
	v_cvt_pk_bf16_f32 v136, v28, v29
	v_cvt_pk_bf16_f32 v137, v30, v31
	ds_write_b16 v151, v136 offset:64
	ds_write_b16_d16_hi v151, v136 offset:208
	ds_write_b16 v151, v137 offset:352
	ds_write_b16_d16_hi v151, v137 offset:496
	v_cvt_pk_bf16_f32 v136, v12, v13
	v_cvt_pk_bf16_f32 v137, v14, v15
	ds_write_b16 v151, v136 offset:96
	ds_write_b16_d16_hi v151, v136 offset:240
	ds_write_b16 v151, v137 offset:384
	ds_write_b16_d16_hi v151, v137 offset:528
	ds_read_b128 v[136:139], v155
	s_waitcnt lgkmcnt(0)
	global_store_dwordx4 v[140:141], v[136:139], off offset:256
	ds_read_b128 v[136:139], v156
	s_waitcnt lgkmcnt(0)
	global_store_dwordx4 v[142:143], v[136:139], off offset:256
	s_nop 1
	v_cvt_pk_bf16_f32 v136, v48, v49
	v_cvt_pk_bf16_f32 v137, v50, v51
	ds_write_b16 v151, v136
	ds_write_b16_d16_hi v151, v136 offset:144
	ds_write_b16 v151, v137 offset:288
	ds_write_b16_d16_hi v151, v137 offset:432
	v_cvt_pk_bf16_f32 v136, v32, v33
	v_cvt_pk_bf16_f32 v137, v34, v35
	ds_write_b16 v151, v136 offset:32
	ds_write_b16_d16_hi v151, v136 offset:176
	ds_write_b16 v151, v137 offset:320
	ds_write_b16_d16_hi v151, v137 offset:464
	v_cvt_pk_bf16_f32 v136, v16, v17
	v_cvt_pk_bf16_f32 v137, v18, v19
	ds_write_b16 v151, v136 offset:64
	ds_write_b16_d16_hi v151, v136 offset:208
	ds_write_b16 v151, v137 offset:352
	ds_write_b16_d16_hi v151, v137 offset:496
	v_cvt_pk_bf16_f32 v136, v4, v5
	v_cvt_pk_bf16_f32 v137, v6, v7
	ds_write_b16 v151, v136 offset:96
	ds_write_b16_d16_hi v151, v136 offset:240
	ds_write_b16 v151, v137 offset:384
	ds_write_b16_d16_hi v151, v137 offset:528
	ds_read_b128 v[136:139], v155
	s_waitcnt lgkmcnt(0)
	global_store_dwordx4 v[146:147], v[136:139], off offset:256
	ds_read_b128 v[136:139], v156
	s_waitcnt lgkmcnt(0)
	global_store_dwordx4 v[164:165], v[136:139], off offset:256
	s_nop 1
	v_cvt_pk_bf16_f32 v136, v40, v41
	v_cvt_pk_bf16_f32 v137, v42, v43
	ds_write_b16 v151, v136
	ds_write_b16_d16_hi v151, v136 offset:144
	ds_write_b16 v151, v137 offset:288
	ds_write_b16_d16_hi v151, v137 offset:432
	v_cvt_pk_bf16_f32 v136, v24, v25
	v_cvt_pk_bf16_f32 v137, v26, v27
	ds_write_b16 v151, v136 offset:32
	ds_write_b16_d16_hi v151, v136 offset:176
	ds_write_b16 v151, v137 offset:320
	ds_write_b16_d16_hi v151, v137 offset:464
	v_cvt_pk_bf16_f32 v136, v8, v9
	v_cvt_pk_bf16_f32 v137, v10, v11
	ds_write_b16 v151, v136 offset:64
	ds_write_b16_d16_hi v151, v136 offset:208
	ds_write_b16 v151, v137 offset:352
	ds_write_b16_d16_hi v151, v137 offset:496
	v_cvt_pk_bf16_f32 v136, v0, v1
	v_cvt_pk_bf16_f32 v137, v2, v3
	ds_write_b16 v151, v136 offset:96
	ds_write_b16_d16_hi v151, v136 offset:240
	ds_write_b16 v151, v137 offset:384
	ds_write_b16_d16_hi v151, v137 offset:528
	ds_read_b128 v[136:139], v155
	s_waitcnt lgkmcnt(0)
	global_store_dwordx4 v[166:167], v[136:139], off offset:256
	ds_read_b128 v[136:139], v156
	s_waitcnt lgkmcnt(0)
	global_store_dwordx4 v[162:163], v[136:139], off offset:256

; #define PG8_STAGE(bufoff, gbase, voff) do { _Pragma("unroll") for (int _i = 0; _i < 2; ++_i) \
;         __builtin_amdgcn_global_load_lds((const unsigned*)((const char*)(gbase) + (voff)[_i]), (LAS unsigned*)(lds + (bufoff) + ldsw + _i * 8192), 16, 0, 0); } while (0)
; #define PG8_LDA(dst, b, h) do { _Pragma("unroll") for (int m = 0; m < 4; ++m) _Pragma("unroll") for (int k = 0; k < 2; ++k) dst[m][k] = *(const LAS bf16x8*)(lds + PG8_SA(b, h) + aoff + m * 2048 + k * 1024); } while (0)
; #define PG8_LDB(dst, b, h) do { _Pragma("unroll") for (int n = 0; n < 2; ++n) _Pragma("unroll") for (int k = 0; k < 2; ++k) dst[n][k] = *(const LAS bf16x8*)(lds + PG8_SB(b, h) + boff + n * 2048 + k * 1024); } while (0)
; #define PG8_MMA(ai, bj, At, Bt) do { __builtin_amdgcn_s_setprio(1); _Pragma("unroll") for (int m = 0; m < 4; ++m) _Pragma("unroll") for (int n = 0; n < 2; ++n) _Pragma("unroll") for (int k = 0; k < 2; ++k) \
;         acc[ai][bj][m][n] = __builtin_amdgcn_mfma_f32_16x16x32_bf16(Bt[n][k], At[m][k], acc[ai][bj][m][n], 0, 0, 0); __builtin_amdgcn_s_setprio(0); } while (0)
; #define PG8_WAIT_L(n) asm volatile("s_waitcnt lgkmcnt(" #n ")" ::: "memory")
; #define PG8_BAR __builtin_amdgcn_s_barrier()
; template <class Epi>
; __device__ __forceinline__ void gemm_phase(LAS unsigned char* lds, const Gemm g, const StaticOrder& S, const Epi& E) {
;     ...
;         const bool has_next = S.next(ui + 1, nxt);
;         const char* nA = has_next ? g.arow(nxt.pm) : cA; const char* nB = has_next ? (const char*)g.Bt + (size_t)nxt.pn * tB : cB;
;         for (int t = 0; t < nt; t += 2) {
;             const bool last = (t == nt - 2);
;             const char* a1 = cA + (size_t)(t + 1) * kstep;
;             const char* a2 = last ? nA : cA + (size_t)(t + 2) * kstep; const char* b2 = last ? nB : cB + (size_t)(t + 2) * kstep;
;             const char* a3 = a2 + kstep; const char* b3 = b2 + kstep;
;             PG8_LDB(B0, 0, 0); PG8_SCHED; PG8_LDA(At, 0, 0); PG8_STAGE(PG8_SA(1, 1), a1 + hA, voffA);
;             PG8_WAIT_L(8); PG8_BAR; PG8_WAIT_L(0); PG8_MMA(0, 0, At, B0); PG8_BAR; PG8_SCHED;
;             PG8_LDB(B1, 0, 1); PG8_STAGE(PG8_SB(0, 0), b2, voffB);
;             PG8_BAR; PG8_WAIT_L(0); PG8_MMA(0, 1, At, B1); PG8_BAR;
;             PG8_LDA(At, 0, 1); PG8_STAGE(PG8_SA(0, 0), a2, voffA);
;             PG8_BAR; PG8_WAIT_L(0); PG8_MMA(1, 0, At, B0); PG8_BAR; PG8_SCHED;
.LBB0_655:
	s_add_u32 s12, s10, 0x100
	s_addc_u32 s13, s11, 0
	s_add_i32 s26, 0, 0x10000
	v_add_u32_e32 v156, s26, v143
	ds_read_b128 v[138:141], v156
	ds_read_b128 v[148:151], v156 offset:1024
	ds_read_b128 v[152:155], v156 offset:2048
	ds_read_b128 v[156:159], v156 offset:3072
	s_cmp_eq_u32 s78, 2
	s_cselect_b32 s21, s5, s13
	s_cselect_b32 s20, s4, s12
	s_cselect_b32 s17, s7, s25
	s_cselect_b32 s16, s6, s24
	s_add_i32 m0, s64, 0xc000
	ds_read_b128 v[160:163], v147
	ds_read_b128 v[164:167], v147 offset:1024
	ds_read_b128 v[168:171], v147 offset:2048
	ds_read_b128 v[172:175], v147 offset:3072
	ds_read_b128 v[176:179], v147 offset:4096
	ds_read_b128 v[180:183], v147 offset:5120
	ds_read_b128 v[196:199], v147 offset:6144
	ds_read_b128 v[200:203], v147 offset:7168
	global_load_lds_dwordx4 v134, s[10:11]
	s_add_i32 m0, s64, 0xe000
	v_lshl_add_u64 v[184:185], s[10:11], 0, v[136:137]
	global_load_lds_dwordx4 v[184:185], off
	s_waitcnt lgkmcnt(8)
	s_barrier
	s_waitcnt lgkmcnt(0)
	v_mfma_f32_16x16x32_bf16 v[124:127], v[138:141], v[160:163], v[124:127]
	v_mfma_f32_16x16x32_bf16 v[120:123], v[152:155], v[160:163], v[120:123]
	v_mfma_f32_16x16x32_bf16 v[116:119], v[138:141], v[168:171], v[116:119]
	v_mfma_f32_16x16x32_bf16 v[108:111], v[152:155], v[168:171], v[108:111]
	v_mfma_f32_16x16x32_bf16 v[100:103], v[138:141], v[176:179], v[100:103]
	v_mfma_f32_16x16x32_bf16 v[92:95], v[152:155], v[176:179], v[92:95]
	v_mfma_f32_16x16x32_bf16 v[84:87], v[138:141], v[196:199], v[84:87]
	v_mfma_f32_16x16x32_bf16 v[76:79], v[152:155], v[196:199], v[76:79]
	v_mfma_f32_16x16x32_bf16 v[124:127], v[148:151], v[164:167], v[124:127]
	v_mfma_f32_16x16x32_bf16 v[120:123], v[156:159], v[164:167], v[120:123]
	v_mfma_f32_16x16x32_bf16 v[116:119], v[148:151], v[172:175], v[116:119]
	v_mfma_f32_16x16x32_bf16 v[108:111], v[156:159], v[172:175], v[108:111]
	v_mfma_f32_16x16x32_bf16 v[100:103], v[148:151], v[180:183], v[100:103]
	v_mfma_f32_16x16x32_bf16 v[92:95], v[156:159], v[180:183], v[92:95]
	v_mfma_f32_16x16x32_bf16 v[84:87], v[148:151], v[200:203], v[84:87]
	v_mfma_f32_16x16x32_bf16 v[76:79], v[156:159], v[200:203], v[76:79]
	s_barrier
	s_add_i32 s27, 0, 0x14000
	v_add_u32_e32 v184, s27, v143
	s_add_i32 s10, s26, s63
	ds_read_b128 v[204:207], v184
	ds_read_b128 v[216:219], v184 offset:1024
	ds_read_b128 v[220:223], v184 offset:2048
	ds_read_b128 v[224:227], v184 offset:3072
	v_lshl_add_u64 v[184:185], s[16:17], 0, v[144:145]
	s_mov_b32 m0, s10
	v_lshl_add_u64 v[186:187], s[16:17], 0, v[132:133]
	global_load_lds_dwordx4 v[184:185], off
	s_add_i32 m0, s10, 0x2000
	s_nop 0
	global_load_lds_dwordx4 v[186:187], off
	s_barrier
	s_waitcnt lgkmcnt(0)
	v_mfma_f32_16x16x32_bf16 v[112:115], v[204:207], v[160:163], v[112:115]
	v_mfma_f32_16x16x32_bf16 v[104:107], v[220:223], v[160:163], v[104:107]
	v_mfma_f32_16x16x32_bf16 v[96:99], v[204:207], v[168:171], v[96:99]
	v_mfma_f32_16x16x32_bf16 v[88:91], v[220:223], v[168:171], v[88:91]
	v_mfma_f32_16x16x32_bf16 v[80:83], v[204:207], v[176:179], v[80:83]
	v_mfma_f32_16x16x32_bf16 v[72:75], v[220:223], v[176:179], v[72:75]
	v_mfma_f32_16x16x32_bf16 v[68:71], v[204:207], v[196:199], v[68:71]
	v_mfma_f32_16x16x32_bf16 v[64:67], v[220:223], v[196:199], v[64:67]
	v_mfma_f32_16x16x32_bf16 v[112:115], v[216:219], v[164:167], v[112:115]
	v_mfma_f32_16x16x32_bf16 v[104:107], v[224:227], v[164:167], v[104:107]
	v_mfma_f32_16x16x32_bf16 v[96:99], v[216:219], v[172:175], v[96:99]
	v_mfma_f32_16x16x32_bf16 v[88:91], v[224:227], v[172:175], v[88:91]
	v_mfma_f32_16x16x32_bf16 v[80:83], v[216:219], v[180:183], v[80:83]
	v_mfma_f32_16x16x32_bf16 v[72:75], v[224:227], v[180:183], v[72:75]
	v_mfma_f32_16x16x32_bf16 v[68:71], v[216:219], v[200:203], v[68:71]
	v_mfma_f32_16x16x32_bf16 v[64:67], v[224:227], v[200:203], v[64:67]
	s_mov_b32 m0, s64
	v_lshl_add_u64 v[188:189], s[20:21], 0, v[128:129]
	s_barrier
	ds_read_b128 v[160:163], v147 offset:16384
	ds_read_b128 v[164:167], v147 offset:17408
	ds_read_b128 v[168:171], v147 offset:18432
	ds_read_b128 v[172:175], v147 offset:19456
	ds_read_b128 v[176:179], v147 offset:20480
	ds_read_b128 v[180:183], v147 offset:21504
	ds_read_b128 v[196:199], v147 offset:22528
	ds_read_b128 v[200:203], v147 offset:23552
	global_load_lds_dwordx4 v[188:189], off
	s_mov_b32 m0, s65
	v_lshl_add_u64 v[192:193], s[20:21], 0, v[130:131]
	global_load_lds_dwordx4 v[192:193], off
	s_barrier
	s_waitcnt lgkmcnt(0)
	v_mfma_f32_16x16x32_bf16 v[60:63], v[138:141], v[160:163], v[60:63]
	v_mfma_f32_16x16x32_bf16 v[56:59], v[152:155], v[160:163], v[56:59]
	v_mfma_f32_16x16x32_bf16 v[52:55], v[138:141], v[168:171], v[52:55]
	v_mfma_f32_16x16x32_bf16 v[44:47], v[152:155], v[168:171], v[44:47]
	v_mfma_f32_16x16x32_bf16 v[36:39], v[138:141], v[176:179], v[36:39]
	v_mfma_f32_16x16x32_bf16 v[28:31], v[152:155], v[176:179], v[28:31]
	v_mfma_f32_16x16x32_bf16 v[20:23], v[138:141], v[196:199], v[20:23]
	v_mfma_f32_16x16x32_bf16 v[12:15], v[152:155], v[196:199], v[12:15]
	v_mfma_f32_16x16x32_bf16 v[60:63], v[148:151], v[164:167], v[60:63]
	v_mfma_f32_16x16x32_bf16 v[56:59], v[156:159], v[164:167], v[56:59]
	v_mfma_f32_16x16x32_bf16 v[52:55], v[148:151], v[172:175], v[52:55]
	v_mfma_f32_16x16x32_bf16 v[44:47], v[156:159], v[172:175], v[44:47]
	v_mfma_f32_16x16x32_bf16 v[36:39], v[148:151], v[180:183], v[36:39]
	v_mfma_f32_16x16x32_bf16 v[28:31], v[156:159], v[180:183], v[28:31]
	v_mfma_f32_16x16x32_bf16 v[20:23], v[148:151], v[200:203], v[20:23]
	v_mfma_f32_16x16x32_bf16 v[12:15], v[156:159], v[200:203], v[12:15]
	s_barrier
; #define PG8_STAGE(bufoff, gbase, voff) do { _Pragma("unroll") for (int _i = 0; _i < 2; ++_i) \
;         __builtin_amdgcn_global_load_lds((const unsigned*)((const char*)(gbase) + (voff)[_i]), (LAS unsigned*)(lds + (bufoff) + ldsw + _i * 8192), 16, 0, 0); } while (0)
; #define PG8_LDA(dst, b, h) do { _Pragma("unroll") for (int m = 0; m < 4; ++m) _Pragma("unroll") for (int k = 0; k < 2; ++k) dst[m][k] = *(const LAS bf16x8*)(lds + PG8_SA(b, h) + aoff + m * 2048 + k * 1024); } while (0)
; #define PG8_LDB(dst, b, h) do { _Pragma("unroll") for (int n = 0; n < 2; ++n) _Pragma("unroll") for (int k = 0; k < 2; ++k) dst[n][k] = *(const LAS bf16x8*)(lds + PG8_SB(b, h) + boff + n * 2048 + k * 1024); } while (0)
; #define PG8_MMA(ai, bj, At, Bt) do { __builtin_amdgcn_s_setprio(1); _Pragma("unroll") for (int m = 0; m < 4; ++m) _Pragma("unroll") for (int n = 0; n < 2; ++n) _Pragma("unroll") for (int k = 0; k < 2; ++k) \
;         acc[ai][bj][m][n] = __builtin_amdgcn_mfma_f32_16x16x32_bf16(Bt[n][k], At[m][k], acc[ai][bj][m][n], 0, 0, 0); __builtin_amdgcn_s_setprio(0); } while (0)
; #define PG8_WAIT_V(n) asm volatile("s_waitcnt vmcnt(" #n ")" ::: "memory")
; #define PG8_WAIT_L(n) asm volatile("s_waitcnt lgkmcnt(" #n ")" ::: "memory")
; #define PG8_BAR __builtin_amdgcn_s_barrier()
; #define PG8_SCHED __builtin_amdgcn_sched_barrier(0)
; template <class Epi>
; __device__ __forceinline__ void gemm_phase(LAS unsigned char* lds, const Gemm g, const StaticOrder& S, const Epi& E) {
;     ...
;             PG8_STAGE(PG8_SB(0, 1), b2 + hB, voffB);
;             PG8_WAIT_V(6); PG8_BAR; PG8_MMA(1, 1, At, B1); PG8_BAR;
;             PG8_LDB(B0, 1, 0); PG8_SCHED; PG8_LDA(At, 1, 0); PG8_STAGE(PG8_SA(0, 1), a2 + hA, voffA);
;             PG8_WAIT_L(8); PG8_BAR; PG8_WAIT_L(0); PG8_MMA(0, 0, At, B0); PG8_BAR; PG8_SCHED;
;             PG8_LDB(B1, 1, 1); PG8_STAGE(PG8_SB(1, 0), b3, voffB);
;             PG8_BAR; PG8_WAIT_L(0); PG8_MMA(0, 1, At, B1); PG8_BAR;
;             PG8_LDA(At, 1, 1); PG8_STAGE(PG8_SA(1, 0), a3, voffA);
	s_add_u32 s10, s16, 0x18000
	s_addc_u32 s11, s17, 0
	s_add_i32 s26, s27, s63
	s_mov_b32 m0, s26
	s_nop 0
	global_load_lds_dwordx4 v144, s[10:11]
	s_add_i32 m0, s26, 0x2000
	s_nop 0
	global_load_lds_dwordx4 v132, s[10:11]
	s_waitcnt vmcnt(6)
	s_barrier
	v_mfma_f32_16x16x32_bf16 v[48:51], v[204:207], v[160:163], v[48:51]
	v_mfma_f32_16x16x32_bf16 v[40:43], v[220:223], v[160:163], v[40:43]
	v_mfma_f32_16x16x32_bf16 v[32:35], v[204:207], v[168:171], v[32:35]
	v_mfma_f32_16x16x32_bf16 v[24:27], v[220:223], v[168:171], v[24:27]
	v_mfma_f32_16x16x32_bf16 v[16:19], v[204:207], v[176:179], v[16:19]
	v_mfma_f32_16x16x32_bf16 v[8:11], v[220:223], v[176:179], v[8:11]
	v_mfma_f32_16x16x32_bf16 v[4:7], v[204:207], v[196:199], v[4:7]
	v_mfma_f32_16x16x32_bf16 v[0:3], v[220:223], v[196:199], v[0:3]
	v_mfma_f32_16x16x32_bf16 v[48:51], v[216:219], v[164:167], v[48:51]
	v_mfma_f32_16x16x32_bf16 v[40:43], v[224:227], v[164:167], v[40:43]
	v_mfma_f32_16x16x32_bf16 v[32:35], v[216:219], v[172:175], v[32:35]
	v_mfma_f32_16x16x32_bf16 v[24:27], v[224:227], v[172:175], v[24:27]
	v_mfma_f32_16x16x32_bf16 v[16:19], v[216:219], v[180:183], v[16:19]
	v_mfma_f32_16x16x32_bf16 v[8:11], v[224:227], v[180:183], v[8:11]
	v_mfma_f32_16x16x32_bf16 v[4:7], v[216:219], v[200:203], v[4:7]
	v_mfma_f32_16x16x32_bf16 v[0:3], v[224:227], v[200:203], v[0:3]
	s_add_i32 s26, 0, 0x18000
	v_add_u32_e32 v156, s26, v143
	s_barrier
	ds_read_b128 v[138:141], v156
	ds_read_b128 v[148:151], v156 offset:1024
	ds_read_b128 v[152:155], v156 offset:2048
	ds_read_b128 v[156:159], v156 offset:3072
	s_add_u32 s10, s20, 0xb0000
	s_addc_u32 s11, s21, 0
	s_mov_b32 m0, s66
	ds_read_b128 v[160:163], v147 offset:32768
	ds_read_b128 v[164:167], v147 offset:33792
	ds_read_b128 v[168:171], v147 offset:34816
	ds_read_b128 v[172:175], v147 offset:35840
	ds_read_b128 v[176:179], v147 offset:36864
	ds_read_b128 v[180:183], v147 offset:37888
	ds_read_b128 v[196:199], v147 offset:38912
	ds_read_b128 v[200:203], v147 offset:39936
	global_load_lds_dwordx4 v128, s[10:11]
	s_mov_b32 m0, s68
	s_nop 0
	global_load_lds_dwordx4 v130, s[10:11]
	s_waitcnt lgkmcnt(8)
	s_barrier
	s_waitcnt lgkmcnt(0)
	v_mfma_f32_16x16x32_bf16 v[124:127], v[138:141], v[160:163], v[124:127]
	v_mfma_f32_16x16x32_bf16 v[120:123], v[152:155], v[160:163], v[120:123]
	v_mfma_f32_16x16x32_bf16 v[116:119], v[138:141], v[168:171], v[116:119]
	v_mfma_f32_16x16x32_bf16 v[108:111], v[152:155], v[168:171], v[108:111]
	v_mfma_f32_16x16x32_bf16 v[100:103], v[138:141], v[176:179], v[100:103]
	v_mfma_f32_16x16x32_bf16 v[92:95], v[152:155], v[176:179], v[92:95]
	v_mfma_f32_16x16x32_bf16 v[84:87], v[138:141], v[196:199], v[84:87]
	v_mfma_f32_16x16x32_bf16 v[76:79], v[152:155], v[196:199], v[76:79]
	v_mfma_f32_16x16x32_bf16 v[124:127], v[148:151], v[164:167], v[124:127]
	v_mfma_f32_16x16x32_bf16 v[120:123], v[156:159], v[164:167], v[120:123]
	v_mfma_f32_16x16x32_bf16 v[116:119], v[148:151], v[172:175], v[116:119]
	v_mfma_f32_16x16x32_bf16 v[108:111], v[156:159], v[172:175], v[108:111]
	v_mfma_f32_16x16x32_bf16 v[100:103], v[148:151], v[180:183], v[100:103]
	v_mfma_f32_16x16x32_bf16 v[92:95], v[156:159], v[180:183], v[92:95]
	v_mfma_f32_16x16x32_bf16 v[84:87], v[148:151], v[200:203], v[84:87]
	v_mfma_f32_16x16x32_bf16 v[76:79], v[156:159], v[200:203], v[76:79]
	s_barrier
	s_add_i32 s20, 0, 0x1c000
	s_add_i32 s10, s26, s63
	v_add_u32_e32 v190, s20, v143
	v_lshl_add_u64 v[184:185], v[184:185], 0, s[88:89]
	s_mov_b32 m0, s10
	ds_read_b128 v[204:207], v190
	ds_read_b128 v[216:219], v190 offset:1024
	ds_read_b128 v[220:223], v190 offset:2048
	ds_read_b128 v[224:227], v190 offset:3072
	global_load_lds_dwordx4 v[184:185], off
	s_add_i32 m0, s10, 0x2000
	v_lshl_add_u64 v[184:185], v[186:187], 0, s[88:89]
	global_load_lds_dwordx4 v[184:185], off
	s_barrier
	s_waitcnt lgkmcnt(0)
	v_mfma_f32_16x16x32_bf16 v[112:115], v[204:207], v[160:163], v[112:115]
	v_mfma_f32_16x16x32_bf16 v[104:107], v[220:223], v[160:163], v[104:107]
	v_mfma_f32_16x16x32_bf16 v[96:99], v[204:207], v[168:171], v[96:99]
	v_mfma_f32_16x16x32_bf16 v[88:91], v[220:223], v[168:171], v[88:91]
	v_mfma_f32_16x16x32_bf16 v[80:83], v[204:207], v[176:179], v[80:83]
	v_mfma_f32_16x16x32_bf16 v[72:75], v[220:223], v[176:179], v[72:75]
	v_mfma_f32_16x16x32_bf16 v[68:71], v[204:207], v[196:199], v[68:71]
	v_mfma_f32_16x16x32_bf16 v[64:67], v[220:223], v[196:199], v[64:67]
	v_mfma_f32_16x16x32_bf16 v[112:115], v[216:219], v[164:167], v[112:115]
	v_mfma_f32_16x16x32_bf16 v[104:107], v[224:227], v[164:167], v[104:107]
	v_mfma_f32_16x16x32_bf16 v[96:99], v[216:219], v[172:175], v[96:99]
	v_mfma_f32_16x16x32_bf16 v[88:91], v[224:227], v[172:175], v[88:91]
	v_mfma_f32_16x16x32_bf16 v[80:83], v[216:219], v[180:183], v[80:83]
	v_mfma_f32_16x16x32_bf16 v[72:75], v[224:227], v[180:183], v[72:75]
	v_mfma_f32_16x16x32_bf16 v[68:71], v[216:219], v[200:203], v[68:71]
	v_mfma_f32_16x16x32_bf16 v[64:67], v[224:227], v[200:203], v[64:67]
	s_mov_b32 m0, s69
	v_lshl_add_u64 v[184:185], v[188:189], 0, s[88:89]
	s_barrier
	ds_read_b128 v[160:163], v147 offset:49152
	ds_read_b128 v[164:167], v147 offset:50176
	ds_read_b128 v[168:171], v147 offset:51200
	ds_read_b128 v[172:175], v147 offset:52224
	ds_read_b128 v[176:179], v147 offset:53248
	ds_read_b128 v[180:183], v147 offset:54272
	ds_read_b128 v[196:199], v147 offset:55296
	ds_read_b128 v[200:203], v147 offset:56320
	global_load_lds_dwordx4 v[184:185], off
	s_mov_b32 m0, s70
	v_lshl_add_u64 v[184:185], v[192:193], 0, s[88:89]
	global_load_lds_dwordx4 v[184:185], off
	s_barrier
; #define PG8_STAGE(bufoff, gbase, voff) do { _Pragma("unroll") for (int _i = 0; _i < 2; ++_i) \
;         __builtin_amdgcn_global_load_lds((const unsigned*)((const char*)(gbase) + (voff)[_i]), (LAS unsigned*)(lds + (bufoff) + ldsw + _i * 8192), 16, 0, 0); } while (0)
; #define PG8_MMA(ai, bj, At, Bt) do { __builtin_amdgcn_s_setprio(1); _Pragma("unroll") for (int m = 0; m < 4; ++m) _Pragma("unroll") for (int n = 0; n < 2; ++n) _Pragma("unroll") for (int k = 0; k < 2; ++k) \
;         acc[ai][bj][m][n] = __builtin_amdgcn_mfma_f32_16x16x32_bf16(Bt[n][k], At[m][k], acc[ai][bj][m][n], 0, 0, 0); __builtin_amdgcn_s_setprio(0); } while (0)
; #define PG8_WAIT_V(n) asm volatile("s_waitcnt vmcnt(" #n ")" ::: "memory")
; #define PG8_WAIT_L(n) asm volatile("s_waitcnt lgkmcnt(" #n ")" ::: "memory")
; #define PG8_BAR __builtin_amdgcn_s_barrier()
; #define PG8_SCHED __builtin_amdgcn_sched_barrier(0)
; template <class Epi>
; __device__ __forceinline__ void gemm_phase(LAS unsigned char* lds, const Gemm g, const StaticOrder& S, const Epi& E) {
;     ...
;             PG8_BAR; PG8_WAIT_L(0); PG8_MMA(1, 0, At, B0); PG8_BAR; PG8_SCHED;
;             PG8_STAGE(PG8_SB(1, 1), b3 + hB, voffB);
;             PG8_WAIT_V(6); PG8_BAR; PG8_MMA(1, 1, At, B1); PG8_BAR;
	s_waitcnt lgkmcnt(0)
	v_mfma_f32_16x16x32_bf16 v[60:63], v[138:141], v[160:163], v[60:63]
	v_mfma_f32_16x16x32_bf16 v[56:59], v[152:155], v[160:163], v[56:59]
	v_mfma_f32_16x16x32_bf16 v[52:55], v[138:141], v[168:171], v[52:55]
	v_mfma_f32_16x16x32_bf16 v[44:47], v[152:155], v[168:171], v[44:47]
	v_mfma_f32_16x16x32_bf16 v[36:39], v[138:141], v[176:179], v[36:39]
	v_mfma_f32_16x16x32_bf16 v[28:31], v[152:155], v[176:179], v[28:31]
	v_mfma_f32_16x16x32_bf16 v[20:23], v[138:141], v[196:199], v[20:23]
	v_mfma_f32_16x16x32_bf16 v[12:15], v[152:155], v[196:199], v[12:15]
	v_mfma_f32_16x16x32_bf16 v[60:63], v[148:151], v[164:167], v[60:63]
	v_mfma_f32_16x16x32_bf16 v[56:59], v[156:159], v[164:167], v[56:59]
	v_mfma_f32_16x16x32_bf16 v[52:55], v[148:151], v[172:175], v[52:55]
	v_mfma_f32_16x16x32_bf16 v[44:47], v[156:159], v[172:175], v[44:47]
	v_mfma_f32_16x16x32_bf16 v[36:39], v[148:151], v[180:183], v[36:39]
	v_mfma_f32_16x16x32_bf16 v[28:31], v[156:159], v[180:183], v[28:31]
	v_mfma_f32_16x16x32_bf16 v[20:23], v[148:151], v[200:203], v[20:23]
	v_mfma_f32_16x16x32_bf16 v[12:15], v[156:159], v[200:203], v[12:15]
	s_barrier
	s_add_u32 s10, s16, 0x18080
	s_addc_u32 s11, s17, 0
	s_add_i32 s16, s20, s63
	s_mov_b32 m0, s16
	s_nop 0
	global_load_lds_dwordx4 v144, s[10:11]
	s_add_i32 m0, s16, 0x2000
	s_nop 0
	global_load_lds_dwordx4 v132, s[10:11]
	s_waitcnt vmcnt(6)
	s_barrier
	v_mfma_f32_16x16x32_bf16 v[48:51], v[204:207], v[160:163], v[48:51]
	v_mfma_f32_16x16x32_bf16 v[40:43], v[220:223], v[160:163], v[40:43]
	v_mfma_f32_16x16x32_bf16 v[32:35], v[204:207], v[168:171], v[32:35]
	v_mfma_f32_16x16x32_bf16 v[24:27], v[220:223], v[168:171], v[24:27]
	v_mfma_f32_16x16x32_bf16 v[16:19], v[204:207], v[176:179], v[16:19]
	v_mfma_f32_16x16x32_bf16 v[8:11], v[220:223], v[176:179], v[8:11]
	v_mfma_f32_16x16x32_bf16 v[4:7], v[204:207], v[196:199], v[4:7]
	v_mfma_f32_16x16x32_bf16 v[0:3], v[220:223], v[196:199], v[0:3]
	v_mfma_f32_16x16x32_bf16 v[48:51], v[216:219], v[164:167], v[48:51]
	v_mfma_f32_16x16x32_bf16 v[40:43], v[224:227], v[164:167], v[40:43]
	v_mfma_f32_16x16x32_bf16 v[32:35], v[216:219], v[172:175], v[32:35]
	v_mfma_f32_16x16x32_bf16 v[24:27], v[224:227], v[172:175], v[24:27]
	v_mfma_f32_16x16x32_bf16 v[16:19], v[216:219], v[180:183], v[16:19]
	v_mfma_f32_16x16x32_bf16 v[8:11], v[224:227], v[180:183], v[8:11]
	v_mfma_f32_16x16x32_bf16 v[4:7], v[216:219], v[200:203], v[4:7]
	v_mfma_f32_16x16x32_bf16 v[0:3], v[224:227], v[200:203], v[0:3]
	s_add_i32 s78, s78, 2
	s_add_u32 s24, s24, 0x100
	s_addc_u32 s25, s25, 0
	s_cmp_gt_u32 s78, 3
	s_mov_b64 s[10:11], s[12:13]
	s_barrier
	s_cbranch_scc0 .LBB0_655
; __device__ __forceinline__ unsigned pk2(float lo, float hi) { unsigned r; asm("v_cvt_pk_bf16_f32 %0, %1, %2" : "=v"(r) : "v"(lo), "v"(hi)); return r; }
;     __device__ __forceinline__ void operator()(const f32x4 (&acc)[2][2][4][2], const Unit& u, int wr, int wc, int fr, int fq) const {
;     ...
;         const int row_t = rmap == 1 ? odd_phys_row0(u.pm, grp) : (rmap == 2 ? odd_phys_row0(u.pm % (BG * TPB), u.pm / (BG * TPB)) : u.pm * BM);
;         int c = col_t + 64 * wc + 16 * fq;
;         if (mode == 2) c = (c >> 6) * 96 + (c & 63);
; #pragma unroll
;         for (int ai = 0; ai < 2; ++ai)
; #pragma unroll
;             for (int m = 0; m < 4; ++m) {
;                 const int row = row_t + ai * HALF + wr * 64 + m * 16 + fr;
;                 bf16_t* rp = O + (size_t)row * ldc + c;
; #pragma unroll
;                 for (int bj = 0; bj < 2; ++bj) {
;                     const f32x4 v0 = acc[ai][bj][m][0], v1 = acc[ai][bj][m][1];
;                     u32x4 o; o.x = pk2(v0[0], v0[1]); o.y = pk2(v0[2], v0[3]); o.z = pk2(v1[0], v1[1]); o.w = pk2(v1[2], v1[3]);
;                     *(u32x4*)(rp + 8 * bj) = o;
;                 }
;             }
	v_lshl_or_b32 v140, s15, 8, v146
	v_lshl_add_u32 v150, s77, 8, v142
	v_ashrrev_i32_e32 v141, 31, v140
	v_mov_b64_e32 v[138:139], s[8:9]
	v_cvt_pk_bf16_f32 v68, v68, v69
	v_cvt_pk_bf16_f32 v69, v70, v71
	v_cvt_pk_bf16_f32 v70, v64, v65
	v_add_u32_e32 v64, 0x80, v150
	v_mad_i64_i32 v[148:149], s[10:11], v150, s90, v[138:139]
	v_lshlrev_b64 v[140:141], 1, v[140:141]
	v_cvt_pk_bf16_f32 v112, v112, v113
	v_cvt_pk_bf16_f32 v113, v114, v115
	v_cvt_pk_bf16_f32 v114, v104, v105
	v_or_b32_e32 v104, 16, v150
	v_mad_i64_i32 v[64:65], s[10:11], v64, s90, v[138:139]
	v_cvt_pk_bf16_f32 v48, v48, v49
	v_cvt_pk_bf16_f32 v49, v50, v51
	v_cvt_pk_bf16_f32 v50, v40, v41
	v_add_u32_e32 v40, 0x90, v150
	v_lshl_add_u64 v[148:149], v[148:149], 0, v[140:141]
	v_mad_i64_i32 v[104:105], s[10:11], v104, s90, v[138:139]
	v_cvt_pk_bf16_f32 v96, v96, v97
	v_cvt_pk_bf16_f32 v97, v98, v99
	v_cvt_pk_bf16_f32 v98, v88, v89
	v_or_b32_e32 v88, 32, v150
	v_lshl_add_u64 v[64:65], v[64:65], 0, v[140:141]
	v_mad_i64_i32 v[40:41], s[10:11], v40, s90, v[138:139]
	v_cvt_pk_bf16_f32 v32, v32, v33
	v_cvt_pk_bf16_f32 v33, v34, v35
	v_cvt_pk_bf16_f32 v34, v24, v25
	v_add_u32_e32 v24, 0xa0, v150
	v_cvt_pk_bf16_f32 v115, v106, v107
	global_store_dwordx4 v[148:149], v[112:115], off offset:16
	v_mad_i64_i32 v[88:89], s[10:11], v88, s90, v[138:139]
	s_nop 0
	v_lshl_add_u64 v[112:113], v[104:105], 0, v[140:141]
	v_cvt_pk_bf16_f32 v80, v80, v81
	v_cvt_pk_bf16_f32 v81, v82, v83
	v_cvt_pk_bf16_f32 v82, v72, v73
	v_or_b32_e32 v72, 48, v150
	v_cvt_pk_bf16_f32 v51, v42, v43
	global_store_dwordx4 v[64:65], v[48:51], off offset:16
	v_mad_i64_i32 v[24:25], s[10:11], v24, s90, v[138:139]
	s_nop 0
	v_lshl_add_u64 v[48:49], v[40:41], 0, v[140:141]
	v_cvt_pk_bf16_f32 v16, v16, v17
	v_cvt_pk_bf16_f32 v17, v18, v19
	v_cvt_pk_bf16_f32 v18, v8, v9
	v_add_u32_e32 v8, 0xb0, v150
	v_cvt_pk_bf16_f32 v99, v90, v91
	global_store_dwordx4 v[112:113], v[96:99], off offset:16
	v_mad_i64_i32 v[72:73], s[10:11], v72, s90, v[138:139]
	s_nop 0
	v_lshl_add_u64 v[96:97], v[88:89], 0, v[140:141]
	v_cvt_pk_bf16_f32 v35, v26, v27
	global_store_dwordx4 v[48:49], v[32:35], off offset:16
	v_mad_i64_i32 v[8:9], s[10:11], v8, s90, v[138:139]
	s_nop 0
	v_lshl_add_u64 v[32:33], v[24:25], 0, v[140:141]
	v_cvt_pk_bf16_f32 v83, v74, v75
	global_store_dwordx4 v[96:97], v[80:83], off offset:16
	v_cvt_pk_bf16_f32 v19, v10, v11
	global_store_dwordx4 v[32:33], v[16:19], off offset:16
	s_and_b64 vcc, exec, s[0:1]
	v_lshl_add_u64 v[80:81], v[72:73], 0, v[140:141]
	v_lshl_add_u64 v[16:17], v[8:9], 0, v[140:141]
	s_mov_b32 s15, s72
	s_mov_b32 s77, s76
	s_mov_b64 s[12:13], s[6:7]
	s_mov_b64 s[10:11], s[4:5]
	v_cvt_pk_bf16_f32 v124, v124, v125
	v_cvt_pk_bf16_f32 v125, v126, v127
	v_cvt_pk_bf16_f32 v126, v120, v121
	v_cvt_pk_bf16_f32 v127, v122, v123
	global_store_dwordx4 v[148:149], v[124:127], off
	v_cvt_pk_bf16_f32 v104, v116, v117
	v_cvt_pk_bf16_f32 v105, v118, v119
	v_cvt_pk_bf16_f32 v106, v108, v109
	v_cvt_pk_bf16_f32 v107, v110, v111
	global_store_dwordx4 v[112:113], v[104:107], off
	v_cvt_pk_bf16_f32 v88, v100, v101
	v_cvt_pk_bf16_f32 v89, v102, v103
	v_cvt_pk_bf16_f32 v90, v92, v93
	v_cvt_pk_bf16_f32 v91, v94, v95
	global_store_dwordx4 v[96:97], v[88:91], off
	v_cvt_pk_bf16_f32 v72, v84, v85
	v_cvt_pk_bf16_f32 v73, v86, v87
	v_cvt_pk_bf16_f32 v74, v76, v77
	v_cvt_pk_bf16_f32 v75, v78, v79
	global_store_dwordx4 v[80:81], v[72:75], off
	v_cvt_pk_bf16_f32 v71, v66, v67
	global_store_dwordx4 v[80:81], v[68:71], off offset:16
	v_cvt_pk_bf16_f32 v60, v60, v61
	v_cvt_pk_bf16_f32 v61, v62, v63
	v_cvt_pk_bf16_f32 v62, v56, v57
	v_cvt_pk_bf16_f32 v63, v58, v59
	global_store_dwordx4 v[64:65], v[60:63], off
	v_cvt_pk_bf16_f32 v40, v52, v53
	v_cvt_pk_bf16_f32 v41, v54, v55
	v_cvt_pk_bf16_f32 v42, v44, v45
	v_cvt_pk_bf16_f32 v43, v46, v47
	global_store_dwordx4 v[48:49], v[40:43], off
	v_cvt_pk_bf16_f32 v24, v36, v37
	v_cvt_pk_bf16_f32 v25, v38, v39
	v_cvt_pk_bf16_f32 v26, v28, v29
	v_cvt_pk_bf16_f32 v27, v30, v31
	global_store_dwordx4 v[32:33], v[24:27], off
	v_cvt_pk_bf16_f32 v8, v20, v21
	v_cvt_pk_bf16_f32 v9, v22, v23
	v_cvt_pk_bf16_f32 v10, v12, v13
	v_cvt_pk_bf16_f32 v11, v14, v15
	global_store_dwordx4 v[16:17], v[8:11], off
	v_cvt_pk_bf16_f32 v4, v4, v5
	v_cvt_pk_bf16_f32 v5, v6, v7
	v_cvt_pk_bf16_f32 v6, v0, v1
	v_cvt_pk_bf16_f32 v7, v2, v3
	global_store_dwordx4 v[16:17], v[4:7], off offset:16
	s_cbranch_vccz .LBB0_644
	s_waitcnt vmcnt(0)
	s_cmpk_gt_u32 s14, 0xff
	s_cbranch_scc1 .LBB0_659
	s_barrier

; #define PG8_STAGE(bufoff, gbase, voff) do { _Pragma("unroll") for (int _i = 0; _i < 2; ++_i) \
;         __builtin_amdgcn_global_load_lds((const unsigned*)((const char*)(gbase) + (voff)[_i]), (LAS unsigned*)(lds + (bufoff) + ldsw + _i * 8192), 16, 0, 0); } while (0)
; #define PG8_LDA(dst, b, h) do { _Pragma("unroll") for (int m = 0; m < 4; ++m) _Pragma("unroll") for (int k = 0; k < 2; ++k) dst[m][k] = *(const LAS bf16x8*)(lds + PG8_SA(b, h) + aoff + m * 2048 + k * 1024); } while (0)
; #define PG8_LDB(dst, b, h) do { _Pragma("unroll") for (int n = 0; n < 2; ++n) _Pragma("unroll") for (int k = 0; k < 2; ++k) dst[n][k] = *(const LAS bf16x8*)(lds + PG8_SB(b, h) + boff + n * 2048 + k * 1024); } while (0)
; #define PG8_MMA(ai, bj, At, Bt) do { __builtin_amdgcn_s_setprio(1); _Pragma("unroll") for (int m = 0; m < 4; ++m) _Pragma("unroll") for (int n = 0; n < 2; ++n) _Pragma("unroll") for (int k = 0; k < 2; ++k) \
;         acc[ai][bj][m][n] = __builtin_amdgcn_mfma_f32_16x16x32_bf16(Bt[n][k], At[m][k], acc[ai][bj][m][n], 0, 0, 0); __builtin_amdgcn_s_setprio(0); } while (0)
; #define PG8_WAIT_L(n) asm volatile("s_waitcnt lgkmcnt(" #n ")" ::: "memory")
; #define PG8_BAR __builtin_amdgcn_s_barrier()
; template <class Epi>
; __device__ __forceinline__ void gemm_phase(LAS unsigned char* lds, const Gemm g, const StaticOrder& S, const Epi& E) {
;     ...
;         const bool has_next = S.next(ui + 1, nxt);
;         const char* nA = has_next ? g.arow(nxt.pm) : cA; const char* nB = has_next ? (const char*)g.Bt + (size_t)nxt.pn * tB : cB;
;         for (int t = 0; t < nt; t += 2) {
;             const bool last = (t == nt - 2);
;             const char* a1 = cA + (size_t)(t + 1) * kstep;
;             const char* a2 = last ? nA : cA + (size_t)(t + 2) * kstep; const char* b2 = last ? nB : cB + (size_t)(t + 2) * kstep;
;             const char* a3 = a2 + kstep; const char* b3 = b2 + kstep;
;             PG8_LDB(B0, 0, 0); PG8_SCHED; PG8_LDA(At, 0, 0); PG8_STAGE(PG8_SA(1, 1), a1 + hA, voffA);
;             PG8_WAIT_L(8); PG8_BAR; PG8_WAIT_L(0); PG8_MMA(0, 0, At, B0); PG8_BAR; PG8_SCHED;
;             PG8_LDB(B1, 0, 1); PG8_STAGE(PG8_SB(0, 0), b2, voffB);
;             PG8_BAR; PG8_WAIT_L(0); PG8_MMA(0, 1, At, B1); PG8_BAR;
;             PG8_LDA(At, 0, 1); PG8_STAGE(PG8_SA(0, 0), a2, voffA);
;             PG8_BAR; PG8_WAIT_L(0); PG8_MMA(1, 0, At, B0); PG8_BAR; PG8_SCHED;
.LBB0_670:
	s_add_u32 s28, s82, s25
	s_addc_u32 s29, s83, 0
	s_add_u32 s30, s28, 0x100
	s_addc_u32 s31, s29, 0
	s_and_b64 s[26:27], s[34:35], exec
	s_cselect_b32 s93, s17, s31
	s_cselect_b32 s92, s16, s30
	s_add_u32 s25, s64, s25
	s_addc_u32 s26, s65, 0
	s_add_u32 s25, s25, 0x100
	s_addc_u32 s30, s26, 0
	s_add_i32 s31, 0, 0x10000
	s_and_b64 s[26:27], s[34:35], exec
	s_cselect_b32 vcc_hi, s13, s30
	s_cselect_b32 vcc_lo, s24, s25
	s_add_u32 s76, s28, 0xb0080
	s_addc_u32 s77, s29, 0
	s_add_i32 s39, s31, s63
	s_add_i32 m0, s40, 0xc000
	s_add_i32 s68, s40, 0xe000
	s_add_i32 s29, 0, 0x14000
	s_add_i32 s37, s39, 0x2000
	s_add_u32 s86, vcc_lo, 0x10000
	v_add_u32_e32 v146, s31, v150
	s_addc_u32 s87, vcc_hi, 0
	s_add_i32 s30, s29, s63
	ds_read_b128 v[136:139], v146
	ds_read_b128 v[140:143], v146 offset:1024
	ds_read_b128 v[158:161], v146 offset:2048
	ds_read_b128 v[162:165], v146 offset:3072
	s_add_i32 s38, s30, 0x2000
	s_add_i32 s27, 0, 0x18000
	s_add_u32 s84, s92, 0xb0000
	s_addc_u32 s85, s93, 0
	s_add_i32 s25, s27, s63
	s_add_i32 s26, 0, 0x1c000
	s_add_i32 s28, s25, 0x2000
	s_add_u32 s34, vcc_lo, 0x10080
	s_addc_u32 s35, vcc_hi, 0
	s_add_i32 s31, s26, s63
	s_add_i32 s36, s31, 0x2000
	ds_read_b128 v[166:169], v154
	ds_read_b128 v[170:173], v154 offset:1024
	ds_read_b128 v[174:177], v154 offset:2048
	ds_read_b128 v[178:181], v154 offset:3072
	ds_read_b128 v[182:185], v154 offset:4096
	ds_read_b128 v[196:199], v154 offset:5120
	ds_read_b128 v[200:203], v154 offset:6144
	ds_read_b128 v[204:207], v154 offset:7168
	global_load_lds_dwordx4 v134, s[76:77]
	s_mov_b32 m0, s68
	v_lshl_add_u64 v[146:147], s[76:77], 0, v[130:131]
	global_load_lds_dwordx4 v[146:147], off
	s_waitcnt lgkmcnt(8)
	s_barrier
	s_waitcnt lgkmcnt(0)
	v_mfma_f32_16x16x32_bf16 v[124:127], v[136:139], v[166:169], v[124:127]
	v_mfma_f32_16x16x32_bf16 v[120:123], v[158:161], v[166:169], v[120:123]
	v_mfma_f32_16x16x32_bf16 v[116:119], v[136:139], v[174:177], v[116:119]
	v_mfma_f32_16x16x32_bf16 v[108:111], v[158:161], v[174:177], v[108:111]
	v_mfma_f32_16x16x32_bf16 v[100:103], v[136:139], v[182:185], v[100:103]
	v_mfma_f32_16x16x32_bf16 v[92:95], v[158:161], v[182:185], v[92:95]
	v_mfma_f32_16x16x32_bf16 v[84:87], v[136:139], v[200:203], v[84:87]
	v_mfma_f32_16x16x32_bf16 v[76:79], v[158:161], v[200:203], v[76:79]
	v_mfma_f32_16x16x32_bf16 v[124:127], v[140:143], v[170:173], v[124:127]
	v_mfma_f32_16x16x32_bf16 v[120:123], v[162:165], v[170:173], v[120:123]
	v_mfma_f32_16x16x32_bf16 v[116:119], v[140:143], v[178:181], v[116:119]
	v_mfma_f32_16x16x32_bf16 v[108:111], v[162:165], v[178:181], v[108:111]
	v_mfma_f32_16x16x32_bf16 v[100:103], v[140:143], v[196:199], v[100:103]
	v_mfma_f32_16x16x32_bf16 v[92:95], v[162:165], v[196:199], v[92:95]
	v_mfma_f32_16x16x32_bf16 v[84:87], v[140:143], v[204:207], v[84:87]
	v_mfma_f32_16x16x32_bf16 v[76:79], v[162:165], v[204:207], v[76:79]
	s_barrier
	v_add_u32_e32 v146, s29, v150
	s_mov_b32 m0, s39
	ds_read_b128 v[216:219], v146
	ds_read_b128 v[220:223], v146 offset:1024
	ds_read_b128 v[224:227], v146 offset:2048
	ds_read_b128 v[228:231], v146 offset:3072
	v_lshl_add_u64 v[146:147], vcc, 0, v[132:133]
	global_load_lds_dwordx4 v[146:147], off
	s_mov_b32 m0, s37
	v_lshl_add_u64 v[186:187], vcc, 0, v[128:129]
	global_load_lds_dwordx4 v[186:187], off
	s_barrier
	s_waitcnt lgkmcnt(0)
	v_mfma_f32_16x16x32_bf16 v[112:115], v[216:219], v[166:169], v[112:115]
	v_mfma_f32_16x16x32_bf16 v[104:107], v[224:227], v[166:169], v[104:107]
	v_mfma_f32_16x16x32_bf16 v[96:99], v[216:219], v[174:177], v[96:99]
	v_mfma_f32_16x16x32_bf16 v[88:91], v[224:227], v[174:177], v[88:91]
	v_mfma_f32_16x16x32_bf16 v[80:83], v[216:219], v[182:185], v[80:83]
	v_mfma_f32_16x16x32_bf16 v[72:75], v[224:227], v[182:185], v[72:75]
	v_mfma_f32_16x16x32_bf16 v[68:71], v[216:219], v[200:203], v[68:71]
	v_mfma_f32_16x16x32_bf16 v[64:67], v[224:227], v[200:203], v[64:67]
	v_mfma_f32_16x16x32_bf16 v[112:115], v[220:223], v[170:173], v[112:115]
	v_mfma_f32_16x16x32_bf16 v[104:107], v[228:231], v[170:173], v[104:107]
	v_mfma_f32_16x16x32_bf16 v[96:99], v[220:223], v[178:181], v[96:99]
	v_mfma_f32_16x16x32_bf16 v[88:91], v[228:231], v[178:181], v[88:91]
	v_mfma_f32_16x16x32_bf16 v[80:83], v[220:223], v[196:199], v[80:83]
	v_mfma_f32_16x16x32_bf16 v[72:75], v[228:231], v[196:199], v[72:75]
	v_mfma_f32_16x16x32_bf16 v[68:71], v[220:223], v[204:207], v[68:71]
	v_mfma_f32_16x16x32_bf16 v[64:67], v[228:231], v[204:207], v[64:67]
	s_mov_b32 m0, s40
	v_lshl_add_u64 v[188:189], s[92:93], 0, v[134:135]
	s_barrier
	ds_read_b128 v[166:169], v154 offset:16384
	ds_read_b128 v[170:173], v154 offset:17408
	ds_read_b128 v[174:177], v154 offset:18432
	ds_read_b128 v[178:181], v154 offset:19456
	ds_read_b128 v[182:185], v154 offset:20480
	ds_read_b128 v[196:199], v154 offset:21504
	ds_read_b128 v[200:203], v154 offset:22528
	ds_read_b128 v[204:207], v154 offset:23552
	global_load_lds_dwordx4 v[188:189], off
	s_mov_b32 m0, s69
	v_lshl_add_u64 v[192:193], s[92:93], 0, v[130:131]
	global_load_lds_dwordx4 v[192:193], off
	s_barrier
	s_waitcnt lgkmcnt(0)
	v_mfma_f32_16x16x32_bf16 v[60:63], v[136:139], v[166:169], v[60:63]
	v_mfma_f32_16x16x32_bf16 v[56:59], v[158:161], v[166:169], v[56:59]
	v_mfma_f32_16x16x32_bf16 v[52:55], v[136:139], v[174:177], v[52:55]
	v_mfma_f32_16x16x32_bf16 v[44:47], v[158:161], v[174:177], v[44:47]
	v_mfma_f32_16x16x32_bf16 v[36:39], v[136:139], v[182:185], v[36:39]
	v_mfma_f32_16x16x32_bf16 v[28:31], v[158:161], v[182:185], v[28:31]
	v_mfma_f32_16x16x32_bf16 v[20:23], v[136:139], v[200:203], v[20:23]
	v_mfma_f32_16x16x32_bf16 v[12:15], v[158:161], v[200:203], v[12:15]
	v_mfma_f32_16x16x32_bf16 v[60:63], v[140:143], v[170:173], v[60:63]
	v_mfma_f32_16x16x32_bf16 v[56:59], v[162:165], v[170:173], v[56:59]
	v_mfma_f32_16x16x32_bf16 v[52:55], v[140:143], v[178:181], v[52:55]
	v_mfma_f32_16x16x32_bf16 v[44:47], v[162:165], v[178:181], v[44:47]
	v_mfma_f32_16x16x32_bf16 v[36:39], v[140:143], v[196:199], v[36:39]
	v_mfma_f32_16x16x32_bf16 v[28:31], v[162:165], v[196:199], v[28:31]
	v_mfma_f32_16x16x32_bf16 v[20:23], v[140:143], v[204:207], v[20:23]
	v_mfma_f32_16x16x32_bf16 v[12:15], v[162:165], v[204:207], v[12:15]
	s_barrier
; #define PG8_STAGE(bufoff, gbase, voff) do { _Pragma("unroll") for (int _i = 0; _i < 2; ++_i) \
;         __builtin_amdgcn_global_load_lds((const unsigned*)((const char*)(gbase) + (voff)[_i]), (LAS unsigned*)(lds + (bufoff) + ldsw + _i * 8192), 16, 0, 0); } while (0)
; #define PG8_LDA(dst, b, h) do { _Pragma("unroll") for (int m = 0; m < 4; ++m) _Pragma("unroll") for (int k = 0; k < 2; ++k) dst[m][k] = *(const LAS bf16x8*)(lds + PG8_SA(b, h) + aoff + m * 2048 + k * 1024); } while (0)
; #define PG8_LDB(dst, b, h) do { _Pragma("unroll") for (int n = 0; n < 2; ++n) _Pragma("unroll") for (int k = 0; k < 2; ++k) dst[n][k] = *(const LAS bf16x8*)(lds + PG8_SB(b, h) + boff + n * 2048 + k * 1024); } while (0)
; #define PG8_MMA(ai, bj, At, Bt) do { __builtin_amdgcn_s_setprio(1); _Pragma("unroll") for (int m = 0; m < 4; ++m) _Pragma("unroll") for (int n = 0; n < 2; ++n) _Pragma("unroll") for (int k = 0; k < 2; ++k) \
;         acc[ai][bj][m][n] = __builtin_amdgcn_mfma_f32_16x16x32_bf16(Bt[n][k], At[m][k], acc[ai][bj][m][n], 0, 0, 0); __builtin_amdgcn_s_setprio(0); } while (0)
; #define PG8_WAIT_V(n) asm volatile("s_waitcnt vmcnt(" #n ")" ::: "memory")
; #define PG8_WAIT_L(n) asm volatile("s_waitcnt lgkmcnt(" #n ")" ::: "memory")
; #define PG8_BAR __builtin_amdgcn_s_barrier()
; #define PG8_SCHED __builtin_amdgcn_sched_barrier(0)
; template <class Epi>
; __device__ __forceinline__ void gemm_phase(LAS unsigned char* lds, const Gemm g, const StaticOrder& S, const Epi& E) {
;     ...
;             PG8_STAGE(PG8_SB(0, 1), b2 + hB, voffB);
;             PG8_WAIT_V(6); PG8_BAR; PG8_MMA(1, 1, At, B1); PG8_BAR;
;             PG8_LDB(B0, 1, 0); PG8_SCHED; PG8_LDA(At, 1, 0); PG8_STAGE(PG8_SA(0, 1), a2 + hA, voffA);
;             PG8_WAIT_L(8); PG8_BAR; PG8_WAIT_L(0); PG8_MMA(0, 0, At, B0); PG8_BAR; PG8_SCHED;
;             PG8_LDB(B1, 1, 1); PG8_STAGE(PG8_SB(1, 0), b3, voffB);
;             PG8_BAR; PG8_WAIT_L(0); PG8_MMA(0, 1, At, B1); PG8_BAR;
;             PG8_LDA(At, 1, 1); PG8_STAGE(PG8_SA(1, 0), a3, voffA);
	s_mov_b32 m0, s30
	s_nop 0
	global_load_lds_dwordx4 v132, s[86:87]
	s_mov_b32 m0, s38
	s_nop 0
	global_load_lds_dwordx4 v128, s[86:87]
	s_waitcnt vmcnt(6)
	s_barrier
	v_mfma_f32_16x16x32_bf16 v[48:51], v[216:219], v[166:169], v[48:51]
	v_mfma_f32_16x16x32_bf16 v[40:43], v[224:227], v[166:169], v[40:43]
	v_mfma_f32_16x16x32_bf16 v[32:35], v[216:219], v[174:177], v[32:35]
	v_mfma_f32_16x16x32_bf16 v[24:27], v[224:227], v[174:177], v[24:27]
	v_mfma_f32_16x16x32_bf16 v[16:19], v[216:219], v[182:185], v[16:19]
	v_mfma_f32_16x16x32_bf16 v[8:11], v[224:227], v[182:185], v[8:11]
	v_mfma_f32_16x16x32_bf16 v[4:7], v[216:219], v[200:203], v[4:7]
	v_mfma_f32_16x16x32_bf16 v[0:3], v[224:227], v[200:203], v[0:3]
	v_mfma_f32_16x16x32_bf16 v[48:51], v[220:223], v[170:173], v[48:51]
	v_mfma_f32_16x16x32_bf16 v[40:43], v[228:231], v[170:173], v[40:43]
	v_mfma_f32_16x16x32_bf16 v[32:35], v[220:223], v[178:181], v[32:35]
	v_mfma_f32_16x16x32_bf16 v[24:27], v[228:231], v[178:181], v[24:27]
	v_mfma_f32_16x16x32_bf16 v[16:19], v[220:223], v[196:199], v[16:19]
	v_mfma_f32_16x16x32_bf16 v[8:11], v[228:231], v[196:199], v[8:11]
	v_mfma_f32_16x16x32_bf16 v[4:7], v[220:223], v[204:207], v[4:7]
	v_mfma_f32_16x16x32_bf16 v[0:3], v[228:231], v[204:207], v[0:3]
	v_add_u32_e32 v157, s27, v150
	s_barrier
	ds_read_b128 v[136:139], v157
	ds_read_b128 v[140:143], v157 offset:1024
	ds_read_b128 v[158:161], v157 offset:2048
	ds_read_b128 v[162:165], v157 offset:3072
	s_mov_b32 m0, s70
	ds_read_b128 v[166:169], v154 offset:32768
	ds_read_b128 v[170:173], v154 offset:33792
	ds_read_b128 v[174:177], v154 offset:34816
	ds_read_b128 v[178:181], v154 offset:35840
	ds_read_b128 v[182:185], v154 offset:36864
	ds_read_b128 v[196:199], v154 offset:37888
	ds_read_b128 v[200:203], v154 offset:38912
	ds_read_b128 v[204:207], v154 offset:39936
	global_load_lds_dwordx4 v134, s[84:85]
	s_mov_b32 m0, s71
	s_nop 0
	global_load_lds_dwordx4 v130, s[84:85]
	s_waitcnt lgkmcnt(8)
	s_barrier
	s_waitcnt lgkmcnt(0)
	v_mfma_f32_16x16x32_bf16 v[124:127], v[136:139], v[166:169], v[124:127]
	v_mfma_f32_16x16x32_bf16 v[120:123], v[158:161], v[166:169], v[120:123]
	v_mfma_f32_16x16x32_bf16 v[116:119], v[136:139], v[174:177], v[116:119]
	v_mfma_f32_16x16x32_bf16 v[108:111], v[158:161], v[174:177], v[108:111]
	v_mfma_f32_16x16x32_bf16 v[100:103], v[136:139], v[182:185], v[100:103]
	v_mfma_f32_16x16x32_bf16 v[92:95], v[158:161], v[182:185], v[92:95]
	v_mfma_f32_16x16x32_bf16 v[84:87], v[136:139], v[200:203], v[84:87]
	v_mfma_f32_16x16x32_bf16 v[76:79], v[158:161], v[200:203], v[76:79]
	v_mfma_f32_16x16x32_bf16 v[124:127], v[140:143], v[170:173], v[124:127]
	v_mfma_f32_16x16x32_bf16 v[120:123], v[162:165], v[170:173], v[120:123]
	v_mfma_f32_16x16x32_bf16 v[116:119], v[140:143], v[178:181], v[116:119]
	v_mfma_f32_16x16x32_bf16 v[108:111], v[162:165], v[178:181], v[108:111]
	v_mfma_f32_16x16x32_bf16 v[100:103], v[140:143], v[196:199], v[100:103]
	v_mfma_f32_16x16x32_bf16 v[92:95], v[162:165], v[196:199], v[92:95]
	v_mfma_f32_16x16x32_bf16 v[84:87], v[140:143], v[204:207], v[84:87]
	v_mfma_f32_16x16x32_bf16 v[76:79], v[162:165], v[204:207], v[76:79]
	s_barrier
	s_mov_b32 m0, s25
	v_add_u32_e32 v157, s26, v150
	v_lshl_add_u64 v[146:147], v[146:147], 0, s[88:89]
	ds_read_b128 v[216:219], v157
	ds_read_b128 v[220:223], v157 offset:1024
	ds_read_b128 v[224:227], v157 offset:2048
	ds_read_b128 v[228:231], v157 offset:3072
	global_load_lds_dwordx4 v[146:147], off
	s_mov_b32 m0, s28
	v_lshl_add_u64 v[146:147], v[186:187], 0, s[88:89]
	global_load_lds_dwordx4 v[146:147], off
	s_barrier
	s_waitcnt lgkmcnt(0)
	v_mfma_f32_16x16x32_bf16 v[112:115], v[216:219], v[166:169], v[112:115]
	v_mfma_f32_16x16x32_bf16 v[104:107], v[224:227], v[166:169], v[104:107]
	v_mfma_f32_16x16x32_bf16 v[96:99], v[216:219], v[174:177], v[96:99]
	v_mfma_f32_16x16x32_bf16 v[88:91], v[224:227], v[174:177], v[88:91]
	v_mfma_f32_16x16x32_bf16 v[80:83], v[216:219], v[182:185], v[80:83]
	v_mfma_f32_16x16x32_bf16 v[72:75], v[224:227], v[182:185], v[72:75]
	v_mfma_f32_16x16x32_bf16 v[68:71], v[216:219], v[200:203], v[68:71]
	v_mfma_f32_16x16x32_bf16 v[64:67], v[224:227], v[200:203], v[64:67]
	v_mfma_f32_16x16x32_bf16 v[112:115], v[220:223], v[170:173], v[112:115]
	v_mfma_f32_16x16x32_bf16 v[104:107], v[228:231], v[170:173], v[104:107]
	v_mfma_f32_16x16x32_bf16 v[96:99], v[220:223], v[178:181], v[96:99]
	v_mfma_f32_16x16x32_bf16 v[88:91], v[228:231], v[178:181], v[88:91]
	v_mfma_f32_16x16x32_bf16 v[80:83], v[220:223], v[196:199], v[80:83]
	v_mfma_f32_16x16x32_bf16 v[72:75], v[228:231], v[196:199], v[72:75]
	v_mfma_f32_16x16x32_bf16 v[68:71], v[220:223], v[204:207], v[68:71]
	v_mfma_f32_16x16x32_bf16 v[64:67], v[228:231], v[204:207], v[64:67]
	s_mov_b32 m0, s72
	v_lshl_add_u64 v[146:147], v[188:189], 0, s[88:89]
	s_barrier
	ds_read_b128 v[166:169], v154 offset:49152
	ds_read_b128 v[170:173], v154 offset:50176
	ds_read_b128 v[174:177], v154 offset:51200
	ds_read_b128 v[178:181], v154 offset:52224
	ds_read_b128 v[182:185], v154 offset:53248
	ds_read_b128 v[196:199], v154 offset:54272
	ds_read_b128 v[200:203], v154 offset:55296
	ds_read_b128 v[204:207], v154 offset:56320
	global_load_lds_dwordx4 v[146:147], off
	s_mov_b32 m0, s78
	v_lshl_add_u64 v[146:147], v[192:193], 0, s[88:89]
	global_load_lds_dwordx4 v[146:147], off
	s_barrier
; #define LAS __attribute__((address_space(3)))
; __device__ __forceinline__ unsigned pk2(float lo, float hi) { unsigned r; asm("v_cvt_pk_bf16_f32 %0, %1, %2" : "=v"(r) : "v"(lo), "v"(hi)); return r; }
; #define PG8_WAIT_V(n) asm volatile("s_waitcnt vmcnt(" #n ")" ::: "memory")
; #define PG8_WAIT_L(n) asm volatile("s_waitcnt lgkmcnt(" #n ")" ::: "memory")
; #define PG8_BAR __builtin_amdgcn_s_barrier()
; template <class Epi>
; __device__ __forceinline__ void gemm_phase(LAS unsigned char* lds, const Gemm g, const StaticOrder& S, const Epi& E) {
;     ...
;             PG8_BAR; PG8_WAIT_L(0); PG8_MMA(1, 0, At, B0); PG8_BAR; PG8_SCHED;
;             PG8_STAGE(PG8_SB(1, 1), b3 + hB, voffB);
;             PG8_WAIT_V(6); PG8_BAR; PG8_MMA(1, 1, At, B1); PG8_BAR;
;     __device__ __forceinline__ void operator()(const f32x4 (&acc)[2][2][4][2], const Unit& u, int wr, int wc, int fr, int fq) const {
;         const int col_t = u.pn * BM;
;         if (mode != 0 && col_t >= vt0) {
;             const int bl = u.pm / TPB, key0 = (u.pm - bl * TPB) * 256;
;             LAS bf16_t* sc = (LAS bf16_t*)(trs + (wr * 4 + wc) * 2304);
;             const int lane = fq * 16 + fr;
; #pragma unroll
;             for (int ai = 0; ai < 2; ++ai)
; #pragma unroll
;                 for (int bj = 0; bj < 2; ++bj)
; #pragma unroll
;                     for (int n = 0; n < 2; ++n) {
; #pragma unroll
;                         for (int m = 0; m < 4; ++m) {
;                             const f32x4 v = acc[ai][bj][m][n];
;                             const unsigned p0 = pk2(v[0], v[1]), p1 = pk2(v[2], v[3]);
;                             LAS bf16_t* w = sc + (4 * fq) * 72 + 16 * m + fr;
;                             w[0] = (bf16_t)(p0 & 0xffffu); w[72] = (bf16_t)(p0 >> 16); w[144] = (bf16_t)(p1 & 0xffffu); w[216] = (bf16_t)(p1 >> 16);
;                         }
; #pragma unroll
;                         for (int j = 0; j < 2; ++j) {
;                             const int ch = lane + 64 * j, fi = ch >> 3, seg = ch & 7;
;                             const u32x4 o = *(const LAS u32x4*)(sc + fi * 72 + 8 * seg);
;                             const int f = col_t - vt0 + 64 * wc + 16 * (fi >> 2) + 8 * bj + 4 * n + (fi & 3);
;                             *(u32x4*)(Vt + ((size_t)bl * vtnf + f) * KEYS + key0 + ai * HALF + wr * 64 + 8 * seg) = o;
;                         }
	s_waitcnt lgkmcnt(0)
	v_mfma_f32_16x16x32_bf16 v[60:63], v[136:139], v[166:169], v[60:63]
	v_mfma_f32_16x16x32_bf16 v[56:59], v[158:161], v[166:169], v[56:59]
	v_mfma_f32_16x16x32_bf16 v[52:55], v[136:139], v[174:177], v[52:55]
	v_mfma_f32_16x16x32_bf16 v[44:47], v[158:161], v[174:177], v[44:47]
	v_mfma_f32_16x16x32_bf16 v[36:39], v[136:139], v[182:185], v[36:39]
	v_mfma_f32_16x16x32_bf16 v[28:31], v[158:161], v[182:185], v[28:31]
	v_mfma_f32_16x16x32_bf16 v[20:23], v[136:139], v[200:203], v[20:23]
	v_mfma_f32_16x16x32_bf16 v[12:15], v[158:161], v[200:203], v[12:15]
	v_mfma_f32_16x16x32_bf16 v[60:63], v[140:143], v[170:173], v[60:63]
	v_mfma_f32_16x16x32_bf16 v[56:59], v[162:165], v[170:173], v[56:59]
	v_mfma_f32_16x16x32_bf16 v[52:55], v[140:143], v[178:181], v[52:55]
	v_mfma_f32_16x16x32_bf16 v[44:47], v[162:165], v[178:181], v[44:47]
	v_mfma_f32_16x16x32_bf16 v[36:39], v[140:143], v[196:199], v[36:39]
	v_mfma_f32_16x16x32_bf16 v[28:31], v[162:165], v[196:199], v[28:31]
	v_mfma_f32_16x16x32_bf16 v[20:23], v[140:143], v[204:207], v[20:23]
	v_mfma_f32_16x16x32_bf16 v[12:15], v[162:165], v[204:207], v[12:15]
	s_barrier
	s_mov_b32 m0, s31
	s_nop 0
	global_load_lds_dwordx4 v132, s[34:35]
	s_mov_b32 m0, s36
	s_nop 0
	global_load_lds_dwordx4 v128, s[34:35]
	s_waitcnt vmcnt(6)
	s_barrier
	v_mfma_f32_16x16x32_bf16 v[48:51], v[216:219], v[166:169], v[48:51]
	v_mfma_f32_16x16x32_bf16 v[40:43], v[224:227], v[166:169], v[40:43]
	v_mfma_f32_16x16x32_bf16 v[32:35], v[216:219], v[174:177], v[32:35]
	v_mfma_f32_16x16x32_bf16 v[24:27], v[224:227], v[174:177], v[24:27]
	v_mfma_f32_16x16x32_bf16 v[16:19], v[216:219], v[182:185], v[16:19]
	v_mfma_f32_16x16x32_bf16 v[8:11], v[224:227], v[182:185], v[8:11]
	v_mfma_f32_16x16x32_bf16 v[4:7], v[216:219], v[200:203], v[4:7]
	v_mfma_f32_16x16x32_bf16 v[0:3], v[224:227], v[200:203], v[0:3]
	v_mfma_f32_16x16x32_bf16 v[48:51], v[220:223], v[170:173], v[48:51]
	v_mfma_f32_16x16x32_bf16 v[40:43], v[228:231], v[170:173], v[40:43]
	v_mfma_f32_16x16x32_bf16 v[32:35], v[220:223], v[178:181], v[32:35]
	v_mfma_f32_16x16x32_bf16 v[24:27], v[228:231], v[178:181], v[24:27]
	v_mfma_f32_16x16x32_bf16 v[16:19], v[220:223], v[196:199], v[16:19]
	v_mfma_f32_16x16x32_bf16 v[8:11], v[228:231], v[196:199], v[8:11]
	v_mfma_f32_16x16x32_bf16 v[4:7], v[220:223], v[204:207], v[4:7]
	v_mfma_f32_16x16x32_bf16 v[0:3], v[228:231], v[204:207], v[0:3]
	s_movk_i32 s25, 0x100
	s_andn2_b64 vcc, exec, s[4:5]
	s_mov_b64 s[34:35], -1
	s_mov_b64 s[4:5], 0
	s_barrier
	s_cbranch_vccz .LBB0_670
	s_lshl_b32 s13, s15, 8
	s_cmp_lt_i32 s15, 2
	s_mov_b64 s[4:5], -1
	s_cbranch_scc1 .LBB0_673
	s_mul_hi_i32 s4, s81, 0x3e0f83e1
	s_lshr_b32 s5, s4, 31
	s_ashr_i32 s4, s4, 3
	v_cvt_pk_bf16_f32 v136, v124, v125
	s_add_i32 s4, s4, s5
	v_cvt_pk_bf16_f32 v137, v126, v127
	ds_write_b16 v151, v136
	ds_write_b16_d16_hi v151, v136 offset:144
	ds_write_b16 v151, v137 offset:288
	ds_write_b16_d16_hi v151, v137 offset:432
	v_cvt_pk_bf16_f32 v136, v116, v117
	s_mul_i32 s5, s4, 0xffffffdf
	v_cvt_pk_bf16_f32 v137, v118, v119
	ds_write_b16 v151, v136 offset:32
	ds_write_b16_d16_hi v151, v136 offset:176
	ds_write_b16 v151, v137 offset:320
	ds_write_b16_d16_hi v151, v137 offset:464
	v_cvt_pk_bf16_f32 v136, v100, v101
	s_add_i32 s5, s5, s81
	s_or_b32 s15, s13, s79
	v_cvt_pk_bf16_f32 v137, v102, v103
	ds_write_b16 v151, v136 offset:64
	ds_write_b16_d16_hi v151, v136 offset:208
	ds_write_b16 v151, v137 offset:352
	ds_write_b16_d16_hi v151, v137 offset:496
	v_cvt_pk_bf16_f32 v136, v84, v85
	s_lshl_b32 s24, s5, 8
	s_ashr_i32 s5, s4, 31
	v_cvt_pk_bf16_f32 v137, v86, v87
	ds_write_b16 v151, v136 offset:96
	ds_write_b16_d16_hi v151, v136 offset:240
	ds_write_b16 v151, v137 offset:384
	ds_write_b16_d16_hi v151, v137 offset:528
	v_add_u32_e32 v136, s15, v152
	s_lshl_b64 s[4:5], s[4:5], 9
	v_ashrrev_i32_e32 v137, 31, v136
	v_lshl_add_u64 v[136:137], s[4:5], 0, v[136:137]
	v_mov_b64_e32 v[162:163], s[8:9]
	s_ashr_i32 s25, s24, 31
	ds_read_b128 v[138:141], v155
	v_mad_u64_u32 v[142:143], s[26:27], v136, s91, v[162:163]
	v_mad_i32_i24 v143, v137, s91, v143
	s_lshl_b64 s[34:35], s[24:25], 1
	v_lshl_add_u64 v[136:137], v[142:143], 0, s[34:35]
	v_lshl_add_u64 v[136:137], v[136:137], 0, s[10:11]
	v_lshl_add_u64 v[136:137], v[136:137], 0, v[144:145]
	s_waitcnt lgkmcnt(0)
	global_store_dwordx4 v[136:137], v[138:141], off
	ds_read_b128 v[140:143], v156
	s_or_b32 s26, s15, 4
	v_add_u32_e32 v138, s15, v153
	v_ashrrev_i32_e32 v139, 31, v138
	v_lshl_add_u64 v[138:139], s[4:5], 0, v[138:139]
	v_mad_u64_u32 v[146:147], s[24:25], v138, s91, v[162:163]
	v_mad_i32_i24 v147, v139, s91, v147
	v_lshl_add_u64 v[138:139], v[146:147], 0, s[34:35]
	v_lshl_add_u64 v[138:139], v[138:139], 0, s[10:11]
	v_lshl_add_u64 v[138:139], v[138:139], 0, v[144:145]
	s_waitcnt lgkmcnt(0)
	global_store_dwordx4 v[138:139], v[140:143], off
	v_cvt_pk_bf16_f32 v157, v104, v105
	s_nop 1
	v_cvt_pk_bf16_f32 v140, v120, v121
	v_cvt_pk_bf16_f32 v141, v122, v123
	ds_write_b16 v151, v140
	ds_write_b16_d16_hi v151, v140 offset:144
	ds_write_b16 v151, v141 offset:288
	ds_write_b16_d16_hi v151, v141 offset:432
	v_cvt_pk_bf16_f32 v140, v108, v109
	v_cvt_pk_bf16_f32 v141, v110, v111
	ds_write_b16 v151, v140 offset:32
	ds_write_b16_d16_hi v151, v140 offset:176
	ds_write_b16 v151, v141 offset:320
	ds_write_b16_d16_hi v151, v141 offset:464
	v_cvt_pk_bf16_f32 v140, v92, v93
	v_cvt_pk_bf16_f32 v141, v94, v95
	ds_write_b16 v151, v140 offset:64
	ds_write_b16_d16_hi v151, v140 offset:208
	ds_write_b16 v151, v141 offset:352
	ds_write_b16_d16_hi v151, v141 offset:496
	v_cvt_pk_bf16_f32 v140, v76, v77
	v_cvt_pk_bf16_f32 v141, v78, v79
	ds_write_b16 v151, v140 offset:96
	ds_write_b16_d16_hi v151, v140 offset:240
	ds_write_b16 v151, v141 offset:384
	ds_write_b16_d16_hi v151, v141 offset:528
	v_add_u32_e32 v140, s26, v152
	v_ashrrev_i32_e32 v141, 31, v140
	v_lshl_add_u64 v[140:141], s[4:5], 0, v[140:141]
	ds_read_b128 v[158:161], v155
	v_mad_u64_u32 v[142:143], s[24:25], v140, s91, v[162:163]
	v_mad_i32_i24 v143, v141, s91, v143
	v_lshl_add_u64 v[140:141], v[142:143], 0, s[34:35]
	v_add_u32_e32 v142, s26, v153
	v_lshl_add_u64 v[140:141], v[140:141], 0, s[10:11]
	v_ashrrev_i32_e32 v143, 31, v142
	v_lshl_add_u64 v[140:141], v[140:141], 0, v[144:145]
	v_lshl_add_u64 v[142:143], s[4:5], 0, v[142:143]
	s_waitcnt lgkmcnt(0)
; #define LAS __attribute__((address_space(3)))
; __device__ __forceinline__ unsigned pk2(float lo, float hi) { unsigned r; asm("v_cvt_pk_bf16_f32 %0, %1, %2" : "=v"(r) : "v"(lo), "v"(hi)); return r; }
;     __device__ __forceinline__ void operator()(const f32x4 (&acc)[2][2][4][2], const Unit& u, int wr, int wc, int fr, int fq) const {
;     ...
; #pragma unroll
;             for (int ai = 0; ai < 2; ++ai)
; #pragma unroll
;                 for (int bj = 0; bj < 2; ++bj)
; #pragma unroll
;                     for (int n = 0; n < 2; ++n) {
; #pragma unroll
;                         for (int m = 0; m < 4; ++m) {
;                             const f32x4 v = acc[ai][bj][m][n];
;                             const unsigned p0 = pk2(v[0], v[1]), p1 = pk2(v[2], v[3]);
;                             LAS bf16_t* w = sc + (4 * fq) * 72 + 16 * m + fr;
;                             w[0] = (bf16_t)(p0 & 0xffffu); w[72] = (bf16_t)(p0 >> 16); w[144] = (bf16_t)(p1 & 0xffffu); w[216] = (bf16_t)(p1 >> 16);
;                         }
; #pragma unroll
;                         for (int j = 0; j < 2; ++j) {
;                             const int ch = lane + 64 * j, fi = ch >> 3, seg = ch & 7;
;                             const u32x4 o = *(const LAS u32x4*)(sc + fi * 72 + 8 * seg);
;                             const int f = col_t - vt0 + 64 * wc + 16 * (fi >> 2) + 8 * bj + 4 * n + (fi & 3);
;                             *(u32x4*)(Vt + ((size_t)bl * vtnf + f) * KEYS + key0 + ai * HALF + wr * 64 + 8 * seg) = o;
;                         }
	global_store_dwordx4 v[140:141], v[158:161], off
	ds_read_b128 v[158:161], v156
	v_mad_u64_u32 v[146:147], s[24:25], v142, s91, v[162:163]
	v_mad_i32_i24 v147, v143, s91, v147
	v_lshl_add_u64 v[142:143], v[146:147], 0, s[34:35]
	v_lshl_add_u64 v[142:143], v[142:143], 0, s[10:11]
	v_lshl_add_u64 v[142:143], v[142:143], 0, v[144:145]
	v_cvt_pk_bf16_f32 v146, v112, v113
	s_waitcnt lgkmcnt(0)
	global_store_dwordx4 v[142:143], v[158:161], off
	v_cvt_pk_bf16_f32 v147, v114, v115
	ds_write_b16 v151, v146
	ds_write_b16_d16_hi v151, v146 offset:144
	ds_write_b16 v151, v147 offset:288
	ds_write_b16_d16_hi v151, v147 offset:432
	v_cvt_pk_bf16_f32 v146, v96, v97
	v_cvt_pk_bf16_f32 v147, v98, v99
	ds_write_b16 v151, v146 offset:32
	ds_write_b16_d16_hi v151, v146 offset:176
	ds_write_b16 v151, v147 offset:320
	ds_write_b16_d16_hi v151, v147 offset:464
	v_cvt_pk_bf16_f32 v146, v80, v81
	s_or_b32 s26, s15, 8
	v_cvt_pk_bf16_f32 v147, v82, v83
	ds_write_b16 v151, v146 offset:64
	ds_write_b16_d16_hi v151, v146 offset:208
	ds_write_b16 v151, v147 offset:352
	ds_write_b16_d16_hi v151, v147 offset:496
	v_cvt_pk_bf16_f32 v146, v68, v69
	v_cvt_pk_bf16_f32 v147, v70, v71
	ds_write_b16 v151, v146 offset:96
	ds_write_b16_d16_hi v151, v146 offset:240
	ds_write_b16 v151, v147 offset:384
	ds_write_b16_d16_hi v151, v147 offset:528
	v_add_u32_e32 v146, s26, v152
	v_ashrrev_i32_e32 v147, 31, v146
	v_lshl_add_u64 v[146:147], s[4:5], 0, v[146:147]
	ds_read_b128 v[158:161], v155
	v_mad_u64_u32 v[164:165], s[24:25], v146, s91, v[162:163]
	v_mad_i32_i24 v165, v147, s91, v165
	v_lshl_add_u64 v[146:147], v[164:165], 0, s[34:35]
	v_add_u32_e32 v164, s26, v153
	v_lshl_add_u64 v[146:147], v[146:147], 0, s[10:11]
	v_ashrrev_i32_e32 v165, 31, v164
	v_lshl_add_u64 v[146:147], v[146:147], 0, v[144:145]
	v_lshl_add_u64 v[164:165], s[4:5], 0, v[164:165]
	s_waitcnt lgkmcnt(0)
	global_store_dwordx4 v[146:147], v[158:161], off
	ds_read_b128 v[158:161], v156
	v_mad_u64_u32 v[166:167], s[24:25], v164, s91, v[162:163]
	v_mad_i32_i24 v167, v165, s91, v167
	v_lshl_add_u64 v[164:165], v[166:167], 0, s[34:35]
	v_lshl_add_u64 v[164:165], v[164:165], 0, s[10:11]
	v_lshl_add_u64 v[164:165], v[164:165], 0, v[144:145]
	s_waitcnt lgkmcnt(0)
	global_store_dwordx4 v[164:165], v[158:161], off
	s_or_b32 s15, s15, 12
	v_add_u32_e32 v166, s15, v152
	v_cvt_pk_bf16_f32 v158, v106, v107
	ds_write_b16 v151, v157
	ds_write_b16_d16_hi v151, v157 offset:144
	ds_write_b16 v151, v158 offset:288
	ds_write_b16_d16_hi v151, v158 offset:432
	v_cvt_pk_bf16_f32 v157, v88, v89
	v_cvt_pk_bf16_f32 v158, v90, v91
	ds_write_b16 v151, v157 offset:32
	ds_write_b16_d16_hi v151, v157 offset:176
	ds_write_b16 v151, v158 offset:320
	ds_write_b16_d16_hi v151, v158 offset:464
	v_cvt_pk_bf16_f32 v157, v72, v73
	v_cvt_pk_bf16_f32 v158, v74, v75
	ds_write_b16 v151, v157 offset:64
	ds_write_b16_d16_hi v151, v157 offset:208
	ds_write_b16 v151, v158 offset:352
	ds_write_b16_d16_hi v151, v158 offset:496
	v_cvt_pk_bf16_f32 v157, v64, v65
	v_ashrrev_i32_e32 v167, 31, v166
	v_cvt_pk_bf16_f32 v158, v66, v67
	ds_write_b16 v151, v157 offset:96
	ds_write_b16_d16_hi v151, v157 offset:240
	ds_write_b16 v151, v158 offset:384
	ds_write_b16_d16_hi v151, v158 offset:528
	v_lshl_add_u64 v[166:167], s[4:5], 0, v[166:167]
	ds_read_b128 v[158:161], v155
	v_mad_u64_u32 v[168:169], s[24:25], v166, s91, v[162:163]
	v_mad_i32_i24 v169, v167, s91, v169
	v_lshl_add_u64 v[166:167], v[168:169], 0, s[34:35]
	v_add_u32_e32 v168, s15, v153
	v_lshl_add_u64 v[166:167], v[166:167], 0, s[10:11]
	v_ashrrev_i32_e32 v169, 31, v168
	v_lshl_add_u64 v[166:167], v[166:167], 0, v[144:145]
	v_lshl_add_u64 v[168:169], s[4:5], 0, v[168:169]
	s_waitcnt lgkmcnt(0)
	global_store_dwordx4 v[166:167], v[158:161], off
	ds_read_b128 v[158:161], v156
	v_mad_u64_u32 v[162:163], s[4:5], v168, s91, v[162:163]
	v_mad_i32_i24 v163, v169, s91, v163
	v_lshl_add_u64 v[162:163], v[162:163], 0, s[34:35]
	v_lshl_add_u64 v[162:163], v[162:163], 0, s[10:11]
	v_lshl_add_u64 v[162:163], v[162:163], 0, v[144:145]
	v_cvt_pk_bf16_f32 v157, v60, v61
	s_waitcnt lgkmcnt(0)
; #define LAS __attribute__((address_space(3)))
; __device__ __forceinline__ unsigned pk2(float lo, float hi) { unsigned r; asm("v_cvt_pk_bf16_f32 %0, %1, %2" : "=v"(r) : "v"(lo), "v"(hi)); return r; }
;     __device__ __forceinline__ void operator()(const f32x4 (&acc)[2][2][4][2], const Unit& u, int wr, int wc, int fr, int fq) const {
;     ...
; #pragma unroll
;             for (int ai = 0; ai < 2; ++ai)
; #pragma unroll
;                 for (int bj = 0; bj < 2; ++bj)
; #pragma unroll
;                     for (int n = 0; n < 2; ++n) {
; #pragma unroll
;                         for (int m = 0; m < 4; ++m) {
;                             const f32x4 v = acc[ai][bj][m][n];
;                             const unsigned p0 = pk2(v[0], v[1]), p1 = pk2(v[2], v[3]);
;                             LAS bf16_t* w = sc + (4 * fq) * 72 + 16 * m + fr;
;                             w[0] = (bf16_t)(p0 & 0xffffu); w[72] = (bf16_t)(p0 >> 16); w[144] = (bf16_t)(p1 & 0xffffu); w[216] = (bf16_t)(p1 >> 16);
;                         }
; #pragma unroll
;                         for (int j = 0; j < 2; ++j) {
;                             const int ch = lane + 64 * j, fi = ch >> 3, seg = ch & 7;
;                             const u32x4 o = *(const LAS u32x4*)(sc + fi * 72 + 8 * seg);
;                             const int f = col_t - vt0 + 64 * wc + 16 * (fi >> 2) + 8 * bj + 4 * n + (fi & 3);
;                             *(u32x4*)(Vt + ((size_t)bl * vtnf + f) * KEYS + key0 + ai * HALF + wr * 64 + 8 * seg) = o;
;                         }
	global_store_dwordx4 v[162:163], v[158:161], off
	s_mov_b64 s[4:5], 0
	s_nop 0
	v_cvt_pk_bf16_f32 v158, v62, v63
	ds_write_b16 v151, v157
	ds_write_b16_d16_hi v151, v157 offset:144
	ds_write_b16 v151, v158 offset:288
	ds_write_b16_d16_hi v151, v158 offset:432
	v_cvt_pk_bf16_f32 v157, v52, v53
	v_cvt_pk_bf16_f32 v158, v54, v55
	ds_write_b16 v151, v157 offset:32
	ds_write_b16_d16_hi v151, v157 offset:176
	ds_write_b16 v151, v158 offset:320
	ds_write_b16_d16_hi v151, v158 offset:464
	v_cvt_pk_bf16_f32 v157, v36, v37
	v_cvt_pk_bf16_f32 v158, v38, v39
	ds_write_b16 v151, v157 offset:64
	ds_write_b16_d16_hi v151, v157 offset:208
	ds_write_b16 v151, v158 offset:352
	ds_write_b16_d16_hi v151, v158 offset:496
	v_cvt_pk_bf16_f32 v157, v20, v21
	v_cvt_pk_bf16_f32 v158, v22, v23
	ds_write_b16 v151, v157 offset:96
	ds_write_b16_d16_hi v151, v157 offset:240
	ds_write_b16 v151, v158 offset:384
	ds_write_b16_d16_hi v151, v158 offset:528
	ds_read_b128 v[158:161], v155
	s_waitcnt lgkmcnt(0)
	global_store_dwordx4 v[136:137], v[158:161], off offset:256
	ds_read_b128 v[158:161], v156
	v_cvt_pk_bf16_f32 v136, v56, v57
	v_cvt_pk_bf16_f32 v137, v58, v59
	s_waitcnt lgkmcnt(0)
	global_store_dwordx4 v[138:139], v[158:161], off offset:256
	ds_write_b16 v151, v136
	ds_write_b16_d16_hi v151, v136 offset:144
	ds_write_b16 v151, v137 offset:288
	ds_write_b16_d16_hi v151, v137 offset:432
	v_cvt_pk_bf16_f32 v136, v44, v45
	v_cvt_pk_bf16_f32 v137, v46, v47
	ds_write_b16 v151, v136 offset:32
	ds_write_b16_d16_hi v151, v136 offset:176
	ds_write_b16 v151, v137 offset:320
	ds_write_b16_d16_hi v151, v137 offset:464
	v_cvt_pk_bf16_f32 v136, v28, v29
	v_cvt_pk_bf16_f32 v137, v30, v31
	ds_write_b16 v151, v136 offset:64
	ds_write_b16_d16_hi v151, v136 offset:208
	ds_write_b16 v151, v137 offset:352
	ds_write_b16_d16_hi v151, v137 offset:496
	v_cvt_pk_bf16_f32 v136, v12, v13
	v_cvt_pk_bf16_f32 v137, v14, v15
	ds_write_b16 v151, v136 offset:96
	ds_write_b16_d16_hi v151, v136 offset:240
	ds_write_b16 v151, v137 offset:384
	ds_write_b16_d16_hi v151, v137 offset:528
	ds_read_b128 v[136:139], v155
	s_waitcnt lgkmcnt(0)
	global_store_dwordx4 v[140:141], v[136:139], off offset:256
	ds_read_b128 v[136:139], v156
	s_waitcnt lgkmcnt(0)
	global_store_dwordx4 v[142:143], v[136:139], off offset:256
	s_nop 1
	v_cvt_pk_bf16_f32 v136, v48, v49
	v_cvt_pk_bf16_f32 v137, v50, v51
	ds_write_b16 v151, v136
	ds_write_b16_d16_hi v151, v136 offset:144
	ds_write_b16 v151, v137 offset:288
	ds_write_b16_d16_hi v151, v137 offset:432
	v_cvt_pk_bf16_f32 v136, v32, v33
	v_cvt_pk_bf16_f32 v137, v34, v35
	ds_write_b16 v151, v136 offset:32
	ds_write_b16_d16_hi v151, v136 offset:176
	ds_write_b16 v151, v137 offset:320
	ds_write_b16_d16_hi v151, v137 offset:464
	v_cvt_pk_bf16_f32 v136, v16, v17
	v_cvt_pk_bf16_f32 v137, v18, v19
	ds_write_b16 v151, v136 offset:64
	ds_write_b16_d16_hi v151, v136 offset:208
	ds_write_b16 v151, v137 offset:352
	ds_write_b16_d16_hi v151, v137 offset:496
	v_cvt_pk_bf16_f32 v136, v4, v5
	v_cvt_pk_bf16_f32 v137, v6, v7
	ds_write_b16 v151, v136 offset:96
	ds_write_b16_d16_hi v151, v136 offset:240
	ds_write_b16 v151, v137 offset:384
	ds_write_b16_d16_hi v151, v137 offset:528
	ds_read_b128 v[136:139], v155
	s_waitcnt lgkmcnt(0)
	global_store_dwordx4 v[146:147], v[136:139], off offset:256
	ds_read_b128 v[136:139], v156
	s_waitcnt lgkmcnt(0)
	global_store_dwordx4 v[164:165], v[136:139], off offset:256
	s_nop 1
	v_cvt_pk_bf16_f32 v136, v40, v41
	v_cvt_pk_bf16_f32 v137, v42, v43
	ds_write_b16 v151, v136
	ds_write_b16_d16_hi v151, v136 offset:144
	ds_write_b16 v151, v137 offset:288
	ds_write_b16_d16_hi v151, v137 offset:432
	v_cvt_pk_bf16_f32 v136, v24, v25
	v_cvt_pk_bf16_f32 v137, v26, v27
	ds_write_b16 v151, v136 offset:32
	ds_write_b16_d16_hi v151, v136 offset:176
	ds_write_b16 v151, v137 offset:320
	ds_write_b16_d16_hi v151, v137 offset:464
	v_cvt_pk_bf16_f32 v136, v8, v9
	v_cvt_pk_bf16_f32 v137, v10, v11
	ds_write_b16 v151, v136 offset:64
	ds_write_b16_d16_hi v151, v136 offset:208
	ds_write_b16 v151, v137 offset:352
	ds_write_b16_d16_hi v151, v137 offset:496
	v_cvt_pk_bf16_f32 v136, v0, v1
	v_cvt_pk_bf16_f32 v137, v2, v3
	ds_write_b16 v151, v136 offset:96
	ds_write_b16_d16_hi v151, v136 offset:240
	ds_write_b16 v151, v137 offset:384
	ds_write_b16_d16_hi v151, v137 offset:528
	ds_read_b128 v[136:139], v155
	s_waitcnt lgkmcnt(0)
	global_store_dwordx4 v[166:167], v[136:139], off offset:256
	ds_read_b128 v[136:139], v156
	s_waitcnt lgkmcnt(0)
	global_store_dwordx4 v[162:163], v[136:139], off offset:256

; #define PG8_STAGE(bufoff, gbase, voff) do { _Pragma("unroll") for (int _i = 0; _i < 2; ++_i) \
;         __builtin_amdgcn_global_load_lds((const unsigned*)((const char*)(gbase) + (voff)[_i]), (LAS unsigned*)(lds + (bufoff) + ldsw + _i * 8192), 16, 0, 0); } while (0)
; #define PG8_LDA(dst, b, h) do { _Pragma("unroll") for (int m = 0; m < 4; ++m) _Pragma("unroll") for (int k = 0; k < 2; ++k) dst[m][k] = *(const LAS bf16x8*)(lds + PG8_SA(b, h) + aoff + m * 2048 + k * 1024); } while (0)
; #define PG8_LDB(dst, b, h) do { _Pragma("unroll") for (int n = 0; n < 2; ++n) _Pragma("unroll") for (int k = 0; k < 2; ++k) dst[n][k] = *(const LAS bf16x8*)(lds + PG8_SB(b, h) + boff + n * 2048 + k * 1024); } while (0)
; #define PG8_MMA(ai, bj, At, Bt) do { __builtin_amdgcn_s_setprio(1); _Pragma("unroll") for (int m = 0; m < 4; ++m) _Pragma("unroll") for (int n = 0; n < 2; ++n) _Pragma("unroll") for (int k = 0; k < 2; ++k) \
;         acc[ai][bj][m][n] = __builtin_amdgcn_mfma_f32_16x16x32_bf16(Bt[n][k], At[m][k], acc[ai][bj][m][n], 0, 0, 0); __builtin_amdgcn_s_setprio(0); } while (0)
; #define PG8_WAIT_L(n) asm volatile("s_waitcnt lgkmcnt(" #n ")" ::: "memory")
; #define PG8_BAR __builtin_amdgcn_s_barrier()
; template <class Epi>
; __device__ __forceinline__ void gemm_phase(LAS unsigned char* lds, const Gemm g, const StaticOrder& S, const Epi& E) {
;     ...
;         const bool has_next = S.next(ui + 1, nxt);
;         const char* nA = has_next ? g.arow(nxt.pm) : cA; const char* nB = has_next ? (const char*)g.Bt + (size_t)nxt.pn * tB : cB;
;         for (int t = 0; t < nt; t += 2) {
;             const bool last = (t == nt - 2);
;             const char* a1 = cA + (size_t)(t + 1) * kstep;
;             const char* a2 = last ? nA : cA + (size_t)(t + 2) * kstep; const char* b2 = last ? nB : cB + (size_t)(t + 2) * kstep;
;             const char* a3 = a2 + kstep; const char* b3 = b2 + kstep;
;             PG8_LDB(B0, 0, 0); PG8_SCHED; PG8_LDA(At, 0, 0); PG8_STAGE(PG8_SA(1, 1), a1 + hA, voffA);
;             PG8_WAIT_L(8); PG8_BAR; PG8_WAIT_L(0); PG8_MMA(0, 0, At, B0); PG8_BAR; PG8_SCHED;
;             PG8_LDB(B1, 0, 1); PG8_STAGE(PG8_SB(0, 0), b2, voffB);
;             PG8_BAR; PG8_WAIT_L(0); PG8_MMA(0, 1, At, B1); PG8_BAR;
;             PG8_LDA(At, 0, 1); PG8_STAGE(PG8_SA(0, 0), a2, voffA);
;             PG8_BAR; PG8_WAIT_L(0); PG8_MMA(1, 0, At, B0); PG8_BAR; PG8_SCHED;
.LBB0_985:
	s_add_u32 s12, s10, 0x100
	s_addc_u32 s13, s11, 0
	s_add_i32 s26, 0, 0x10000
	v_add_u32_e32 v142, s26, v139
	ds_read_b128 v[134:137], v142
	ds_read_b128 v[146:149], v142 offset:1024
	ds_read_b128 v[150:153], v142 offset:2048
	ds_read_b128 v[154:157], v142 offset:3072
	s_cmp_eq_u32 s72, 20
	s_cselect_b32 s21, s5, s13
	s_cselect_b32 s20, s4, s12
	s_cselect_b32 s17, s7, s25
	s_cselect_b32 s16, s6, s24
	s_add_i32 m0, s61, 0xc000
	ds_read_b128 v[158:161], v141
	ds_read_b128 v[162:165], v141 offset:1024
	ds_read_b128 v[166:169], v141 offset:2048
	ds_read_b128 v[170:173], v141 offset:3072
	ds_read_b128 v[174:177], v141 offset:4096
	ds_read_b128 v[178:181], v141 offset:5120
	ds_read_b128 v[182:185], v141 offset:6144
	ds_read_b128 v[186:189], v141 offset:7168
	global_load_lds_dwordx4 v130, s[10:11]
	s_add_i32 m0, s61, 0xe000
	v_lshl_add_u64 v[142:143], s[10:11], 0, v[132:133]
	global_load_lds_dwordx4 v[142:143], off
	s_waitcnt lgkmcnt(8)
	s_barrier
	s_waitcnt lgkmcnt(0)
	v_mfma_f32_16x16x32_bf16 v[124:127], v[134:137], v[158:161], v[124:127]
	v_mfma_f32_16x16x32_bf16 v[120:123], v[150:153], v[158:161], v[120:123]
	v_mfma_f32_16x16x32_bf16 v[116:119], v[134:137], v[166:169], v[116:119]
	v_mfma_f32_16x16x32_bf16 v[108:111], v[150:153], v[166:169], v[108:111]
	v_mfma_f32_16x16x32_bf16 v[100:103], v[134:137], v[174:177], v[100:103]
	v_mfma_f32_16x16x32_bf16 v[92:95], v[150:153], v[174:177], v[92:95]
	v_mfma_f32_16x16x32_bf16 v[84:87], v[134:137], v[182:185], v[84:87]
	v_mfma_f32_16x16x32_bf16 v[76:79], v[150:153], v[182:185], v[76:79]
	v_mfma_f32_16x16x32_bf16 v[124:127], v[146:149], v[162:165], v[124:127]
	v_mfma_f32_16x16x32_bf16 v[120:123], v[154:157], v[162:165], v[120:123]
	v_mfma_f32_16x16x32_bf16 v[116:119], v[146:149], v[170:173], v[116:119]
	v_mfma_f32_16x16x32_bf16 v[108:111], v[154:157], v[170:173], v[108:111]
	v_mfma_f32_16x16x32_bf16 v[100:103], v[146:149], v[178:181], v[100:103]
	v_mfma_f32_16x16x32_bf16 v[92:95], v[154:157], v[178:181], v[92:95]
	v_mfma_f32_16x16x32_bf16 v[84:87], v[146:149], v[186:189], v[84:87]
	v_mfma_f32_16x16x32_bf16 v[76:79], v[154:157], v[186:189], v[76:79]
	s_barrier
	s_add_i32 s27, 0, 0x14000
	v_add_u32_e32 v142, s27, v139
	s_add_i32 s10, s26, s35
	ds_read_b128 v[196:199], v142
	ds_read_b128 v[200:203], v142 offset:1024
	ds_read_b128 v[204:207], v142 offset:2048
	ds_read_b128 v[214:217], v142 offset:3072
	v_lshl_add_u64 v[142:143], s[16:17], 0, v[144:145]
	s_mov_b32 m0, s10
	v_lshl_add_u64 v[192:193], s[16:17], 0, v[128:129]
	global_load_lds_dwordx4 v[142:143], off
	s_add_i32 m0, s10, 0x2000
	s_nop 0
	global_load_lds_dwordx4 v[192:193], off
	s_barrier
	s_waitcnt lgkmcnt(0)
	v_mfma_f32_16x16x32_bf16 v[112:115], v[196:199], v[158:161], v[112:115]
	v_mfma_f32_16x16x32_bf16 v[104:107], v[204:207], v[158:161], v[104:107]
	v_mfma_f32_16x16x32_bf16 v[96:99], v[196:199], v[166:169], v[96:99]
	v_mfma_f32_16x16x32_bf16 v[88:91], v[204:207], v[166:169], v[88:91]
	v_mfma_f32_16x16x32_bf16 v[80:83], v[196:199], v[174:177], v[80:83]
	v_mfma_f32_16x16x32_bf16 v[72:75], v[204:207], v[174:177], v[72:75]
	v_mfma_f32_16x16x32_bf16 v[68:71], v[196:199], v[182:185], v[68:71]
	v_mfma_f32_16x16x32_bf16 v[64:67], v[204:207], v[182:185], v[64:67]
	v_mfma_f32_16x16x32_bf16 v[112:115], v[200:203], v[162:165], v[112:115]
	v_mfma_f32_16x16x32_bf16 v[104:107], v[214:217], v[162:165], v[104:107]
	v_mfma_f32_16x16x32_bf16 v[96:99], v[200:203], v[170:173], v[96:99]
	v_mfma_f32_16x16x32_bf16 v[88:91], v[214:217], v[170:173], v[88:91]
	v_mfma_f32_16x16x32_bf16 v[80:83], v[200:203], v[178:181], v[80:83]
	v_mfma_f32_16x16x32_bf16 v[72:75], v[214:217], v[178:181], v[72:75]
	v_mfma_f32_16x16x32_bf16 v[68:71], v[200:203], v[186:189], v[68:71]
	v_mfma_f32_16x16x32_bf16 v[64:67], v[214:217], v[186:189], v[64:67]
	s_mov_b32 m0, s61
	v_lshl_add_u64 v[218:219], s[20:21], 0, v[144:145]
	s_barrier
	ds_read_b128 v[158:161], v141 offset:16384
	ds_read_b128 v[162:165], v141 offset:17408
	ds_read_b128 v[166:169], v141 offset:18432
	ds_read_b128 v[170:173], v141 offset:19456
	ds_read_b128 v[174:177], v141 offset:20480
	ds_read_b128 v[178:181], v141 offset:21504
	ds_read_b128 v[182:185], v141 offset:22528
	ds_read_b128 v[186:189], v141 offset:23552
	global_load_lds_dwordx4 v[218:219], off
	s_mov_b32 m0, s62
	v_lshl_add_u64 v[220:221], s[20:21], 0, v[128:129]
	global_load_lds_dwordx4 v[220:221], off
	s_barrier
	s_waitcnt lgkmcnt(0)
	v_mfma_f32_16x16x32_bf16 v[60:63], v[134:137], v[158:161], v[60:63]
	v_mfma_f32_16x16x32_bf16 v[56:59], v[150:153], v[158:161], v[56:59]
	v_mfma_f32_16x16x32_bf16 v[52:55], v[134:137], v[166:169], v[52:55]
	v_mfma_f32_16x16x32_bf16 v[44:47], v[150:153], v[166:169], v[44:47]
	v_mfma_f32_16x16x32_bf16 v[36:39], v[134:137], v[174:177], v[36:39]
	v_mfma_f32_16x16x32_bf16 v[28:31], v[150:153], v[174:177], v[28:31]
	v_mfma_f32_16x16x32_bf16 v[20:23], v[134:137], v[182:185], v[20:23]
	v_mfma_f32_16x16x32_bf16 v[12:15], v[150:153], v[182:185], v[12:15]
	v_mfma_f32_16x16x32_bf16 v[60:63], v[146:149], v[162:165], v[60:63]
	v_mfma_f32_16x16x32_bf16 v[56:59], v[154:157], v[162:165], v[56:59]
	v_mfma_f32_16x16x32_bf16 v[52:55], v[146:149], v[170:173], v[52:55]
	v_mfma_f32_16x16x32_bf16 v[44:47], v[154:157], v[170:173], v[44:47]
	v_mfma_f32_16x16x32_bf16 v[36:39], v[146:149], v[178:181], v[36:39]
	v_mfma_f32_16x16x32_bf16 v[28:31], v[154:157], v[178:181], v[28:31]
	v_mfma_f32_16x16x32_bf16 v[20:23], v[146:149], v[186:189], v[20:23]
	v_mfma_f32_16x16x32_bf16 v[12:15], v[154:157], v[186:189], v[12:15]
	s_barrier
; #define PG8_STAGE(bufoff, gbase, voff) do { _Pragma("unroll") for (int _i = 0; _i < 2; ++_i) \
;         __builtin_amdgcn_global_load_lds((const unsigned*)((const char*)(gbase) + (voff)[_i]), (LAS unsigned*)(lds + (bufoff) + ldsw + _i * 8192), 16, 0, 0); } while (0)
; #define PG8_LDA(dst, b, h) do { _Pragma("unroll") for (int m = 0; m < 4; ++m) _Pragma("unroll") for (int k = 0; k < 2; ++k) dst[m][k] = *(const LAS bf16x8*)(lds + PG8_SA(b, h) + aoff + m * 2048 + k * 1024); } while (0)
; #define PG8_LDB(dst, b, h) do { _Pragma("unroll") for (int n = 0; n < 2; ++n) _Pragma("unroll") for (int k = 0; k < 2; ++k) dst[n][k] = *(const LAS bf16x8*)(lds + PG8_SB(b, h) + boff + n * 2048 + k * 1024); } while (0)
; #define PG8_MMA(ai, bj, At, Bt) do { __builtin_amdgcn_s_setprio(1); _Pragma("unroll") for (int m = 0; m < 4; ++m) _Pragma("unroll") for (int n = 0; n < 2; ++n) _Pragma("unroll") for (int k = 0; k < 2; ++k) \
;         acc[ai][bj][m][n] = __builtin_amdgcn_mfma_f32_16x16x32_bf16(Bt[n][k], At[m][k], acc[ai][bj][m][n], 0, 0, 0); __builtin_amdgcn_s_setprio(0); } while (0)
; #define PG8_WAIT_V(n) asm volatile("s_waitcnt vmcnt(" #n ")" ::: "memory")
; #define PG8_WAIT_L(n) asm volatile("s_waitcnt lgkmcnt(" #n ")" ::: "memory")
; #define PG8_BAR __builtin_amdgcn_s_barrier()
; #define PG8_SCHED __builtin_amdgcn_sched_barrier(0)
; template <class Epi>
; __device__ __forceinline__ void gemm_phase(LAS unsigned char* lds, const Gemm g, const StaticOrder& S, const Epi& E) {
;     ...
;             PG8_STAGE(PG8_SB(0, 1), b2 + hB, voffB);
;             PG8_WAIT_V(6); PG8_BAR; PG8_MMA(1, 1, At, B1); PG8_BAR;
;             PG8_LDB(B0, 1, 0); PG8_SCHED; PG8_LDA(At, 1, 0); PG8_STAGE(PG8_SA(0, 1), a2 + hA, voffA);
;             PG8_WAIT_L(8); PG8_BAR; PG8_WAIT_L(0); PG8_MMA(0, 0, At, B0); PG8_BAR; PG8_SCHED;
;             PG8_LDB(B1, 1, 1); PG8_STAGE(PG8_SB(1, 0), b3, voffB);
;             PG8_BAR; PG8_WAIT_L(0); PG8_MMA(0, 1, At, B1); PG8_BAR;
;             PG8_LDA(At, 1, 1); PG8_STAGE(PG8_SA(1, 0), a3, voffA);
	s_add_u32 s10, s16, 0x60000
	s_addc_u32 s11, s17, 0
	s_add_i32 s26, s27, s35
	s_mov_b32 m0, s26
	s_nop 0
	global_load_lds_dwordx4 v144, s[10:11]
	s_add_i32 m0, s26, 0x2000
	s_nop 0
	global_load_lds_dwordx4 v128, s[10:11]
	s_waitcnt vmcnt(6)
	s_barrier
	v_mfma_f32_16x16x32_bf16 v[48:51], v[196:199], v[158:161], v[48:51]
	v_mfma_f32_16x16x32_bf16 v[40:43], v[204:207], v[158:161], v[40:43]
	v_mfma_f32_16x16x32_bf16 v[32:35], v[196:199], v[166:169], v[32:35]
	v_mfma_f32_16x16x32_bf16 v[24:27], v[204:207], v[166:169], v[24:27]
	v_mfma_f32_16x16x32_bf16 v[16:19], v[196:199], v[174:177], v[16:19]
	v_mfma_f32_16x16x32_bf16 v[8:11], v[204:207], v[174:177], v[8:11]
	v_mfma_f32_16x16x32_bf16 v[4:7], v[196:199], v[182:185], v[4:7]
	v_mfma_f32_16x16x32_bf16 v[0:3], v[204:207], v[182:185], v[0:3]
	v_mfma_f32_16x16x32_bf16 v[48:51], v[200:203], v[162:165], v[48:51]
	v_mfma_f32_16x16x32_bf16 v[40:43], v[214:217], v[162:165], v[40:43]
	v_mfma_f32_16x16x32_bf16 v[32:35], v[200:203], v[170:173], v[32:35]
	v_mfma_f32_16x16x32_bf16 v[24:27], v[214:217], v[170:173], v[24:27]
	v_mfma_f32_16x16x32_bf16 v[16:19], v[200:203], v[178:181], v[16:19]
	v_mfma_f32_16x16x32_bf16 v[8:11], v[214:217], v[178:181], v[8:11]
	v_mfma_f32_16x16x32_bf16 v[4:7], v[200:203], v[186:189], v[4:7]
	v_mfma_f32_16x16x32_bf16 v[0:3], v[214:217], v[186:189], v[0:3]
	s_add_i32 s26, 0, 0x18000
	v_add_u32_e32 v154, s26, v139
	s_barrier
	ds_read_b128 v[134:137], v154
	ds_read_b128 v[146:149], v154 offset:1024
	ds_read_b128 v[150:153], v154 offset:2048
	ds_read_b128 v[154:157], v154 offset:3072
	s_add_u32 s10, s20, 0x60000
	s_addc_u32 s11, s21, 0
	s_mov_b32 m0, s63
	ds_read_b128 v[158:161], v141 offset:32768
	ds_read_b128 v[162:165], v141 offset:33792
	ds_read_b128 v[166:169], v141 offset:34816
	ds_read_b128 v[170:173], v141 offset:35840
	ds_read_b128 v[174:177], v141 offset:36864
	ds_read_b128 v[178:181], v141 offset:37888
	ds_read_b128 v[182:185], v141 offset:38912
	ds_read_b128 v[186:189], v141 offset:39936
	global_load_lds_dwordx4 v144, s[10:11]
	s_mov_b32 m0, s64
	s_nop 0
	global_load_lds_dwordx4 v128, s[10:11]
	s_waitcnt lgkmcnt(8)
	s_barrier
	s_waitcnt lgkmcnt(0)
	v_mfma_f32_16x16x32_bf16 v[124:127], v[134:137], v[158:161], v[124:127]
	v_mfma_f32_16x16x32_bf16 v[120:123], v[150:153], v[158:161], v[120:123]
	v_mfma_f32_16x16x32_bf16 v[116:119], v[134:137], v[166:169], v[116:119]
	v_mfma_f32_16x16x32_bf16 v[108:111], v[150:153], v[166:169], v[108:111]
	v_mfma_f32_16x16x32_bf16 v[100:103], v[134:137], v[174:177], v[100:103]
	v_mfma_f32_16x16x32_bf16 v[92:95], v[150:153], v[174:177], v[92:95]
	v_mfma_f32_16x16x32_bf16 v[84:87], v[134:137], v[182:185], v[84:87]
	v_mfma_f32_16x16x32_bf16 v[76:79], v[150:153], v[182:185], v[76:79]
	v_mfma_f32_16x16x32_bf16 v[124:127], v[146:149], v[162:165], v[124:127]
	v_mfma_f32_16x16x32_bf16 v[120:123], v[154:157], v[162:165], v[120:123]
	v_mfma_f32_16x16x32_bf16 v[116:119], v[146:149], v[170:173], v[116:119]
	v_mfma_f32_16x16x32_bf16 v[108:111], v[154:157], v[170:173], v[108:111]
	v_mfma_f32_16x16x32_bf16 v[100:103], v[146:149], v[178:181], v[100:103]
	v_mfma_f32_16x16x32_bf16 v[92:95], v[154:157], v[178:181], v[92:95]
	v_mfma_f32_16x16x32_bf16 v[84:87], v[146:149], v[186:189], v[84:87]
	v_mfma_f32_16x16x32_bf16 v[76:79], v[154:157], v[186:189], v[76:79]
	s_barrier
	s_add_i32 s20, 0, 0x1c000
	s_add_i32 s10, s26, s35
	v_add_u32_e32 v190, s20, v139
	v_lshl_add_u64 v[142:143], v[142:143], 0, s[88:89]
	s_mov_b32 m0, s10
	ds_read_b128 v[196:199], v190
	ds_read_b128 v[200:203], v190 offset:1024
	ds_read_b128 v[204:207], v190 offset:2048
	ds_read_b128 v[214:217], v190 offset:3072
	global_load_lds_dwordx4 v[142:143], off
	s_add_i32 m0, s10, 0x2000
	v_lshl_add_u64 v[142:143], v[192:193], 0, s[88:89]
	global_load_lds_dwordx4 v[142:143], off
	s_barrier
; #define PG8_STAGE(bufoff, gbase, voff) do { _Pragma("unroll") for (int _i = 0; _i < 2; ++_i) \
;         __builtin_amdgcn_global_load_lds((const unsigned*)((const char*)(gbase) + (voff)[_i]), (LAS unsigned*)(lds + (bufoff) + ldsw + _i * 8192), 16, 0, 0); } while (0)
; #define PG8_MMA(ai, bj, At, Bt) do { __builtin_amdgcn_s_setprio(1); _Pragma("unroll") for (int m = 0; m < 4; ++m) _Pragma("unroll") for (int n = 0; n < 2; ++n) _Pragma("unroll") for (int k = 0; k < 2; ++k) \
;         acc[ai][bj][m][n] = __builtin_amdgcn_mfma_f32_16x16x32_bf16(Bt[n][k], At[m][k], acc[ai][bj][m][n], 0, 0, 0); __builtin_amdgcn_s_setprio(0); } while (0)
; #define PG8_WAIT_V(n) asm volatile("s_waitcnt vmcnt(" #n ")" ::: "memory")
; #define PG8_WAIT_L(n) asm volatile("s_waitcnt lgkmcnt(" #n ")" ::: "memory")
; #define PG8_BAR __builtin_amdgcn_s_barrier()
; #define PG8_SCHED __builtin_amdgcn_sched_barrier(0)
; template <class Epi>
; __device__ __forceinline__ void gemm_phase(LAS unsigned char* lds, const Gemm g, const StaticOrder& S, const Epi& E) {
;     ...
;             PG8_BAR; PG8_WAIT_L(0); PG8_MMA(1, 0, At, B0); PG8_BAR; PG8_SCHED;
;             PG8_STAGE(PG8_SB(1, 1), b3 + hB, voffB);
;             PG8_WAIT_V(6); PG8_BAR; PG8_MMA(1, 1, At, B1); PG8_BAR;
	s_waitcnt lgkmcnt(0)
	v_mfma_f32_16x16x32_bf16 v[112:115], v[196:199], v[158:161], v[112:115]
	v_mfma_f32_16x16x32_bf16 v[104:107], v[204:207], v[158:161], v[104:107]
	v_mfma_f32_16x16x32_bf16 v[96:99], v[196:199], v[166:169], v[96:99]
	v_mfma_f32_16x16x32_bf16 v[88:91], v[204:207], v[166:169], v[88:91]
	v_mfma_f32_16x16x32_bf16 v[80:83], v[196:199], v[174:177], v[80:83]
	v_mfma_f32_16x16x32_bf16 v[72:75], v[204:207], v[174:177], v[72:75]
	v_mfma_f32_16x16x32_bf16 v[68:71], v[196:199], v[182:185], v[68:71]
	v_mfma_f32_16x16x32_bf16 v[64:67], v[204:207], v[182:185], v[64:67]
	v_mfma_f32_16x16x32_bf16 v[112:115], v[200:203], v[162:165], v[112:115]
	v_mfma_f32_16x16x32_bf16 v[104:107], v[214:217], v[162:165], v[104:107]
	v_mfma_f32_16x16x32_bf16 v[96:99], v[200:203], v[170:173], v[96:99]
	v_mfma_f32_16x16x32_bf16 v[88:91], v[214:217], v[170:173], v[88:91]
	v_mfma_f32_16x16x32_bf16 v[80:83], v[200:203], v[178:181], v[80:83]
	v_mfma_f32_16x16x32_bf16 v[72:75], v[214:217], v[178:181], v[72:75]
	v_mfma_f32_16x16x32_bf16 v[68:71], v[200:203], v[186:189], v[68:71]
	v_mfma_f32_16x16x32_bf16 v[64:67], v[214:217], v[186:189], v[64:67]
	s_mov_b32 m0, s65
	v_lshl_add_u64 v[142:143], v[218:219], 0, s[88:89]
	s_barrier
	ds_read_b128 v[158:161], v141 offset:49152
	ds_read_b128 v[162:165], v141 offset:50176
	ds_read_b128 v[166:169], v141 offset:51200
	ds_read_b128 v[170:173], v141 offset:52224
	ds_read_b128 v[174:177], v141 offset:53248
	ds_read_b128 v[178:181], v141 offset:54272
	ds_read_b128 v[182:185], v141 offset:55296
	ds_read_b128 v[186:189], v141 offset:56320
	global_load_lds_dwordx4 v[142:143], off
	s_mov_b32 m0, s66
	v_lshl_add_u64 v[142:143], v[220:221], 0, s[88:89]
	global_load_lds_dwordx4 v[142:143], off
	s_barrier
	s_waitcnt lgkmcnt(0)
	v_mfma_f32_16x16x32_bf16 v[60:63], v[134:137], v[158:161], v[60:63]
	v_mfma_f32_16x16x32_bf16 v[56:59], v[150:153], v[158:161], v[56:59]
	v_mfma_f32_16x16x32_bf16 v[52:55], v[134:137], v[166:169], v[52:55]
	v_mfma_f32_16x16x32_bf16 v[44:47], v[150:153], v[166:169], v[44:47]
	v_mfma_f32_16x16x32_bf16 v[36:39], v[134:137], v[174:177], v[36:39]
	v_mfma_f32_16x16x32_bf16 v[28:31], v[150:153], v[174:177], v[28:31]
	v_mfma_f32_16x16x32_bf16 v[20:23], v[134:137], v[182:185], v[20:23]
	v_mfma_f32_16x16x32_bf16 v[12:15], v[150:153], v[182:185], v[12:15]
	v_mfma_f32_16x16x32_bf16 v[60:63], v[146:149], v[162:165], v[60:63]
	v_mfma_f32_16x16x32_bf16 v[56:59], v[154:157], v[162:165], v[56:59]
	v_mfma_f32_16x16x32_bf16 v[52:55], v[146:149], v[170:173], v[52:55]
	v_mfma_f32_16x16x32_bf16 v[44:47], v[154:157], v[170:173], v[44:47]
	v_mfma_f32_16x16x32_bf16 v[36:39], v[146:149], v[178:181], v[36:39]
	v_mfma_f32_16x16x32_bf16 v[28:31], v[154:157], v[178:181], v[28:31]
	v_mfma_f32_16x16x32_bf16 v[20:23], v[146:149], v[186:189], v[20:23]
	v_mfma_f32_16x16x32_bf16 v[12:15], v[154:157], v[186:189], v[12:15]
	s_barrier
	s_add_u32 s10, s16, 0x60080
	s_addc_u32 s11, s17, 0
	s_add_i32 s16, s20, s35
	s_mov_b32 m0, s16
	s_nop 0
	global_load_lds_dwordx4 v144, s[10:11]
	s_add_i32 m0, s16, 0x2000
	s_nop 0
	global_load_lds_dwordx4 v128, s[10:11]
	s_waitcnt vmcnt(6)
	s_barrier
	v_mfma_f32_16x16x32_bf16 v[48:51], v[196:199], v[158:161], v[48:51]
	v_mfma_f32_16x16x32_bf16 v[40:43], v[204:207], v[158:161], v[40:43]
	v_mfma_f32_16x16x32_bf16 v[32:35], v[196:199], v[166:169], v[32:35]
	v_mfma_f32_16x16x32_bf16 v[24:27], v[204:207], v[166:169], v[24:27]
	v_mfma_f32_16x16x32_bf16 v[16:19], v[196:199], v[174:177], v[16:19]
	v_mfma_f32_16x16x32_bf16 v[8:11], v[204:207], v[174:177], v[8:11]
	v_mfma_f32_16x16x32_bf16 v[4:7], v[196:199], v[182:185], v[4:7]
	v_mfma_f32_16x16x32_bf16 v[0:3], v[204:207], v[182:185], v[0:3]
	v_mfma_f32_16x16x32_bf16 v[48:51], v[200:203], v[162:165], v[48:51]
	v_mfma_f32_16x16x32_bf16 v[40:43], v[214:217], v[162:165], v[40:43]
	v_mfma_f32_16x16x32_bf16 v[32:35], v[200:203], v[170:173], v[32:35]
	v_mfma_f32_16x16x32_bf16 v[24:27], v[214:217], v[170:173], v[24:27]
	v_mfma_f32_16x16x32_bf16 v[16:19], v[200:203], v[178:181], v[16:19]
	v_mfma_f32_16x16x32_bf16 v[8:11], v[214:217], v[178:181], v[8:11]
	v_mfma_f32_16x16x32_bf16 v[4:7], v[200:203], v[186:189], v[4:7]
	v_mfma_f32_16x16x32_bf16 v[0:3], v[214:217], v[186:189], v[0:3]
	s_add_i32 s72, s72, 2
	s_add_u32 s24, s24, 0x100
	s_addc_u32 s25, s25, 0
	s_cmp_gt_u32 s72, 21
	s_mov_b64 s[10:11], s[12:13]
	s_barrier
	s_cbranch_scc0 .LBB0_985
	s_mul_hi_i32 s10, s71, 0x3e0f83e1
	s_lshr_b32 s11, s10, 31
	s_ashr_i32 s10, s10, 5
	s_add_i32 s11, s10, s11
	s_mul_i32 s10, s11, 0x84
	s_sub_i32 s10, s71, s10
	s_mul_i32 s12, s10, 0x7c2
	s_lshr_b32 s13, s12, 31
	s_lshr_b32 s12, s12, 16
	s_add_i32 s12, s12, s13
	s_sext_i32_i16 s12, s12
	s_mul_i32 s13, s12, 0xffffffdf
	s_lshl_b32 s11, s11, 2
	s_add_i32 s10, s13, s10
	s_add_i32 s12, s11, s12
	s_cmp_lg_u32 s10, 0
	s_cbranch_scc0 .LBB0_988
	s_lshl_b32 s11, s12, 13
	s_lshl_b32 s10, s10, 8
	s_add_i32 s10, s11, s10
	s_add_i32 s13, s10, 0xffffff00
	s_cbranch_execnz .LBB0_977
	s_branch .LBB0_976

; #define PG8_STAGE(bufoff, gbase, voff) do { _Pragma("unroll") for (int _i = 0; _i < 2; ++_i) \
;         __builtin_amdgcn_global_load_lds((const unsigned*)((const char*)(gbase) + (voff)[_i]), (LAS unsigned*)(lds + (bufoff) + ldsw + _i * 8192), 16, 0, 0); } while (0)
; #define PG8_LDA(dst, b, h) do { _Pragma("unroll") for (int m = 0; m < 4; ++m) _Pragma("unroll") for (int k = 0; k < 2; ++k) dst[m][k] = *(const LAS bf16x8*)(lds + PG8_SA(b, h) + aoff + m * 2048 + k * 1024); } while (0)
; #define PG8_LDB(dst, b, h) do { _Pragma("unroll") for (int n = 0; n < 2; ++n) _Pragma("unroll") for (int k = 0; k < 2; ++k) dst[n][k] = *(const LAS bf16x8*)(lds + PG8_SB(b, h) + boff + n * 2048 + k * 1024); } while (0)
; #define PG8_MMA(ai, bj, At, Bt) do { __builtin_amdgcn_s_setprio(1); _Pragma("unroll") for (int m = 0; m < 4; ++m) _Pragma("unroll") for (int n = 0; n < 2; ++n) _Pragma("unroll") for (int k = 0; k < 2; ++k) \
;         acc[ai][bj][m][n] = __builtin_amdgcn_mfma_f32_16x16x32_bf16(Bt[n][k], At[m][k], acc[ai][bj][m][n], 0, 0, 0); __builtin_amdgcn_s_setprio(0); } while (0)
; #define PG8_WAIT_L(n) asm volatile("s_waitcnt lgkmcnt(" #n ")" ::: "memory")
; #define PG8_BAR __builtin_amdgcn_s_barrier()
; #define PG8_SCHED __builtin_amdgcn_sched_barrier(0)
; template <class Epi>
; __device__ __forceinline__ void gemm_phase(LAS unsigned char* lds, const Gemm g, const StaticOrder& S, const Epi& E) {
;     ...
;             const bool last = (t == nt - 2);
;             const char* a1 = cA + (size_t)(t + 1) * kstep;
;             const char* a2 = last ? nA : cA + (size_t)(t + 2) * kstep; const char* b2 = last ? nB : cB + (size_t)(t + 2) * kstep;
;             const char* a3 = a2 + kstep; const char* b3 = b2 + kstep;
;             PG8_LDB(B0, 0, 0); PG8_SCHED; PG8_LDA(At, 0, 0); PG8_STAGE(PG8_SA(1, 1), a1 + hA, voffA);
;             PG8_WAIT_L(8); PG8_BAR; PG8_WAIT_L(0); PG8_MMA(0, 0, At, B0); PG8_BAR; PG8_SCHED;
;             PG8_LDB(B1, 0, 1); PG8_STAGE(PG8_SB(0, 0), b2, voffB);
;             PG8_BAR; PG8_WAIT_L(0); PG8_MMA(0, 1, At, B1); PG8_BAR;
;             PG8_LDA(At, 0, 1); PG8_STAGE(PG8_SA(0, 0), a2, voffA);
;             PG8_BAR; PG8_WAIT_L(0); PG8_MMA(1, 0, At, B0); PG8_BAR; PG8_SCHED;
.LBB0_1013:
	s_add_u32 s12, s10, 0x100
	s_addc_u32 s13, s11, 0
	s_add_i32 s26, 0, 0x10000
	v_add_u32_e32 v142, s26, v139
	ds_read_b128 v[134:137], v142
	ds_read_b128 v[146:149], v142 offset:1024
	ds_read_b128 v[150:153], v142 offset:2048
	ds_read_b128 v[154:157], v142 offset:3072
	s_cmp_eq_u32 s72, 20
	s_cselect_b32 s21, s5, s13
	s_cselect_b32 s20, s4, s12
	s_cselect_b32 s17, s7, s25
	s_cselect_b32 s16, s6, s24
	s_add_i32 m0, s61, 0xc000
	ds_read_b128 v[158:161], v141
	ds_read_b128 v[162:165], v141 offset:1024
	ds_read_b128 v[166:169], v141 offset:2048
	ds_read_b128 v[170:173], v141 offset:3072
	ds_read_b128 v[174:177], v141 offset:4096
	ds_read_b128 v[178:181], v141 offset:5120
	ds_read_b128 v[182:185], v141 offset:6144
	ds_read_b128 v[186:189], v141 offset:7168
	global_load_lds_dwordx4 v130, s[10:11]
	s_add_i32 m0, s61, 0xe000
	v_lshl_add_u64 v[142:143], s[10:11], 0, v[132:133]
	global_load_lds_dwordx4 v[142:143], off
	s_waitcnt lgkmcnt(8)
	s_barrier
	s_waitcnt lgkmcnt(0)
	v_mfma_f32_16x16x32_bf16 v[124:127], v[134:137], v[158:161], v[124:127]
	v_mfma_f32_16x16x32_bf16 v[120:123], v[150:153], v[158:161], v[120:123]
	v_mfma_f32_16x16x32_bf16 v[116:119], v[134:137], v[166:169], v[116:119]
	v_mfma_f32_16x16x32_bf16 v[108:111], v[150:153], v[166:169], v[108:111]
	v_mfma_f32_16x16x32_bf16 v[100:103], v[134:137], v[174:177], v[100:103]
	v_mfma_f32_16x16x32_bf16 v[92:95], v[150:153], v[174:177], v[92:95]
	v_mfma_f32_16x16x32_bf16 v[84:87], v[134:137], v[182:185], v[84:87]
	v_mfma_f32_16x16x32_bf16 v[76:79], v[150:153], v[182:185], v[76:79]
	v_mfma_f32_16x16x32_bf16 v[124:127], v[146:149], v[162:165], v[124:127]
	v_mfma_f32_16x16x32_bf16 v[120:123], v[154:157], v[162:165], v[120:123]
	v_mfma_f32_16x16x32_bf16 v[116:119], v[146:149], v[170:173], v[116:119]
	v_mfma_f32_16x16x32_bf16 v[108:111], v[154:157], v[170:173], v[108:111]
	v_mfma_f32_16x16x32_bf16 v[100:103], v[146:149], v[178:181], v[100:103]
	v_mfma_f32_16x16x32_bf16 v[92:95], v[154:157], v[178:181], v[92:95]
	v_mfma_f32_16x16x32_bf16 v[84:87], v[146:149], v[186:189], v[84:87]
	v_mfma_f32_16x16x32_bf16 v[76:79], v[154:157], v[186:189], v[76:79]
	s_barrier
	s_add_i32 s27, 0, 0x14000
	v_add_u32_e32 v142, s27, v139
	s_add_i32 s10, s26, s60
	ds_read_b128 v[196:199], v142
	ds_read_b128 v[200:203], v142 offset:1024
	ds_read_b128 v[204:207], v142 offset:2048
	ds_read_b128 v[214:217], v142 offset:3072
	v_lshl_add_u64 v[142:143], s[16:17], 0, v[144:145]
	s_mov_b32 m0, s10
	v_lshl_add_u64 v[192:193], s[16:17], 0, v[128:129]
	global_load_lds_dwordx4 v[142:143], off
	s_add_i32 m0, s10, 0x2000
	s_nop 0
	global_load_lds_dwordx4 v[192:193], off
	s_barrier
	s_waitcnt lgkmcnt(0)
	v_mfma_f32_16x16x32_bf16 v[112:115], v[196:199], v[158:161], v[112:115]
	v_mfma_f32_16x16x32_bf16 v[104:107], v[204:207], v[158:161], v[104:107]
	v_mfma_f32_16x16x32_bf16 v[96:99], v[196:199], v[166:169], v[96:99]
	v_mfma_f32_16x16x32_bf16 v[88:91], v[204:207], v[166:169], v[88:91]
	v_mfma_f32_16x16x32_bf16 v[80:83], v[196:199], v[174:177], v[80:83]
	v_mfma_f32_16x16x32_bf16 v[72:75], v[204:207], v[174:177], v[72:75]
	v_mfma_f32_16x16x32_bf16 v[68:71], v[196:199], v[182:185], v[68:71]
	v_mfma_f32_16x16x32_bf16 v[64:67], v[204:207], v[182:185], v[64:67]
	v_mfma_f32_16x16x32_bf16 v[112:115], v[200:203], v[162:165], v[112:115]
	v_mfma_f32_16x16x32_bf16 v[104:107], v[214:217], v[162:165], v[104:107]
	v_mfma_f32_16x16x32_bf16 v[96:99], v[200:203], v[170:173], v[96:99]
	v_mfma_f32_16x16x32_bf16 v[88:91], v[214:217], v[170:173], v[88:91]
	v_mfma_f32_16x16x32_bf16 v[80:83], v[200:203], v[178:181], v[80:83]
	v_mfma_f32_16x16x32_bf16 v[72:75], v[214:217], v[178:181], v[72:75]
	v_mfma_f32_16x16x32_bf16 v[68:71], v[200:203], v[186:189], v[68:71]
	v_mfma_f32_16x16x32_bf16 v[64:67], v[214:217], v[186:189], v[64:67]
	s_mov_b32 m0, s61
	v_lshl_add_u64 v[218:219], s[20:21], 0, v[144:145]
	s_barrier
	ds_read_b128 v[158:161], v141 offset:16384
	ds_read_b128 v[162:165], v141 offset:17408
	ds_read_b128 v[166:169], v141 offset:18432
	ds_read_b128 v[170:173], v141 offset:19456
	ds_read_b128 v[174:177], v141 offset:20480
	ds_read_b128 v[178:181], v141 offset:21504
	ds_read_b128 v[182:185], v141 offset:22528
	ds_read_b128 v[186:189], v141 offset:23552
	global_load_lds_dwordx4 v[218:219], off
	s_mov_b32 m0, s62
	v_lshl_add_u64 v[220:221], s[20:21], 0, v[128:129]
	global_load_lds_dwordx4 v[220:221], off
	s_barrier
	s_waitcnt lgkmcnt(0)
	v_mfma_f32_16x16x32_bf16 v[60:63], v[134:137], v[158:161], v[60:63]
	v_mfma_f32_16x16x32_bf16 v[56:59], v[150:153], v[158:161], v[56:59]
	v_mfma_f32_16x16x32_bf16 v[52:55], v[134:137], v[166:169], v[52:55]
	v_mfma_f32_16x16x32_bf16 v[44:47], v[150:153], v[166:169], v[44:47]
	v_mfma_f32_16x16x32_bf16 v[36:39], v[134:137], v[174:177], v[36:39]
	v_mfma_f32_16x16x32_bf16 v[28:31], v[150:153], v[174:177], v[28:31]
	v_mfma_f32_16x16x32_bf16 v[20:23], v[134:137], v[182:185], v[20:23]
	v_mfma_f32_16x16x32_bf16 v[12:15], v[150:153], v[182:185], v[12:15]
	v_mfma_f32_16x16x32_bf16 v[60:63], v[146:149], v[162:165], v[60:63]
	v_mfma_f32_16x16x32_bf16 v[56:59], v[154:157], v[162:165], v[56:59]
	v_mfma_f32_16x16x32_bf16 v[52:55], v[146:149], v[170:173], v[52:55]
	v_mfma_f32_16x16x32_bf16 v[44:47], v[154:157], v[170:173], v[44:47]
	v_mfma_f32_16x16x32_bf16 v[36:39], v[146:149], v[178:181], v[36:39]
	v_mfma_f32_16x16x32_bf16 v[28:31], v[154:157], v[178:181], v[28:31]
	v_mfma_f32_16x16x32_bf16 v[20:23], v[146:149], v[186:189], v[20:23]
	v_mfma_f32_16x16x32_bf16 v[12:15], v[154:157], v[186:189], v[12:15]
	s_barrier
; #define PG8_STAGE(bufoff, gbase, voff) do { _Pragma("unroll") for (int _i = 0; _i < 2; ++_i) \
;         __builtin_amdgcn_global_load_lds((const unsigned*)((const char*)(gbase) + (voff)[_i]), (LAS unsigned*)(lds + (bufoff) + ldsw + _i * 8192), 16, 0, 0); } while (0)
; #define PG8_LDA(dst, b, h) do { _Pragma("unroll") for (int m = 0; m < 4; ++m) _Pragma("unroll") for (int k = 0; k < 2; ++k) dst[m][k] = *(const LAS bf16x8*)(lds + PG8_SA(b, h) + aoff + m * 2048 + k * 1024); } while (0)
; #define PG8_LDB(dst, b, h) do { _Pragma("unroll") for (int n = 0; n < 2; ++n) _Pragma("unroll") for (int k = 0; k < 2; ++k) dst[n][k] = *(const LAS bf16x8*)(lds + PG8_SB(b, h) + boff + n * 2048 + k * 1024); } while (0)
; #define PG8_MMA(ai, bj, At, Bt) do { __builtin_amdgcn_s_setprio(1); _Pragma("unroll") for (int m = 0; m < 4; ++m) _Pragma("unroll") for (int n = 0; n < 2; ++n) _Pragma("unroll") for (int k = 0; k < 2; ++k) \
;         acc[ai][bj][m][n] = __builtin_amdgcn_mfma_f32_16x16x32_bf16(Bt[n][k], At[m][k], acc[ai][bj][m][n], 0, 0, 0); __builtin_amdgcn_s_setprio(0); } while (0)
; #define PG8_WAIT_V(n) asm volatile("s_waitcnt vmcnt(" #n ")" ::: "memory")
; #define PG8_WAIT_L(n) asm volatile("s_waitcnt lgkmcnt(" #n ")" ::: "memory")
; #define PG8_BAR __builtin_amdgcn_s_barrier()
; #define PG8_SCHED __builtin_amdgcn_sched_barrier(0)
; template <class Epi>
; __device__ __forceinline__ void gemm_phase(LAS unsigned char* lds, const Gemm g, const StaticOrder& S, const Epi& E) {
;     ...
;             PG8_STAGE(PG8_SB(0, 1), b2 + hB, voffB);
;             PG8_WAIT_V(6); PG8_BAR; PG8_MMA(1, 1, At, B1); PG8_BAR;
;             PG8_LDB(B0, 1, 0); PG8_SCHED; PG8_LDA(At, 1, 0); PG8_STAGE(PG8_SA(0, 1), a2 + hA, voffA);
;             PG8_WAIT_L(8); PG8_BAR; PG8_WAIT_L(0); PG8_MMA(0, 0, At, B0); PG8_BAR; PG8_SCHED;
;             PG8_LDB(B1, 1, 1); PG8_STAGE(PG8_SB(1, 0), b3, voffB);
;             PG8_BAR; PG8_WAIT_L(0); PG8_MMA(0, 1, At, B1); PG8_BAR;
;             PG8_LDA(At, 1, 1); PG8_STAGE(PG8_SA(1, 0), a3, voffA);
;             PG8_BAR; PG8_WAIT_L(0); PG8_MMA(1, 0, At, B0); PG8_BAR; PG8_SCHED;
	s_add_u32 s10, s16, 0x60000
	s_addc_u32 s11, s17, 0
	s_add_i32 s26, s27, s60
	s_mov_b32 m0, s26
	s_nop 0
	global_load_lds_dwordx4 v144, s[10:11]
	s_add_i32 m0, s26, 0x2000
	s_nop 0
	global_load_lds_dwordx4 v128, s[10:11]
	s_waitcnt vmcnt(6)
	s_barrier
	v_mfma_f32_16x16x32_bf16 v[48:51], v[196:199], v[158:161], v[48:51]
	v_mfma_f32_16x16x32_bf16 v[40:43], v[204:207], v[158:161], v[40:43]
	v_mfma_f32_16x16x32_bf16 v[32:35], v[196:199], v[166:169], v[32:35]
	v_mfma_f32_16x16x32_bf16 v[24:27], v[204:207], v[166:169], v[24:27]
	v_mfma_f32_16x16x32_bf16 v[16:19], v[196:199], v[174:177], v[16:19]
	v_mfma_f32_16x16x32_bf16 v[8:11], v[204:207], v[174:177], v[8:11]
	v_mfma_f32_16x16x32_bf16 v[4:7], v[196:199], v[182:185], v[4:7]
	v_mfma_f32_16x16x32_bf16 v[0:3], v[204:207], v[182:185], v[0:3]
	v_mfma_f32_16x16x32_bf16 v[48:51], v[200:203], v[162:165], v[48:51]
	v_mfma_f32_16x16x32_bf16 v[40:43], v[214:217], v[162:165], v[40:43]
	v_mfma_f32_16x16x32_bf16 v[32:35], v[200:203], v[170:173], v[32:35]
	v_mfma_f32_16x16x32_bf16 v[24:27], v[214:217], v[170:173], v[24:27]
	v_mfma_f32_16x16x32_bf16 v[16:19], v[200:203], v[178:181], v[16:19]
	v_mfma_f32_16x16x32_bf16 v[8:11], v[214:217], v[178:181], v[8:11]
	v_mfma_f32_16x16x32_bf16 v[4:7], v[200:203], v[186:189], v[4:7]
	v_mfma_f32_16x16x32_bf16 v[0:3], v[214:217], v[186:189], v[0:3]
	s_add_i32 s26, 0, 0x18000
	v_add_u32_e32 v154, s26, v139
	s_barrier
	ds_read_b128 v[134:137], v154
	ds_read_b128 v[146:149], v154 offset:1024
	ds_read_b128 v[150:153], v154 offset:2048
	ds_read_b128 v[154:157], v154 offset:3072
	s_add_u32 s10, s20, 0x60000
	s_addc_u32 s11, s21, 0
	s_mov_b32 m0, s63
	ds_read_b128 v[158:161], v141 offset:32768
	ds_read_b128 v[162:165], v141 offset:33792
	ds_read_b128 v[166:169], v141 offset:34816
	ds_read_b128 v[170:173], v141 offset:35840
	ds_read_b128 v[174:177], v141 offset:36864
	ds_read_b128 v[178:181], v141 offset:37888
	ds_read_b128 v[182:185], v141 offset:38912
	ds_read_b128 v[186:189], v141 offset:39936
	global_load_lds_dwordx4 v144, s[10:11]
	s_mov_b32 m0, s64
	s_nop 0
	global_load_lds_dwordx4 v128, s[10:11]
	s_waitcnt lgkmcnt(8)
	s_barrier
	s_waitcnt lgkmcnt(0)
	v_mfma_f32_16x16x32_bf16 v[124:127], v[134:137], v[158:161], v[124:127]
	v_mfma_f32_16x16x32_bf16 v[120:123], v[150:153], v[158:161], v[120:123]
	v_mfma_f32_16x16x32_bf16 v[116:119], v[134:137], v[166:169], v[116:119]
	v_mfma_f32_16x16x32_bf16 v[108:111], v[150:153], v[166:169], v[108:111]
	v_mfma_f32_16x16x32_bf16 v[100:103], v[134:137], v[174:177], v[100:103]
	v_mfma_f32_16x16x32_bf16 v[92:95], v[150:153], v[174:177], v[92:95]
	v_mfma_f32_16x16x32_bf16 v[84:87], v[134:137], v[182:185], v[84:87]
	v_mfma_f32_16x16x32_bf16 v[76:79], v[150:153], v[182:185], v[76:79]
	v_mfma_f32_16x16x32_bf16 v[124:127], v[146:149], v[162:165], v[124:127]
	v_mfma_f32_16x16x32_bf16 v[120:123], v[154:157], v[162:165], v[120:123]
	v_mfma_f32_16x16x32_bf16 v[116:119], v[146:149], v[170:173], v[116:119]
	v_mfma_f32_16x16x32_bf16 v[108:111], v[154:157], v[170:173], v[108:111]
	v_mfma_f32_16x16x32_bf16 v[100:103], v[146:149], v[178:181], v[100:103]
	v_mfma_f32_16x16x32_bf16 v[92:95], v[154:157], v[178:181], v[92:95]
	v_mfma_f32_16x16x32_bf16 v[84:87], v[146:149], v[186:189], v[84:87]
	v_mfma_f32_16x16x32_bf16 v[76:79], v[154:157], v[186:189], v[76:79]
	s_barrier
	s_add_i32 s20, 0, 0x1c000
	s_add_i32 s10, s26, s60
	v_add_u32_e32 v190, s20, v139
	v_lshl_add_u64 v[142:143], v[142:143], 0, s[88:89]
	s_mov_b32 m0, s10
	ds_read_b128 v[196:199], v190
	ds_read_b128 v[200:203], v190 offset:1024
	ds_read_b128 v[204:207], v190 offset:2048
	ds_read_b128 v[214:217], v190 offset:3072
	global_load_lds_dwordx4 v[142:143], off
	s_add_i32 m0, s10, 0x2000
	v_lshl_add_u64 v[142:143], v[192:193], 0, s[88:89]
	global_load_lds_dwordx4 v[142:143], off
	s_barrier
	s_waitcnt lgkmcnt(0)
	v_mfma_f32_16x16x32_bf16 v[112:115], v[196:199], v[158:161], v[112:115]
	v_mfma_f32_16x16x32_bf16 v[104:107], v[204:207], v[158:161], v[104:107]
	v_mfma_f32_16x16x32_bf16 v[96:99], v[196:199], v[166:169], v[96:99]
	v_mfma_f32_16x16x32_bf16 v[88:91], v[204:207], v[166:169], v[88:91]
	v_mfma_f32_16x16x32_bf16 v[80:83], v[196:199], v[174:177], v[80:83]
	v_mfma_f32_16x16x32_bf16 v[72:75], v[204:207], v[174:177], v[72:75]
	v_mfma_f32_16x16x32_bf16 v[68:71], v[196:199], v[182:185], v[68:71]
	v_mfma_f32_16x16x32_bf16 v[64:67], v[204:207], v[182:185], v[64:67]
	v_mfma_f32_16x16x32_bf16 v[112:115], v[200:203], v[162:165], v[112:115]
	v_mfma_f32_16x16x32_bf16 v[104:107], v[214:217], v[162:165], v[104:107]
	v_mfma_f32_16x16x32_bf16 v[96:99], v[200:203], v[170:173], v[96:99]
	v_mfma_f32_16x16x32_bf16 v[88:91], v[214:217], v[170:173], v[88:91]
	v_mfma_f32_16x16x32_bf16 v[80:83], v[200:203], v[178:181], v[80:83]
	v_mfma_f32_16x16x32_bf16 v[72:75], v[214:217], v[178:181], v[72:75]
	v_mfma_f32_16x16x32_bf16 v[68:71], v[200:203], v[186:189], v[68:71]
	v_mfma_f32_16x16x32_bf16 v[64:67], v[214:217], v[186:189], v[64:67]
	s_mov_b32 m0, s65
	v_lshl_add_u64 v[142:143], v[218:219], 0, s[88:89]
	s_barrier
	ds_read_b128 v[158:161], v141 offset:49152
	ds_read_b128 v[162:165], v141 offset:50176
	ds_read_b128 v[166:169], v141 offset:51200
	ds_read_b128 v[170:173], v141 offset:52224
	ds_read_b128 v[174:177], v141 offset:53248
	ds_read_b128 v[178:181], v141 offset:54272
	ds_read_b128 v[182:185], v141 offset:55296
	ds_read_b128 v[186:189], v141 offset:56320
	global_load_lds_dwordx4 v[142:143], off
	s_mov_b32 m0, s66
	v_lshl_add_u64 v[142:143], v[220:221], 0, s[88:89]
	global_load_lds_dwordx4 v[142:143], off
	s_barrier
; #define PG8_STAGE(bufoff, gbase, voff) do { _Pragma("unroll") for (int _i = 0; _i < 2; ++_i) \
;         __builtin_amdgcn_global_load_lds((const unsigned*)((const char*)(gbase) + (voff)[_i]), (LAS unsigned*)(lds + (bufoff) + ldsw + _i * 8192), 16, 0, 0); } while (0)
; #define PG8_MMA(ai, bj, At, Bt) do { __builtin_amdgcn_s_setprio(1); _Pragma("unroll") for (int m = 0; m < 4; ++m) _Pragma("unroll") for (int n = 0; n < 2; ++n) _Pragma("unroll") for (int k = 0; k < 2; ++k) \
;         acc[ai][bj][m][n] = __builtin_amdgcn_mfma_f32_16x16x32_bf16(Bt[n][k], At[m][k], acc[ai][bj][m][n], 0, 0, 0); __builtin_amdgcn_s_setprio(0); } while (0)
; #define PG8_WAIT_V(n) asm volatile("s_waitcnt vmcnt(" #n ")" ::: "memory")
; #define PG8_WAIT_L(n) asm volatile("s_waitcnt lgkmcnt(" #n ")" ::: "memory")
; #define PG8_BAR __builtin_amdgcn_s_barrier()
; #define PG8_SCHED __builtin_amdgcn_sched_barrier(0)
; template <class Epi>
; __device__ __forceinline__ void gemm_phase(LAS unsigned char* lds, const Gemm g, const StaticOrder& S, const Epi& E) {
;     ...
;             PG8_BAR; PG8_WAIT_L(0); PG8_MMA(1, 0, At, B0); PG8_BAR; PG8_SCHED;
;             PG8_STAGE(PG8_SB(1, 1), b3 + hB, voffB);
;             PG8_WAIT_V(6); PG8_BAR; PG8_MMA(1, 1, At, B1); PG8_BAR;
	s_waitcnt lgkmcnt(0)
	v_mfma_f32_16x16x32_bf16 v[60:63], v[134:137], v[158:161], v[60:63]
	v_mfma_f32_16x16x32_bf16 v[56:59], v[150:153], v[158:161], v[56:59]
	v_mfma_f32_16x16x32_bf16 v[52:55], v[134:137], v[166:169], v[52:55]
	v_mfma_f32_16x16x32_bf16 v[44:47], v[150:153], v[166:169], v[44:47]
	v_mfma_f32_16x16x32_bf16 v[36:39], v[134:137], v[174:177], v[36:39]
	v_mfma_f32_16x16x32_bf16 v[28:31], v[150:153], v[174:177], v[28:31]
	v_mfma_f32_16x16x32_bf16 v[20:23], v[134:137], v[182:185], v[20:23]
	v_mfma_f32_16x16x32_bf16 v[12:15], v[150:153], v[182:185], v[12:15]
	v_mfma_f32_16x16x32_bf16 v[60:63], v[146:149], v[162:165], v[60:63]
	v_mfma_f32_16x16x32_bf16 v[56:59], v[154:157], v[162:165], v[56:59]
	v_mfma_f32_16x16x32_bf16 v[52:55], v[146:149], v[170:173], v[52:55]
	v_mfma_f32_16x16x32_bf16 v[44:47], v[154:157], v[170:173], v[44:47]
	v_mfma_f32_16x16x32_bf16 v[36:39], v[146:149], v[178:181], v[36:39]
	v_mfma_f32_16x16x32_bf16 v[28:31], v[154:157], v[178:181], v[28:31]
	v_mfma_f32_16x16x32_bf16 v[20:23], v[146:149], v[186:189], v[20:23]
	v_mfma_f32_16x16x32_bf16 v[12:15], v[154:157], v[186:189], v[12:15]
	s_barrier
	s_add_u32 s10, s16, 0x60080
	s_addc_u32 s11, s17, 0
	s_add_i32 s16, s20, s60
	s_mov_b32 m0, s16
	s_nop 0
	global_load_lds_dwordx4 v144, s[10:11]
	s_add_i32 m0, s16, 0x2000
	s_nop 0
	global_load_lds_dwordx4 v128, s[10:11]
	s_waitcnt vmcnt(6)
	s_barrier
	v_mfma_f32_16x16x32_bf16 v[48:51], v[196:199], v[158:161], v[48:51]
	v_mfma_f32_16x16x32_bf16 v[40:43], v[204:207], v[158:161], v[40:43]
	v_mfma_f32_16x16x32_bf16 v[32:35], v[196:199], v[166:169], v[32:35]
	v_mfma_f32_16x16x32_bf16 v[24:27], v[204:207], v[166:169], v[24:27]
	v_mfma_f32_16x16x32_bf16 v[16:19], v[196:199], v[174:177], v[16:19]
	v_mfma_f32_16x16x32_bf16 v[8:11], v[204:207], v[174:177], v[8:11]
	v_mfma_f32_16x16x32_bf16 v[4:7], v[196:199], v[182:185], v[4:7]
	v_mfma_f32_16x16x32_bf16 v[0:3], v[204:207], v[182:185], v[0:3]
	v_mfma_f32_16x16x32_bf16 v[48:51], v[200:203], v[162:165], v[48:51]
	v_mfma_f32_16x16x32_bf16 v[40:43], v[214:217], v[162:165], v[40:43]
	v_mfma_f32_16x16x32_bf16 v[32:35], v[200:203], v[170:173], v[32:35]
	v_mfma_f32_16x16x32_bf16 v[24:27], v[214:217], v[170:173], v[24:27]
	v_mfma_f32_16x16x32_bf16 v[16:19], v[200:203], v[178:181], v[16:19]
	v_mfma_f32_16x16x32_bf16 v[8:11], v[214:217], v[178:181], v[8:11]
	v_mfma_f32_16x16x32_bf16 v[4:7], v[200:203], v[186:189], v[4:7]
	v_mfma_f32_16x16x32_bf16 v[0:3], v[214:217], v[186:189], v[0:3]
	s_add_i32 s72, s72, 2
	s_add_u32 s24, s24, 0x100
	s_addc_u32 s25, s25, 0
	s_cmp_gt_u32 s72, 21
	s_mov_b64 s[10:11], s[12:13]
	s_barrier
	s_cbranch_scc0 .LBB0_1013
; __device__ __forceinline__ unsigned pk2(float lo, float hi) { unsigned r; asm("v_cvt_pk_bf16_f32 %0, %1, %2" : "=v"(r) : "v"(lo), "v"(hi)); return r; }
;     __device__ __forceinline__ void operator()(const f32x4 (&acc)[2][2][4][2], const Unit& u, int wr, int wc, int fr, int fq) const {
;     ...
;         const int row_t = rmap == 1 ? odd_phys_row0(u.pm, grp) : (rmap == 2 ? odd_phys_row0(u.pm % (BG * TPB), u.pm / (BG * TPB)) : u.pm * BM);
;         int c = col_t + 64 * wc + 16 * fq;
;         if (mode == 2) c = (c >> 6) * 96 + (c & 63);
; #pragma unroll
;         for (int ai = 0; ai < 2; ++ai)
; #pragma unroll
;             for (int m = 0; m < 4; ++m) {
;                 const int row = row_t + ai * HALF + wr * 64 + m * 16 + fr;
;                 bf16_t* rp = O + (size_t)row * ldc + c;
; #pragma unroll
;                 for (int bj = 0; bj < 2; ++bj) {
;                     const f32x4 v0 = acc[ai][bj][m][0], v1 = acc[ai][bj][m][1];
;                     u32x4 o; o.x = pk2(v0[0], v0[1]); o.y = pk2(v0[2], v0[3]); o.z = pk2(v1[0], v1[1]); o.w = pk2(v1[2], v1[3]);
;                     *(u32x4*)(rp + 8 * bj) = o;
;                 }
;             }
	v_lshl_add_u32 v134, s71, 8, v138
	v_cvt_pk_bf16_f32 v68, v68, v69
	v_cvt_pk_bf16_f32 v69, v70, v71
	v_cvt_pk_bf16_f32 v70, v64, v65
	v_add_u32_e32 v64, 0x80, v134
	v_lshl_or_b32 v136, s15, 8, v140
	v_ashrrev_i32_e32 v135, 31, v134
	v_cvt_pk_bf16_f32 v112, v112, v113
	v_cvt_pk_bf16_f32 v113, v114, v115
	v_cvt_pk_bf16_f32 v114, v104, v105
	v_or_b32_e32 v104, 16, v134
	v_ashrrev_i32_e32 v65, 31, v64
	v_cvt_pk_bf16_f32 v48, v48, v49
	v_cvt_pk_bf16_f32 v49, v50, v51
	v_cvt_pk_bf16_f32 v50, v40, v41
	v_add_u32_e32 v40, 0x90, v134
	v_ashrrev_i32_e32 v137, 31, v136
	v_lshlrev_b64 v[142:143], 11, v[134:135]
	v_ashrrev_i32_e32 v105, 31, v104
	v_cvt_pk_bf16_f32 v96, v96, v97
	v_cvt_pk_bf16_f32 v97, v98, v99
	v_cvt_pk_bf16_f32 v98, v88, v89
	v_or_b32_e32 v88, 32, v134
	v_lshlrev_b64 v[64:65], 11, v[64:65]
	v_ashrrev_i32_e32 v41, 31, v40
	v_cvt_pk_bf16_f32 v32, v32, v33
	v_cvt_pk_bf16_f32 v33, v34, v35
	v_cvt_pk_bf16_f32 v34, v24, v25
	v_add_u32_e32 v24, 0xa0, v134
	v_lshl_add_u64 v[142:143], s[8:9], 0, v[142:143]
	v_lshlrev_b64 v[136:137], 1, v[136:137]
	v_lshlrev_b64 v[104:105], 11, v[104:105]
	v_ashrrev_i32_e32 v89, 31, v88
	v_cvt_pk_bf16_f32 v80, v80, v81
	v_cvt_pk_bf16_f32 v81, v82, v83
	v_cvt_pk_bf16_f32 v82, v72, v73
	v_or_b32_e32 v72, 48, v134
	v_lshl_add_u64 v[64:65], s[8:9], 0, v[64:65]
	v_lshlrev_b64 v[40:41], 11, v[40:41]
	v_ashrrev_i32_e32 v25, 31, v24
	v_cvt_pk_bf16_f32 v16, v16, v17
	v_cvt_pk_bf16_f32 v17, v18, v19
	v_cvt_pk_bf16_f32 v18, v8, v9
	v_add_u32_e32 v8, 0xb0, v134
	v_lshl_add_u64 v[142:143], v[142:143], 0, v[136:137]
	v_lshl_add_u64 v[104:105], s[8:9], 0, v[104:105]
	v_lshlrev_b64 v[88:89], 11, v[88:89]
	v_ashrrev_i32_e32 v73, 31, v72
	v_lshl_add_u64 v[64:65], v[64:65], 0, v[136:137]
	v_lshl_add_u64 v[40:41], s[8:9], 0, v[40:41]
	v_lshlrev_b64 v[24:25], 11, v[24:25]
	v_ashrrev_i32_e32 v9, 31, v8
	v_cvt_pk_bf16_f32 v115, v106, v107
	global_store_dwordx4 v[142:143], v[112:115], off offset:16
	v_lshl_add_u64 v[88:89], s[8:9], 0, v[88:89]
	v_lshlrev_b64 v[72:73], 11, v[72:73]
	v_lshl_add_u64 v[112:113], v[104:105], 0, v[136:137]
	v_cvt_pk_bf16_f32 v51, v42, v43
	global_store_dwordx4 v[64:65], v[48:51], off offset:16
	v_lshl_add_u64 v[24:25], s[8:9], 0, v[24:25]
	v_lshlrev_b64 v[8:9], 11, v[8:9]
	v_lshl_add_u64 v[48:49], v[40:41], 0, v[136:137]
	v_cvt_pk_bf16_f32 v99, v90, v91
	global_store_dwordx4 v[112:113], v[96:99], off offset:16
	v_lshl_add_u64 v[72:73], s[8:9], 0, v[72:73]
	v_cvt_pk_bf16_f32 v35, v26, v27
	global_store_dwordx4 v[48:49], v[32:35], off offset:16
	v_lshl_add_u64 v[96:97], v[88:89], 0, v[136:137]
	v_lshl_add_u64 v[8:9], s[8:9], 0, v[8:9]
	v_lshl_add_u64 v[32:33], v[24:25], 0, v[136:137]
	v_cvt_pk_bf16_f32 v83, v74, v75
	global_store_dwordx4 v[96:97], v[80:83], off offset:16
	v_cvt_pk_bf16_f32 v19, v10, v11
	global_store_dwordx4 v[32:33], v[16:19], off offset:16
	s_and_b64 vcc, exec, s[0:1]
	v_lshl_add_u64 v[80:81], v[72:73], 0, v[136:137]
	v_lshl_add_u64 v[16:17], v[8:9], 0, v[136:137]
	s_mov_b32 s15, s69
	s_mov_b32 s71, s70
	s_mov_b64 s[12:13], s[6:7]
	s_mov_b64 s[10:11], s[4:5]
	v_cvt_pk_bf16_f32 v124, v124, v125
	v_cvt_pk_bf16_f32 v125, v126, v127
	v_cvt_pk_bf16_f32 v126, v120, v121
	v_cvt_pk_bf16_f32 v127, v122, v123
	global_store_dwordx4 v[142:143], v[124:127], off
	v_cvt_pk_bf16_f32 v104, v116, v117
	v_cvt_pk_bf16_f32 v105, v118, v119
	v_cvt_pk_bf16_f32 v106, v108, v109
	v_cvt_pk_bf16_f32 v107, v110, v111
	global_store_dwordx4 v[112:113], v[104:107], off
	v_cvt_pk_bf16_f32 v88, v100, v101
	v_cvt_pk_bf16_f32 v89, v102, v103
	v_cvt_pk_bf16_f32 v90, v92, v93
	v_cvt_pk_bf16_f32 v91, v94, v95
	global_store_dwordx4 v[96:97], v[88:91], off
	v_cvt_pk_bf16_f32 v72, v84, v85
	v_cvt_pk_bf16_f32 v73, v86, v87
	v_cvt_pk_bf16_f32 v74, v76, v77
	v_cvt_pk_bf16_f32 v75, v78, v79
	global_store_dwordx4 v[80:81], v[72:75], off
	v_cvt_pk_bf16_f32 v71, v66, v67
	global_store_dwordx4 v[80:81], v[68:71], off offset:16
	v_cvt_pk_bf16_f32 v60, v60, v61
	v_cvt_pk_bf16_f32 v61, v62, v63
	v_cvt_pk_bf16_f32 v62, v56, v57
	v_cvt_pk_bf16_f32 v63, v58, v59
	global_store_dwordx4 v[64:65], v[60:63], off
	v_cvt_pk_bf16_f32 v40, v52, v53
	v_cvt_pk_bf16_f32 v41, v54, v55
	v_cvt_pk_bf16_f32 v42, v44, v45
	v_cvt_pk_bf16_f32 v43, v46, v47
	global_store_dwordx4 v[48:49], v[40:43], off
	v_cvt_pk_bf16_f32 v24, v36, v37
	v_cvt_pk_bf16_f32 v25, v38, v39
	v_cvt_pk_bf16_f32 v26, v28, v29
	v_cvt_pk_bf16_f32 v27, v30, v31
	global_store_dwordx4 v[32:33], v[24:27], off
	v_cvt_pk_bf16_f32 v8, v20, v21
	v_cvt_pk_bf16_f32 v9, v22, v23
	v_cvt_pk_bf16_f32 v10, v12, v13
	v_cvt_pk_bf16_f32 v11, v14, v15
	global_store_dwordx4 v[16:17], v[8:11], off
	v_cvt_pk_bf16_f32 v4, v4, v5
	v_cvt_pk_bf16_f32 v5, v6, v7
	v_cvt_pk_bf16_f32 v6, v0, v1
	v_cvt_pk_bf16_f32 v7, v2, v3
	global_store_dwordx4 v[16:17], v[4:7], off offset:16
	s_cbranch_vccz .LBB0_1002
	s_waitcnt vmcnt(0)
	s_cmpk_gt_u32 s34, 0xff
	s_cbranch_scc1 .LBB0_1017
	s_barrier

; #define PG8_STAGE(bufoff, gbase, voff) do { _Pragma("unroll") for (int _i = 0; _i < 2; ++_i) \
;         __builtin_amdgcn_global_load_lds((const unsigned*)((const char*)(gbase) + (voff)[_i]), (LAS unsigned*)(lds + (bufoff) + ldsw + _i * 8192), 16, 0, 0); } while (0)
; #define PG8_LDA(dst, b, h) do { _Pragma("unroll") for (int m = 0; m < 4; ++m) _Pragma("unroll") for (int k = 0; k < 2; ++k) dst[m][k] = *(const LAS bf16x8*)(lds + PG8_SA(b, h) + aoff + m * 2048 + k * 1024); } while (0)
; #define PG8_LDB(dst, b, h) do { _Pragma("unroll") for (int n = 0; n < 2; ++n) _Pragma("unroll") for (int k = 0; k < 2; ++k) dst[n][k] = *(const LAS bf16x8*)(lds + PG8_SB(b, h) + boff + n * 2048 + k * 1024); } while (0)
; #define PG8_MMA(ai, bj, At, Bt) do { __builtin_amdgcn_s_setprio(1); _Pragma("unroll") for (int m = 0; m < 4; ++m) _Pragma("unroll") for (int n = 0; n < 2; ++n) _Pragma("unroll") for (int k = 0; k < 2; ++k) \
;         acc[ai][bj][m][n] = __builtin_amdgcn_mfma_f32_16x16x32_bf16(Bt[n][k], At[m][k], acc[ai][bj][m][n], 0, 0, 0); __builtin_amdgcn_s_setprio(0); } while (0)
; #define PG8_WAIT_L(n) asm volatile("s_waitcnt lgkmcnt(" #n ")" ::: "memory")
; #define PG8_BAR __builtin_amdgcn_s_barrier()
; #define PG8_SCHED __builtin_amdgcn_sched_barrier(0)
; template <class Epi>
; __device__ __forceinline__ void gemm_phase(LAS unsigned char* lds, const Gemm g, const StaticOrder& S, const Epi& E) {
;     ...
;             const bool last = (t == nt - 2);
;             const char* a1 = cA + (size_t)(t + 1) * kstep;
;             const char* a2 = last ? nA : cA + (size_t)(t + 2) * kstep; const char* b2 = last ? nB : cB + (size_t)(t + 2) * kstep;
;             const char* a3 = a2 + kstep; const char* b3 = b2 + kstep;
;             PG8_LDB(B0, 0, 0); PG8_SCHED; PG8_LDA(At, 0, 0); PG8_STAGE(PG8_SA(1, 1), a1 + hA, voffA);
;             PG8_WAIT_L(8); PG8_BAR; PG8_WAIT_L(0); PG8_MMA(0, 0, At, B0); PG8_BAR; PG8_SCHED;
;             PG8_LDB(B1, 0, 1); PG8_STAGE(PG8_SB(0, 0), b2, voffB);
;             PG8_BAR; PG8_WAIT_L(0); PG8_MMA(0, 1, At, B1); PG8_BAR;
;             PG8_LDA(At, 0, 1); PG8_STAGE(PG8_SA(0, 0), a2, voffA);
;             PG8_BAR; PG8_WAIT_L(0); PG8_MMA(1, 0, At, B0); PG8_BAR; PG8_SCHED;
.LBB0_1079:
	s_add_u32 s16, s12, 0xfffc0080
	s_addc_u32 s17, s13, -1
	s_add_i32 s26, 0, 0x10000
	v_add_u32_e32 v142, s26, v139
	ds_read_b128 v[134:137], v142
	ds_read_b128 v[146:149], v142 offset:1024
	ds_read_b128 v[150:153], v142 offset:2048
	ds_read_b128 v[154:157], v142 offset:3072
	s_cmp_eq_u32 s77, 12
	s_cselect_b32 s21, s71, s17
	s_cselect_b32 s20, s72, s16
	s_cselect_b32 s17, s7, s76
	s_cselect_b32 s16, s24, s25
	s_add_i32 m0, s61, 0xc000
	ds_read_b128 v[158:161], v141
	ds_read_b128 v[162:165], v141 offset:1024
	ds_read_b128 v[166:169], v141 offset:2048
	ds_read_b128 v[170:173], v141 offset:3072
	ds_read_b128 v[174:177], v141 offset:4096
	ds_read_b128 v[178:181], v141 offset:5120
	ds_read_b128 v[182:185], v141 offset:6144
	ds_read_b128 v[196:199], v141 offset:7168
	global_load_lds_dwordx4 v130, s[12:13]
	s_add_i32 m0, s61, 0xe000
	v_lshl_add_u64 v[142:143], s[12:13], 0, v[132:133]
	global_load_lds_dwordx4 v[142:143], off
	s_waitcnt lgkmcnt(8)
	s_barrier
	s_waitcnt lgkmcnt(0)
	v_mfma_f32_16x16x32_bf16 v[124:127], v[134:137], v[158:161], v[124:127]
	v_mfma_f32_16x16x32_bf16 v[120:123], v[150:153], v[158:161], v[120:123]
	v_mfma_f32_16x16x32_bf16 v[116:119], v[134:137], v[166:169], v[116:119]
	v_mfma_f32_16x16x32_bf16 v[108:111], v[150:153], v[166:169], v[108:111]
	v_mfma_f32_16x16x32_bf16 v[100:103], v[134:137], v[174:177], v[100:103]
	v_mfma_f32_16x16x32_bf16 v[92:95], v[150:153], v[174:177], v[92:95]
	v_mfma_f32_16x16x32_bf16 v[84:87], v[134:137], v[182:185], v[84:87]
	v_mfma_f32_16x16x32_bf16 v[76:79], v[150:153], v[182:185], v[76:79]
	v_mfma_f32_16x16x32_bf16 v[124:127], v[146:149], v[162:165], v[124:127]
	v_mfma_f32_16x16x32_bf16 v[120:123], v[154:157], v[162:165], v[120:123]
	v_mfma_f32_16x16x32_bf16 v[116:119], v[146:149], v[170:173], v[116:119]
	v_mfma_f32_16x16x32_bf16 v[108:111], v[154:157], v[170:173], v[108:111]
	v_mfma_f32_16x16x32_bf16 v[100:103], v[146:149], v[178:181], v[100:103]
	v_mfma_f32_16x16x32_bf16 v[92:95], v[154:157], v[178:181], v[92:95]
	v_mfma_f32_16x16x32_bf16 v[84:87], v[146:149], v[196:199], v[84:87]
	v_mfma_f32_16x16x32_bf16 v[76:79], v[154:157], v[196:199], v[76:79]
	s_barrier
	s_add_i32 s28, 0, 0x14000
	v_add_u32_e32 v142, s28, v139
	s_add_i32 s26, s26, s35
	ds_read_b128 v[200:203], v142
	ds_read_b128 v[204:207], v142 offset:1024
	ds_read_b128 v[214:217], v142 offset:2048
	ds_read_b128 v[218:221], v142 offset:3072
	v_lshl_add_u64 v[142:143], s[16:17], 0, v[144:145]
	s_mov_b32 m0, s26
	v_lshl_add_u64 v[186:187], s[16:17], 0, v[128:129]
	global_load_lds_dwordx4 v[142:143], off
	s_add_i32 m0, s26, 0x2000
	s_nop 0
	global_load_lds_dwordx4 v[186:187], off
	s_barrier
	s_waitcnt lgkmcnt(0)
	v_mfma_f32_16x16x32_bf16 v[112:115], v[200:203], v[158:161], v[112:115]
	v_mfma_f32_16x16x32_bf16 v[104:107], v[214:217], v[158:161], v[104:107]
	v_mfma_f32_16x16x32_bf16 v[96:99], v[200:203], v[166:169], v[96:99]
	v_mfma_f32_16x16x32_bf16 v[88:91], v[214:217], v[166:169], v[88:91]
	v_mfma_f32_16x16x32_bf16 v[80:83], v[200:203], v[174:177], v[80:83]
	v_mfma_f32_16x16x32_bf16 v[72:75], v[214:217], v[174:177], v[72:75]
	v_mfma_f32_16x16x32_bf16 v[68:71], v[200:203], v[182:185], v[68:71]
	v_mfma_f32_16x16x32_bf16 v[64:67], v[214:217], v[182:185], v[64:67]
	v_mfma_f32_16x16x32_bf16 v[112:115], v[204:207], v[162:165], v[112:115]
	v_mfma_f32_16x16x32_bf16 v[104:107], v[218:221], v[162:165], v[104:107]
	v_mfma_f32_16x16x32_bf16 v[96:99], v[204:207], v[170:173], v[96:99]
	v_mfma_f32_16x16x32_bf16 v[88:91], v[218:221], v[170:173], v[88:91]
	v_mfma_f32_16x16x32_bf16 v[80:83], v[204:207], v[178:181], v[80:83]
	v_mfma_f32_16x16x32_bf16 v[72:75], v[218:221], v[178:181], v[72:75]
	v_mfma_f32_16x16x32_bf16 v[68:71], v[204:207], v[196:199], v[68:71]
	v_mfma_f32_16x16x32_bf16 v[64:67], v[218:221], v[196:199], v[64:67]
	s_mov_b32 m0, s61
	v_lshl_add_u64 v[188:189], s[20:21], 0, v[144:145]
	s_barrier
	ds_read_b128 v[158:161], v141 offset:16384
	ds_read_b128 v[162:165], v141 offset:17408
	ds_read_b128 v[166:169], v141 offset:18432
	ds_read_b128 v[170:173], v141 offset:19456
	ds_read_b128 v[174:177], v141 offset:20480
	ds_read_b128 v[178:181], v141 offset:21504
	ds_read_b128 v[182:185], v141 offset:22528
	ds_read_b128 v[196:199], v141 offset:23552
	global_load_lds_dwordx4 v[188:189], off
	s_mov_b32 m0, s62
	v_lshl_add_u64 v[192:193], s[20:21], 0, v[128:129]
	global_load_lds_dwordx4 v[192:193], off
	s_barrier
	s_waitcnt lgkmcnt(0)
	v_mfma_f32_16x16x32_bf16 v[60:63], v[134:137], v[158:161], v[60:63]
	v_mfma_f32_16x16x32_bf16 v[56:59], v[150:153], v[158:161], v[56:59]
	v_mfma_f32_16x16x32_bf16 v[52:55], v[134:137], v[166:169], v[52:55]
	v_mfma_f32_16x16x32_bf16 v[44:47], v[150:153], v[166:169], v[44:47]
	v_mfma_f32_16x16x32_bf16 v[36:39], v[134:137], v[174:177], v[36:39]
	v_mfma_f32_16x16x32_bf16 v[28:31], v[150:153], v[174:177], v[28:31]
	v_mfma_f32_16x16x32_bf16 v[20:23], v[134:137], v[182:185], v[20:23]
	v_mfma_f32_16x16x32_bf16 v[12:15], v[150:153], v[182:185], v[12:15]
	v_mfma_f32_16x16x32_bf16 v[60:63], v[146:149], v[162:165], v[60:63]
	v_mfma_f32_16x16x32_bf16 v[56:59], v[154:157], v[162:165], v[56:59]
	v_mfma_f32_16x16x32_bf16 v[52:55], v[146:149], v[170:173], v[52:55]
	v_mfma_f32_16x16x32_bf16 v[44:47], v[154:157], v[170:173], v[44:47]
	v_mfma_f32_16x16x32_bf16 v[36:39], v[146:149], v[178:181], v[36:39]
	v_mfma_f32_16x16x32_bf16 v[28:31], v[154:157], v[178:181], v[28:31]
	v_mfma_f32_16x16x32_bf16 v[20:23], v[146:149], v[196:199], v[20:23]
	v_mfma_f32_16x16x32_bf16 v[12:15], v[154:157], v[196:199], v[12:15]
	s_barrier
; #define PG8_STAGE(bufoff, gbase, voff) do { _Pragma("unroll") for (int _i = 0; _i < 2; ++_i) \
;         __builtin_amdgcn_global_load_lds((const unsigned*)((const char*)(gbase) + (voff)[_i]), (LAS unsigned*)(lds + (bufoff) + ldsw + _i * 8192), 16, 0, 0); } while (0)
; #define PG8_LDA(dst, b, h) do { _Pragma("unroll") for (int m = 0; m < 4; ++m) _Pragma("unroll") for (int k = 0; k < 2; ++k) dst[m][k] = *(const LAS bf16x8*)(lds + PG8_SA(b, h) + aoff + m * 2048 + k * 1024); } while (0)
; #define PG8_LDB(dst, b, h) do { _Pragma("unroll") for (int n = 0; n < 2; ++n) _Pragma("unroll") for (int k = 0; k < 2; ++k) dst[n][k] = *(const LAS bf16x8*)(lds + PG8_SB(b, h) + boff + n * 2048 + k * 1024); } while (0)
; #define PG8_MMA(ai, bj, At, Bt) do { __builtin_amdgcn_s_setprio(1); _Pragma("unroll") for (int m = 0; m < 4; ++m) _Pragma("unroll") for (int n = 0; n < 2; ++n) _Pragma("unroll") for (int k = 0; k < 2; ++k) \
;         acc[ai][bj][m][n] = __builtin_amdgcn_mfma_f32_16x16x32_bf16(Bt[n][k], At[m][k], acc[ai][bj][m][n], 0, 0, 0); __builtin_amdgcn_s_setprio(0); } while (0)
; #define PG8_WAIT_V(n) asm volatile("s_waitcnt vmcnt(" #n ")" ::: "memory")
; #define PG8_WAIT_L(n) asm volatile("s_waitcnt lgkmcnt(" #n ")" ::: "memory")
; #define PG8_BAR __builtin_amdgcn_s_barrier()
; #define PG8_SCHED __builtin_amdgcn_sched_barrier(0)
; template <class Epi>
; __device__ __forceinline__ void gemm_phase(LAS unsigned char* lds, const Gemm g, const StaticOrder& S, const Epi& E) {
;     ...
;             PG8_STAGE(PG8_SB(0, 1), b2 + hB, voffB);
;             PG8_WAIT_V(6); PG8_BAR; PG8_MMA(1, 1, At, B1); PG8_BAR;
;             PG8_LDB(B0, 1, 0); PG8_SCHED; PG8_LDA(At, 1, 0); PG8_STAGE(PG8_SA(0, 1), a2 + hA, voffA);
;             PG8_WAIT_L(8); PG8_BAR; PG8_WAIT_L(0); PG8_MMA(0, 0, At, B0); PG8_BAR; PG8_SCHED;
;             PG8_LDB(B1, 1, 1); PG8_STAGE(PG8_SB(1, 0), b3, voffB);
;             PG8_BAR; PG8_WAIT_L(0); PG8_MMA(0, 1, At, B1); PG8_BAR;
;             PG8_LDA(At, 1, 1); PG8_STAGE(PG8_SA(1, 0), a3, voffA);
;             PG8_BAR; PG8_WAIT_L(0); PG8_MMA(1, 0, At, B0); PG8_BAR; PG8_SCHED;
	s_add_u32 s26, s16, 0x40000
	s_addc_u32 s27, s17, 0
	s_add_i32 s28, s28, s35
	s_mov_b32 m0, s28
	s_nop 0
	global_load_lds_dwordx4 v144, s[26:27]
	s_add_i32 m0, s28, 0x2000
	s_nop 0
	global_load_lds_dwordx4 v128, s[26:27]
	s_waitcnt vmcnt(6)
	s_barrier
	v_mfma_f32_16x16x32_bf16 v[48:51], v[200:203], v[158:161], v[48:51]
	v_mfma_f32_16x16x32_bf16 v[40:43], v[214:217], v[158:161], v[40:43]
	v_mfma_f32_16x16x32_bf16 v[32:35], v[200:203], v[166:169], v[32:35]
	v_mfma_f32_16x16x32_bf16 v[24:27], v[214:217], v[166:169], v[24:27]
	v_mfma_f32_16x16x32_bf16 v[16:19], v[200:203], v[174:177], v[16:19]
	v_mfma_f32_16x16x32_bf16 v[8:11], v[214:217], v[174:177], v[8:11]
	v_mfma_f32_16x16x32_bf16 v[4:7], v[200:203], v[182:185], v[4:7]
	v_mfma_f32_16x16x32_bf16 v[0:3], v[214:217], v[182:185], v[0:3]
	v_mfma_f32_16x16x32_bf16 v[48:51], v[204:207], v[162:165], v[48:51]
	v_mfma_f32_16x16x32_bf16 v[40:43], v[218:221], v[162:165], v[40:43]
	v_mfma_f32_16x16x32_bf16 v[32:35], v[204:207], v[170:173], v[32:35]
	v_mfma_f32_16x16x32_bf16 v[24:27], v[218:221], v[170:173], v[24:27]
	v_mfma_f32_16x16x32_bf16 v[16:19], v[204:207], v[178:181], v[16:19]
	v_mfma_f32_16x16x32_bf16 v[8:11], v[218:221], v[178:181], v[8:11]
	v_mfma_f32_16x16x32_bf16 v[4:7], v[204:207], v[196:199], v[4:7]
	v_mfma_f32_16x16x32_bf16 v[0:3], v[218:221], v[196:199], v[0:3]
	s_add_i32 s26, 0, 0x18000
	v_add_u32_e32 v154, s26, v139
	s_barrier
	ds_read_b128 v[134:137], v154
	ds_read_b128 v[146:149], v154 offset:1024
	ds_read_b128 v[150:153], v154 offset:2048
	ds_read_b128 v[154:157], v154 offset:3072
	s_add_u32 s20, s20, 0x40000
	s_addc_u32 s21, s21, 0
	s_mov_b32 m0, s63
	ds_read_b128 v[158:161], v141 offset:32768
	ds_read_b128 v[162:165], v141 offset:33792
	ds_read_b128 v[166:169], v141 offset:34816
	ds_read_b128 v[170:173], v141 offset:35840
	ds_read_b128 v[174:177], v141 offset:36864
	ds_read_b128 v[178:181], v141 offset:37888
	ds_read_b128 v[182:185], v141 offset:38912
	ds_read_b128 v[196:199], v141 offset:39936
	global_load_lds_dwordx4 v144, s[20:21]
	s_mov_b32 m0, s64
	s_nop 0
	global_load_lds_dwordx4 v128, s[20:21]
	s_waitcnt lgkmcnt(8)
	s_barrier
	s_waitcnt lgkmcnt(0)
	v_mfma_f32_16x16x32_bf16 v[124:127], v[134:137], v[158:161], v[124:127]
	v_mfma_f32_16x16x32_bf16 v[120:123], v[150:153], v[158:161], v[120:123]
	v_mfma_f32_16x16x32_bf16 v[116:119], v[134:137], v[166:169], v[116:119]
	v_mfma_f32_16x16x32_bf16 v[108:111], v[150:153], v[166:169], v[108:111]
	v_mfma_f32_16x16x32_bf16 v[100:103], v[134:137], v[174:177], v[100:103]
	v_mfma_f32_16x16x32_bf16 v[92:95], v[150:153], v[174:177], v[92:95]
	v_mfma_f32_16x16x32_bf16 v[84:87], v[134:137], v[182:185], v[84:87]
	v_mfma_f32_16x16x32_bf16 v[76:79], v[150:153], v[182:185], v[76:79]
	v_mfma_f32_16x16x32_bf16 v[124:127], v[146:149], v[162:165], v[124:127]
	v_mfma_f32_16x16x32_bf16 v[120:123], v[154:157], v[162:165], v[120:123]
	v_mfma_f32_16x16x32_bf16 v[116:119], v[146:149], v[170:173], v[116:119]
	v_mfma_f32_16x16x32_bf16 v[108:111], v[154:157], v[170:173], v[108:111]
	v_mfma_f32_16x16x32_bf16 v[100:103], v[146:149], v[178:181], v[100:103]
	v_mfma_f32_16x16x32_bf16 v[92:95], v[154:157], v[178:181], v[92:95]
	v_mfma_f32_16x16x32_bf16 v[84:87], v[146:149], v[196:199], v[84:87]
	v_mfma_f32_16x16x32_bf16 v[76:79], v[154:157], v[196:199], v[76:79]
	s_barrier
	s_add_i32 s20, 0, 0x1c000
	s_add_i32 s21, s26, s35
	v_add_u32_e32 v190, s20, v139
	v_lshl_add_u64 v[142:143], v[142:143], 0, s[88:89]
	s_mov_b32 m0, s21
	ds_read_b128 v[200:203], v190
	ds_read_b128 v[204:207], v190 offset:1024
	ds_read_b128 v[214:217], v190 offset:2048
	ds_read_b128 v[218:221], v190 offset:3072
	global_load_lds_dwordx4 v[142:143], off
	s_add_i32 m0, s21, 0x2000
	v_lshl_add_u64 v[142:143], v[186:187], 0, s[88:89]
	global_load_lds_dwordx4 v[142:143], off
	s_barrier
	s_waitcnt lgkmcnt(0)
	v_mfma_f32_16x16x32_bf16 v[112:115], v[200:203], v[158:161], v[112:115]
	v_mfma_f32_16x16x32_bf16 v[104:107], v[214:217], v[158:161], v[104:107]
	v_mfma_f32_16x16x32_bf16 v[96:99], v[200:203], v[166:169], v[96:99]
	v_mfma_f32_16x16x32_bf16 v[88:91], v[214:217], v[166:169], v[88:91]
	v_mfma_f32_16x16x32_bf16 v[80:83], v[200:203], v[174:177], v[80:83]
	v_mfma_f32_16x16x32_bf16 v[72:75], v[214:217], v[174:177], v[72:75]
	v_mfma_f32_16x16x32_bf16 v[68:71], v[200:203], v[182:185], v[68:71]
	v_mfma_f32_16x16x32_bf16 v[64:67], v[214:217], v[182:185], v[64:67]
	v_mfma_f32_16x16x32_bf16 v[112:115], v[204:207], v[162:165], v[112:115]
	v_mfma_f32_16x16x32_bf16 v[104:107], v[218:221], v[162:165], v[104:107]
	v_mfma_f32_16x16x32_bf16 v[96:99], v[204:207], v[170:173], v[96:99]
	v_mfma_f32_16x16x32_bf16 v[88:91], v[218:221], v[170:173], v[88:91]
	v_mfma_f32_16x16x32_bf16 v[80:83], v[204:207], v[178:181], v[80:83]
	v_mfma_f32_16x16x32_bf16 v[72:75], v[218:221], v[178:181], v[72:75]
	v_mfma_f32_16x16x32_bf16 v[68:71], v[204:207], v[196:199], v[68:71]
	v_mfma_f32_16x16x32_bf16 v[64:67], v[218:221], v[196:199], v[64:67]
	s_mov_b32 m0, s65
	v_lshl_add_u64 v[142:143], v[188:189], 0, s[88:89]
	s_barrier
	ds_read_b128 v[158:161], v141 offset:49152
	ds_read_b128 v[162:165], v141 offset:50176
	ds_read_b128 v[166:169], v141 offset:51200
	ds_read_b128 v[170:173], v141 offset:52224
	ds_read_b128 v[174:177], v141 offset:53248
	ds_read_b128 v[178:181], v141 offset:54272
	ds_read_b128 v[182:185], v141 offset:55296
	ds_read_b128 v[196:199], v141 offset:56320
	global_load_lds_dwordx4 v[142:143], off
	s_mov_b32 m0, s66
	v_lshl_add_u64 v[142:143], v[192:193], 0, s[88:89]
	global_load_lds_dwordx4 v[142:143], off
	s_barrier
; #define PG8_STAGE(bufoff, gbase, voff) do { _Pragma("unroll") for (int _i = 0; _i < 2; ++_i) \
;         __builtin_amdgcn_global_load_lds((const unsigned*)((const char*)(gbase) + (voff)[_i]), (LAS unsigned*)(lds + (bufoff) + ldsw + _i * 8192), 16, 0, 0); } while (0)
; #define PG8_MMA(ai, bj, At, Bt) do { __builtin_amdgcn_s_setprio(1); _Pragma("unroll") for (int m = 0; m < 4; ++m) _Pragma("unroll") for (int n = 0; n < 2; ++n) _Pragma("unroll") for (int k = 0; k < 2; ++k) \
;         acc[ai][bj][m][n] = __builtin_amdgcn_mfma_f32_16x16x32_bf16(Bt[n][k], At[m][k], acc[ai][bj][m][n], 0, 0, 0); __builtin_amdgcn_s_setprio(0); } while (0)
; #define PG8_WAIT_V(n) asm volatile("s_waitcnt vmcnt(" #n ")" ::: "memory")
; #define PG8_WAIT_L(n) asm volatile("s_waitcnt lgkmcnt(" #n ")" ::: "memory")
; #define PG8_BAR __builtin_amdgcn_s_barrier()
; #define PG8_SCHED __builtin_amdgcn_sched_barrier(0)
; template <class Epi>
; __device__ __forceinline__ void gemm_phase(LAS unsigned char* lds, const Gemm g, const StaticOrder& S, const Epi& E) {
;     ...
;             PG8_BAR; PG8_WAIT_L(0); PG8_MMA(1, 0, At, B0); PG8_BAR; PG8_SCHED;
;             PG8_STAGE(PG8_SB(1, 1), b3 + hB, voffB);
;             PG8_WAIT_V(6); PG8_BAR; PG8_MMA(1, 1, At, B1); PG8_BAR;
	s_waitcnt lgkmcnt(0)
	v_mfma_f32_16x16x32_bf16 v[60:63], v[134:137], v[158:161], v[60:63]
	v_mfma_f32_16x16x32_bf16 v[56:59], v[150:153], v[158:161], v[56:59]
	v_mfma_f32_16x16x32_bf16 v[52:55], v[134:137], v[166:169], v[52:55]
	v_mfma_f32_16x16x32_bf16 v[44:47], v[150:153], v[166:169], v[44:47]
	v_mfma_f32_16x16x32_bf16 v[36:39], v[134:137], v[174:177], v[36:39]
	v_mfma_f32_16x16x32_bf16 v[28:31], v[150:153], v[174:177], v[28:31]
	v_mfma_f32_16x16x32_bf16 v[20:23], v[134:137], v[182:185], v[20:23]
	v_mfma_f32_16x16x32_bf16 v[12:15], v[150:153], v[182:185], v[12:15]
	v_mfma_f32_16x16x32_bf16 v[60:63], v[146:149], v[162:165], v[60:63]
	v_mfma_f32_16x16x32_bf16 v[56:59], v[154:157], v[162:165], v[56:59]
	v_mfma_f32_16x16x32_bf16 v[52:55], v[146:149], v[170:173], v[52:55]
	v_mfma_f32_16x16x32_bf16 v[44:47], v[154:157], v[170:173], v[44:47]
	v_mfma_f32_16x16x32_bf16 v[36:39], v[146:149], v[178:181], v[36:39]
	v_mfma_f32_16x16x32_bf16 v[28:31], v[154:157], v[178:181], v[28:31]
	v_mfma_f32_16x16x32_bf16 v[20:23], v[146:149], v[196:199], v[20:23]
	v_mfma_f32_16x16x32_bf16 v[12:15], v[154:157], v[196:199], v[12:15]
	s_barrier
	s_add_u32 s16, s16, 0x40080
	s_addc_u32 s17, s17, 0
	s_add_i32 s20, s20, s35
	s_mov_b32 m0, s20
	s_nop 0
	global_load_lds_dwordx4 v144, s[16:17]
	s_add_i32 m0, s20, 0x2000
	s_nop 0
	global_load_lds_dwordx4 v128, s[16:17]
	s_waitcnt vmcnt(6)
	s_barrier
	v_mfma_f32_16x16x32_bf16 v[48:51], v[200:203], v[158:161], v[48:51]
	v_mfma_f32_16x16x32_bf16 v[40:43], v[214:217], v[158:161], v[40:43]
	v_mfma_f32_16x16x32_bf16 v[32:35], v[200:203], v[166:169], v[32:35]
	v_mfma_f32_16x16x32_bf16 v[24:27], v[214:217], v[166:169], v[24:27]
	v_mfma_f32_16x16x32_bf16 v[16:19], v[200:203], v[174:177], v[16:19]
	v_mfma_f32_16x16x32_bf16 v[8:11], v[214:217], v[174:177], v[8:11]
	v_mfma_f32_16x16x32_bf16 v[4:7], v[200:203], v[182:185], v[4:7]
	v_mfma_f32_16x16x32_bf16 v[0:3], v[214:217], v[182:185], v[0:3]
	v_mfma_f32_16x16x32_bf16 v[48:51], v[204:207], v[162:165], v[48:51]
	v_mfma_f32_16x16x32_bf16 v[40:43], v[218:221], v[162:165], v[40:43]
	v_mfma_f32_16x16x32_bf16 v[32:35], v[204:207], v[170:173], v[32:35]
	v_mfma_f32_16x16x32_bf16 v[24:27], v[218:221], v[170:173], v[24:27]
	v_mfma_f32_16x16x32_bf16 v[16:19], v[204:207], v[178:181], v[16:19]
	v_mfma_f32_16x16x32_bf16 v[8:11], v[218:221], v[178:181], v[8:11]
	v_mfma_f32_16x16x32_bf16 v[4:7], v[204:207], v[196:199], v[4:7]
	v_mfma_f32_16x16x32_bf16 v[0:3], v[218:221], v[196:199], v[0:3]
	s_add_i32 s77, s77, 2
	s_add_u32 s12, s12, 0x100
	s_addc_u32 s13, s13, 0
	s_add_u32 s25, s25, 0x100
	s_addc_u32 s76, s76, 0
	s_cmp_gt_u32 s77, 13
	s_barrier
	s_cbranch_scc0 .LBB0_1079
; __device__ __forceinline__ unsigned pk2(float lo, float hi) { unsigned r; asm("v_cvt_pk_bf16_f32 %0, %1, %2" : "=v"(r) : "v"(lo), "v"(hi)); return r; }
;     __device__ __forceinline__ void operator()(const f32x4 (&acc)[2][2][4][2], const Unit& u, int wr, int wc, int fr, int fq) const {
;     ...
;         const int row_t = rmap == 1 ? odd_phys_row0(u.pm, grp) : (rmap == 2 ? odd_phys_row0(u.pm % (BG * TPB), u.pm / (BG * TPB)) : u.pm * BM);
;         int c = col_t + 64 * wc + 16 * fq;
;         if (mode == 2) c = (c >> 6) * 96 + (c & 63);
; #pragma unroll
;         for (int ai = 0; ai < 2; ++ai)
; #pragma unroll
;             for (int m = 0; m < 4; ++m) {
;                 const int row = row_t + ai * HALF + wr * 64 + m * 16 + fr;
;                 bf16_t* rp = O + (size_t)row * ldc + c;
; #pragma unroll
;                 for (int bj = 0; bj < 2; ++bj) {
;                     const f32x4 v0 = acc[ai][bj][m][0], v1 = acc[ai][bj][m][1];
;                     u32x4 o; o.x = pk2(v0[0], v0[1]); o.y = pk2(v0[2], v0[3]); o.z = pk2(v1[0], v1[1]); o.w = pk2(v1[2], v1[3]);
;                     *(u32x4*)(rp + 8 * bj) = o;
;                 }
;             }
	v_lshl_or_b32 v136, s15, 8, v140
	v_lshl_add_u32 v146, s70, 8, v138
	v_ashrrev_i32_e32 v137, 31, v136
	v_mov_b64_e32 v[134:135], s[4:5]
	s_movk_i32 s7, 0x1400
	v_cvt_pk_bf16_f32 v68, v68, v69
	v_cvt_pk_bf16_f32 v69, v70, v71
	v_cvt_pk_bf16_f32 v70, v64, v65
	v_add_u32_e32 v64, 0x80, v146
	v_mad_i64_i32 v[142:143], s[12:13], v146, s7, v[134:135]
	v_lshlrev_b64 v[136:137], 1, v[136:137]
	v_cvt_pk_bf16_f32 v112, v112, v113
	v_cvt_pk_bf16_f32 v113, v114, v115
	v_cvt_pk_bf16_f32 v114, v104, v105
	v_or_b32_e32 v104, 16, v146
	v_mad_i64_i32 v[64:65], s[12:13], v64, s7, v[134:135]
	v_cvt_pk_bf16_f32 v48, v48, v49
	v_cvt_pk_bf16_f32 v49, v50, v51
	v_cvt_pk_bf16_f32 v50, v40, v41
	v_add_u32_e32 v40, 0x90, v146
	v_lshl_add_u64 v[142:143], v[142:143], 0, v[136:137]
	v_mad_i64_i32 v[104:105], s[12:13], v104, s7, v[134:135]
	v_cvt_pk_bf16_f32 v96, v96, v97
	v_cvt_pk_bf16_f32 v97, v98, v99
	v_cvt_pk_bf16_f32 v98, v88, v89
	v_or_b32_e32 v88, 32, v146
	v_lshl_add_u64 v[64:65], v[64:65], 0, v[136:137]
	v_mad_i64_i32 v[40:41], s[12:13], v40, s7, v[134:135]
	v_cvt_pk_bf16_f32 v32, v32, v33
	v_cvt_pk_bf16_f32 v33, v34, v35
	v_cvt_pk_bf16_f32 v34, v24, v25
	v_add_u32_e32 v24, 0xa0, v146
	v_cvt_pk_bf16_f32 v115, v106, v107
	global_store_dwordx4 v[142:143], v[112:115], off offset:16
	v_mad_i64_i32 v[88:89], s[12:13], v88, s7, v[134:135]
	s_nop 0
	v_lshl_add_u64 v[112:113], v[104:105], 0, v[136:137]
	v_cvt_pk_bf16_f32 v80, v80, v81
	v_cvt_pk_bf16_f32 v81, v82, v83
	v_cvt_pk_bf16_f32 v82, v72, v73
	v_or_b32_e32 v72, 48, v146
	v_cvt_pk_bf16_f32 v51, v42, v43
	global_store_dwordx4 v[64:65], v[48:51], off offset:16
	v_mad_i64_i32 v[24:25], s[12:13], v24, s7, v[134:135]
	s_nop 0
	v_lshl_add_u64 v[48:49], v[40:41], 0, v[136:137]
	v_cvt_pk_bf16_f32 v16, v16, v17
	v_cvt_pk_bf16_f32 v17, v18, v19
	v_cvt_pk_bf16_f32 v18, v8, v9
	v_add_u32_e32 v8, 0xb0, v146
	v_cvt_pk_bf16_f32 v99, v90, v91
	global_store_dwordx4 v[112:113], v[96:99], off offset:16
	v_mad_i64_i32 v[72:73], s[12:13], v72, s7, v[134:135]
	s_nop 0
	v_lshl_add_u64 v[96:97], v[88:89], 0, v[136:137]
	v_cvt_pk_bf16_f32 v35, v26, v27
	global_store_dwordx4 v[48:49], v[32:35], off offset:16
	v_mad_i64_i32 v[8:9], s[12:13], v8, s7, v[134:135]
	s_nop 0
	v_lshl_add_u64 v[32:33], v[24:25], 0, v[136:137]
	v_cvt_pk_bf16_f32 v83, v74, v75
	global_store_dwordx4 v[96:97], v[80:83], off offset:16
	v_cvt_pk_bf16_f32 v19, v10, v11
	global_store_dwordx4 v[32:33], v[16:19], off offset:16
	s_and_b64 vcc, exec, s[0:1]
	v_lshl_add_u64 v[80:81], v[72:73], 0, v[136:137]
	v_lshl_add_u64 v[16:17], v[8:9], 0, v[136:137]
	s_mov_b32 s15, s6
	s_mov_b32 s70, s69
	s_mov_b64 s[16:17], s[10:11]
	s_mov_b64 s[12:13], s[8:9]
	v_cvt_pk_bf16_f32 v124, v124, v125
	v_cvt_pk_bf16_f32 v125, v126, v127
	v_cvt_pk_bf16_f32 v126, v120, v121
	v_cvt_pk_bf16_f32 v127, v122, v123
	global_store_dwordx4 v[142:143], v[124:127], off
	v_cvt_pk_bf16_f32 v104, v116, v117
	v_cvt_pk_bf16_f32 v105, v118, v119
	v_cvt_pk_bf16_f32 v106, v108, v109
	v_cvt_pk_bf16_f32 v107, v110, v111
	global_store_dwordx4 v[112:113], v[104:107], off
	v_cvt_pk_bf16_f32 v88, v100, v101
	v_cvt_pk_bf16_f32 v89, v102, v103
	v_cvt_pk_bf16_f32 v90, v92, v93
	v_cvt_pk_bf16_f32 v91, v94, v95
	global_store_dwordx4 v[96:97], v[88:91], off
	v_cvt_pk_bf16_f32 v72, v84, v85
	v_cvt_pk_bf16_f32 v73, v86, v87
	v_cvt_pk_bf16_f32 v74, v76, v77
	v_cvt_pk_bf16_f32 v75, v78, v79
	global_store_dwordx4 v[80:81], v[72:75], off
	v_cvt_pk_bf16_f32 v71, v66, v67
	global_store_dwordx4 v[80:81], v[68:71], off offset:16
	v_cvt_pk_bf16_f32 v60, v60, v61
	v_cvt_pk_bf16_f32 v61, v62, v63
	v_cvt_pk_bf16_f32 v62, v56, v57
	v_cvt_pk_bf16_f32 v63, v58, v59
	global_store_dwordx4 v[64:65], v[60:63], off
	v_cvt_pk_bf16_f32 v40, v52, v53
	v_cvt_pk_bf16_f32 v41, v54, v55
	v_cvt_pk_bf16_f32 v42, v44, v45
	v_cvt_pk_bf16_f32 v43, v46, v47
	global_store_dwordx4 v[48:49], v[40:43], off
	v_cvt_pk_bf16_f32 v24, v36, v37
	v_cvt_pk_bf16_f32 v25, v38, v39
	v_cvt_pk_bf16_f32 v26, v28, v29
	v_cvt_pk_bf16_f32 v27, v30, v31
	global_store_dwordx4 v[32:33], v[24:27], off
	v_cvt_pk_bf16_f32 v8, v20, v21
	v_cvt_pk_bf16_f32 v9, v22, v23
	v_cvt_pk_bf16_f32 v10, v12, v13
	v_cvt_pk_bf16_f32 v11, v14, v15
	global_store_dwordx4 v[16:17], v[8:11], off
	v_cvt_pk_bf16_f32 v4, v4, v5
	v_cvt_pk_bf16_f32 v5, v6, v7
	v_cvt_pk_bf16_f32 v6, v0, v1
	v_cvt_pk_bf16_f32 v7, v2, v3
	global_store_dwordx4 v[16:17], v[4:7], off offset:16
	s_cbranch_vccz .LBB0_1076
	s_waitcnt vmcnt(0)
	s_cmpk_gt_u32 s3, 0xff
	s_cbranch_scc1 .LBB0_1083
	s_barrier

; #define PG8_STAGE(bufoff, gbase, voff) do { _Pragma("unroll") for (int _i = 0; _i < 2; ++_i) \
;         __builtin_amdgcn_global_load_lds((const unsigned*)((const char*)(gbase) + (voff)[_i]), (LAS unsigned*)(lds + (bufoff) + ldsw + _i * 8192), 16, 0, 0); } while (0)
; #define PG8_LDA(dst, b, h) do { _Pragma("unroll") for (int m = 0; m < 4; ++m) _Pragma("unroll") for (int k = 0; k < 2; ++k) dst[m][k] = *(const LAS bf16x8*)(lds + PG8_SA(b, h) + aoff + m * 2048 + k * 1024); } while (0)
; #define PG8_LDB(dst, b, h) do { _Pragma("unroll") for (int n = 0; n < 2; ++n) _Pragma("unroll") for (int k = 0; k < 2; ++k) dst[n][k] = *(const LAS bf16x8*)(lds + PG8_SB(b, h) + boff + n * 2048 + k * 1024); } while (0)
; #define PG8_MMA(ai, bj, At, Bt) do { __builtin_amdgcn_s_setprio(1); _Pragma("unroll") for (int m = 0; m < 4; ++m) _Pragma("unroll") for (int n = 0; n < 2; ++n) _Pragma("unroll") for (int k = 0; k < 2; ++k) \
;         acc[ai][bj][m][n] = __builtin_amdgcn_mfma_f32_16x16x32_bf16(Bt[n][k], At[m][k], acc[ai][bj][m][n], 0, 0, 0); __builtin_amdgcn_s_setprio(0); } while (0)
; #define PG8_WAIT_L(n) asm volatile("s_waitcnt lgkmcnt(" #n ")" ::: "memory")
; #define PG8_BAR __builtin_amdgcn_s_barrier()
; #define PG8_SCHED __builtin_amdgcn_sched_barrier(0)
; template <class Epi>
; __device__ __forceinline__ void gemm_phase(LAS unsigned char* lds, const Gemm g, const StaticOrder& S, const Epi& E) {
;     ...
;             const bool last = (t == nt - 2);
;             const char* a1 = cA + (size_t)(t + 1) * kstep;
;             const char* a2 = last ? nA : cA + (size_t)(t + 2) * kstep; const char* b2 = last ? nB : cB + (size_t)(t + 2) * kstep;
;             const char* a3 = a2 + kstep; const char* b3 = b2 + kstep;
;             PG8_LDB(B0, 0, 0); PG8_SCHED; PG8_LDA(At, 0, 0); PG8_STAGE(PG8_SA(1, 1), a1 + hA, voffA);
;             PG8_WAIT_L(8); PG8_BAR; PG8_WAIT_L(0); PG8_MMA(0, 0, At, B0); PG8_BAR; PG8_SCHED;
;             PG8_LDB(B1, 0, 1); PG8_STAGE(PG8_SB(0, 0), b2, voffB);
;             PG8_BAR; PG8_WAIT_L(0); PG8_MMA(0, 1, At, B1); PG8_BAR;
;             PG8_LDA(At, 0, 1); PG8_STAGE(PG8_SA(0, 0), a2, voffA);
;             PG8_BAR; PG8_WAIT_L(0); PG8_MMA(1, 0, At, B0); PG8_BAR; PG8_SCHED;
.LBB0_1270:
	s_add_u32 s16, s12, 0xfffc0080
	s_addc_u32 s17, s13, -1
	s_add_i32 s26, 0, 0x10000
	v_add_u32_e32 v142, s26, v139
	ds_read_b128 v[134:137], v142
	ds_read_b128 v[146:149], v142 offset:1024
	ds_read_b128 v[150:153], v142 offset:2048
	ds_read_b128 v[154:157], v142 offset:3072
	s_cmp_eq_u32 s77, 12
	s_cselect_b32 s21, s71, s17
	s_cselect_b32 s20, s72, s16
	s_cselect_b32 s17, s7, s76
	s_cselect_b32 s16, s24, s25
	s_add_i32 m0, s61, 0xc000
	ds_read_b128 v[158:161], v141
	ds_read_b128 v[162:165], v141 offset:1024
	ds_read_b128 v[166:169], v141 offset:2048
	ds_read_b128 v[170:173], v141 offset:3072
	ds_read_b128 v[174:177], v141 offset:4096
	ds_read_b128 v[178:181], v141 offset:5120
	ds_read_b128 v[182:185], v141 offset:6144
	ds_read_b128 v[196:199], v141 offset:7168
	global_load_lds_dwordx4 v130, s[12:13]
	s_add_i32 m0, s61, 0xe000
	v_lshl_add_u64 v[142:143], s[12:13], 0, v[132:133]
	global_load_lds_dwordx4 v[142:143], off
	s_waitcnt lgkmcnt(8)
	s_barrier
	s_waitcnt lgkmcnt(0)
	v_mfma_f32_16x16x32_bf16 v[124:127], v[134:137], v[158:161], v[124:127]
	v_mfma_f32_16x16x32_bf16 v[120:123], v[150:153], v[158:161], v[120:123]
	v_mfma_f32_16x16x32_bf16 v[116:119], v[134:137], v[166:169], v[116:119]
	v_mfma_f32_16x16x32_bf16 v[108:111], v[150:153], v[166:169], v[108:111]
	v_mfma_f32_16x16x32_bf16 v[100:103], v[134:137], v[174:177], v[100:103]
	v_mfma_f32_16x16x32_bf16 v[92:95], v[150:153], v[174:177], v[92:95]
	v_mfma_f32_16x16x32_bf16 v[84:87], v[134:137], v[182:185], v[84:87]
	v_mfma_f32_16x16x32_bf16 v[76:79], v[150:153], v[182:185], v[76:79]
	v_mfma_f32_16x16x32_bf16 v[124:127], v[146:149], v[162:165], v[124:127]
	v_mfma_f32_16x16x32_bf16 v[120:123], v[154:157], v[162:165], v[120:123]
	v_mfma_f32_16x16x32_bf16 v[116:119], v[146:149], v[170:173], v[116:119]
	v_mfma_f32_16x16x32_bf16 v[108:111], v[154:157], v[170:173], v[108:111]
	v_mfma_f32_16x16x32_bf16 v[100:103], v[146:149], v[178:181], v[100:103]
	v_mfma_f32_16x16x32_bf16 v[92:95], v[154:157], v[178:181], v[92:95]
	v_mfma_f32_16x16x32_bf16 v[84:87], v[146:149], v[196:199], v[84:87]
	v_mfma_f32_16x16x32_bf16 v[76:79], v[154:157], v[196:199], v[76:79]
	s_barrier
	s_add_i32 s28, 0, 0x14000
	v_add_u32_e32 v142, s28, v139
	s_add_i32 s26, s26, s35
	ds_read_b128 v[200:203], v142
	ds_read_b128 v[204:207], v142 offset:1024
	ds_read_b128 v[214:217], v142 offset:2048
	ds_read_b128 v[218:221], v142 offset:3072
	v_lshl_add_u64 v[142:143], s[16:17], 0, v[144:145]
	s_mov_b32 m0, s26
	v_lshl_add_u64 v[186:187], s[16:17], 0, v[128:129]
	global_load_lds_dwordx4 v[142:143], off
	s_add_i32 m0, s26, 0x2000
	s_nop 0
	global_load_lds_dwordx4 v[186:187], off
	s_barrier
	s_waitcnt lgkmcnt(0)
	v_mfma_f32_16x16x32_bf16 v[112:115], v[200:203], v[158:161], v[112:115]
	v_mfma_f32_16x16x32_bf16 v[104:107], v[214:217], v[158:161], v[104:107]
	v_mfma_f32_16x16x32_bf16 v[96:99], v[200:203], v[166:169], v[96:99]
	v_mfma_f32_16x16x32_bf16 v[88:91], v[214:217], v[166:169], v[88:91]
	v_mfma_f32_16x16x32_bf16 v[80:83], v[200:203], v[174:177], v[80:83]
	v_mfma_f32_16x16x32_bf16 v[72:75], v[214:217], v[174:177], v[72:75]
	v_mfma_f32_16x16x32_bf16 v[68:71], v[200:203], v[182:185], v[68:71]
	v_mfma_f32_16x16x32_bf16 v[64:67], v[214:217], v[182:185], v[64:67]
	v_mfma_f32_16x16x32_bf16 v[112:115], v[204:207], v[162:165], v[112:115]
	v_mfma_f32_16x16x32_bf16 v[104:107], v[218:221], v[162:165], v[104:107]
	v_mfma_f32_16x16x32_bf16 v[96:99], v[204:207], v[170:173], v[96:99]
	v_mfma_f32_16x16x32_bf16 v[88:91], v[218:221], v[170:173], v[88:91]
	v_mfma_f32_16x16x32_bf16 v[80:83], v[204:207], v[178:181], v[80:83]
	v_mfma_f32_16x16x32_bf16 v[72:75], v[218:221], v[178:181], v[72:75]
	v_mfma_f32_16x16x32_bf16 v[68:71], v[204:207], v[196:199], v[68:71]
	v_mfma_f32_16x16x32_bf16 v[64:67], v[218:221], v[196:199], v[64:67]
	s_mov_b32 m0, s61
	v_lshl_add_u64 v[188:189], s[20:21], 0, v[144:145]
	s_barrier
	ds_read_b128 v[158:161], v141 offset:16384
	ds_read_b128 v[162:165], v141 offset:17408
	ds_read_b128 v[166:169], v141 offset:18432
	ds_read_b128 v[170:173], v141 offset:19456
	ds_read_b128 v[174:177], v141 offset:20480
	ds_read_b128 v[178:181], v141 offset:21504
	ds_read_b128 v[182:185], v141 offset:22528
	ds_read_b128 v[196:199], v141 offset:23552
	global_load_lds_dwordx4 v[188:189], off
	s_mov_b32 m0, s62
	v_lshl_add_u64 v[192:193], s[20:21], 0, v[128:129]
	global_load_lds_dwordx4 v[192:193], off
	s_barrier
	s_waitcnt lgkmcnt(0)
	v_mfma_f32_16x16x32_bf16 v[60:63], v[134:137], v[158:161], v[60:63]
	v_mfma_f32_16x16x32_bf16 v[56:59], v[150:153], v[158:161], v[56:59]
	v_mfma_f32_16x16x32_bf16 v[52:55], v[134:137], v[166:169], v[52:55]
	v_mfma_f32_16x16x32_bf16 v[44:47], v[150:153], v[166:169], v[44:47]
	v_mfma_f32_16x16x32_bf16 v[36:39], v[134:137], v[174:177], v[36:39]
	v_mfma_f32_16x16x32_bf16 v[28:31], v[150:153], v[174:177], v[28:31]
	v_mfma_f32_16x16x32_bf16 v[20:23], v[134:137], v[182:185], v[20:23]
	v_mfma_f32_16x16x32_bf16 v[12:15], v[150:153], v[182:185], v[12:15]
	v_mfma_f32_16x16x32_bf16 v[60:63], v[146:149], v[162:165], v[60:63]
	v_mfma_f32_16x16x32_bf16 v[56:59], v[154:157], v[162:165], v[56:59]
	v_mfma_f32_16x16x32_bf16 v[52:55], v[146:149], v[170:173], v[52:55]
	v_mfma_f32_16x16x32_bf16 v[44:47], v[154:157], v[170:173], v[44:47]
	v_mfma_f32_16x16x32_bf16 v[36:39], v[146:149], v[178:181], v[36:39]
	v_mfma_f32_16x16x32_bf16 v[28:31], v[154:157], v[178:181], v[28:31]
	v_mfma_f32_16x16x32_bf16 v[20:23], v[146:149], v[196:199], v[20:23]
	v_mfma_f32_16x16x32_bf16 v[12:15], v[154:157], v[196:199], v[12:15]
	s_barrier
; #define PG8_STAGE(bufoff, gbase, voff) do { _Pragma("unroll") for (int _i = 0; _i < 2; ++_i) \
;         __builtin_amdgcn_global_load_lds((const unsigned*)((const char*)(gbase) + (voff)[_i]), (LAS unsigned*)(lds + (bufoff) + ldsw + _i * 8192), 16, 0, 0); } while (0)
; #define PG8_LDA(dst, b, h) do { _Pragma("unroll") for (int m = 0; m < 4; ++m) _Pragma("unroll") for (int k = 0; k < 2; ++k) dst[m][k] = *(const LAS bf16x8*)(lds + PG8_SA(b, h) + aoff + m * 2048 + k * 1024); } while (0)
; #define PG8_LDB(dst, b, h) do { _Pragma("unroll") for (int n = 0; n < 2; ++n) _Pragma("unroll") for (int k = 0; k < 2; ++k) dst[n][k] = *(const LAS bf16x8*)(lds + PG8_SB(b, h) + boff + n * 2048 + k * 1024); } while (0)
; #define PG8_MMA(ai, bj, At, Bt) do { __builtin_amdgcn_s_setprio(1); _Pragma("unroll") for (int m = 0; m < 4; ++m) _Pragma("unroll") for (int n = 0; n < 2; ++n) _Pragma("unroll") for (int k = 0; k < 2; ++k) \
;         acc[ai][bj][m][n] = __builtin_amdgcn_mfma_f32_16x16x32_bf16(Bt[n][k], At[m][k], acc[ai][bj][m][n], 0, 0, 0); __builtin_amdgcn_s_setprio(0); } while (0)
; #define PG8_WAIT_V(n) asm volatile("s_waitcnt vmcnt(" #n ")" ::: "memory")
; #define PG8_WAIT_L(n) asm volatile("s_waitcnt lgkmcnt(" #n ")" ::: "memory")
; #define PG8_BAR __builtin_amdgcn_s_barrier()
; #define PG8_SCHED __builtin_amdgcn_sched_barrier(0)
; template <class Epi>
; __device__ __forceinline__ void gemm_phase(LAS unsigned char* lds, const Gemm g, const StaticOrder& S, const Epi& E) {
;     ...
;             PG8_STAGE(PG8_SB(0, 1), b2 + hB, voffB);
;             PG8_WAIT_V(6); PG8_BAR; PG8_MMA(1, 1, At, B1); PG8_BAR;
;             PG8_LDB(B0, 1, 0); PG8_SCHED; PG8_LDA(At, 1, 0); PG8_STAGE(PG8_SA(0, 1), a2 + hA, voffA);
;             PG8_WAIT_L(8); PG8_BAR; PG8_WAIT_L(0); PG8_MMA(0, 0, At, B0); PG8_BAR; PG8_SCHED;
;             PG8_LDB(B1, 1, 1); PG8_STAGE(PG8_SB(1, 0), b3, voffB);
;             PG8_BAR; PG8_WAIT_L(0); PG8_MMA(0, 1, At, B1); PG8_BAR;
;             PG8_LDA(At, 1, 1); PG8_STAGE(PG8_SA(1, 0), a3, voffA);
;             PG8_BAR; PG8_WAIT_L(0); PG8_MMA(1, 0, At, B0); PG8_BAR; PG8_SCHED;
	s_add_u32 s26, s16, 0x40000
	s_addc_u32 s27, s17, 0
	s_add_i32 s28, s28, s35
	s_mov_b32 m0, s28
	s_nop 0
	global_load_lds_dwordx4 v144, s[26:27]
	s_add_i32 m0, s28, 0x2000
	s_nop 0
	global_load_lds_dwordx4 v128, s[26:27]
	s_waitcnt vmcnt(6)
	s_barrier
	v_mfma_f32_16x16x32_bf16 v[48:51], v[200:203], v[158:161], v[48:51]
	v_mfma_f32_16x16x32_bf16 v[40:43], v[214:217], v[158:161], v[40:43]
	v_mfma_f32_16x16x32_bf16 v[32:35], v[200:203], v[166:169], v[32:35]
	v_mfma_f32_16x16x32_bf16 v[24:27], v[214:217], v[166:169], v[24:27]
	v_mfma_f32_16x16x32_bf16 v[16:19], v[200:203], v[174:177], v[16:19]
	v_mfma_f32_16x16x32_bf16 v[8:11], v[214:217], v[174:177], v[8:11]
	v_mfma_f32_16x16x32_bf16 v[4:7], v[200:203], v[182:185], v[4:7]
	v_mfma_f32_16x16x32_bf16 v[0:3], v[214:217], v[182:185], v[0:3]
	v_mfma_f32_16x16x32_bf16 v[48:51], v[204:207], v[162:165], v[48:51]
	v_mfma_f32_16x16x32_bf16 v[40:43], v[218:221], v[162:165], v[40:43]
	v_mfma_f32_16x16x32_bf16 v[32:35], v[204:207], v[170:173], v[32:35]
	v_mfma_f32_16x16x32_bf16 v[24:27], v[218:221], v[170:173], v[24:27]
	v_mfma_f32_16x16x32_bf16 v[16:19], v[204:207], v[178:181], v[16:19]
	v_mfma_f32_16x16x32_bf16 v[8:11], v[218:221], v[178:181], v[8:11]
	v_mfma_f32_16x16x32_bf16 v[4:7], v[204:207], v[196:199], v[4:7]
	v_mfma_f32_16x16x32_bf16 v[0:3], v[218:221], v[196:199], v[0:3]
	s_add_i32 s26, 0, 0x18000
	v_add_u32_e32 v154, s26, v139
	s_barrier
	ds_read_b128 v[134:137], v154
	ds_read_b128 v[146:149], v154 offset:1024
	ds_read_b128 v[150:153], v154 offset:2048
	ds_read_b128 v[154:157], v154 offset:3072
	s_add_u32 s20, s20, 0x40000
	s_addc_u32 s21, s21, 0
	s_mov_b32 m0, s63
	ds_read_b128 v[158:161], v141 offset:32768
	ds_read_b128 v[162:165], v141 offset:33792
	ds_read_b128 v[166:169], v141 offset:34816
	ds_read_b128 v[170:173], v141 offset:35840
	ds_read_b128 v[174:177], v141 offset:36864
	ds_read_b128 v[178:181], v141 offset:37888
	ds_read_b128 v[182:185], v141 offset:38912
	ds_read_b128 v[196:199], v141 offset:39936
	global_load_lds_dwordx4 v144, s[20:21]
	s_mov_b32 m0, s64
	s_nop 0
	global_load_lds_dwordx4 v128, s[20:21]
	s_waitcnt lgkmcnt(8)
	s_barrier
	s_waitcnt lgkmcnt(0)
	v_mfma_f32_16x16x32_bf16 v[124:127], v[134:137], v[158:161], v[124:127]
	v_mfma_f32_16x16x32_bf16 v[120:123], v[150:153], v[158:161], v[120:123]
	v_mfma_f32_16x16x32_bf16 v[116:119], v[134:137], v[166:169], v[116:119]
	v_mfma_f32_16x16x32_bf16 v[108:111], v[150:153], v[166:169], v[108:111]
	v_mfma_f32_16x16x32_bf16 v[100:103], v[134:137], v[174:177], v[100:103]
	v_mfma_f32_16x16x32_bf16 v[92:95], v[150:153], v[174:177], v[92:95]
	v_mfma_f32_16x16x32_bf16 v[84:87], v[134:137], v[182:185], v[84:87]
	v_mfma_f32_16x16x32_bf16 v[76:79], v[150:153], v[182:185], v[76:79]
	v_mfma_f32_16x16x32_bf16 v[124:127], v[146:149], v[162:165], v[124:127]
	v_mfma_f32_16x16x32_bf16 v[120:123], v[154:157], v[162:165], v[120:123]
	v_mfma_f32_16x16x32_bf16 v[116:119], v[146:149], v[170:173], v[116:119]
	v_mfma_f32_16x16x32_bf16 v[108:111], v[154:157], v[170:173], v[108:111]
	v_mfma_f32_16x16x32_bf16 v[100:103], v[146:149], v[178:181], v[100:103]
	v_mfma_f32_16x16x32_bf16 v[92:95], v[154:157], v[178:181], v[92:95]
	v_mfma_f32_16x16x32_bf16 v[84:87], v[146:149], v[196:199], v[84:87]
	v_mfma_f32_16x16x32_bf16 v[76:79], v[154:157], v[196:199], v[76:79]
	s_barrier
	s_add_i32 s20, 0, 0x1c000
	s_add_i32 s21, s26, s35
	v_add_u32_e32 v190, s20, v139
	v_lshl_add_u64 v[142:143], v[142:143], 0, s[88:89]
	s_mov_b32 m0, s21
	ds_read_b128 v[200:203], v190
	ds_read_b128 v[204:207], v190 offset:1024
	ds_read_b128 v[214:217], v190 offset:2048
	ds_read_b128 v[218:221], v190 offset:3072
	global_load_lds_dwordx4 v[142:143], off
	s_add_i32 m0, s21, 0x2000
	v_lshl_add_u64 v[142:143], v[186:187], 0, s[88:89]
	global_load_lds_dwordx4 v[142:143], off
	s_barrier
	s_waitcnt lgkmcnt(0)
	v_mfma_f32_16x16x32_bf16 v[112:115], v[200:203], v[158:161], v[112:115]
	v_mfma_f32_16x16x32_bf16 v[104:107], v[214:217], v[158:161], v[104:107]
	v_mfma_f32_16x16x32_bf16 v[96:99], v[200:203], v[166:169], v[96:99]
	v_mfma_f32_16x16x32_bf16 v[88:91], v[214:217], v[166:169], v[88:91]
	v_mfma_f32_16x16x32_bf16 v[80:83], v[200:203], v[174:177], v[80:83]
	v_mfma_f32_16x16x32_bf16 v[72:75], v[214:217], v[174:177], v[72:75]
	v_mfma_f32_16x16x32_bf16 v[68:71], v[200:203], v[182:185], v[68:71]
	v_mfma_f32_16x16x32_bf16 v[64:67], v[214:217], v[182:185], v[64:67]
	v_mfma_f32_16x16x32_bf16 v[112:115], v[204:207], v[162:165], v[112:115]
	v_mfma_f32_16x16x32_bf16 v[104:107], v[218:221], v[162:165], v[104:107]
	v_mfma_f32_16x16x32_bf16 v[96:99], v[204:207], v[170:173], v[96:99]
	v_mfma_f32_16x16x32_bf16 v[88:91], v[218:221], v[170:173], v[88:91]
	v_mfma_f32_16x16x32_bf16 v[80:83], v[204:207], v[178:181], v[80:83]
	v_mfma_f32_16x16x32_bf16 v[72:75], v[218:221], v[178:181], v[72:75]
	v_mfma_f32_16x16x32_bf16 v[68:71], v[204:207], v[196:199], v[68:71]
	v_mfma_f32_16x16x32_bf16 v[64:67], v[218:221], v[196:199], v[64:67]
	s_mov_b32 m0, s65
	v_lshl_add_u64 v[142:143], v[188:189], 0, s[88:89]
	s_barrier
	ds_read_b128 v[158:161], v141 offset:49152
	ds_read_b128 v[162:165], v141 offset:50176
	ds_read_b128 v[166:169], v141 offset:51200
	ds_read_b128 v[170:173], v141 offset:52224
	ds_read_b128 v[174:177], v141 offset:53248
	ds_read_b128 v[178:181], v141 offset:54272
	ds_read_b128 v[182:185], v141 offset:55296
	ds_read_b128 v[196:199], v141 offset:56320
	global_load_lds_dwordx4 v[142:143], off
	s_mov_b32 m0, s66
	v_lshl_add_u64 v[142:143], v[192:193], 0, s[88:89]
	global_load_lds_dwordx4 v[142:143], off
	s_barrier
; #define PG8_STAGE(bufoff, gbase, voff) do { _Pragma("unroll") for (int _i = 0; _i < 2; ++_i) \
;         __builtin_amdgcn_global_load_lds((const unsigned*)((const char*)(gbase) + (voff)[_i]), (LAS unsigned*)(lds + (bufoff) + ldsw + _i * 8192), 16, 0, 0); } while (0)
; #define PG8_MMA(ai, bj, At, Bt) do { __builtin_amdgcn_s_setprio(1); _Pragma("unroll") for (int m = 0; m < 4; ++m) _Pragma("unroll") for (int n = 0; n < 2; ++n) _Pragma("unroll") for (int k = 0; k < 2; ++k) \
;         acc[ai][bj][m][n] = __builtin_amdgcn_mfma_f32_16x16x32_bf16(Bt[n][k], At[m][k], acc[ai][bj][m][n], 0, 0, 0); __builtin_amdgcn_s_setprio(0); } while (0)
; #define PG8_WAIT_V(n) asm volatile("s_waitcnt vmcnt(" #n ")" ::: "memory")
; #define PG8_WAIT_L(n) asm volatile("s_waitcnt lgkmcnt(" #n ")" ::: "memory")
; #define PG8_BAR __builtin_amdgcn_s_barrier()
; #define PG8_SCHED __builtin_amdgcn_sched_barrier(0)
; template <class Epi>
; __device__ __forceinline__ void gemm_phase(LAS unsigned char* lds, const Gemm g, const StaticOrder& S, const Epi& E) {
;     ...
;             PG8_BAR; PG8_WAIT_L(0); PG8_MMA(1, 0, At, B0); PG8_BAR; PG8_SCHED;
;             PG8_STAGE(PG8_SB(1, 1), b3 + hB, voffB);
;             PG8_WAIT_V(6); PG8_BAR; PG8_MMA(1, 1, At, B1); PG8_BAR;
	s_waitcnt lgkmcnt(0)
	v_mfma_f32_16x16x32_bf16 v[60:63], v[134:137], v[158:161], v[60:63]
	v_mfma_f32_16x16x32_bf16 v[56:59], v[150:153], v[158:161], v[56:59]
	v_mfma_f32_16x16x32_bf16 v[52:55], v[134:137], v[166:169], v[52:55]
	v_mfma_f32_16x16x32_bf16 v[44:47], v[150:153], v[166:169], v[44:47]
	v_mfma_f32_16x16x32_bf16 v[36:39], v[134:137], v[174:177], v[36:39]
	v_mfma_f32_16x16x32_bf16 v[28:31], v[150:153], v[174:177], v[28:31]
	v_mfma_f32_16x16x32_bf16 v[20:23], v[134:137], v[182:185], v[20:23]
	v_mfma_f32_16x16x32_bf16 v[12:15], v[150:153], v[182:185], v[12:15]
	v_mfma_f32_16x16x32_bf16 v[60:63], v[146:149], v[162:165], v[60:63]
	v_mfma_f32_16x16x32_bf16 v[56:59], v[154:157], v[162:165], v[56:59]
	v_mfma_f32_16x16x32_bf16 v[52:55], v[146:149], v[170:173], v[52:55]
	v_mfma_f32_16x16x32_bf16 v[44:47], v[154:157], v[170:173], v[44:47]
	v_mfma_f32_16x16x32_bf16 v[36:39], v[146:149], v[178:181], v[36:39]
	v_mfma_f32_16x16x32_bf16 v[28:31], v[154:157], v[178:181], v[28:31]
	v_mfma_f32_16x16x32_bf16 v[20:23], v[146:149], v[196:199], v[20:23]
	v_mfma_f32_16x16x32_bf16 v[12:15], v[154:157], v[196:199], v[12:15]
	s_barrier
	s_add_u32 s16, s16, 0x40080
	s_addc_u32 s17, s17, 0
	s_add_i32 s20, s20, s35
	s_mov_b32 m0, s20
	s_nop 0
	global_load_lds_dwordx4 v144, s[16:17]
	s_add_i32 m0, s20, 0x2000
	s_nop 0
	global_load_lds_dwordx4 v128, s[16:17]
	s_waitcnt vmcnt(6)
	s_barrier
	v_mfma_f32_16x16x32_bf16 v[48:51], v[200:203], v[158:161], v[48:51]
	v_mfma_f32_16x16x32_bf16 v[40:43], v[214:217], v[158:161], v[40:43]
	v_mfma_f32_16x16x32_bf16 v[32:35], v[200:203], v[166:169], v[32:35]
	v_mfma_f32_16x16x32_bf16 v[24:27], v[214:217], v[166:169], v[24:27]
	v_mfma_f32_16x16x32_bf16 v[16:19], v[200:203], v[174:177], v[16:19]
	v_mfma_f32_16x16x32_bf16 v[8:11], v[214:217], v[174:177], v[8:11]
	v_mfma_f32_16x16x32_bf16 v[4:7], v[200:203], v[182:185], v[4:7]
	v_mfma_f32_16x16x32_bf16 v[0:3], v[214:217], v[182:185], v[0:3]
	v_mfma_f32_16x16x32_bf16 v[48:51], v[204:207], v[162:165], v[48:51]
	v_mfma_f32_16x16x32_bf16 v[40:43], v[218:221], v[162:165], v[40:43]
	v_mfma_f32_16x16x32_bf16 v[32:35], v[204:207], v[170:173], v[32:35]
	v_mfma_f32_16x16x32_bf16 v[24:27], v[218:221], v[170:173], v[24:27]
	v_mfma_f32_16x16x32_bf16 v[16:19], v[204:207], v[178:181], v[16:19]
	v_mfma_f32_16x16x32_bf16 v[8:11], v[218:221], v[178:181], v[8:11]
	v_mfma_f32_16x16x32_bf16 v[4:7], v[204:207], v[196:199], v[4:7]
	v_mfma_f32_16x16x32_bf16 v[0:3], v[218:221], v[196:199], v[0:3]
	s_add_i32 s77, s77, 2
	s_add_u32 s12, s12, 0x100
	s_addc_u32 s13, s13, 0
	s_add_u32 s25, s25, 0x100
	s_addc_u32 s76, s76, 0
	s_cmp_gt_u32 s77, 13
	s_barrier
	s_cbranch_scc0 .LBB0_1270
; __device__ __forceinline__ unsigned pk2(float lo, float hi) { unsigned r; asm("v_cvt_pk_bf16_f32 %0, %1, %2" : "=v"(r) : "v"(lo), "v"(hi)); return r; }
;     __device__ __forceinline__ void operator()(const f32x4 (&acc)[2][2][4][2], const Unit& u, int wr, int wc, int fr, int fq) const {
;     ...
;         const int row_t = rmap == 1 ? odd_phys_row0(u.pm, grp) : (rmap == 2 ? odd_phys_row0(u.pm % (BG * TPB), u.pm / (BG * TPB)) : u.pm * BM);
;         int c = col_t + 64 * wc + 16 * fq;
;         if (mode == 2) c = (c >> 6) * 96 + (c & 63);
; #pragma unroll
;         for (int ai = 0; ai < 2; ++ai)
; #pragma unroll
;             for (int m = 0; m < 4; ++m) {
;                 const int row = row_t + ai * HALF + wr * 64 + m * 16 + fr;
;                 bf16_t* rp = O + (size_t)row * ldc + c;
; #pragma unroll
;                 for (int bj = 0; bj < 2; ++bj) {
;                     const f32x4 v0 = acc[ai][bj][m][0], v1 = acc[ai][bj][m][1];
;                     u32x4 o; o.x = pk2(v0[0], v0[1]); o.y = pk2(v0[2], v0[3]); o.z = pk2(v1[0], v1[1]); o.w = pk2(v1[2], v1[3]);
;                     *(u32x4*)(rp + 8 * bj) = o;
;                 }
;             }
	v_lshl_add_u32 v134, s70, 8, v138
	v_cvt_pk_bf16_f32 v68, v68, v69
	v_cvt_pk_bf16_f32 v69, v70, v71
	v_cvt_pk_bf16_f32 v70, v64, v65
	v_add_u32_e32 v64, 0x80, v134
	v_lshl_or_b32 v136, s15, 8, v140
	v_ashrrev_i32_e32 v135, 31, v134
	v_cvt_pk_bf16_f32 v112, v112, v113
	v_cvt_pk_bf16_f32 v113, v114, v115
	v_cvt_pk_bf16_f32 v114, v104, v105
	v_or_b32_e32 v104, 16, v134
	v_ashrrev_i32_e32 v65, 31, v64
	v_cvt_pk_bf16_f32 v48, v48, v49
	v_cvt_pk_bf16_f32 v49, v50, v51
	v_cvt_pk_bf16_f32 v50, v40, v41
	v_add_u32_e32 v40, 0x90, v134
	v_ashrrev_i32_e32 v137, 31, v136
	v_lshlrev_b64 v[142:143], 11, v[134:135]
	v_ashrrev_i32_e32 v105, 31, v104
	v_cvt_pk_bf16_f32 v96, v96, v97
	v_cvt_pk_bf16_f32 v97, v98, v99
	v_cvt_pk_bf16_f32 v98, v88, v89
	v_or_b32_e32 v88, 32, v134
	v_lshlrev_b64 v[64:65], 11, v[64:65]
	v_ashrrev_i32_e32 v41, 31, v40
	v_cvt_pk_bf16_f32 v32, v32, v33
	v_cvt_pk_bf16_f32 v33, v34, v35
	v_cvt_pk_bf16_f32 v34, v24, v25
	v_add_u32_e32 v24, 0xa0, v134
	v_lshl_add_u64 v[142:143], s[4:5], 0, v[142:143]
	v_lshlrev_b64 v[136:137], 1, v[136:137]
	v_lshlrev_b64 v[104:105], 11, v[104:105]
	v_ashrrev_i32_e32 v89, 31, v88
	v_cvt_pk_bf16_f32 v80, v80, v81
	v_cvt_pk_bf16_f32 v81, v82, v83
	v_cvt_pk_bf16_f32 v82, v72, v73
	v_or_b32_e32 v72, 48, v134
	v_lshl_add_u64 v[64:65], s[4:5], 0, v[64:65]
	v_lshlrev_b64 v[40:41], 11, v[40:41]
	v_ashrrev_i32_e32 v25, 31, v24
	v_cvt_pk_bf16_f32 v16, v16, v17
	v_cvt_pk_bf16_f32 v17, v18, v19
	v_cvt_pk_bf16_f32 v18, v8, v9
	v_add_u32_e32 v8, 0xb0, v134
	v_lshl_add_u64 v[142:143], v[142:143], 0, v[136:137]
	v_lshl_add_u64 v[104:105], s[4:5], 0, v[104:105]
	v_lshlrev_b64 v[88:89], 11, v[88:89]
	v_ashrrev_i32_e32 v73, 31, v72
	v_lshl_add_u64 v[64:65], v[64:65], 0, v[136:137]
	v_lshl_add_u64 v[40:41], s[4:5], 0, v[40:41]
	v_lshlrev_b64 v[24:25], 11, v[24:25]
	v_ashrrev_i32_e32 v9, 31, v8
	v_cvt_pk_bf16_f32 v115, v106, v107
	global_store_dwordx4 v[142:143], v[112:115], off offset:16
	v_lshl_add_u64 v[88:89], s[4:5], 0, v[88:89]
	v_lshlrev_b64 v[72:73], 11, v[72:73]
	v_lshl_add_u64 v[112:113], v[104:105], 0, v[136:137]
	v_cvt_pk_bf16_f32 v51, v42, v43
	global_store_dwordx4 v[64:65], v[48:51], off offset:16
	v_lshl_add_u64 v[24:25], s[4:5], 0, v[24:25]
	v_lshlrev_b64 v[8:9], 11, v[8:9]
	v_lshl_add_u64 v[48:49], v[40:41], 0, v[136:137]
	v_cvt_pk_bf16_f32 v99, v90, v91
	global_store_dwordx4 v[112:113], v[96:99], off offset:16
	v_lshl_add_u64 v[72:73], s[4:5], 0, v[72:73]
	v_cvt_pk_bf16_f32 v35, v26, v27
	global_store_dwordx4 v[48:49], v[32:35], off offset:16
	v_lshl_add_u64 v[96:97], v[88:89], 0, v[136:137]
	v_lshl_add_u64 v[8:9], s[4:5], 0, v[8:9]
	v_lshl_add_u64 v[32:33], v[24:25], 0, v[136:137]
	v_cvt_pk_bf16_f32 v83, v74, v75
	global_store_dwordx4 v[96:97], v[80:83], off offset:16
	v_cvt_pk_bf16_f32 v19, v10, v11
	global_store_dwordx4 v[32:33], v[16:19], off offset:16
	s_and_b64 vcc, exec, s[0:1]
	v_lshl_add_u64 v[80:81], v[72:73], 0, v[136:137]
	v_lshl_add_u64 v[16:17], v[8:9], 0, v[136:137]
	s_mov_b32 s15, s6
	s_mov_b32 s70, s69
	s_mov_b64 s[16:17], s[10:11]
	s_mov_b64 s[12:13], s[8:9]
	v_cvt_pk_bf16_f32 v124, v124, v125
	v_cvt_pk_bf16_f32 v125, v126, v127
	v_cvt_pk_bf16_f32 v126, v120, v121
	v_cvt_pk_bf16_f32 v127, v122, v123
	global_store_dwordx4 v[142:143], v[124:127], off
	v_cvt_pk_bf16_f32 v104, v116, v117
	v_cvt_pk_bf16_f32 v105, v118, v119
	v_cvt_pk_bf16_f32 v106, v108, v109
	v_cvt_pk_bf16_f32 v107, v110, v111
	global_store_dwordx4 v[112:113], v[104:107], off
	v_cvt_pk_bf16_f32 v88, v100, v101
	v_cvt_pk_bf16_f32 v89, v102, v103
	v_cvt_pk_bf16_f32 v90, v92, v93
	v_cvt_pk_bf16_f32 v91, v94, v95
	global_store_dwordx4 v[96:97], v[88:91], off
	v_cvt_pk_bf16_f32 v72, v84, v85
	v_cvt_pk_bf16_f32 v73, v86, v87
	v_cvt_pk_bf16_f32 v74, v76, v77
	v_cvt_pk_bf16_f32 v75, v78, v79
	global_store_dwordx4 v[80:81], v[72:75], off
	v_cvt_pk_bf16_f32 v71, v66, v67
	global_store_dwordx4 v[80:81], v[68:71], off offset:16
	v_cvt_pk_bf16_f32 v60, v60, v61
	v_cvt_pk_bf16_f32 v61, v62, v63
	v_cvt_pk_bf16_f32 v62, v56, v57
	v_cvt_pk_bf16_f32 v63, v58, v59
	global_store_dwordx4 v[64:65], v[60:63], off
	v_cvt_pk_bf16_f32 v40, v52, v53
	v_cvt_pk_bf16_f32 v41, v54, v55
	v_cvt_pk_bf16_f32 v42, v44, v45
	v_cvt_pk_bf16_f32 v43, v46, v47
	global_store_dwordx4 v[48:49], v[40:43], off
	v_cvt_pk_bf16_f32 v24, v36, v37
	v_cvt_pk_bf16_f32 v25, v38, v39
	v_cvt_pk_bf16_f32 v26, v28, v29
	v_cvt_pk_bf16_f32 v27, v30, v31
	global_store_dwordx4 v[32:33], v[24:27], off
	v_cvt_pk_bf16_f32 v8, v20, v21
	v_cvt_pk_bf16_f32 v9, v22, v23
	v_cvt_pk_bf16_f32 v10, v12, v13
	v_cvt_pk_bf16_f32 v11, v14, v15
	global_store_dwordx4 v[16:17], v[8:11], off
	v_cvt_pk_bf16_f32 v4, v4, v5
	v_cvt_pk_bf16_f32 v5, v6, v7
	v_cvt_pk_bf16_f32 v6, v0, v1
	v_cvt_pk_bf16_f32 v7, v2, v3
	global_store_dwordx4 v[16:17], v[4:7], off offset:16
	s_cbranch_vccz .LBB0_1267
	s_waitcnt vmcnt(0)
	s_cmpk_gt_u32 s3, 0xff
	s_cbranch_scc1 .LBB0_1274
	s_barrier

; #define PG8_STAGE(bufoff, gbase, voff) do { _Pragma("unroll") for (int _i = 0; _i < 2; ++_i) \
;         __builtin_amdgcn_global_load_lds((const unsigned*)((const char*)(gbase) + (voff)[_i]), (LAS unsigned*)(lds + (bufoff) + ldsw + _i * 8192), 16, 0, 0); } while (0)
; #define PG8_LDA(dst, b, h) do { _Pragma("unroll") for (int m = 0; m < 4; ++m) _Pragma("unroll") for (int k = 0; k < 2; ++k) dst[m][k] = *(const LAS bf16x8*)(lds + PG8_SA(b, h) + aoff + m * 2048 + k * 1024); } while (0)
; #define PG8_LDB(dst, b, h) do { _Pragma("unroll") for (int n = 0; n < 2; ++n) _Pragma("unroll") for (int k = 0; k < 2; ++k) dst[n][k] = *(const LAS bf16x8*)(lds + PG8_SB(b, h) + boff + n * 2048 + k * 1024); } while (0)
; #define PG8_WAIT_V(n) asm volatile("s_waitcnt vmcnt(" #n ")" ::: "memory")
; #define PG8_WAIT_L(n) asm volatile("s_waitcnt lgkmcnt(" #n ")" ::: "memory")
; #define PG8_BAR __builtin_amdgcn_s_barrier()
; #define PG8_SCHED __builtin_amdgcn_sched_barrier(0)
; template <class Epi>
; __device__ __forceinline__ void gemm_phase(LAS unsigned char* lds, const Gemm g, const StaticOrder& S, const Epi& E) {
;     ...
;             const bool last = (t == nt - 2);
;             const char* a1 = cA + (size_t)(t + 1) * kstep;
;             const char* a2 = last ? nA : cA + (size_t)(t + 2) * kstep; const char* b2 = last ? nB : cB + (size_t)(t + 2) * kstep;
;             const char* a3 = a2 + kstep; const char* b3 = b2 + kstep;
;             PG8_LDB(B0, 0, 0); PG8_SCHED; PG8_LDA(At, 0, 0); PG8_STAGE(PG8_SA(1, 1), a1 + hA, voffA);
;             PG8_WAIT_L(8); PG8_BAR; PG8_WAIT_L(0); PG8_MMA(0, 0, At, B0); PG8_BAR; PG8_SCHED;
;             PG8_LDB(B1, 0, 1); PG8_STAGE(PG8_SB(0, 0), b2, voffB);
;             PG8_BAR; PG8_WAIT_L(0); PG8_MMA(0, 1, At, B1); PG8_BAR;
;             PG8_LDA(At, 0, 1); PG8_STAGE(PG8_SA(0, 0), a2, voffA);
;             PG8_BAR; PG8_WAIT_L(0); PG8_MMA(1, 0, At, B0); PG8_BAR; PG8_SCHED;
;             PG8_STAGE(PG8_SB(0, 1), b2 + hB, voffB);
;             PG8_WAIT_V(6); PG8_BAR; PG8_MMA(1, 1, At, B1); PG8_BAR;
;             PG8_LDB(B0, 1, 0); PG8_SCHED; PG8_LDA(At, 1, 0); PG8_STAGE(PG8_SA(0, 1), a2 + hA, voffA);
;             PG8_WAIT_L(8); PG8_BAR; PG8_WAIT_L(0); PG8_MMA(0, 0, At, B0); PG8_BAR; PG8_SCHED;
;             PG8_LDB(B1, 1, 1); PG8_STAGE(PG8_SB(1, 0), b3, voffB);
;             PG8_BAR; PG8_WAIT_L(0); PG8_MMA(0, 1, At, B1); PG8_BAR;
.LBB0_1394:
	s_add_u32 s20, s16, 0xfffc0080
	s_addc_u32 s21, s17, -1
	s_add_i32 s26, 0, 0x10000
	v_add_u32_e32 v139, s26, v137
	ds_read_b128 v[140:143], v139
	ds_read_b128 v[146:149], v139 offset:1024
	ds_read_b128 v[150:153], v139 offset:2048
	ds_read_b128 v[154:157], v139 offset:3072
	s_cmp_eq_u32 s85, 12
	s_cselect_b32 s35, s82, s21
	s_cselect_b32 s34, s83, s20
	s_cselect_b32 s21, s9, s84
	s_cselect_b32 s20, s24, s25
	s_add_i32 m0, s70, 0xc000
	ds_read_b128 v[158:161], v138
	ds_read_b128 v[162:165], v138 offset:1024
	ds_read_b128 v[166:169], v138 offset:2048
	ds_read_b128 v[170:173], v138 offset:3072
	ds_read_b128 v[174:177], v138 offset:4096
	ds_read_b128 v[178:181], v138 offset:5120
	ds_read_b128 v[182:185], v138 offset:6144
	ds_read_b128 v[186:189], v138 offset:7168
	global_load_lds_dwordx4 v132, s[16:17]
	s_add_i32 m0, s70, 0xe000
	s_nop 0
	global_load_lds_dwordx4 v134, s[16:17]
	s_waitcnt lgkmcnt(8)
	s_barrier
	s_waitcnt lgkmcnt(0)
	v_mfma_f32_16x16x32_bf16 v[120:123], v[140:143], v[158:161], v[120:123]
	v_mfma_f32_16x16x32_bf16 v[124:127], v[150:153], v[158:161], v[124:127]
	v_mfma_f32_16x16x32_bf16 v[104:107], v[140:143], v[166:169], v[104:107]
	v_mfma_f32_16x16x32_bf16 v[108:111], v[150:153], v[166:169], v[108:111]
	v_mfma_f32_16x16x32_bf16 v[88:91], v[140:143], v[174:177], v[88:91]
	v_mfma_f32_16x16x32_bf16 v[92:95], v[150:153], v[174:177], v[92:95]
	v_mfma_f32_16x16x32_bf16 v[72:75], v[140:143], v[182:185], v[72:75]
	v_mfma_f32_16x16x32_bf16 v[76:79], v[150:153], v[182:185], v[76:79]
	v_mfma_f32_16x16x32_bf16 v[120:123], v[146:149], v[162:165], v[120:123]
	v_mfma_f32_16x16x32_bf16 v[124:127], v[154:157], v[162:165], v[124:127]
	v_mfma_f32_16x16x32_bf16 v[104:107], v[146:149], v[170:173], v[104:107]
	v_mfma_f32_16x16x32_bf16 v[108:111], v[154:157], v[170:173], v[108:111]
	v_mfma_f32_16x16x32_bf16 v[88:91], v[146:149], v[178:181], v[88:91]
	v_mfma_f32_16x16x32_bf16 v[92:95], v[154:157], v[178:181], v[92:95]
	v_mfma_f32_16x16x32_bf16 v[72:75], v[146:149], v[186:189], v[72:75]
	v_mfma_f32_16x16x32_bf16 v[76:79], v[154:157], v[186:189], v[76:79]
	s_barrier
	s_add_i32 s28, 0, 0x14000
	s_add_i32 s26, s26, s64
	v_add_u32_e32 v139, s28, v137
	v_lshl_add_u64 v[192:193], s[20:21], 0, v[130:131]
	s_mov_b32 m0, s26
	ds_read_b128 v[196:199], v139
	ds_read_b128 v[200:203], v139 offset:1024
	ds_read_b128 v[204:207], v139 offset:2048
	ds_read_b128 v[214:217], v139 offset:3072
	global_load_lds_dwordx4 v[192:193], off
	s_add_i32 m0, s26, 0x2000
	v_lshl_add_u64 v[218:219], s[20:21], 0, v[128:129]
	global_load_lds_dwordx4 v[218:219], off
	s_barrier
	s_waitcnt lgkmcnt(0)
	v_mfma_f32_16x16x32_bf16 v[112:115], v[196:199], v[158:161], v[112:115]
	v_mfma_f32_16x16x32_bf16 v[116:119], v[204:207], v[158:161], v[116:119]
	v_mfma_f32_16x16x32_bf16 v[96:99], v[196:199], v[166:169], v[96:99]
	v_mfma_f32_16x16x32_bf16 v[100:103], v[204:207], v[166:169], v[100:103]
	v_mfma_f32_16x16x32_bf16 v[80:83], v[196:199], v[174:177], v[80:83]
	v_mfma_f32_16x16x32_bf16 v[84:87], v[204:207], v[174:177], v[84:87]
	v_mfma_f32_16x16x32_bf16 v[64:67], v[196:199], v[182:185], v[64:67]
	v_mfma_f32_16x16x32_bf16 v[68:71], v[204:207], v[182:185], v[68:71]
	v_mfma_f32_16x16x32_bf16 v[112:115], v[200:203], v[162:165], v[112:115]
	v_mfma_f32_16x16x32_bf16 v[116:119], v[214:217], v[162:165], v[116:119]
	v_mfma_f32_16x16x32_bf16 v[96:99], v[200:203], v[170:173], v[96:99]
	v_mfma_f32_16x16x32_bf16 v[100:103], v[214:217], v[170:173], v[100:103]
	v_mfma_f32_16x16x32_bf16 v[80:83], v[200:203], v[178:181], v[80:83]
	v_mfma_f32_16x16x32_bf16 v[84:87], v[214:217], v[178:181], v[84:87]
	v_mfma_f32_16x16x32_bf16 v[64:67], v[200:203], v[186:189], v[64:67]
	v_mfma_f32_16x16x32_bf16 v[68:71], v[214:217], v[186:189], v[68:71]
	s_mov_b32 m0, s70
	v_lshl_add_u64 v[220:221], s[34:35], 0, v[130:131]
	s_barrier
	ds_read_b128 v[158:161], v138 offset:16384
	ds_read_b128 v[162:165], v138 offset:17408
	ds_read_b128 v[166:169], v138 offset:18432
	ds_read_b128 v[170:173], v138 offset:19456
	ds_read_b128 v[174:177], v138 offset:20480
	ds_read_b128 v[178:181], v138 offset:21504
	ds_read_b128 v[182:185], v138 offset:22528
	ds_read_b128 v[186:189], v138 offset:23552
	global_load_lds_dwordx4 v[220:221], off
	s_mov_b32 m0, s71
	v_lshl_add_u64 v[222:223], s[34:35], 0, v[128:129]
	global_load_lds_dwordx4 v[222:223], off
	s_barrier
	s_waitcnt lgkmcnt(0)
	v_mfma_f32_16x16x32_bf16 v[56:59], v[140:143], v[158:161], v[56:59]
	v_mfma_f32_16x16x32_bf16 v[60:63], v[150:153], v[158:161], v[60:63]
	v_mfma_f32_16x16x32_bf16 v[40:43], v[140:143], v[166:169], v[40:43]
	v_mfma_f32_16x16x32_bf16 v[44:47], v[150:153], v[166:169], v[44:47]
	v_mfma_f32_16x16x32_bf16 v[24:27], v[140:143], v[174:177], v[24:27]
	v_mfma_f32_16x16x32_bf16 v[28:31], v[150:153], v[174:177], v[28:31]
	v_mfma_f32_16x16x32_bf16 v[8:11], v[140:143], v[182:185], v[8:11]
	v_mfma_f32_16x16x32_bf16 v[12:15], v[150:153], v[182:185], v[12:15]
	v_mfma_f32_16x16x32_bf16 v[56:59], v[146:149], v[162:165], v[56:59]
	v_mfma_f32_16x16x32_bf16 v[60:63], v[154:157], v[162:165], v[60:63]
	v_mfma_f32_16x16x32_bf16 v[40:43], v[146:149], v[170:173], v[40:43]
	v_mfma_f32_16x16x32_bf16 v[44:47], v[154:157], v[170:173], v[44:47]
	v_mfma_f32_16x16x32_bf16 v[24:27], v[146:149], v[178:181], v[24:27]
	v_mfma_f32_16x16x32_bf16 v[28:31], v[154:157], v[178:181], v[28:31]
	v_mfma_f32_16x16x32_bf16 v[8:11], v[146:149], v[186:189], v[8:11]
	v_mfma_f32_16x16x32_bf16 v[12:15], v[154:157], v[186:189], v[12:15]
	s_barrier
	s_add_u32 s26, s20, 0x40000
	s_addc_u32 s27, s21, 0
	s_add_i32 s28, s28, s64
	s_mov_b32 m0, s28
	s_nop 0
	global_load_lds_dwordx4 v130, s[26:27]
	s_add_i32 m0, s28, 0x2000
	s_nop 0
	global_load_lds_dwordx4 v128, s[26:27]
	s_waitcnt vmcnt(6)
	s_barrier
; #define PG8_STAGE(bufoff, gbase, voff) do { _Pragma("unroll") for (int _i = 0; _i < 2; ++_i) \
;         __builtin_amdgcn_global_load_lds((const unsigned*)((const char*)(gbase) + (voff)[_i]), (LAS unsigned*)(lds + (bufoff) + ldsw + _i * 8192), 16, 0, 0); } while (0)
; #define PG8_LDA(dst, b, h) do { _Pragma("unroll") for (int m = 0; m < 4; ++m) _Pragma("unroll") for (int k = 0; k < 2; ++k) dst[m][k] = *(const LAS bf16x8*)(lds + PG8_SA(b, h) + aoff + m * 2048 + k * 1024); } while (0)
; #define PG8_LDB(dst, b, h) do { _Pragma("unroll") for (int n = 0; n < 2; ++n) _Pragma("unroll") for (int k = 0; k < 2; ++k) dst[n][k] = *(const LAS bf16x8*)(lds + PG8_SB(b, h) + boff + n * 2048 + k * 1024); } while (0)
; #define PG8_MMA(ai, bj, At, Bt) do { __builtin_amdgcn_s_setprio(1); _Pragma("unroll") for (int m = 0; m < 4; ++m) _Pragma("unroll") for (int n = 0; n < 2; ++n) _Pragma("unroll") for (int k = 0; k < 2; ++k) \
;         acc[ai][bj][m][n] = __builtin_amdgcn_mfma_f32_16x16x32_bf16(Bt[n][k], At[m][k], acc[ai][bj][m][n], 0, 0, 0); __builtin_amdgcn_s_setprio(0); } while (0)
; #define PG8_WAIT_V(n) asm volatile("s_waitcnt vmcnt(" #n ")" ::: "memory")
; #define PG8_WAIT_L(n) asm volatile("s_waitcnt lgkmcnt(" #n ")" ::: "memory")
; #define PG8_BAR __builtin_amdgcn_s_barrier()
; #define PG8_SCHED __builtin_amdgcn_sched_barrier(0)
; template <class Epi>
; __device__ __forceinline__ void gemm_phase(LAS unsigned char* lds, const Gemm g, const StaticOrder& S, const Epi& E) {
;     ...
;             PG8_WAIT_V(6); PG8_BAR; PG8_MMA(1, 1, At, B1); PG8_BAR;
;             PG8_LDB(B0, 1, 0); PG8_SCHED; PG8_LDA(At, 1, 0); PG8_STAGE(PG8_SA(0, 1), a2 + hA, voffA);
;             PG8_WAIT_L(8); PG8_BAR; PG8_WAIT_L(0); PG8_MMA(0, 0, At, B0); PG8_BAR; PG8_SCHED;
;             PG8_LDB(B1, 1, 1); PG8_STAGE(PG8_SB(1, 0), b3, voffB);
;             PG8_BAR; PG8_WAIT_L(0); PG8_MMA(0, 1, At, B1); PG8_BAR;
;             PG8_LDA(At, 1, 1); PG8_STAGE(PG8_SA(1, 0), a3, voffA);
;             PG8_BAR; PG8_WAIT_L(0); PG8_MMA(1, 0, At, B0); PG8_BAR; PG8_SCHED;
	v_mfma_f32_16x16x32_bf16 v[48:51], v[196:199], v[158:161], v[48:51]
	v_mfma_f32_16x16x32_bf16 v[52:55], v[204:207], v[158:161], v[52:55]
	v_mfma_f32_16x16x32_bf16 v[32:35], v[196:199], v[166:169], v[32:35]
	v_mfma_f32_16x16x32_bf16 v[36:39], v[204:207], v[166:169], v[36:39]
	v_mfma_f32_16x16x32_bf16 v[16:19], v[196:199], v[174:177], v[16:19]
	v_mfma_f32_16x16x32_bf16 v[20:23], v[204:207], v[174:177], v[20:23]
	v_mfma_f32_16x16x32_bf16 v[0:3], v[196:199], v[182:185], v[0:3]
	v_mfma_f32_16x16x32_bf16 v[4:7], v[204:207], v[182:185], v[4:7]
	v_mfma_f32_16x16x32_bf16 v[48:51], v[200:203], v[162:165], v[48:51]
	v_mfma_f32_16x16x32_bf16 v[52:55], v[214:217], v[162:165], v[52:55]
	v_mfma_f32_16x16x32_bf16 v[32:35], v[200:203], v[170:173], v[32:35]
	v_mfma_f32_16x16x32_bf16 v[36:39], v[214:217], v[170:173], v[36:39]
	v_mfma_f32_16x16x32_bf16 v[16:19], v[200:203], v[178:181], v[16:19]
	v_mfma_f32_16x16x32_bf16 v[20:23], v[214:217], v[178:181], v[20:23]
	v_mfma_f32_16x16x32_bf16 v[0:3], v[200:203], v[186:189], v[0:3]
	v_mfma_f32_16x16x32_bf16 v[4:7], v[214:217], v[186:189], v[4:7]
	s_add_i32 s28, 0, 0x18000
	v_add_u32_e32 v139, s28, v137
	s_barrier
	ds_read_b128 v[140:143], v139
	ds_read_b128 v[146:149], v139 offset:1024
	ds_read_b128 v[150:153], v139 offset:2048
	ds_read_b128 v[154:157], v139 offset:3072
	s_add_u32 s26, s34, 0x40000
	s_addc_u32 s27, s35, 0
	s_mov_b32 m0, s72
	ds_read_b128 v[158:161], v138 offset:32768
	ds_read_b128 v[162:165], v138 offset:33792
	ds_read_b128 v[166:169], v138 offset:34816
	ds_read_b128 v[170:173], v138 offset:35840
	ds_read_b128 v[174:177], v138 offset:36864
	ds_read_b128 v[178:181], v138 offset:37888
	ds_read_b128 v[182:185], v138 offset:38912
	ds_read_b128 v[186:189], v138 offset:39936
	global_load_lds_dwordx4 v130, s[26:27]
	s_mov_b32 m0, s76
	s_nop 0
	global_load_lds_dwordx4 v128, s[26:27]
	s_waitcnt lgkmcnt(8)
	s_barrier
	s_waitcnt lgkmcnt(0)
	v_mfma_f32_16x16x32_bf16 v[120:123], v[140:143], v[158:161], v[120:123]
	v_mfma_f32_16x16x32_bf16 v[124:127], v[150:153], v[158:161], v[124:127]
	v_mfma_f32_16x16x32_bf16 v[104:107], v[140:143], v[166:169], v[104:107]
	v_mfma_f32_16x16x32_bf16 v[108:111], v[150:153], v[166:169], v[108:111]
	v_mfma_f32_16x16x32_bf16 v[88:91], v[140:143], v[174:177], v[88:91]
	v_mfma_f32_16x16x32_bf16 v[92:95], v[150:153], v[174:177], v[92:95]
	v_mfma_f32_16x16x32_bf16 v[72:75], v[140:143], v[182:185], v[72:75]
	v_mfma_f32_16x16x32_bf16 v[76:79], v[150:153], v[182:185], v[76:79]
	v_mfma_f32_16x16x32_bf16 v[120:123], v[146:149], v[162:165], v[120:123]
	v_mfma_f32_16x16x32_bf16 v[124:127], v[154:157], v[162:165], v[124:127]
	v_mfma_f32_16x16x32_bf16 v[104:107], v[146:149], v[170:173], v[104:107]
	v_mfma_f32_16x16x32_bf16 v[108:111], v[154:157], v[170:173], v[108:111]
	v_mfma_f32_16x16x32_bf16 v[88:91], v[146:149], v[178:181], v[88:91]
	v_mfma_f32_16x16x32_bf16 v[92:95], v[154:157], v[178:181], v[92:95]
	v_mfma_f32_16x16x32_bf16 v[72:75], v[146:149], v[186:189], v[72:75]
	v_mfma_f32_16x16x32_bf16 v[76:79], v[154:157], v[186:189], v[76:79]
	s_barrier
	s_add_i32 s26, 0, 0x1c000
	s_add_i32 s27, s28, s64
	v_add_u32_e32 v139, s26, v137
	v_lshl_add_u64 v[192:193], v[192:193], 0, s[88:89]
	s_mov_b32 m0, s27
	ds_read_b128 v[196:199], v139
	ds_read_b128 v[200:203], v139 offset:1024
	ds_read_b128 v[204:207], v139 offset:2048
	ds_read_b128 v[214:217], v139 offset:3072
	global_load_lds_dwordx4 v[192:193], off
	s_add_i32 m0, s27, 0x2000
	v_lshl_add_u64 v[192:193], v[218:219], 0, s[88:89]
	global_load_lds_dwordx4 v[192:193], off
	s_barrier
	s_waitcnt lgkmcnt(0)
	v_mfma_f32_16x16x32_bf16 v[112:115], v[196:199], v[158:161], v[112:115]
	v_mfma_f32_16x16x32_bf16 v[116:119], v[204:207], v[158:161], v[116:119]
	v_mfma_f32_16x16x32_bf16 v[96:99], v[196:199], v[166:169], v[96:99]
	v_mfma_f32_16x16x32_bf16 v[100:103], v[204:207], v[166:169], v[100:103]
	v_mfma_f32_16x16x32_bf16 v[80:83], v[196:199], v[174:177], v[80:83]
	v_mfma_f32_16x16x32_bf16 v[84:87], v[204:207], v[174:177], v[84:87]
	v_mfma_f32_16x16x32_bf16 v[64:67], v[196:199], v[182:185], v[64:67]
	v_mfma_f32_16x16x32_bf16 v[68:71], v[204:207], v[182:185], v[68:71]
	v_mfma_f32_16x16x32_bf16 v[112:115], v[200:203], v[162:165], v[112:115]
	v_mfma_f32_16x16x32_bf16 v[116:119], v[214:217], v[162:165], v[116:119]
	v_mfma_f32_16x16x32_bf16 v[96:99], v[200:203], v[170:173], v[96:99]
	v_mfma_f32_16x16x32_bf16 v[100:103], v[214:217], v[170:173], v[100:103]
	v_mfma_f32_16x16x32_bf16 v[80:83], v[200:203], v[178:181], v[80:83]
	v_mfma_f32_16x16x32_bf16 v[84:87], v[214:217], v[178:181], v[84:87]
	v_mfma_f32_16x16x32_bf16 v[64:67], v[200:203], v[186:189], v[64:67]
	v_mfma_f32_16x16x32_bf16 v[68:71], v[214:217], v[186:189], v[68:71]
	s_mov_b32 m0, s77
	v_lshl_add_u64 v[192:193], v[220:221], 0, s[88:89]
	s_barrier
	ds_read_b128 v[158:161], v138 offset:49152
	ds_read_b128 v[162:165], v138 offset:50176
	ds_read_b128 v[166:169], v138 offset:51200
	ds_read_b128 v[170:173], v138 offset:52224
	ds_read_b128 v[174:177], v138 offset:53248
	ds_read_b128 v[178:181], v138 offset:54272
	ds_read_b128 v[182:185], v138 offset:55296
	ds_read_b128 v[186:189], v138 offset:56320
	global_load_lds_dwordx4 v[192:193], off
	s_mov_b32 m0, s78
	v_lshl_add_u64 v[192:193], v[222:223], 0, s[88:89]
	global_load_lds_dwordx4 v[192:193], off
	s_barrier
; __device__ __forceinline__ unsigned pk2(float lo, float hi) { unsigned r; asm("v_cvt_pk_bf16_f32 %0, %1, %2" : "=v"(r) : "v"(lo), "v"(hi)); return r; }
; #define PG8_STAGE(bufoff, gbase, voff) do { _Pragma("unroll") for (int _i = 0; _i < 2; ++_i) \
;         __builtin_amdgcn_global_load_lds((const unsigned*)((const char*)(gbase) + (voff)[_i]), (LAS unsigned*)(lds + (bufoff) + ldsw + _i * 8192), 16, 0, 0); } while (0)
; #define PG8_MMA(ai, bj, At, Bt) do { __builtin_amdgcn_s_setprio(1); _Pragma("unroll") for (int m = 0; m < 4; ++m) _Pragma("unroll") for (int n = 0; n < 2; ++n) _Pragma("unroll") for (int k = 0; k < 2; ++k) \
;         acc[ai][bj][m][n] = __builtin_amdgcn_mfma_f32_16x16x32_bf16(Bt[n][k], At[m][k], acc[ai][bj][m][n], 0, 0, 0); __builtin_amdgcn_s_setprio(0); } while (0)
; #define PG8_WAIT_V(n) asm volatile("s_waitcnt vmcnt(" #n ")" ::: "memory")
; #define PG8_WAIT_L(n) asm volatile("s_waitcnt lgkmcnt(" #n ")" ::: "memory")
; #define PG8_BAR __builtin_amdgcn_s_barrier()
; #define PG8_SCHED __builtin_amdgcn_sched_barrier(0)
;     static __device__ __forceinline__ float sg(float g, float u) { return (g * u) * __builtin_amdgcn_rcpf(1.f + __builtin_amdgcn_exp2f(-g)); }
; template <class Epi>
; __device__ __forceinline__ void gemm_phase(LAS unsigned char* lds, const Gemm g, const StaticOrder& S, const Epi& E) {
;     ...
;             PG8_BAR; PG8_WAIT_L(0); PG8_MMA(1, 0, At, B0); PG8_BAR; PG8_SCHED;
;             PG8_STAGE(PG8_SB(1, 1), b3 + hB, voffB);
;             PG8_WAIT_V(6); PG8_BAR; PG8_MMA(1, 1, At, B1); PG8_BAR;
;     __device__ __forceinline__ void operator()(const f32x4 (&acc)[2][2][4][2], const Unit& u, int wr, int wc, int fr, int fq) const {
; #pragma unroll
;         for (int ai = 0; ai < 2; ++ai)
; #pragma unroll
;             for (int m = 0; m < 4; ++m) {
;                 const int row = u.pm * BM + ai * HALF + wr * 64 + m * 16 + fr;
;                 const f32x4 g0 = acc[ai][0][m][0], u0 = acc[ai][0][m][1], g1 = acc[ai][1][m][0], u1 = acc[ai][1][m][1];
;                 u32x4 o; o.x = pk2(sg(g0[0], u0[0]), sg(g0[1], u0[1])); o.y = pk2(sg(g0[2], u0[2]), sg(g0[3], u0[3]));
;                 o.z = pk2(sg(g1[0], u1[0]), sg(g1[1], u1[1])); o.w = pk2(sg(g1[2], u1[2]), sg(g1[3], u1[3]));
;                 *(u32x4*)(O + (size_t)row * DFF + u.pn * 128 + wc * 32 + fq * 8) = o;
	s_waitcnt lgkmcnt(0)
	v_mfma_f32_16x16x32_bf16 v[56:59], v[140:143], v[158:161], v[56:59]
	v_mfma_f32_16x16x32_bf16 v[60:63], v[150:153], v[158:161], v[60:63]
	v_mfma_f32_16x16x32_bf16 v[40:43], v[140:143], v[166:169], v[40:43]
	v_mfma_f32_16x16x32_bf16 v[44:47], v[150:153], v[166:169], v[44:47]
	v_mfma_f32_16x16x32_bf16 v[24:27], v[140:143], v[174:177], v[24:27]
	v_mfma_f32_16x16x32_bf16 v[28:31], v[150:153], v[174:177], v[28:31]
	v_mfma_f32_16x16x32_bf16 v[8:11], v[140:143], v[182:185], v[8:11]
	v_mfma_f32_16x16x32_bf16 v[12:15], v[150:153], v[182:185], v[12:15]
	v_mfma_f32_16x16x32_bf16 v[56:59], v[146:149], v[162:165], v[56:59]
	v_mfma_f32_16x16x32_bf16 v[60:63], v[154:157], v[162:165], v[60:63]
	v_mfma_f32_16x16x32_bf16 v[40:43], v[146:149], v[170:173], v[40:43]
	v_mfma_f32_16x16x32_bf16 v[44:47], v[154:157], v[170:173], v[44:47]
	v_mfma_f32_16x16x32_bf16 v[24:27], v[146:149], v[178:181], v[24:27]
	v_mfma_f32_16x16x32_bf16 v[28:31], v[154:157], v[178:181], v[28:31]
	v_mfma_f32_16x16x32_bf16 v[8:11], v[146:149], v[186:189], v[8:11]
	v_mfma_f32_16x16x32_bf16 v[12:15], v[154:157], v[186:189], v[12:15]
	s_barrier
	s_add_u32 s20, s20, 0x40080
	s_addc_u32 s21, s21, 0
	s_add_i32 s26, s26, s64
	s_mov_b32 m0, s26
	s_nop 0
	global_load_lds_dwordx4 v130, s[20:21]
	s_add_i32 m0, s26, 0x2000
	s_nop 0
	global_load_lds_dwordx4 v128, s[20:21]
	s_waitcnt vmcnt(6)
	s_barrier
	v_mfma_f32_16x16x32_bf16 v[48:51], v[196:199], v[158:161], v[48:51]
	v_mfma_f32_16x16x32_bf16 v[52:55], v[204:207], v[158:161], v[52:55]
	v_mfma_f32_16x16x32_bf16 v[32:35], v[196:199], v[166:169], v[32:35]
	v_mfma_f32_16x16x32_bf16 v[36:39], v[204:207], v[166:169], v[36:39]
	v_mfma_f32_16x16x32_bf16 v[16:19], v[196:199], v[174:177], v[16:19]
	v_mfma_f32_16x16x32_bf16 v[20:23], v[204:207], v[174:177], v[20:23]
	v_mfma_f32_16x16x32_bf16 v[0:3], v[196:199], v[182:185], v[0:3]
	v_mfma_f32_16x16x32_bf16 v[4:7], v[204:207], v[182:185], v[4:7]
	v_mfma_f32_16x16x32_bf16 v[48:51], v[200:203], v[162:165], v[48:51]
	v_mfma_f32_16x16x32_bf16 v[52:55], v[214:217], v[162:165], v[52:55]
	v_mfma_f32_16x16x32_bf16 v[32:35], v[200:203], v[170:173], v[32:35]
	v_mfma_f32_16x16x32_bf16 v[36:39], v[214:217], v[170:173], v[36:39]
	v_mfma_f32_16x16x32_bf16 v[16:19], v[200:203], v[178:181], v[16:19]
	v_mfma_f32_16x16x32_bf16 v[20:23], v[214:217], v[178:181], v[20:23]
	v_mfma_f32_16x16x32_bf16 v[0:3], v[200:203], v[186:189], v[0:3]
	v_mfma_f32_16x16x32_bf16 v[4:7], v[214:217], v[186:189], v[4:7]
	s_add_i32 s85, s85, 2
	s_add_u32 s16, s16, 0x100
	s_addc_u32 s17, s17, 0
	s_add_u32 s25, s25, 0x100
	s_addc_u32 s84, s84, 0
	s_cmp_gt_u32 s85, 13
	s_barrier
	s_cbranch_scc0 .LBB0_1394
	v_mul_f32_e32 v124, v120, v124
	v_exp_f32_e64 v120, -v120
	v_mul_f32_e32 v108, v104, v108
	v_exp_f32_e64 v104, -v104
	v_mul_f32_e32 v92, v88, v92
	v_add_f32_e32 v120, 1.0, v120
	v_rcp_f32_e32 v120, v120
	v_add_f32_e32 v104, 1.0, v104
	v_rcp_f32_e32 v104, v104
	v_exp_f32_e64 v88, -v88
	v_mul_f32_e32 v120, v124, v120
	v_mul_f32_e32 v124, v121, v125
	v_exp_f32_e64 v121, -v121
	v_mul_f32_e32 v104, v108, v104
	v_mul_f32_e32 v108, v105, v109
	v_exp_f32_e64 v105, -v105
	v_add_f32_e32 v121, 1.0, v121
	v_rcp_f32_e32 v121, v121
	v_add_f32_e32 v88, 1.0, v88
	v_rcp_f32_e32 v88, v88
	v_mul_f32_e32 v76, v72, v76
	v_exp_f32_e64 v72, -v72
	v_mul_f32_e32 v121, v124, v121
	v_cvt_pk_bf16_f32 v120, v120, v121
	v_mul_f32_e32 v121, v122, v126
	v_exp_f32_e64 v122, -v122
	v_mul_f32_e32 v116, v112, v116
	v_exp_f32_e64 v112, -v112
	v_add_f32_e32 v105, 1.0, v105
	v_rcp_f32_e32 v105, v105
	v_mul_f32_e32 v88, v92, v88
	v_mul_f32_e32 v92, v89, v93
	v_exp_f32_e64 v89, -v89
	v_add_f32_e32 v72, 1.0, v72
	v_rcp_f32_e32 v72, v72
	v_mul_f32_e32 v60, v56, v60
	v_exp_f32_e64 v56, -v56
	v_add_f32_e32 v122, 1.0, v122
	v_add_f32_e32 v112, 1.0, v112
	v_rcp_f32_e32 v122, v122
	v_rcp_f32_e32 v112, v112
	v_mul_f32_e32 v105, v108, v105
	v_add_f32_e32 v89, 1.0, v89
	v_cvt_pk_bf16_f32 v104, v104, v105
	v_mul_f32_e32 v105, v106, v110
	v_exp_f32_e64 v106, -v106
	v_mul_f32_e32 v100, v96, v100
	v_exp_f32_e64 v96, -v96
	v_rcp_f32_e32 v89, v89
	v_mul_f32_e32 v72, v76, v72
	v_mul_f32_e32 v76, v73, v77
	v_exp_f32_e64 v73, -v73
	v_add_f32_e32 v56, 1.0, v56
	v_rcp_f32_e32 v56, v56
	v_mul_f32_e32 v44, v40, v44
	v_exp_f32_e64 v40, -v40
	v_mul_f32_e32 v121, v121, v122
	v_mul_f32_e32 v122, v123, v127
	v_exp_f32_e64 v123, -v123
	v_mul_f32_e32 v112, v116, v112
	v_mul_f32_e32 v116, v113, v117
	v_exp_f32_e64 v113, -v113
	v_add_f32_e32 v106, 1.0, v106
	v_add_f32_e32 v96, 1.0, v96
	v_mul_f32_e32 v89, v92, v89
	v_add_f32_e32 v73, 1.0, v73
	v_rcp_f32_e32 v106, v106
	v_rcp_f32_e32 v96, v96
	v_cvt_pk_bf16_f32 v88, v88, v89
	v_mul_f32_e32 v89, v90, v94
	v_exp_f32_e64 v90, -v90
	v_mul_f32_e32 v84, v80, v84
	v_exp_f32_e64 v80, -v80
	v_rcp_f32_e32 v73, v73
	v_mul_f32_e32 v56, v60, v56
	v_mul_f32_e32 v60, v57, v61
	v_exp_f32_e64 v57, -v57
	v_add_f32_e32 v40, 1.0, v40
	v_rcp_f32_e32 v40, v40
	v_mul_f32_e32 v28, v24, v28
	v_exp_f32_e64 v24, -v24
	v_add_f32_e32 v123, 1.0, v123
	v_add_f32_e32 v113, 1.0, v113
	v_rcp_f32_e32 v123, v123
	v_rcp_f32_e32 v113, v113
	v_mul_f32_e32 v105, v105, v106
	v_mul_f32_e32 v106, v107, v111
	v_exp_f32_e64 v107, -v107
	v_mul_f32_e32 v96, v100, v96
	v_mul_f32_e32 v100, v97, v101
	v_exp_f32_e64 v97, -v97
	v_add_f32_e32 v90, 1.0, v90
	v_add_f32_e32 v80, 1.0, v80
	v_mul_f32_e32 v73, v76, v73
	v_add_f32_e32 v57, 1.0, v57
	v_rcp_f32_e32 v90, v90
	v_rcp_f32_e32 v80, v80
	v_cvt_pk_bf16_f32 v72, v72, v73
	v_mul_f32_e32 v73, v74, v78
	v_exp_f32_e64 v74, -v74
	v_mul_f32_e32 v68, v64, v68
	v_exp_f32_e64 v64, -v64
	v_rcp_f32_e32 v57, v57
	v_mul_f32_e32 v40, v44, v40
	v_mul_f32_e32 v44, v41, v45
; __device__ __forceinline__ unsigned pk2(float lo, float hi) { unsigned r; asm("v_cvt_pk_bf16_f32 %0, %1, %2" : "=v"(r) : "v"(lo), "v"(hi)); return r; }
;     static __device__ __forceinline__ float sg(float g, float u) { return (g * u) * __builtin_amdgcn_rcpf(1.f + __builtin_amdgcn_exp2f(-g)); }
;     __device__ __forceinline__ void operator()(const f32x4 (&acc)[2][2][4][2], const Unit& u, int wr, int wc, int fr, int fq) const {
; #pragma unroll
;         for (int ai = 0; ai < 2; ++ai)
; #pragma unroll
;             for (int m = 0; m < 4; ++m) {
;                 const int row = u.pm * BM + ai * HALF + wr * 64 + m * 16 + fr;
;                 const f32x4 g0 = acc[ai][0][m][0], u0 = acc[ai][0][m][1], g1 = acc[ai][1][m][0], u1 = acc[ai][1][m][1];
;                 u32x4 o; o.x = pk2(sg(g0[0], u0[0]), sg(g0[1], u0[1])); o.y = pk2(sg(g0[2], u0[2]), sg(g0[3], u0[3]));
;                 o.z = pk2(sg(g1[0], u1[0]), sg(g1[1], u1[1])); o.w = pk2(sg(g1[2], u1[2]), sg(g1[3], u1[3]));
;                 *(u32x4*)(O + (size_t)row * DFF + u.pn * 128 + wc * 32 + fq * 8) = o;
;             }
	v_exp_f32_e64 v41, -v41
	v_add_f32_e32 v24, 1.0, v24
	v_rcp_f32_e32 v24, v24
	v_mul_f32_e32 v12, v8, v12
	v_exp_f32_e64 v8, -v8
	v_mul_f32_e32 v122, v122, v123
	v_mul_f32_e32 v113, v116, v113
	v_cvt_pk_bf16_f32 v121, v121, v122
	v_cvt_pk_bf16_f32 v122, v112, v113
	v_exp_f32_e64 v113, -v114
	v_add_f32_e32 v107, 1.0, v107
	v_add_f32_e32 v97, 1.0, v97
	v_mul_f32_e32 v112, v114, v118
	v_exp_f32_e64 v114, -v115
	v_rcp_f32_e32 v107, v107
	v_rcp_f32_e32 v97, v97
	v_mul_f32_e32 v89, v89, v90
	v_mul_f32_e32 v90, v91, v95
	v_exp_f32_e64 v91, -v91
	v_mul_f32_e32 v80, v84, v80
	v_mul_f32_e32 v84, v81, v85
	v_exp_f32_e64 v81, -v81
	v_add_f32_e32 v74, 1.0, v74
	v_add_f32_e32 v64, 1.0, v64
	v_mul_f32_e32 v57, v60, v57
	v_add_f32_e32 v41, 1.0, v41
	v_rcp_f32_e32 v74, v74
	v_rcp_f32_e32 v64, v64
	v_cvt_pk_bf16_f32 v56, v56, v57
	v_mul_f32_e32 v57, v58, v62
	v_exp_f32_e64 v58, -v58
	v_mul_f32_e32 v52, v48, v52
	v_exp_f32_e64 v48, -v48
	v_rcp_f32_e32 v41, v41
	v_mul_f32_e32 v24, v28, v24
	v_mul_f32_e32 v28, v25, v29
	v_exp_f32_e64 v25, -v25
	v_add_f32_e32 v8, 1.0, v8
	v_rcp_f32_e32 v8, v8
	v_add_f32_e32 v113, 1.0, v113
	v_rcp_f32_e32 v113, v113
	v_add_f32_e32 v114, 1.0, v114
	v_mul_f32_e32 v106, v106, v107
	v_mul_f32_e32 v97, v100, v97
	v_add_f32_e32 v91, 1.0, v91
	v_add_f32_e32 v81, 1.0, v81
	v_rcp_f32_e32 v114, v114
	v_cvt_pk_bf16_f32 v105, v105, v106
	v_cvt_pk_bf16_f32 v106, v96, v97
	v_exp_f32_e64 v97, -v98
	v_rcp_f32_e32 v91, v91
	v_rcp_f32_e32 v81, v81
	v_mul_f32_e32 v73, v73, v74
	v_mul_f32_e32 v74, v75, v79
	v_exp_f32_e64 v75, -v75
	v_mul_f32_e32 v64, v68, v64
	v_mul_f32_e32 v68, v65, v69
	v_exp_f32_e64 v65, -v65
	v_add_f32_e32 v58, 1.0, v58
	v_add_f32_e32 v48, 1.0, v48
	v_mul_f32_e32 v41, v44, v41
	v_add_f32_e32 v25, 1.0, v25
	v_mul_f32_e32 v96, v98, v102
	v_exp_f32_e64 v98, -v99
	v_rcp_f32_e32 v58, v58
	v_rcp_f32_e32 v48, v48
	v_cvt_pk_bf16_f32 v40, v40, v41
	v_mul_f32_e32 v41, v42, v46
	v_exp_f32_e64 v42, -v42
	v_mul_f32_e32 v36, v32, v36
	v_exp_f32_e64 v32, -v32
	v_rcp_f32_e32 v25, v25
	v_mul_f32_e32 v8, v12, v8
	v_mul_f32_e32 v12, v9, v13
	v_exp_f32_e64 v9, -v9
	v_mul_f32_e32 v112, v112, v113
	v_mul_f32_e32 v113, v115, v119
	s_lshl_b32 s16, s15, 7
	v_mul_f32_e32 v113, v113, v114
	v_add_f32_e32 v97, 1.0, v97
	v_mul_f32_e32 v90, v90, v91
	v_mul_f32_e32 v81, v84, v81
	v_add_f32_e32 v75, 1.0, v75
	v_add_f32_e32 v65, 1.0, v65
	v_lshl_add_u32 v139, s81, 8, v136
	s_ashr_i32 s17, s16, 31
	v_cvt_pk_bf16_f32 v123, v112, v113
	v_mov_b64_e32 v[112:113], s[6:7]
	v_rcp_f32_e32 v97, v97
	v_add_f32_e32 v98, 1.0, v98
	v_cvt_pk_bf16_f32 v89, v89, v90
	v_cvt_pk_bf16_f32 v90, v80, v81
	v_exp_f32_e64 v81, -v82
	v_rcp_f32_e32 v75, v75
	v_rcp_f32_e32 v65, v65
	v_mul_f32_e32 v57, v57, v58
	v_mul_f32_e32 v58, v59, v63
	v_exp_f32_e64 v59, -v59
	v_mul_f32_e32 v48, v52, v48
	v_mul_f32_e32 v52, v49, v53
	v_exp_f32_e64 v49, -v49
	v_add_f32_e32 v42, 1.0, v42
	v_add_f32_e32 v32, 1.0, v32
	v_mul_f32_e32 v25, v28, v25
	v_add_f32_e32 v9, 1.0, v9
	v_mad_i64_i32 v[114:115], s[20:21], v139, s33, v[112:113]
	s_lshl_b64 s[16:17], s[16:17], 1
	v_rcp_f32_e32 v98, v98
	v_mul_f32_e32 v80, v82, v86
	v_exp_f32_e64 v82, -v83
	v_rcp_f32_e32 v42, v42
	v_rcp_f32_e32 v32, v32
	v_cvt_pk_bf16_f32 v24, v24, v25
	v_mul_f32_e32 v25, v26, v30
	v_exp_f32_e64 v26, -v26
	v_mul_f32_e32 v20, v16, v20
	v_exp_f32_e64 v16, -v16
	v_rcp_f32_e32 v9, v9
	v_lshl_add_u64 v[114:115], v[114:115], 0, s[16:17]
	v_lshl_add_u64 v[114:115], v[114:115], 0, s[66:67]
	v_lshl_add_u64 v[114:115], v[114:115], 0, v[144:145]
	v_mul_f32_e32 v96, v96, v97
	v_mul_f32_e32 v97, v99, v103
	v_add_f32_e32 v81, 1.0, v81
	v_mul_f32_e32 v74, v74, v75
	v_mul_f32_e32 v65, v68, v65
	v_add_f32_e32 v59, 1.0, v59
	v_add_f32_e32 v49, 1.0, v49
	global_store_dwordx4 v[114:115], v[120:123], off
	v_or_b32_e32 v114, 16, v139
	v_mul_f32_e32 v97, v97, v98
	v_rcp_f32_e32 v81, v81
	v_add_f32_e32 v82, 1.0, v82
	v_cvt_pk_bf16_f32 v73, v73, v74
	v_cvt_pk_bf16_f32 v74, v64, v65
	v_exp_f32_e64 v65, -v66
	v_rcp_f32_e32 v59, v59
	v_rcp_f32_e32 v49, v49
	v_mul_f32_e32 v41, v41, v42
	v_mul_f32_e32 v42, v43, v47
	v_exp_f32_e64 v43, -v43
	v_mul_f32_e32 v32, v36, v32
	v_mul_f32_e32 v36, v33, v37
	v_exp_f32_e64 v33, -v33
	v_add_f32_e32 v26, 1.0, v26
	v_add_f32_e32 v16, 1.0, v16
	v_mul_f32_e32 v9, v12, v9
	v_cvt_pk_bf16_f32 v107, v96, v97
	v_mad_i64_i32 v[96:97], s[20:21], v114, s33, v[112:113]
	v_rcp_f32_e32 v82, v82
	v_mul_f32_e32 v64, v66, v70
	v_exp_f32_e64 v66, -v67
	v_rcp_f32_e32 v26, v26
	v_rcp_f32_e32 v16, v16
	v_cvt_pk_bf16_f32 v8, v8, v9
	v_mul_f32_e32 v9, v10, v14
	v_exp_f32_e64 v10, -v10
	v_mul_f32_e32 v4, v0, v4
	v_exp_f32_e64 v0, -v0
	v_lshl_add_u64 v[96:97], v[96:97], 0, s[16:17]
	v_lshl_add_u64 v[96:97], v[96:97], 0, s[66:67]
	v_lshl_add_u64 v[96:97], v[96:97], 0, v[144:145]
; __device__ __forceinline__ unsigned pk2(float lo, float hi) { unsigned r; asm("v_cvt_pk_bf16_f32 %0, %1, %2" : "=v"(r) : "v"(lo), "v"(hi)); return r; }
;     static __device__ __forceinline__ float sg(float g, float u) { return (g * u) * __builtin_amdgcn_rcpf(1.f + __builtin_amdgcn_exp2f(-g)); }
; template <class Epi>
; __device__ __forceinline__ void gemm_phase(LAS unsigned char* lds, const Gemm g, const StaticOrder& S, const Epi& E) {
;     ...
;         E(acc, cur, wr, wc, fr, fq);
;         if (!has_next) break;
; #pragma unroll
;         for (int a = 0; a < 2; ++a)
; #pragma unroll
;             for (int b = 0; b < 2; ++b)
; #pragma unroll
;                 for (int m = 0; m < 4; ++m)
; #pragma unroll
;                     for (int n = 0; n < 2; ++n) acc[a][b][m][n] = (f32x4){0.f, 0.f, 0.f, 0.f};
;         cur = nxt; cA = nA; cB = nB; ++ui;
;     __device__ __forceinline__ void operator()(const f32x4 (&acc)[2][2][4][2], const Unit& u, int wr, int wc, int fr, int fq) const {
; #pragma unroll
;         for (int ai = 0; ai < 2; ++ai)
; #pragma unroll
;             for (int m = 0; m < 4; ++m) {
;                 const int row = u.pm * BM + ai * HALF + wr * 64 + m * 16 + fr;
;                 const f32x4 g0 = acc[ai][0][m][0], u0 = acc[ai][0][m][1], g1 = acc[ai][1][m][0], u1 = acc[ai][1][m][1];
;                 u32x4 o; o.x = pk2(sg(g0[0], u0[0]), sg(g0[1], u0[1])); o.y = pk2(sg(g0[2], u0[2]), sg(g0[3], u0[3]));
;                 o.z = pk2(sg(g1[0], u1[0]), sg(g1[1], u1[1])); o.w = pk2(sg(g1[2], u1[2]), sg(g1[3], u1[3]));
;                 *(u32x4*)(O + (size_t)row * DFF + u.pn * 128 + wc * 32 + fq * 8) = o;
;             }
	v_mul_f32_e32 v80, v80, v81
	v_mul_f32_e32 v81, v83, v87
	v_add_f32_e32 v65, 1.0, v65
	v_mul_f32_e32 v58, v58, v59
	v_mul_f32_e32 v49, v52, v49
	v_add_f32_e32 v43, 1.0, v43
	v_add_f32_e32 v33, 1.0, v33
	global_store_dwordx4 v[96:97], v[104:107], off
	v_or_b32_e32 v96, 32, v139
	v_mul_f32_e32 v81, v81, v82
	v_rcp_f32_e32 v65, v65
	v_add_f32_e32 v66, 1.0, v66
	v_cvt_pk_bf16_f32 v57, v57, v58
	v_cvt_pk_bf16_f32 v58, v48, v49
	v_exp_f32_e64 v49, -v50
	v_rcp_f32_e32 v43, v43
	v_rcp_f32_e32 v33, v33
	v_mul_f32_e32 v25, v25, v26
	v_mul_f32_e32 v26, v27, v31
	v_exp_f32_e64 v27, -v27
	v_mul_f32_e32 v16, v20, v16
	v_mul_f32_e32 v20, v17, v21
	v_exp_f32_e64 v17, -v17
	v_add_f32_e32 v10, 1.0, v10
	v_add_f32_e32 v0, 1.0, v0
	v_cvt_pk_bf16_f32 v91, v80, v81
	v_mad_i64_i32 v[80:81], s[20:21], v96, s33, v[112:113]
	v_rcp_f32_e32 v66, v66
	v_mul_f32_e32 v48, v50, v54
	v_exp_f32_e64 v50, -v51
	v_rcp_f32_e32 v10, v10
	v_rcp_f32_e32 v0, v0
	v_lshl_add_u64 v[80:81], v[80:81], 0, s[16:17]
	v_lshl_add_u64 v[80:81], v[80:81], 0, s[66:67]
	v_lshl_add_u64 v[80:81], v[80:81], 0, v[144:145]
	v_mul_f32_e32 v64, v64, v65
	v_mul_f32_e32 v65, v67, v71
	v_add_f32_e32 v49, 1.0, v49
	v_mul_f32_e32 v42, v42, v43
	v_mul_f32_e32 v33, v36, v33
	v_add_f32_e32 v27, 1.0, v27
	v_add_f32_e32 v17, 1.0, v17
	global_store_dwordx4 v[80:81], v[88:91], off
	v_or_b32_e32 v80, 48, v139
	v_mul_f32_e32 v65, v65, v66
	v_rcp_f32_e32 v49, v49
	v_add_f32_e32 v50, 1.0, v50
	v_cvt_pk_bf16_f32 v41, v41, v42
	v_cvt_pk_bf16_f32 v42, v32, v33
	v_exp_f32_e64 v33, -v34
	v_rcp_f32_e32 v27, v27
	v_rcp_f32_e32 v17, v17
	v_mul_f32_e32 v9, v9, v10
	v_mul_f32_e32 v10, v11, v15
	v_exp_f32_e64 v11, -v11
	v_mul_f32_e32 v0, v4, v0
	v_mul_f32_e32 v4, v1, v5
	v_exp_f32_e64 v1, -v1
	v_cvt_pk_bf16_f32 v75, v64, v65
	v_mad_i64_i32 v[64:65], s[20:21], v80, s33, v[112:113]
	v_rcp_f32_e32 v50, v50
	v_mul_f32_e32 v32, v34, v38
	v_exp_f32_e64 v34, -v35
	v_lshl_add_u64 v[64:65], v[64:65], 0, s[16:17]
	v_lshl_add_u64 v[64:65], v[64:65], 0, s[66:67]
	v_lshl_add_u64 v[64:65], v[64:65], 0, v[144:145]
	v_mul_f32_e32 v48, v48, v49
	v_mul_f32_e32 v49, v51, v55
	v_add_f32_e32 v33, 1.0, v33
	v_mul_f32_e32 v26, v26, v27
	v_mul_f32_e32 v17, v20, v17
	v_add_f32_e32 v11, 1.0, v11
	v_add_f32_e32 v1, 1.0, v1
	global_store_dwordx4 v[64:65], v[72:75], off
	v_add_u32_e32 v64, 0x80, v139
	v_mul_f32_e32 v49, v49, v50
	v_rcp_f32_e32 v33, v33
	v_add_f32_e32 v34, 1.0, v34
	v_cvt_pk_bf16_f32 v25, v25, v26
	v_cvt_pk_bf16_f32 v26, v16, v17
	v_exp_f32_e64 v17, -v18
	v_rcp_f32_e32 v11, v11
	v_rcp_f32_e32 v1, v1
	v_cvt_pk_bf16_f32 v59, v48, v49
	v_mad_i64_i32 v[48:49], s[20:21], v64, s33, v[112:113]
	v_rcp_f32_e32 v34, v34
	v_mul_f32_e32 v16, v18, v22
	v_exp_f32_e64 v18, -v19
	v_lshl_add_u64 v[48:49], v[48:49], 0, s[16:17]
	v_lshl_add_u64 v[48:49], v[48:49], 0, s[66:67]
	v_lshl_add_u64 v[48:49], v[48:49], 0, v[144:145]
	v_mul_f32_e32 v32, v32, v33
	v_mul_f32_e32 v33, v35, v39
	v_add_f32_e32 v17, 1.0, v17
	v_mul_f32_e32 v10, v10, v11
	v_mul_f32_e32 v1, v4, v1
	global_store_dwordx4 v[48:49], v[56:59], off
	v_add_u32_e32 v48, 0x90, v139
	v_mul_f32_e32 v33, v33, v34
	v_rcp_f32_e32 v17, v17
	v_add_f32_e32 v18, 1.0, v18
	v_cvt_pk_bf16_f32 v9, v9, v10
	v_cvt_pk_bf16_f32 v10, v0, v1
	v_exp_f32_e64 v1, -v2
	v_cvt_pk_bf16_f32 v43, v32, v33
	v_mad_i64_i32 v[32:33], s[20:21], v48, s33, v[112:113]
	v_rcp_f32_e32 v18, v18
	v_mul_f32_e32 v0, v2, v6
	v_exp_f32_e64 v2, -v3
	v_lshl_add_u64 v[32:33], v[32:33], 0, s[16:17]
	v_lshl_add_u64 v[32:33], v[32:33], 0, s[66:67]
	v_lshl_add_u64 v[32:33], v[32:33], 0, v[144:145]
	v_mul_f32_e32 v16, v16, v17
	v_mul_f32_e32 v17, v19, v23
	v_add_f32_e32 v1, 1.0, v1
	global_store_dwordx4 v[32:33], v[40:43], off
	v_add_u32_e32 v32, 0xa0, v139
	v_mul_f32_e32 v17, v17, v18
	v_rcp_f32_e32 v1, v1
	v_add_f32_e32 v2, 1.0, v2
	v_cvt_pk_bf16_f32 v27, v16, v17
	v_mad_i64_i32 v[16:17], s[20:21], v32, s33, v[112:113]
	v_rcp_f32_e32 v2, v2
	v_lshl_add_u64 v[16:17], v[16:17], 0, s[16:17]
	v_lshl_add_u64 v[16:17], v[16:17], 0, s[66:67]
	v_lshl_add_u64 v[16:17], v[16:17], 0, v[144:145]
	v_mul_f32_e32 v0, v0, v1
	v_mul_f32_e32 v1, v3, v7
	global_store_dwordx4 v[16:17], v[24:27], off
	v_add_u32_e32 v16, 0xb0, v139
	v_mul_f32_e32 v1, v1, v2
	v_cvt_pk_bf16_f32 v11, v0, v1
	v_mad_i64_i32 v[0:1], s[20:21], v16, s33, v[112:113]
	v_lshl_add_u64 v[0:1], v[0:1], 0, s[16:17]
	v_lshl_add_u64 v[0:1], v[0:1], 0, s[66:67]
	v_lshl_add_u64 v[0:1], v[0:1], 0, v[144:145]
	s_and_b64 vcc, exec, s[0:1]
	s_mov_b32 s15, s8
	s_mov_b32 s81, s80
	s_mov_b64 s[20:21], s[12:13]
	s_mov_b64 s[16:17], s[10:11]
	global_store_dwordx4 v[0:1], v[8:11], off
	s_cbranch_vccz .LBB0_1391
	s_waitcnt vmcnt(0)
	s_cmpk_gt_u32 s23, 0xff
	s_cbranch_scc1 .LBB0_1398
	s_barrier

; #define PG8_STAGE(bufoff, gbase, voff) do { _Pragma("unroll") for (int _i = 0; _i < 2; ++_i) \
;         __builtin_amdgcn_global_load_lds((const unsigned*)((const char*)(gbase) + (voff)[_i]), (LAS unsigned*)(lds + (bufoff) + ldsw + _i * 8192), 16, 0, 0); } while (0)
; #define PG8_LDA(dst, b, h) do { _Pragma("unroll") for (int m = 0; m < 4; ++m) _Pragma("unroll") for (int k = 0; k < 2; ++k) dst[m][k] = *(const LAS bf16x8*)(lds + PG8_SA(b, h) + aoff + m * 2048 + k * 1024); } while (0)
; #define PG8_LDB(dst, b, h) do { _Pragma("unroll") for (int n = 0; n < 2; ++n) _Pragma("unroll") for (int k = 0; k < 2; ++k) dst[n][k] = *(const LAS bf16x8*)(lds + PG8_SB(b, h) + boff + n * 2048 + k * 1024); } while (0)
; #define PG8_MMA(ai, bj, At, Bt) do { __builtin_amdgcn_s_setprio(1); _Pragma("unroll") for (int m = 0; m < 4; ++m) _Pragma("unroll") for (int n = 0; n < 2; ++n) _Pragma("unroll") for (int k = 0; k < 2; ++k) \
;         acc[ai][bj][m][n] = __builtin_amdgcn_mfma_f32_16x16x32_bf16(Bt[n][k], At[m][k], acc[ai][bj][m][n], 0, 0, 0); __builtin_amdgcn_s_setprio(0); } while (0)
; #define PG8_WAIT_L(n) asm volatile("s_waitcnt lgkmcnt(" #n ")" ::: "memory")
; #define PG8_BAR __builtin_amdgcn_s_barrier()
; #define PG8_SCHED __builtin_amdgcn_sched_barrier(0)
; template <class Epi>
; __device__ __forceinline__ void gemm_phase(LAS unsigned char* lds, const Gemm g, const StaticOrder& S, const Epi& E) {
;     ...
;             const bool last = (t == nt - 2);
;             const char* a1 = cA + (size_t)(t + 1) * kstep;
;             const char* a2 = last ? nA : cA + (size_t)(t + 2) * kstep; const char* b2 = last ? nB : cB + (size_t)(t + 2) * kstep;
;             const char* a3 = a2 + kstep; const char* b3 = b2 + kstep;
;             PG8_LDB(B0, 0, 0); PG8_SCHED; PG8_LDA(At, 0, 0); PG8_STAGE(PG8_SA(1, 1), a1 + hA, voffA);
;             PG8_WAIT_L(8); PG8_BAR; PG8_WAIT_L(0); PG8_MMA(0, 0, At, B0); PG8_BAR; PG8_SCHED;
;             PG8_LDB(B1, 0, 1); PG8_STAGE(PG8_SB(0, 0), b2, voffB);
;             PG8_BAR; PG8_WAIT_L(0); PG8_MMA(0, 1, At, B1); PG8_BAR;
;             PG8_LDA(At, 0, 1); PG8_STAGE(PG8_SA(0, 0), a2, voffA);
;             PG8_BAR; PG8_WAIT_L(0); PG8_MMA(1, 0, At, B0); PG8_BAR; PG8_SCHED;
.LBB0_1462:
	s_add_u32 s12, s10, 0x100
	s_addc_u32 s13, s11, 0
	s_add_i32 s26, 0, 0x10000
	v_add_u32_e32 v142, s26, v139
	ds_read_b128 v[134:137], v142
	ds_read_b128 v[146:149], v142 offset:1024
	ds_read_b128 v[150:153], v142 offset:2048
	ds_read_b128 v[154:157], v142 offset:3072
	s_cmp_eq_u32 s78, 40
	s_cselect_b32 s21, s5, s13
	s_cselect_b32 s20, s4, s12
	s_cselect_b32 s17, s7, s25
	s_cselect_b32 s16, s6, s24
	s_add_i32 m0, s63, 0xc000
	ds_read_b128 v[158:161], v141
	ds_read_b128 v[162:165], v141 offset:1024
	ds_read_b128 v[166:169], v141 offset:2048
	ds_read_b128 v[170:173], v141 offset:3072
	ds_read_b128 v[174:177], v141 offset:4096
	ds_read_b128 v[178:181], v141 offset:5120
	ds_read_b128 v[182:185], v141 offset:6144
	ds_read_b128 v[186:189], v141 offset:7168
	global_load_lds_dwordx4 v130, s[10:11]
	s_add_i32 m0, s63, 0xe000
	v_lshl_add_u64 v[142:143], s[10:11], 0, v[132:133]
	global_load_lds_dwordx4 v[142:143], off
	s_waitcnt lgkmcnt(8)
	s_barrier
	s_waitcnt lgkmcnt(0)
	v_mfma_f32_16x16x32_bf16 v[124:127], v[134:137], v[158:161], v[124:127]
	v_mfma_f32_16x16x32_bf16 v[120:123], v[150:153], v[158:161], v[120:123]
	v_mfma_f32_16x16x32_bf16 v[116:119], v[134:137], v[166:169], v[116:119]
	v_mfma_f32_16x16x32_bf16 v[108:111], v[150:153], v[166:169], v[108:111]
	v_mfma_f32_16x16x32_bf16 v[100:103], v[134:137], v[174:177], v[100:103]
	v_mfma_f32_16x16x32_bf16 v[92:95], v[150:153], v[174:177], v[92:95]
	v_mfma_f32_16x16x32_bf16 v[84:87], v[134:137], v[182:185], v[84:87]
	v_mfma_f32_16x16x32_bf16 v[76:79], v[150:153], v[182:185], v[76:79]
	v_mfma_f32_16x16x32_bf16 v[124:127], v[146:149], v[162:165], v[124:127]
	v_mfma_f32_16x16x32_bf16 v[120:123], v[154:157], v[162:165], v[120:123]
	v_mfma_f32_16x16x32_bf16 v[116:119], v[146:149], v[170:173], v[116:119]
	v_mfma_f32_16x16x32_bf16 v[108:111], v[154:157], v[170:173], v[108:111]
	v_mfma_f32_16x16x32_bf16 v[100:103], v[146:149], v[178:181], v[100:103]
	v_mfma_f32_16x16x32_bf16 v[92:95], v[154:157], v[178:181], v[92:95]
	v_mfma_f32_16x16x32_bf16 v[84:87], v[146:149], v[186:189], v[84:87]
	v_mfma_f32_16x16x32_bf16 v[76:79], v[154:157], v[186:189], v[76:79]
	s_barrier
	s_add_i32 s27, 0, 0x14000
	v_add_u32_e32 v142, s27, v139
	s_add_i32 s10, s26, s61
	ds_read_b128 v[196:199], v142
	ds_read_b128 v[200:203], v142 offset:1024
	ds_read_b128 v[204:207], v142 offset:2048
	ds_read_b128 v[214:217], v142 offset:3072
	v_lshl_add_u64 v[142:143], s[16:17], 0, v[144:145]
	s_mov_b32 m0, s10
	v_lshl_add_u64 v[192:193], s[16:17], 0, v[128:129]
	global_load_lds_dwordx4 v[142:143], off
	s_add_i32 m0, s10, 0x2000
	s_nop 0
	global_load_lds_dwordx4 v[192:193], off
	s_barrier
	s_waitcnt lgkmcnt(0)
	v_mfma_f32_16x16x32_bf16 v[112:115], v[196:199], v[158:161], v[112:115]
	v_mfma_f32_16x16x32_bf16 v[104:107], v[204:207], v[158:161], v[104:107]
	v_mfma_f32_16x16x32_bf16 v[96:99], v[196:199], v[166:169], v[96:99]
	v_mfma_f32_16x16x32_bf16 v[88:91], v[204:207], v[166:169], v[88:91]
	v_mfma_f32_16x16x32_bf16 v[80:83], v[196:199], v[174:177], v[80:83]
	v_mfma_f32_16x16x32_bf16 v[72:75], v[204:207], v[174:177], v[72:75]
	v_mfma_f32_16x16x32_bf16 v[68:71], v[196:199], v[182:185], v[68:71]
	v_mfma_f32_16x16x32_bf16 v[64:67], v[204:207], v[182:185], v[64:67]
	v_mfma_f32_16x16x32_bf16 v[112:115], v[200:203], v[162:165], v[112:115]
	v_mfma_f32_16x16x32_bf16 v[104:107], v[214:217], v[162:165], v[104:107]
	v_mfma_f32_16x16x32_bf16 v[96:99], v[200:203], v[170:173], v[96:99]
	v_mfma_f32_16x16x32_bf16 v[88:91], v[214:217], v[170:173], v[88:91]
	v_mfma_f32_16x16x32_bf16 v[80:83], v[200:203], v[178:181], v[80:83]
	v_mfma_f32_16x16x32_bf16 v[72:75], v[214:217], v[178:181], v[72:75]
	v_mfma_f32_16x16x32_bf16 v[68:71], v[200:203], v[186:189], v[68:71]
	v_mfma_f32_16x16x32_bf16 v[64:67], v[214:217], v[186:189], v[64:67]
	s_mov_b32 m0, s63
	v_lshl_add_u64 v[218:219], s[20:21], 0, v[144:145]
	s_barrier
	ds_read_b128 v[158:161], v141 offset:16384
	ds_read_b128 v[162:165], v141 offset:17408
	ds_read_b128 v[166:169], v141 offset:18432
	ds_read_b128 v[170:173], v141 offset:19456
	ds_read_b128 v[174:177], v141 offset:20480
	ds_read_b128 v[178:181], v141 offset:21504
	ds_read_b128 v[182:185], v141 offset:22528
	ds_read_b128 v[186:189], v141 offset:23552
	global_load_lds_dwordx4 v[218:219], off
	s_mov_b32 m0, s64
	v_lshl_add_u64 v[220:221], s[20:21], 0, v[128:129]
	global_load_lds_dwordx4 v[220:221], off
	s_barrier
	s_waitcnt lgkmcnt(0)
	v_mfma_f32_16x16x32_bf16 v[60:63], v[134:137], v[158:161], v[60:63]
	v_mfma_f32_16x16x32_bf16 v[56:59], v[150:153], v[158:161], v[56:59]
	v_mfma_f32_16x16x32_bf16 v[52:55], v[134:137], v[166:169], v[52:55]
	v_mfma_f32_16x16x32_bf16 v[44:47], v[150:153], v[166:169], v[44:47]
	v_mfma_f32_16x16x32_bf16 v[36:39], v[134:137], v[174:177], v[36:39]
	v_mfma_f32_16x16x32_bf16 v[28:31], v[150:153], v[174:177], v[28:31]
	v_mfma_f32_16x16x32_bf16 v[20:23], v[134:137], v[182:185], v[20:23]
	v_mfma_f32_16x16x32_bf16 v[12:15], v[150:153], v[182:185], v[12:15]
	v_mfma_f32_16x16x32_bf16 v[60:63], v[146:149], v[162:165], v[60:63]
	v_mfma_f32_16x16x32_bf16 v[56:59], v[154:157], v[162:165], v[56:59]
	v_mfma_f32_16x16x32_bf16 v[52:55], v[146:149], v[170:173], v[52:55]
	v_mfma_f32_16x16x32_bf16 v[44:47], v[154:157], v[170:173], v[44:47]
	v_mfma_f32_16x16x32_bf16 v[36:39], v[146:149], v[178:181], v[36:39]
	v_mfma_f32_16x16x32_bf16 v[28:31], v[154:157], v[178:181], v[28:31]
	v_mfma_f32_16x16x32_bf16 v[20:23], v[146:149], v[186:189], v[20:23]
	v_mfma_f32_16x16x32_bf16 v[12:15], v[154:157], v[186:189], v[12:15]
	s_barrier
; #define PG8_STAGE(bufoff, gbase, voff) do { _Pragma("unroll") for (int _i = 0; _i < 2; ++_i) \
;         __builtin_amdgcn_global_load_lds((const unsigned*)((const char*)(gbase) + (voff)[_i]), (LAS unsigned*)(lds + (bufoff) + ldsw + _i * 8192), 16, 0, 0); } while (0)
; #define PG8_LDA(dst, b, h) do { _Pragma("unroll") for (int m = 0; m < 4; ++m) _Pragma("unroll") for (int k = 0; k < 2; ++k) dst[m][k] = *(const LAS bf16x8*)(lds + PG8_SA(b, h) + aoff + m * 2048 + k * 1024); } while (0)
; #define PG8_LDB(dst, b, h) do { _Pragma("unroll") for (int n = 0; n < 2; ++n) _Pragma("unroll") for (int k = 0; k < 2; ++k) dst[n][k] = *(const LAS bf16x8*)(lds + PG8_SB(b, h) + boff + n * 2048 + k * 1024); } while (0)
; #define PG8_MMA(ai, bj, At, Bt) do { __builtin_amdgcn_s_setprio(1); _Pragma("unroll") for (int m = 0; m < 4; ++m) _Pragma("unroll") for (int n = 0; n < 2; ++n) _Pragma("unroll") for (int k = 0; k < 2; ++k) \
;         acc[ai][bj][m][n] = __builtin_amdgcn_mfma_f32_16x16x32_bf16(Bt[n][k], At[m][k], acc[ai][bj][m][n], 0, 0, 0); __builtin_amdgcn_s_setprio(0); } while (0)
; #define PG8_WAIT_V(n) asm volatile("s_waitcnt vmcnt(" #n ")" ::: "memory")
; #define PG8_WAIT_L(n) asm volatile("s_waitcnt lgkmcnt(" #n ")" ::: "memory")
; #define PG8_BAR __builtin_amdgcn_s_barrier()
; #define PG8_SCHED __builtin_amdgcn_sched_barrier(0)
; template <class Epi>
; __device__ __forceinline__ void gemm_phase(LAS unsigned char* lds, const Gemm g, const StaticOrder& S, const Epi& E) {
;     ...
;             PG8_STAGE(PG8_SB(0, 1), b2 + hB, voffB);
;             PG8_WAIT_V(6); PG8_BAR; PG8_MMA(1, 1, At, B1); PG8_BAR;
;             PG8_LDB(B0, 1, 0); PG8_SCHED; PG8_LDA(At, 1, 0); PG8_STAGE(PG8_SA(0, 1), a2 + hA, voffA);
;             PG8_WAIT_L(8); PG8_BAR; PG8_WAIT_L(0); PG8_MMA(0, 0, At, B0); PG8_BAR; PG8_SCHED;
;             PG8_LDB(B1, 1, 1); PG8_STAGE(PG8_SB(1, 0), b3, voffB);
;             PG8_BAR; PG8_WAIT_L(0); PG8_MMA(0, 1, At, B1); PG8_BAR;
;             PG8_LDA(At, 1, 1); PG8_STAGE(PG8_SA(1, 0), a3, voffA);
;             PG8_BAR; PG8_WAIT_L(0); PG8_MMA(1, 0, At, B0); PG8_BAR; PG8_SCHED;
	s_add_u32 s10, s16, 0xb0000
	s_addc_u32 s11, s17, 0
	s_add_i32 s26, s27, s61
	s_mov_b32 m0, s26
	s_nop 0
	global_load_lds_dwordx4 v144, s[10:11]
	s_add_i32 m0, s26, 0x2000
	s_nop 0
	global_load_lds_dwordx4 v128, s[10:11]
	s_waitcnt vmcnt(6)
	s_barrier
	v_mfma_f32_16x16x32_bf16 v[48:51], v[196:199], v[158:161], v[48:51]
	v_mfma_f32_16x16x32_bf16 v[40:43], v[204:207], v[158:161], v[40:43]
	v_mfma_f32_16x16x32_bf16 v[32:35], v[196:199], v[166:169], v[32:35]
	v_mfma_f32_16x16x32_bf16 v[24:27], v[204:207], v[166:169], v[24:27]
	v_mfma_f32_16x16x32_bf16 v[16:19], v[196:199], v[174:177], v[16:19]
	v_mfma_f32_16x16x32_bf16 v[8:11], v[204:207], v[174:177], v[8:11]
	v_mfma_f32_16x16x32_bf16 v[4:7], v[196:199], v[182:185], v[4:7]
	v_mfma_f32_16x16x32_bf16 v[0:3], v[204:207], v[182:185], v[0:3]
	v_mfma_f32_16x16x32_bf16 v[48:51], v[200:203], v[162:165], v[48:51]
	v_mfma_f32_16x16x32_bf16 v[40:43], v[214:217], v[162:165], v[40:43]
	v_mfma_f32_16x16x32_bf16 v[32:35], v[200:203], v[170:173], v[32:35]
	v_mfma_f32_16x16x32_bf16 v[24:27], v[214:217], v[170:173], v[24:27]
	v_mfma_f32_16x16x32_bf16 v[16:19], v[200:203], v[178:181], v[16:19]
	v_mfma_f32_16x16x32_bf16 v[8:11], v[214:217], v[178:181], v[8:11]
	v_mfma_f32_16x16x32_bf16 v[4:7], v[200:203], v[186:189], v[4:7]
	v_mfma_f32_16x16x32_bf16 v[0:3], v[214:217], v[186:189], v[0:3]
	s_add_i32 s26, 0, 0x18000
	v_add_u32_e32 v154, s26, v139
	s_barrier
	ds_read_b128 v[134:137], v154
	ds_read_b128 v[146:149], v154 offset:1024
	ds_read_b128 v[150:153], v154 offset:2048
	ds_read_b128 v[154:157], v154 offset:3072
	s_add_u32 s10, s20, 0xb0000
	s_addc_u32 s11, s21, 0
	s_mov_b32 m0, s65
	ds_read_b128 v[158:161], v141 offset:32768
	ds_read_b128 v[162:165], v141 offset:33792
	ds_read_b128 v[166:169], v141 offset:34816
	ds_read_b128 v[170:173], v141 offset:35840
	ds_read_b128 v[174:177], v141 offset:36864
	ds_read_b128 v[178:181], v141 offset:37888
	ds_read_b128 v[182:185], v141 offset:38912
	ds_read_b128 v[186:189], v141 offset:39936
	global_load_lds_dwordx4 v144, s[10:11]
	s_mov_b32 m0, s68
	s_nop 0
	global_load_lds_dwordx4 v128, s[10:11]
	s_waitcnt lgkmcnt(8)
	s_barrier
	s_waitcnt lgkmcnt(0)
	v_mfma_f32_16x16x32_bf16 v[124:127], v[134:137], v[158:161], v[124:127]
	v_mfma_f32_16x16x32_bf16 v[120:123], v[150:153], v[158:161], v[120:123]
	v_mfma_f32_16x16x32_bf16 v[116:119], v[134:137], v[166:169], v[116:119]
	v_mfma_f32_16x16x32_bf16 v[108:111], v[150:153], v[166:169], v[108:111]
	v_mfma_f32_16x16x32_bf16 v[100:103], v[134:137], v[174:177], v[100:103]
	v_mfma_f32_16x16x32_bf16 v[92:95], v[150:153], v[174:177], v[92:95]
	v_mfma_f32_16x16x32_bf16 v[84:87], v[134:137], v[182:185], v[84:87]
	v_mfma_f32_16x16x32_bf16 v[76:79], v[150:153], v[182:185], v[76:79]
	v_mfma_f32_16x16x32_bf16 v[124:127], v[146:149], v[162:165], v[124:127]
	v_mfma_f32_16x16x32_bf16 v[120:123], v[154:157], v[162:165], v[120:123]
	v_mfma_f32_16x16x32_bf16 v[116:119], v[146:149], v[170:173], v[116:119]
	v_mfma_f32_16x16x32_bf16 v[108:111], v[154:157], v[170:173], v[108:111]
	v_mfma_f32_16x16x32_bf16 v[100:103], v[146:149], v[178:181], v[100:103]
	v_mfma_f32_16x16x32_bf16 v[92:95], v[154:157], v[178:181], v[92:95]
	v_mfma_f32_16x16x32_bf16 v[84:87], v[146:149], v[186:189], v[84:87]
	v_mfma_f32_16x16x32_bf16 v[76:79], v[154:157], v[186:189], v[76:79]
	s_barrier
	s_add_i32 s20, 0, 0x1c000
	s_add_i32 s10, s26, s61
	v_add_u32_e32 v190, s20, v139
	v_lshl_add_u64 v[142:143], v[142:143], 0, s[88:89]
	s_mov_b32 m0, s10
	ds_read_b128 v[196:199], v190
	ds_read_b128 v[200:203], v190 offset:1024
	ds_read_b128 v[204:207], v190 offset:2048
	ds_read_b128 v[214:217], v190 offset:3072
	global_load_lds_dwordx4 v[142:143], off
	s_add_i32 m0, s10, 0x2000
	v_lshl_add_u64 v[142:143], v[192:193], 0, s[88:89]
	global_load_lds_dwordx4 v[142:143], off
	s_barrier
	s_waitcnt lgkmcnt(0)
	v_mfma_f32_16x16x32_bf16 v[112:115], v[196:199], v[158:161], v[112:115]
	v_mfma_f32_16x16x32_bf16 v[104:107], v[204:207], v[158:161], v[104:107]
	v_mfma_f32_16x16x32_bf16 v[96:99], v[196:199], v[166:169], v[96:99]
	v_mfma_f32_16x16x32_bf16 v[88:91], v[204:207], v[166:169], v[88:91]
	v_mfma_f32_16x16x32_bf16 v[80:83], v[196:199], v[174:177], v[80:83]
	v_mfma_f32_16x16x32_bf16 v[72:75], v[204:207], v[174:177], v[72:75]
	v_mfma_f32_16x16x32_bf16 v[68:71], v[196:199], v[182:185], v[68:71]
	v_mfma_f32_16x16x32_bf16 v[64:67], v[204:207], v[182:185], v[64:67]
	v_mfma_f32_16x16x32_bf16 v[112:115], v[200:203], v[162:165], v[112:115]
	v_mfma_f32_16x16x32_bf16 v[104:107], v[214:217], v[162:165], v[104:107]
	v_mfma_f32_16x16x32_bf16 v[96:99], v[200:203], v[170:173], v[96:99]
	v_mfma_f32_16x16x32_bf16 v[88:91], v[214:217], v[170:173], v[88:91]
	v_mfma_f32_16x16x32_bf16 v[80:83], v[200:203], v[178:181], v[80:83]
	v_mfma_f32_16x16x32_bf16 v[72:75], v[214:217], v[178:181], v[72:75]
	v_mfma_f32_16x16x32_bf16 v[68:71], v[200:203], v[186:189], v[68:71]
	v_mfma_f32_16x16x32_bf16 v[64:67], v[214:217], v[186:189], v[64:67]
	s_mov_b32 m0, s69
	v_lshl_add_u64 v[142:143], v[218:219], 0, s[88:89]
	s_barrier
	ds_read_b128 v[158:161], v141 offset:49152
	ds_read_b128 v[162:165], v141 offset:50176
	ds_read_b128 v[166:169], v141 offset:51200
	ds_read_b128 v[170:173], v141 offset:52224
	ds_read_b128 v[174:177], v141 offset:53248
	ds_read_b128 v[178:181], v141 offset:54272
	ds_read_b128 v[182:185], v141 offset:55296
	ds_read_b128 v[186:189], v141 offset:56320
	global_load_lds_dwordx4 v[142:143], off
	s_mov_b32 m0, s70
	v_lshl_add_u64 v[142:143], v[220:221], 0, s[88:89]
	global_load_lds_dwordx4 v[142:143], off
	s_barrier
; #define PG8_STAGE(bufoff, gbase, voff) do { _Pragma("unroll") for (int _i = 0; _i < 2; ++_i) \
;         __builtin_amdgcn_global_load_lds((const unsigned*)((const char*)(gbase) + (voff)[_i]), (LAS unsigned*)(lds + (bufoff) + ldsw + _i * 8192), 16, 0, 0); } while (0)
; #define PG8_MMA(ai, bj, At, Bt) do { __builtin_amdgcn_s_setprio(1); _Pragma("unroll") for (int m = 0; m < 4; ++m) _Pragma("unroll") for (int n = 0; n < 2; ++n) _Pragma("unroll") for (int k = 0; k < 2; ++k) \
;         acc[ai][bj][m][n] = __builtin_amdgcn_mfma_f32_16x16x32_bf16(Bt[n][k], At[m][k], acc[ai][bj][m][n], 0, 0, 0); __builtin_amdgcn_s_setprio(0); } while (0)
; #define PG8_WAIT_V(n) asm volatile("s_waitcnt vmcnt(" #n ")" ::: "memory")
; #define PG8_WAIT_L(n) asm volatile("s_waitcnt lgkmcnt(" #n ")" ::: "memory")
; #define PG8_BAR __builtin_amdgcn_s_barrier()
; #define PG8_SCHED __builtin_amdgcn_sched_barrier(0)
; template <class Epi>
; __device__ __forceinline__ void gemm_phase(LAS unsigned char* lds, const Gemm g, const StaticOrder& S, const Epi& E) {
;     ...
;             PG8_BAR; PG8_WAIT_L(0); PG8_MMA(1, 0, At, B0); PG8_BAR; PG8_SCHED;
;             PG8_STAGE(PG8_SB(1, 1), b3 + hB, voffB);
;             PG8_WAIT_V(6); PG8_BAR; PG8_MMA(1, 1, At, B1); PG8_BAR;
	s_waitcnt lgkmcnt(0)
	v_mfma_f32_16x16x32_bf16 v[60:63], v[134:137], v[158:161], v[60:63]
	v_mfma_f32_16x16x32_bf16 v[56:59], v[150:153], v[158:161], v[56:59]
	v_mfma_f32_16x16x32_bf16 v[52:55], v[134:137], v[166:169], v[52:55]
	v_mfma_f32_16x16x32_bf16 v[44:47], v[150:153], v[166:169], v[44:47]
	v_mfma_f32_16x16x32_bf16 v[36:39], v[134:137], v[174:177], v[36:39]
	v_mfma_f32_16x16x32_bf16 v[28:31], v[150:153], v[174:177], v[28:31]
	v_mfma_f32_16x16x32_bf16 v[20:23], v[134:137], v[182:185], v[20:23]
	v_mfma_f32_16x16x32_bf16 v[12:15], v[150:153], v[182:185], v[12:15]
	v_mfma_f32_16x16x32_bf16 v[60:63], v[146:149], v[162:165], v[60:63]
	v_mfma_f32_16x16x32_bf16 v[56:59], v[154:157], v[162:165], v[56:59]
	v_mfma_f32_16x16x32_bf16 v[52:55], v[146:149], v[170:173], v[52:55]
	v_mfma_f32_16x16x32_bf16 v[44:47], v[154:157], v[170:173], v[44:47]
	v_mfma_f32_16x16x32_bf16 v[36:39], v[146:149], v[178:181], v[36:39]
	v_mfma_f32_16x16x32_bf16 v[28:31], v[154:157], v[178:181], v[28:31]
	v_mfma_f32_16x16x32_bf16 v[20:23], v[146:149], v[186:189], v[20:23]
	v_mfma_f32_16x16x32_bf16 v[12:15], v[154:157], v[186:189], v[12:15]
	s_barrier
	s_add_u32 s10, s16, 0xb0080
	s_addc_u32 s11, s17, 0
	s_add_i32 s16, s20, s61
	s_mov_b32 m0, s16
	s_nop 0
	global_load_lds_dwordx4 v144, s[10:11]
	s_add_i32 m0, s16, 0x2000
	s_nop 0
	global_load_lds_dwordx4 v128, s[10:11]
	s_waitcnt vmcnt(6)
	s_barrier
	v_mfma_f32_16x16x32_bf16 v[48:51], v[196:199], v[158:161], v[48:51]
	v_mfma_f32_16x16x32_bf16 v[40:43], v[204:207], v[158:161], v[40:43]
	v_mfma_f32_16x16x32_bf16 v[32:35], v[196:199], v[166:169], v[32:35]
	v_mfma_f32_16x16x32_bf16 v[24:27], v[204:207], v[166:169], v[24:27]
	v_mfma_f32_16x16x32_bf16 v[16:19], v[196:199], v[174:177], v[16:19]
	v_mfma_f32_16x16x32_bf16 v[8:11], v[204:207], v[174:177], v[8:11]
	v_mfma_f32_16x16x32_bf16 v[4:7], v[196:199], v[182:185], v[4:7]
	v_mfma_f32_16x16x32_bf16 v[0:3], v[204:207], v[182:185], v[0:3]
	v_mfma_f32_16x16x32_bf16 v[48:51], v[200:203], v[162:165], v[48:51]
	v_mfma_f32_16x16x32_bf16 v[40:43], v[214:217], v[162:165], v[40:43]
	v_mfma_f32_16x16x32_bf16 v[32:35], v[200:203], v[170:173], v[32:35]
	v_mfma_f32_16x16x32_bf16 v[24:27], v[214:217], v[170:173], v[24:27]
	v_mfma_f32_16x16x32_bf16 v[16:19], v[200:203], v[178:181], v[16:19]
	v_mfma_f32_16x16x32_bf16 v[8:11], v[214:217], v[178:181], v[8:11]
	v_mfma_f32_16x16x32_bf16 v[4:7], v[200:203], v[186:189], v[4:7]
	v_mfma_f32_16x16x32_bf16 v[0:3], v[214:217], v[186:189], v[0:3]
	s_add_i32 s78, s78, 2
	s_add_u32 s24, s24, 0x100
	s_addc_u32 s25, s25, 0
	s_cmp_gt_u32 s78, 41
	s_mov_b64 s[10:11], s[12:13]
	s_barrier
	s_cbranch_scc0 .LBB0_1462
; __device__ __forceinline__ unsigned pk2(float lo, float hi) { unsigned r; asm("v_cvt_pk_bf16_f32 %0, %1, %2" : "=v"(r) : "v"(lo), "v"(hi)); return r; }
;     __device__ __forceinline__ void operator()(const f32x4 (&acc)[2][2][4][2], const Unit& u, int wr, int wc, int fr, int fq) const {
;     ...
;         const int row_t = rmap == 1 ? odd_phys_row0(u.pm, grp) : (rmap == 2 ? odd_phys_row0(u.pm % (BG * TPB), u.pm / (BG * TPB)) : u.pm * BM);
;         int c = col_t + 64 * wc + 16 * fq;
;         if (mode == 2) c = (c >> 6) * 96 + (c & 63);
; #pragma unroll
;         for (int ai = 0; ai < 2; ++ai)
; #pragma unroll
;             for (int m = 0; m < 4; ++m) {
;                 const int row = row_t + ai * HALF + wr * 64 + m * 16 + fr;
;                 bf16_t* rp = O + (size_t)row * ldc + c;
; #pragma unroll
;                 for (int bj = 0; bj < 2; ++bj) {
;                     const f32x4 v0 = acc[ai][bj][m][0], v1 = acc[ai][bj][m][1];
;                     u32x4 o; o.x = pk2(v0[0], v0[1]); o.y = pk2(v0[2], v0[3]); o.z = pk2(v1[0], v1[1]); o.w = pk2(v1[2], v1[3]);
;                     *(u32x4*)(rp + 8 * bj) = o;
;                 }
;             }
	v_lshl_add_u32 v134, s77, 8, v138
	v_cvt_pk_bf16_f32 v68, v68, v69
	v_cvt_pk_bf16_f32 v69, v70, v71
	v_cvt_pk_bf16_f32 v70, v64, v65
	v_add_u32_e32 v64, 0x80, v134
	v_lshl_or_b32 v136, s15, 8, v140
	v_ashrrev_i32_e32 v135, 31, v134
	v_cvt_pk_bf16_f32 v112, v112, v113
	v_cvt_pk_bf16_f32 v113, v114, v115
	v_cvt_pk_bf16_f32 v114, v104, v105
	v_or_b32_e32 v104, 16, v134
	v_ashrrev_i32_e32 v65, 31, v64
	v_cvt_pk_bf16_f32 v48, v48, v49
	v_cvt_pk_bf16_f32 v49, v50, v51
	v_cvt_pk_bf16_f32 v50, v40, v41
	v_add_u32_e32 v40, 0x90, v134
	v_ashrrev_i32_e32 v137, 31, v136
	v_lshlrev_b64 v[142:143], 11, v[134:135]
	v_ashrrev_i32_e32 v105, 31, v104
	v_cvt_pk_bf16_f32 v96, v96, v97
	v_cvt_pk_bf16_f32 v97, v98, v99
	v_cvt_pk_bf16_f32 v98, v88, v89
	v_or_b32_e32 v88, 32, v134
	v_lshlrev_b64 v[64:65], 11, v[64:65]
	v_ashrrev_i32_e32 v41, 31, v40
	v_cvt_pk_bf16_f32 v32, v32, v33
	v_cvt_pk_bf16_f32 v33, v34, v35
	v_cvt_pk_bf16_f32 v34, v24, v25
	v_add_u32_e32 v24, 0xa0, v134
	v_lshl_add_u64 v[142:143], s[8:9], 0, v[142:143]
	v_lshlrev_b64 v[136:137], 1, v[136:137]
	v_lshlrev_b64 v[104:105], 11, v[104:105]
	v_ashrrev_i32_e32 v89, 31, v88
	v_cvt_pk_bf16_f32 v80, v80, v81
	v_cvt_pk_bf16_f32 v81, v82, v83
	v_cvt_pk_bf16_f32 v82, v72, v73
	v_or_b32_e32 v72, 48, v134
	v_lshl_add_u64 v[64:65], s[8:9], 0, v[64:65]
	v_lshlrev_b64 v[40:41], 11, v[40:41]
	v_ashrrev_i32_e32 v25, 31, v24
	v_cvt_pk_bf16_f32 v16, v16, v17
	v_cvt_pk_bf16_f32 v17, v18, v19
	v_cvt_pk_bf16_f32 v18, v8, v9
	v_add_u32_e32 v8, 0xb0, v134
	v_lshl_add_u64 v[142:143], v[142:143], 0, v[136:137]
	v_lshl_add_u64 v[104:105], s[8:9], 0, v[104:105]
	v_lshlrev_b64 v[88:89], 11, v[88:89]
	v_ashrrev_i32_e32 v73, 31, v72
	v_lshl_add_u64 v[64:65], v[64:65], 0, v[136:137]
	v_lshl_add_u64 v[40:41], s[8:9], 0, v[40:41]
	v_lshlrev_b64 v[24:25], 11, v[24:25]
	v_ashrrev_i32_e32 v9, 31, v8
	v_cvt_pk_bf16_f32 v115, v106, v107
	global_store_dwordx4 v[142:143], v[112:115], off offset:16
	v_lshl_add_u64 v[88:89], s[8:9], 0, v[88:89]
	v_lshlrev_b64 v[72:73], 11, v[72:73]
	v_lshl_add_u64 v[112:113], v[104:105], 0, v[136:137]
	v_cvt_pk_bf16_f32 v51, v42, v43
	global_store_dwordx4 v[64:65], v[48:51], off offset:16
	v_lshl_add_u64 v[24:25], s[8:9], 0, v[24:25]
	v_lshlrev_b64 v[8:9], 11, v[8:9]
	v_lshl_add_u64 v[48:49], v[40:41], 0, v[136:137]
	v_cvt_pk_bf16_f32 v99, v90, v91
	global_store_dwordx4 v[112:113], v[96:99], off offset:16
	v_lshl_add_u64 v[72:73], s[8:9], 0, v[72:73]
	v_cvt_pk_bf16_f32 v35, v26, v27
	global_store_dwordx4 v[48:49], v[32:35], off offset:16
	v_lshl_add_u64 v[96:97], v[88:89], 0, v[136:137]
	v_lshl_add_u64 v[8:9], s[8:9], 0, v[8:9]
	v_lshl_add_u64 v[32:33], v[24:25], 0, v[136:137]
	v_cvt_pk_bf16_f32 v83, v74, v75
	global_store_dwordx4 v[96:97], v[80:83], off offset:16
	v_cvt_pk_bf16_f32 v19, v10, v11
	global_store_dwordx4 v[32:33], v[16:19], off offset:16
	s_and_b64 vcc, exec, s[0:1]
	v_lshl_add_u64 v[80:81], v[72:73], 0, v[136:137]
	v_lshl_add_u64 v[16:17], v[8:9], 0, v[136:137]
	s_mov_b32 s15, s72
	s_mov_b32 s77, s76
	s_mov_b64 s[12:13], s[6:7]
	s_mov_b64 s[10:11], s[4:5]
	v_cvt_pk_bf16_f32 v124, v124, v125
	v_cvt_pk_bf16_f32 v125, v126, v127
	v_cvt_pk_bf16_f32 v126, v120, v121
	v_cvt_pk_bf16_f32 v127, v122, v123
	global_store_dwordx4 v[142:143], v[124:127], off
	v_cvt_pk_bf16_f32 v104, v116, v117
	v_cvt_pk_bf16_f32 v105, v118, v119
	v_cvt_pk_bf16_f32 v106, v108, v109
	v_cvt_pk_bf16_f32 v107, v110, v111
	global_store_dwordx4 v[112:113], v[104:107], off
	v_cvt_pk_bf16_f32 v88, v100, v101
	v_cvt_pk_bf16_f32 v89, v102, v103
	v_cvt_pk_bf16_f32 v90, v92, v93
	v_cvt_pk_bf16_f32 v91, v94, v95
	global_store_dwordx4 v[96:97], v[88:91], off
	v_cvt_pk_bf16_f32 v72, v84, v85
	v_cvt_pk_bf16_f32 v73, v86, v87
	v_cvt_pk_bf16_f32 v74, v76, v77
	v_cvt_pk_bf16_f32 v75, v78, v79
	global_store_dwordx4 v[80:81], v[72:75], off
	v_cvt_pk_bf16_f32 v71, v66, v67
	global_store_dwordx4 v[80:81], v[68:71], off offset:16
	v_cvt_pk_bf16_f32 v60, v60, v61
	v_cvt_pk_bf16_f32 v61, v62, v63
	v_cvt_pk_bf16_f32 v62, v56, v57
	v_cvt_pk_bf16_f32 v63, v58, v59
	global_store_dwordx4 v[64:65], v[60:63], off
	v_cvt_pk_bf16_f32 v40, v52, v53
	v_cvt_pk_bf16_f32 v41, v54, v55
	v_cvt_pk_bf16_f32 v42, v44, v45
	v_cvt_pk_bf16_f32 v43, v46, v47
	global_store_dwordx4 v[48:49], v[40:43], off
	v_cvt_pk_bf16_f32 v24, v36, v37
	v_cvt_pk_bf16_f32 v25, v38, v39
	v_cvt_pk_bf16_f32 v26, v28, v29
	v_cvt_pk_bf16_f32 v27, v30, v31
	global_store_dwordx4 v[32:33], v[24:27], off
	v_cvt_pk_bf16_f32 v8, v20, v21
	v_cvt_pk_bf16_f32 v9, v22, v23
	v_cvt_pk_bf16_f32 v10, v12, v13
	v_cvt_pk_bf16_f32 v11, v14, v15
	global_store_dwordx4 v[16:17], v[8:11], off
	v_cvt_pk_bf16_f32 v4, v4, v5
	v_cvt_pk_bf16_f32 v5, v6, v7
	v_cvt_pk_bf16_f32 v6, v0, v1
	v_cvt_pk_bf16_f32 v7, v2, v3
	global_store_dwordx4 v[16:17], v[4:7], off offset:16
	s_cbranch_vccz .LBB0_1455
	s_waitcnt vmcnt(0)
	s_cmpk_gt_u32 s23, 0xff
	s_cbranch_scc1 .LBB0_1466
	s_barrier
